# MFMA blocks keep priority 1 across both 16-MFMA halves (mid-block s_setprio 0/1 pair removed)
# speedup vs baseline: 1.0057x; 1.0041x over previous
.Lmy_nb_0:
	s_nop 0
	v_readfirstlane_b32 s86, v152
	v_readfirstlane_b32 s87, v153
	v_readfirstlane_b32 s88, v150
	v_readfirstlane_b32 s89, v151
	v_readfirstlane_b32 s90, v146
	v_readfirstlane_b32 s91, v147
	v_readfirstlane_b32 s92, v148
	v_readfirstlane_b32 s93, v149
	v_readfirstlane_b32 s100, v154
	v_readfirstlane_b32 s101, v138
	v_add_u32_e32 v230, s76, v141
	v_add_u32_e32 v231, s77, v141
	v_add_u32_e32 v232, 0x18000, v141
	v_add_u32_e32 v233, 0x1c000, v141
	s_add_u32 s98, s86, 0xfffc0080
	s_addc_u32 s99, s87, -1
	s_cmp_eq_u32 s7, s100
	s_cselect_b64 s[94:95], s[90:91], s[98:99]
	s_cselect_b64 s[96:97], s[92:93], s[88:89]
	s_add_i32 s51, s7, 2
	s_mov_b32 m0, s78
	ds_read_b128 v[164:167], v230
	global_load_lds_dwordx4 v144, s[86:87]
	s_mov_b32 m0, s79
	ds_read_b128 v[168:171], v230 offset:1024
	global_load_lds_dwordx4 v142, s[86:87]
	ds_read_b128 v[172:175], v230 offset:2048
	ds_read_b128 v[176:179], v230 offset:3072
	ds_read_b128 v[180:183], v231
	ds_read_b128 v[184:187], v231 offset:1024
	ds_read_b128 v[188:191], v231 offset:2048
	ds_read_b128 v[192:195], v231 offset:3072
	ds_read_b128 v[196:199], v160
	ds_read_b128 v[200:203], v160 offset:1024
	ds_read_b128 v[204:207], v160 offset:2048
	ds_read_b128 v[208:211], v160 offset:3072
	ds_read_b128 v[212:215], v160 offset:4096
	ds_read_b128 v[216:219], v160 offset:5120
	ds_read_b128 v[220:223], v160 offset:6144
	ds_read_b128 v[224:227], v160 offset:7168
	s_waitcnt vmcnt(8)
	s_waitcnt lgkmcnt(0)
	s_setprio 1
	s_barrier
	v_mfma_f32_16x16x32_bf16 v[122:125], v[164:167], v[196:199], 0
	v_mfma_f32_16x16x32_bf16 v[118:121], v[172:175], v[196:199], 0
	v_mfma_f32_16x16x32_bf16 v[110:113], v[164:167], v[204:207], 0
	v_mfma_f32_16x16x32_bf16 v[102:105], v[172:175], v[204:207], 0
	v_mfma_f32_16x16x32_bf16 v[94:97], v[164:167], v[212:215], 0
	v_mfma_f32_16x16x32_bf16 v[86:89], v[172:175], v[212:215], 0
	v_mfma_f32_16x16x32_bf16 v[78:81], v[164:167], v[220:223], 0
	v_mfma_f32_16x16x32_bf16 v[70:73], v[172:175], v[220:223], 0
	v_mfma_f32_16x16x32_bf16 v[122:125], v[168:171], v[200:203], v[122:125]
	v_mfma_f32_16x16x32_bf16 v[118:121], v[176:179], v[200:203], v[118:121]
	v_mfma_f32_16x16x32_bf16 v[110:113], v[168:171], v[208:211], v[110:113]
	v_mfma_f32_16x16x32_bf16 v[102:105], v[176:179], v[208:211], v[102:105]
	v_mfma_f32_16x16x32_bf16 v[94:97], v[168:171], v[216:219], v[94:97]
	v_mfma_f32_16x16x32_bf16 v[86:89], v[176:179], v[216:219], v[86:89]
	v_mfma_f32_16x16x32_bf16 v[78:81], v[168:171], v[224:227], v[78:81]
	v_mfma_f32_16x16x32_bf16 v[70:73], v[176:179], v[224:227], v[70:73]
	v_mfma_f32_16x16x32_bf16 v[126:129], v[180:183], v[196:199], 0
	v_mfma_f32_16x16x32_bf16 v[114:117], v[188:191], v[196:199], 0
	v_mfma_f32_16x16x32_bf16 v[106:109], v[180:183], v[204:207], 0
	v_mfma_f32_16x16x32_bf16 v[98:101], v[188:191], v[204:207], 0
	v_mfma_f32_16x16x32_bf16 v[90:93], v[180:183], v[212:215], 0
	v_mfma_f32_16x16x32_bf16 v[82:85], v[188:191], v[212:215], 0
	v_mfma_f32_16x16x32_bf16 v[74:77], v[180:183], v[220:223], 0
	v_mfma_f32_16x16x32_bf16 v[66:69], v[188:191], v[220:223], 0
	v_mfma_f32_16x16x32_bf16 v[126:129], v[184:187], v[200:203], v[126:129]
	v_mfma_f32_16x16x32_bf16 v[114:117], v[192:195], v[200:203], v[114:117]
	v_mfma_f32_16x16x32_bf16 v[106:109], v[184:187], v[208:211], v[106:109]
	v_mfma_f32_16x16x32_bf16 v[98:101], v[192:195], v[208:211], v[98:101]
	v_mfma_f32_16x16x32_bf16 v[90:93], v[184:187], v[216:219], v[90:93]
	v_mfma_f32_16x16x32_bf16 v[82:85], v[192:195], v[216:219], v[82:85]
	v_mfma_f32_16x16x32_bf16 v[74:77], v[184:187], v[224:227], v[74:77]
	v_mfma_f32_16x16x32_bf16 v[66:69], v[192:195], v[224:227], v[66:69]
	s_barrier
	s_setprio 0
	s_add_u32 s98, s96, 0x40000
	s_addc_u32 s99, s97, 0
	s_mov_b32 m0, s80
	ds_read_b128 v[196:199], v160 offset:16384
	global_load_lds_dwordx4 v132, s[96:97]
	s_mov_b32 m0, s81
	s_add_i32 s7, s77, s47
	global_load_lds_dwordx4 v136, s[96:97]
	s_mov_b32 m0, s7
	ds_read_b128 v[200:203], v160 offset:17408
	global_load_lds_dwordx4 v132, s[98:99]
	s_add_i32 m0, s7, 0x2000
	ds_read_b128 v[204:207], v160 offset:18432
	global_load_lds_dwordx4 v136, s[98:99]
	s_mov_b32 m0, s57
	ds_read_b128 v[208:211], v160 offset:19456
	global_load_lds_dwordx4 v130, s[94:95]
	s_mov_b32 m0, s62
	ds_read_b128 v[212:215], v160 offset:20480
	global_load_lds_dwordx4 v134, s[94:95]
	ds_read_b128 v[216:219], v160 offset:21504
	ds_read_b128 v[220:223], v160 offset:22528
	ds_read_b128 v[224:227], v160 offset:23552
	s_waitcnt vmcnt(8)
	s_waitcnt lgkmcnt(0)
	s_setprio 1
	s_barrier
	v_mfma_f32_16x16x32_bf16 v[62:65], v[164:167], v[196:199], 0
	v_mfma_f32_16x16x32_bf16 v[54:57], v[172:175], v[196:199], 0
	v_mfma_f32_16x16x32_bf16 v[46:49], v[164:167], v[204:207], 0
	v_mfma_f32_16x16x32_bf16 v[38:41], v[172:175], v[204:207], 0
	v_mfma_f32_16x16x32_bf16 v[30:33], v[164:167], v[212:215], 0
	v_mfma_f32_16x16x32_bf16 v[22:25], v[172:175], v[212:215], 0
	v_mfma_f32_16x16x32_bf16 v[14:17], v[164:167], v[220:223], 0
	v_mfma_f32_16x16x32_bf16 v[6:9], v[172:175], v[220:223], 0
	v_mfma_f32_16x16x32_bf16 v[62:65], v[168:171], v[200:203], v[62:65]
	v_mfma_f32_16x16x32_bf16 v[54:57], v[176:179], v[200:203], v[54:57]
	v_mfma_f32_16x16x32_bf16 v[46:49], v[168:171], v[208:211], v[46:49]
	v_mfma_f32_16x16x32_bf16 v[38:41], v[176:179], v[208:211], v[38:41]
	v_mfma_f32_16x16x32_bf16 v[30:33], v[168:171], v[216:219], v[30:33]
	v_mfma_f32_16x16x32_bf16 v[22:25], v[176:179], v[216:219], v[22:25]
	v_mfma_f32_16x16x32_bf16 v[14:17], v[168:171], v[224:227], v[14:17]
	v_mfma_f32_16x16x32_bf16 v[6:9], v[176:179], v[224:227], v[6:9]
	v_mfma_f32_16x16x32_bf16 v[58:61], v[180:183], v[196:199], 0
	v_mfma_f32_16x16x32_bf16 v[50:53], v[188:191], v[196:199], 0
	v_mfma_f32_16x16x32_bf16 v[42:45], v[180:183], v[204:207], 0
	v_mfma_f32_16x16x32_bf16 v[34:37], v[188:191], v[204:207], 0
	v_mfma_f32_16x16x32_bf16 v[26:29], v[180:183], v[212:215], 0
	v_mfma_f32_16x16x32_bf16 v[18:21], v[188:191], v[212:215], 0
	v_mfma_f32_16x16x32_bf16 v[10:13], v[180:183], v[220:223], 0
	v_mfma_f32_16x16x32_bf16 v[2:5], v[188:191], v[220:223], 0
	v_mfma_f32_16x16x32_bf16 v[58:61], v[184:187], v[200:203], v[58:61]
	v_mfma_f32_16x16x32_bf16 v[50:53], v[192:195], v[200:203], v[50:53]
	v_mfma_f32_16x16x32_bf16 v[42:45], v[184:187], v[208:211], v[42:45]
	v_mfma_f32_16x16x32_bf16 v[34:37], v[192:195], v[208:211], v[34:37]
	v_mfma_f32_16x16x32_bf16 v[26:29], v[184:187], v[216:219], v[26:29]
	v_mfma_f32_16x16x32_bf16 v[18:21], v[192:195], v[216:219], v[18:21]
	v_mfma_f32_16x16x32_bf16 v[10:13], v[184:187], v[224:227], v[10:13]
	v_mfma_f32_16x16x32_bf16 v[2:5], v[192:195], v[224:227], v[2:5]
	s_barrier
	s_setprio 0
	s_add_u32 s98, s94, 0x40000
	s_addc_u32 s99, s95, 0
	s_add_i32 s7, 0, 0x18000
	s_add_i32 s55, 0, 0x1c000
	s_mov_b32 m0, s63
	ds_read_b128 v[164:167], v232
	global_load_lds_dwordx4 v130, s[98:99]
	s_mov_b32 m0, s64
	ds_read_b128 v[168:171], v232 offset:1024
	global_load_lds_dwordx4 v134, s[98:99]
	ds_read_b128 v[172:175], v232 offset:2048
	ds_read_b128 v[176:179], v232 offset:3072
	ds_read_b128 v[180:183], v233
	ds_read_b128 v[184:187], v233 offset:1024
	ds_read_b128 v[188:191], v233 offset:2048
	ds_read_b128 v[192:195], v233 offset:3072
	ds_read_b128 v[196:199], v160 offset:32768
	ds_read_b128 v[200:203], v160 offset:33792
	ds_read_b128 v[204:207], v160 offset:34816
	ds_read_b128 v[208:211], v160 offset:35840
	ds_read_b128 v[212:215], v160 offset:36864
	ds_read_b128 v[216:219], v160 offset:37888
	ds_read_b128 v[220:223], v160 offset:38912
	ds_read_b128 v[224:227], v160 offset:39936
	s_waitcnt vmcnt(8)
	s_waitcnt lgkmcnt(0)
	s_setprio 1
	s_barrier
	v_mfma_f32_16x16x32_bf16 v[122:125], v[164:167], v[196:199], v[122:125]
	v_mfma_f32_16x16x32_bf16 v[118:121], v[172:175], v[196:199], v[118:121]
	v_mfma_f32_16x16x32_bf16 v[110:113], v[164:167], v[204:207], v[110:113]
	v_mfma_f32_16x16x32_bf16 v[102:105], v[172:175], v[204:207], v[102:105]
	v_mfma_f32_16x16x32_bf16 v[94:97], v[164:167], v[212:215], v[94:97]
	v_mfma_f32_16x16x32_bf16 v[86:89], v[172:175], v[212:215], v[86:89]
	v_mfma_f32_16x16x32_bf16 v[78:81], v[164:167], v[220:223], v[78:81]
	v_mfma_f32_16x16x32_bf16 v[70:73], v[172:175], v[220:223], v[70:73]
	v_mfma_f32_16x16x32_bf16 v[122:125], v[168:171], v[200:203], v[122:125]
	v_mfma_f32_16x16x32_bf16 v[118:121], v[176:179], v[200:203], v[118:121]
	v_mfma_f32_16x16x32_bf16 v[110:113], v[168:171], v[208:211], v[110:113]
	v_mfma_f32_16x16x32_bf16 v[102:105], v[176:179], v[208:211], v[102:105]
	v_mfma_f32_16x16x32_bf16 v[94:97], v[168:171], v[216:219], v[94:97]
	v_mfma_f32_16x16x32_bf16 v[86:89], v[176:179], v[216:219], v[86:89]
	v_mfma_f32_16x16x32_bf16 v[78:81], v[168:171], v[224:227], v[78:81]
	v_mfma_f32_16x16x32_bf16 v[70:73], v[176:179], v[224:227], v[70:73]
	v_mfma_f32_16x16x32_bf16 v[126:129], v[180:183], v[196:199], v[126:129]
	v_mfma_f32_16x16x32_bf16 v[114:117], v[188:191], v[196:199], v[114:117]
	v_mfma_f32_16x16x32_bf16 v[106:109], v[180:183], v[204:207], v[106:109]
	v_mfma_f32_16x16x32_bf16 v[98:101], v[188:191], v[204:207], v[98:101]
	v_mfma_f32_16x16x32_bf16 v[90:93], v[180:183], v[212:215], v[90:93]
	v_mfma_f32_16x16x32_bf16 v[82:85], v[188:191], v[212:215], v[82:85]
	v_mfma_f32_16x16x32_bf16 v[74:77], v[180:183], v[220:223], v[74:77]
	v_mfma_f32_16x16x32_bf16 v[66:69], v[188:191], v[220:223], v[66:69]
	v_mfma_f32_16x16x32_bf16 v[126:129], v[184:187], v[200:203], v[126:129]
	v_mfma_f32_16x16x32_bf16 v[114:117], v[192:195], v[200:203], v[114:117]
	v_mfma_f32_16x16x32_bf16 v[106:109], v[184:187], v[208:211], v[106:109]
	v_mfma_f32_16x16x32_bf16 v[98:101], v[192:195], v[208:211], v[98:101]
	v_mfma_f32_16x16x32_bf16 v[90:93], v[184:187], v[216:219], v[90:93]
	v_mfma_f32_16x16x32_bf16 v[82:85], v[192:195], v[216:219], v[82:85]
	v_mfma_f32_16x16x32_bf16 v[74:77], v[184:187], v[224:227], v[74:77]
	v_mfma_f32_16x16x32_bf16 v[66:69], v[192:195], v[224:227], v[66:69]
	s_barrier
	s_setprio 0
	s_add_u32 s96, s96, 0x80
	s_addc_u32 s97, s97, 0
	s_add_u32 s98, s96, 0x40000
	s_addc_u32 s99, s97, 0
	s_add_u32 s94, s94, 0x80
	s_addc_u32 s95, s95, 0
	s_add_i32 s7, s7, s47
	s_mov_b32 m0, s7
	ds_read_b128 v[196:199], v160 offset:49152
	global_load_lds_dwordx4 v132, s[96:97]
	s_add_i32 m0, s7, 0x2000
	s_add_i32 s7, s55, s47
	global_load_lds_dwordx4 v136, s[96:97]
	s_mov_b32 m0, s7
	ds_read_b128 v[200:203], v160 offset:50176
	global_load_lds_dwordx4 v132, s[98:99]
	s_add_i32 m0, s7, 0x2000
	ds_read_b128 v[204:207], v160 offset:51200
	global_load_lds_dwordx4 v136, s[98:99]
	s_mov_b32 m0, s65
	ds_read_b128 v[208:211], v160 offset:52224
	global_load_lds_dwordx4 v130, s[94:95]
	s_mov_b32 m0, s66
	ds_read_b128 v[212:215], v160 offset:53248
	global_load_lds_dwordx4 v134, s[94:95]
	ds_read_b128 v[216:219], v160 offset:54272
	ds_read_b128 v[220:223], v160 offset:55296
	ds_read_b128 v[224:227], v160 offset:56320
	s_waitcnt vmcnt(8)
	s_waitcnt lgkmcnt(0)
	s_setprio 1
	s_barrier
	v_mfma_f32_16x16x32_bf16 v[62:65], v[164:167], v[196:199], v[62:65]
	v_mfma_f32_16x16x32_bf16 v[54:57], v[172:175], v[196:199], v[54:57]
	v_mfma_f32_16x16x32_bf16 v[46:49], v[164:167], v[204:207], v[46:49]
	v_mfma_f32_16x16x32_bf16 v[38:41], v[172:175], v[204:207], v[38:41]
	v_mfma_f32_16x16x32_bf16 v[30:33], v[164:167], v[212:215], v[30:33]
	v_mfma_f32_16x16x32_bf16 v[22:25], v[172:175], v[212:215], v[22:25]
	v_mfma_f32_16x16x32_bf16 v[14:17], v[164:167], v[220:223], v[14:17]
	v_mfma_f32_16x16x32_bf16 v[6:9], v[172:175], v[220:223], v[6:9]
	v_mfma_f32_16x16x32_bf16 v[62:65], v[168:171], v[200:203], v[62:65]
	v_mfma_f32_16x16x32_bf16 v[54:57], v[176:179], v[200:203], v[54:57]
	v_mfma_f32_16x16x32_bf16 v[46:49], v[168:171], v[208:211], v[46:49]
	v_mfma_f32_16x16x32_bf16 v[38:41], v[176:179], v[208:211], v[38:41]
	v_mfma_f32_16x16x32_bf16 v[30:33], v[168:171], v[216:219], v[30:33]
	v_mfma_f32_16x16x32_bf16 v[22:25], v[176:179], v[216:219], v[22:25]
	v_mfma_f32_16x16x32_bf16 v[14:17], v[168:171], v[224:227], v[14:17]
	v_mfma_f32_16x16x32_bf16 v[6:9], v[176:179], v[224:227], v[6:9]
	v_mfma_f32_16x16x32_bf16 v[58:61], v[180:183], v[196:199], v[58:61]
	v_mfma_f32_16x16x32_bf16 v[50:53], v[188:191], v[196:199], v[50:53]
	v_mfma_f32_16x16x32_bf16 v[42:45], v[180:183], v[204:207], v[42:45]
	v_mfma_f32_16x16x32_bf16 v[34:37], v[188:191], v[204:207], v[34:37]
	v_mfma_f32_16x16x32_bf16 v[26:29], v[180:183], v[212:215], v[26:29]
	v_mfma_f32_16x16x32_bf16 v[18:21], v[188:191], v[212:215], v[18:21]
	v_mfma_f32_16x16x32_bf16 v[10:13], v[180:183], v[220:223], v[10:13]
	v_mfma_f32_16x16x32_bf16 v[2:5], v[188:191], v[220:223], v[2:5]
	v_mfma_f32_16x16x32_bf16 v[58:61], v[184:187], v[200:203], v[58:61]
	v_mfma_f32_16x16x32_bf16 v[50:53], v[192:195], v[200:203], v[50:53]
	v_mfma_f32_16x16x32_bf16 v[42:45], v[184:187], v[208:211], v[42:45]
	v_mfma_f32_16x16x32_bf16 v[34:37], v[192:195], v[208:211], v[34:37]
	v_mfma_f32_16x16x32_bf16 v[26:29], v[184:187], v[216:219], v[26:29]
	v_mfma_f32_16x16x32_bf16 v[18:21], v[192:195], v[216:219], v[18:21]
	v_mfma_f32_16x16x32_bf16 v[10:13], v[184:187], v[224:227], v[10:13]
	v_mfma_f32_16x16x32_bf16 v[2:5], v[192:195], v[224:227], v[2:5]
	s_barrier
	s_setprio 0
	s_mov_b32 s7, s51
	s_add_u32 s88, s88, 0x100
	s_addc_u32 s89, s89, 0
	s_add_u32 s86, s86, 0x100
	s_addc_u32 s87, s87, 0
	s_cmp_ge_i32 s51, s101
	s_cbranch_scc1 .Lmy_kexit_0
.LBB0_171:
	s_add_u32 s98, s86, 0xfffc0080
	s_addc_u32 s99, s87, -1
	s_cmp_eq_u32 s7, s100
	s_cselect_b64 s[94:95], s[90:91], s[98:99]
	s_cselect_b64 s[96:97], s[92:93], s[88:89]
	s_add_i32 s51, s7, 2
	s_mov_b32 m0, s78
	ds_read_b128 v[164:167], v230
	global_load_lds_dwordx4 v144, s[86:87]
	s_mov_b32 m0, s79
	ds_read_b128 v[168:171], v230 offset:1024
	global_load_lds_dwordx4 v142, s[86:87]
	ds_read_b128 v[172:175], v230 offset:2048
	ds_read_b128 v[176:179], v230 offset:3072
	ds_read_b128 v[180:183], v231
	ds_read_b128 v[184:187], v231 offset:1024
	ds_read_b128 v[188:191], v231 offset:2048
	ds_read_b128 v[192:195], v231 offset:3072
	ds_read_b128 v[196:199], v160
	ds_read_b128 v[200:203], v160 offset:1024
	ds_read_b128 v[204:207], v160 offset:2048
	ds_read_b128 v[208:211], v160 offset:3072
	ds_read_b128 v[212:215], v160 offset:4096
	ds_read_b128 v[216:219], v160 offset:5120
	ds_read_b128 v[220:223], v160 offset:6144
	ds_read_b128 v[224:227], v160 offset:7168
	s_waitcnt vmcnt(8)
	s_waitcnt lgkmcnt(0)
	s_setprio 1
	s_barrier
	v_mfma_f32_16x16x32_bf16 v[122:125], v[164:167], v[196:199], v[122:125]
	v_mfma_f32_16x16x32_bf16 v[118:121], v[172:175], v[196:199], v[118:121]
	v_mfma_f32_16x16x32_bf16 v[110:113], v[164:167], v[204:207], v[110:113]
	v_mfma_f32_16x16x32_bf16 v[102:105], v[172:175], v[204:207], v[102:105]
	v_mfma_f32_16x16x32_bf16 v[94:97], v[164:167], v[212:215], v[94:97]
	v_mfma_f32_16x16x32_bf16 v[86:89], v[172:175], v[212:215], v[86:89]
	v_mfma_f32_16x16x32_bf16 v[78:81], v[164:167], v[220:223], v[78:81]
	v_mfma_f32_16x16x32_bf16 v[70:73], v[172:175], v[220:223], v[70:73]
	v_mfma_f32_16x16x32_bf16 v[122:125], v[168:171], v[200:203], v[122:125]
	v_mfma_f32_16x16x32_bf16 v[118:121], v[176:179], v[200:203], v[118:121]
	v_mfma_f32_16x16x32_bf16 v[110:113], v[168:171], v[208:211], v[110:113]
	v_mfma_f32_16x16x32_bf16 v[102:105], v[176:179], v[208:211], v[102:105]
	v_mfma_f32_16x16x32_bf16 v[94:97], v[168:171], v[216:219], v[94:97]
	v_mfma_f32_16x16x32_bf16 v[86:89], v[176:179], v[216:219], v[86:89]
	v_mfma_f32_16x16x32_bf16 v[78:81], v[168:171], v[224:227], v[78:81]
	v_mfma_f32_16x16x32_bf16 v[70:73], v[176:179], v[224:227], v[70:73]
	v_mfma_f32_16x16x32_bf16 v[126:129], v[180:183], v[196:199], v[126:129]
	v_mfma_f32_16x16x32_bf16 v[114:117], v[188:191], v[196:199], v[114:117]
	v_mfma_f32_16x16x32_bf16 v[106:109], v[180:183], v[204:207], v[106:109]
	v_mfma_f32_16x16x32_bf16 v[98:101], v[188:191], v[204:207], v[98:101]
	v_mfma_f32_16x16x32_bf16 v[90:93], v[180:183], v[212:215], v[90:93]
	v_mfma_f32_16x16x32_bf16 v[82:85], v[188:191], v[212:215], v[82:85]
	v_mfma_f32_16x16x32_bf16 v[74:77], v[180:183], v[220:223], v[74:77]
	v_mfma_f32_16x16x32_bf16 v[66:69], v[188:191], v[220:223], v[66:69]
	v_mfma_f32_16x16x32_bf16 v[126:129], v[184:187], v[200:203], v[126:129]
	v_mfma_f32_16x16x32_bf16 v[114:117], v[192:195], v[200:203], v[114:117]
	v_mfma_f32_16x16x32_bf16 v[106:109], v[184:187], v[208:211], v[106:109]
	v_mfma_f32_16x16x32_bf16 v[98:101], v[192:195], v[208:211], v[98:101]
	v_mfma_f32_16x16x32_bf16 v[90:93], v[184:187], v[216:219], v[90:93]
	v_mfma_f32_16x16x32_bf16 v[82:85], v[192:195], v[216:219], v[82:85]
	v_mfma_f32_16x16x32_bf16 v[74:77], v[184:187], v[224:227], v[74:77]
	v_mfma_f32_16x16x32_bf16 v[66:69], v[192:195], v[224:227], v[66:69]
	s_barrier
	s_setprio 0
	s_add_u32 s98, s96, 0x40000
	s_addc_u32 s99, s97, 0
	s_mov_b32 m0, s80
	ds_read_b128 v[196:199], v160 offset:16384
	global_load_lds_dwordx4 v132, s[96:97]
	s_mov_b32 m0, s81
	s_add_i32 s7, s77, s47
	global_load_lds_dwordx4 v136, s[96:97]
	s_mov_b32 m0, s7
	ds_read_b128 v[200:203], v160 offset:17408
	global_load_lds_dwordx4 v132, s[98:99]
	s_add_i32 m0, s7, 0x2000
	ds_read_b128 v[204:207], v160 offset:18432
	global_load_lds_dwordx4 v136, s[98:99]
	s_mov_b32 m0, s57
	ds_read_b128 v[208:211], v160 offset:19456
	global_load_lds_dwordx4 v130, s[94:95]
	s_mov_b32 m0, s62
	ds_read_b128 v[212:215], v160 offset:20480
	global_load_lds_dwordx4 v134, s[94:95]
	ds_read_b128 v[216:219], v160 offset:21504
	ds_read_b128 v[220:223], v160 offset:22528
	ds_read_b128 v[224:227], v160 offset:23552
	s_waitcnt vmcnt(8)
	s_waitcnt lgkmcnt(0)
	s_setprio 1
	s_barrier
	v_mfma_f32_16x16x32_bf16 v[62:65], v[164:167], v[196:199], v[62:65]
	v_mfma_f32_16x16x32_bf16 v[54:57], v[172:175], v[196:199], v[54:57]
	v_mfma_f32_16x16x32_bf16 v[46:49], v[164:167], v[204:207], v[46:49]
	v_mfma_f32_16x16x32_bf16 v[38:41], v[172:175], v[204:207], v[38:41]
	v_mfma_f32_16x16x32_bf16 v[30:33], v[164:167], v[212:215], v[30:33]
	v_mfma_f32_16x16x32_bf16 v[22:25], v[172:175], v[212:215], v[22:25]
	v_mfma_f32_16x16x32_bf16 v[14:17], v[164:167], v[220:223], v[14:17]
	v_mfma_f32_16x16x32_bf16 v[6:9], v[172:175], v[220:223], v[6:9]
	v_mfma_f32_16x16x32_bf16 v[62:65], v[168:171], v[200:203], v[62:65]
	v_mfma_f32_16x16x32_bf16 v[54:57], v[176:179], v[200:203], v[54:57]
	v_mfma_f32_16x16x32_bf16 v[46:49], v[168:171], v[208:211], v[46:49]
	v_mfma_f32_16x16x32_bf16 v[38:41], v[176:179], v[208:211], v[38:41]
	v_mfma_f32_16x16x32_bf16 v[30:33], v[168:171], v[216:219], v[30:33]
	v_mfma_f32_16x16x32_bf16 v[22:25], v[176:179], v[216:219], v[22:25]
	v_mfma_f32_16x16x32_bf16 v[14:17], v[168:171], v[224:227], v[14:17]
	v_mfma_f32_16x16x32_bf16 v[6:9], v[176:179], v[224:227], v[6:9]
	v_mfma_f32_16x16x32_bf16 v[58:61], v[180:183], v[196:199], v[58:61]
	v_mfma_f32_16x16x32_bf16 v[50:53], v[188:191], v[196:199], v[50:53]
	v_mfma_f32_16x16x32_bf16 v[42:45], v[180:183], v[204:207], v[42:45]
	v_mfma_f32_16x16x32_bf16 v[34:37], v[188:191], v[204:207], v[34:37]
	v_mfma_f32_16x16x32_bf16 v[26:29], v[180:183], v[212:215], v[26:29]
	v_mfma_f32_16x16x32_bf16 v[18:21], v[188:191], v[212:215], v[18:21]
	v_mfma_f32_16x16x32_bf16 v[10:13], v[180:183], v[220:223], v[10:13]
	v_mfma_f32_16x16x32_bf16 v[2:5], v[188:191], v[220:223], v[2:5]
	v_mfma_f32_16x16x32_bf16 v[58:61], v[184:187], v[200:203], v[58:61]
	v_mfma_f32_16x16x32_bf16 v[50:53], v[192:195], v[200:203], v[50:53]
	v_mfma_f32_16x16x32_bf16 v[42:45], v[184:187], v[208:211], v[42:45]
	v_mfma_f32_16x16x32_bf16 v[34:37], v[192:195], v[208:211], v[34:37]
	v_mfma_f32_16x16x32_bf16 v[26:29], v[184:187], v[216:219], v[26:29]
	v_mfma_f32_16x16x32_bf16 v[18:21], v[192:195], v[216:219], v[18:21]
	v_mfma_f32_16x16x32_bf16 v[10:13], v[184:187], v[224:227], v[10:13]
	v_mfma_f32_16x16x32_bf16 v[2:5], v[192:195], v[224:227], v[2:5]
	s_barrier
	s_setprio 0
	s_add_u32 s98, s94, 0x40000
	s_addc_u32 s99, s95, 0
	s_add_i32 s7, 0, 0x18000
	s_add_i32 s55, 0, 0x1c000
	s_mov_b32 m0, s63
	ds_read_b128 v[164:167], v232
	global_load_lds_dwordx4 v130, s[98:99]
	s_mov_b32 m0, s64
	ds_read_b128 v[168:171], v232 offset:1024
	global_load_lds_dwordx4 v134, s[98:99]
	ds_read_b128 v[172:175], v232 offset:2048
	ds_read_b128 v[176:179], v232 offset:3072
	ds_read_b128 v[180:183], v233
	ds_read_b128 v[184:187], v233 offset:1024
	ds_read_b128 v[188:191], v233 offset:2048
	ds_read_b128 v[192:195], v233 offset:3072
	ds_read_b128 v[196:199], v160 offset:32768
	ds_read_b128 v[200:203], v160 offset:33792
	ds_read_b128 v[204:207], v160 offset:34816
	ds_read_b128 v[208:211], v160 offset:35840
	ds_read_b128 v[212:215], v160 offset:36864
	ds_read_b128 v[216:219], v160 offset:37888
	ds_read_b128 v[220:223], v160 offset:38912
	ds_read_b128 v[224:227], v160 offset:39936
	s_waitcnt vmcnt(8)
	s_waitcnt lgkmcnt(0)
	s_setprio 1
	s_barrier
	v_mfma_f32_16x16x32_bf16 v[122:125], v[164:167], v[196:199], v[122:125]
	v_mfma_f32_16x16x32_bf16 v[118:121], v[172:175], v[196:199], v[118:121]
	v_mfma_f32_16x16x32_bf16 v[110:113], v[164:167], v[204:207], v[110:113]
	v_mfma_f32_16x16x32_bf16 v[102:105], v[172:175], v[204:207], v[102:105]
	v_mfma_f32_16x16x32_bf16 v[94:97], v[164:167], v[212:215], v[94:97]
	v_mfma_f32_16x16x32_bf16 v[86:89], v[172:175], v[212:215], v[86:89]
	v_mfma_f32_16x16x32_bf16 v[78:81], v[164:167], v[220:223], v[78:81]
	v_mfma_f32_16x16x32_bf16 v[70:73], v[172:175], v[220:223], v[70:73]
	v_mfma_f32_16x16x32_bf16 v[122:125], v[168:171], v[200:203], v[122:125]
	v_mfma_f32_16x16x32_bf16 v[118:121], v[176:179], v[200:203], v[118:121]
	v_mfma_f32_16x16x32_bf16 v[110:113], v[168:171], v[208:211], v[110:113]
	v_mfma_f32_16x16x32_bf16 v[102:105], v[176:179], v[208:211], v[102:105]
	v_mfma_f32_16x16x32_bf16 v[94:97], v[168:171], v[216:219], v[94:97]
	v_mfma_f32_16x16x32_bf16 v[86:89], v[176:179], v[216:219], v[86:89]
	v_mfma_f32_16x16x32_bf16 v[78:81], v[168:171], v[224:227], v[78:81]
	v_mfma_f32_16x16x32_bf16 v[70:73], v[176:179], v[224:227], v[70:73]
	v_mfma_f32_16x16x32_bf16 v[126:129], v[180:183], v[196:199], v[126:129]
	v_mfma_f32_16x16x32_bf16 v[114:117], v[188:191], v[196:199], v[114:117]
	v_mfma_f32_16x16x32_bf16 v[106:109], v[180:183], v[204:207], v[106:109]
	v_mfma_f32_16x16x32_bf16 v[98:101], v[188:191], v[204:207], v[98:101]
	v_mfma_f32_16x16x32_bf16 v[90:93], v[180:183], v[212:215], v[90:93]
	v_mfma_f32_16x16x32_bf16 v[82:85], v[188:191], v[212:215], v[82:85]
	v_mfma_f32_16x16x32_bf16 v[74:77], v[180:183], v[220:223], v[74:77]
	v_mfma_f32_16x16x32_bf16 v[66:69], v[188:191], v[220:223], v[66:69]
	v_mfma_f32_16x16x32_bf16 v[126:129], v[184:187], v[200:203], v[126:129]
	v_mfma_f32_16x16x32_bf16 v[114:117], v[192:195], v[200:203], v[114:117]
	v_mfma_f32_16x16x32_bf16 v[106:109], v[184:187], v[208:211], v[106:109]
	v_mfma_f32_16x16x32_bf16 v[98:101], v[192:195], v[208:211], v[98:101]
	v_mfma_f32_16x16x32_bf16 v[90:93], v[184:187], v[216:219], v[90:93]
	v_mfma_f32_16x16x32_bf16 v[82:85], v[192:195], v[216:219], v[82:85]
	v_mfma_f32_16x16x32_bf16 v[74:77], v[184:187], v[224:227], v[74:77]
	v_mfma_f32_16x16x32_bf16 v[66:69], v[192:195], v[224:227], v[66:69]
	s_barrier
	s_setprio 0
	s_add_u32 s96, s96, 0x80
	s_addc_u32 s97, s97, 0
	s_add_u32 s98, s96, 0x40000
	s_addc_u32 s99, s97, 0
	s_add_u32 s94, s94, 0x80
	s_addc_u32 s95, s95, 0
	s_add_i32 s7, s7, s47
	s_mov_b32 m0, s7
	ds_read_b128 v[196:199], v160 offset:49152
	global_load_lds_dwordx4 v132, s[96:97]
	s_add_i32 m0, s7, 0x2000
	s_add_i32 s7, s55, s47
	global_load_lds_dwordx4 v136, s[96:97]
	s_mov_b32 m0, s7
	ds_read_b128 v[200:203], v160 offset:50176
	global_load_lds_dwordx4 v132, s[98:99]
	s_add_i32 m0, s7, 0x2000
	ds_read_b128 v[204:207], v160 offset:51200
	global_load_lds_dwordx4 v136, s[98:99]
	s_mov_b32 m0, s65
	ds_read_b128 v[208:211], v160 offset:52224
	global_load_lds_dwordx4 v130, s[94:95]
	s_mov_b32 m0, s66
	ds_read_b128 v[212:215], v160 offset:53248
	global_load_lds_dwordx4 v134, s[94:95]
	ds_read_b128 v[216:219], v160 offset:54272
	ds_read_b128 v[220:223], v160 offset:55296
	ds_read_b128 v[224:227], v160 offset:56320
	s_waitcnt vmcnt(8)
	s_waitcnt lgkmcnt(0)
	s_setprio 1
	s_barrier
	v_mfma_f32_16x16x32_bf16 v[62:65], v[164:167], v[196:199], v[62:65]
	v_mfma_f32_16x16x32_bf16 v[54:57], v[172:175], v[196:199], v[54:57]
	v_mfma_f32_16x16x32_bf16 v[46:49], v[164:167], v[204:207], v[46:49]
	v_mfma_f32_16x16x32_bf16 v[38:41], v[172:175], v[204:207], v[38:41]
	v_mfma_f32_16x16x32_bf16 v[30:33], v[164:167], v[212:215], v[30:33]
	v_mfma_f32_16x16x32_bf16 v[22:25], v[172:175], v[212:215], v[22:25]
	v_mfma_f32_16x16x32_bf16 v[14:17], v[164:167], v[220:223], v[14:17]
	v_mfma_f32_16x16x32_bf16 v[6:9], v[172:175], v[220:223], v[6:9]
	v_mfma_f32_16x16x32_bf16 v[62:65], v[168:171], v[200:203], v[62:65]
	v_mfma_f32_16x16x32_bf16 v[54:57], v[176:179], v[200:203], v[54:57]
	v_mfma_f32_16x16x32_bf16 v[46:49], v[168:171], v[208:211], v[46:49]
	v_mfma_f32_16x16x32_bf16 v[38:41], v[176:179], v[208:211], v[38:41]
	v_mfma_f32_16x16x32_bf16 v[30:33], v[168:171], v[216:219], v[30:33]
	v_mfma_f32_16x16x32_bf16 v[22:25], v[176:179], v[216:219], v[22:25]
	v_mfma_f32_16x16x32_bf16 v[14:17], v[168:171], v[224:227], v[14:17]
	v_mfma_f32_16x16x32_bf16 v[6:9], v[176:179], v[224:227], v[6:9]
	v_mfma_f32_16x16x32_bf16 v[58:61], v[180:183], v[196:199], v[58:61]
	v_mfma_f32_16x16x32_bf16 v[50:53], v[188:191], v[196:199], v[50:53]
	v_mfma_f32_16x16x32_bf16 v[42:45], v[180:183], v[204:207], v[42:45]
	v_mfma_f32_16x16x32_bf16 v[34:37], v[188:191], v[204:207], v[34:37]
	v_mfma_f32_16x16x32_bf16 v[26:29], v[180:183], v[212:215], v[26:29]
	v_mfma_f32_16x16x32_bf16 v[18:21], v[188:191], v[212:215], v[18:21]
	v_mfma_f32_16x16x32_bf16 v[10:13], v[180:183], v[220:223], v[10:13]
	v_mfma_f32_16x16x32_bf16 v[2:5], v[188:191], v[220:223], v[2:5]
	v_mfma_f32_16x16x32_bf16 v[58:61], v[184:187], v[200:203], v[58:61]
	v_mfma_f32_16x16x32_bf16 v[50:53], v[192:195], v[200:203], v[50:53]
	v_mfma_f32_16x16x32_bf16 v[42:45], v[184:187], v[208:211], v[42:45]
	v_mfma_f32_16x16x32_bf16 v[34:37], v[192:195], v[208:211], v[34:37]
	v_mfma_f32_16x16x32_bf16 v[26:29], v[184:187], v[216:219], v[26:29]
	v_mfma_f32_16x16x32_bf16 v[18:21], v[192:195], v[216:219], v[18:21]
	v_mfma_f32_16x16x32_bf16 v[10:13], v[184:187], v[224:227], v[10:13]
	v_mfma_f32_16x16x32_bf16 v[2:5], v[192:195], v[224:227], v[2:5]
	s_barrier
	s_setprio 0
	s_mov_b32 s7, s51
	s_add_u32 s88, s88, 0x100
	s_addc_u32 s89, s89, 0
	s_add_u32 s86, s86, 0x100
	s_addc_u32 s87, s87, 0
	s_cmp_ge_i32 s51, s101
	s_cbranch_scc0 .LBB0_171

.Lmy_nb_1:
	s_nop 0
	v_readfirstlane_b32 s86, v152
	v_readfirstlane_b32 s87, v153
	v_readfirstlane_b32 s88, v154
	v_readfirstlane_b32 s89, v155
	v_readfirstlane_b32 s90, v148
	v_readfirstlane_b32 s91, v149
	v_readfirstlane_b32 s92, v150
	v_readfirstlane_b32 s93, v151
	v_readfirstlane_b32 s100, v138
	v_readfirstlane_b32 s101, v141
	v_add_u32_e32 v230, s69, v160
	v_add_u32_e32 v231, s72, v160
	v_add_u32_e32 v232, 0x18000, v160
	v_add_u32_e32 v233, 0x1c000, v160
	s_add_u32 s98, s86, 0x100
	s_addc_u32 s99, s87, 0
	s_cmp_eq_u32 s8, s100
	s_cselect_b64 s[94:95], s[90:91], s[98:99]
	s_cselect_b64 s[96:97], s[92:93], s[88:89]
	s_add_i32 s9, s8, 2
	s_add_i32 m0, s55, 0xc000
	ds_read_b128 v[166:169], v230
	global_load_lds_dwordx4 v144, s[86:87]
	s_add_i32 m0, s55, 0xe000
	ds_read_b128 v[170:173], v230 offset:1024
	global_load_lds_dwordx4 v142, s[86:87]
	ds_read_b128 v[174:177], v230 offset:2048
	ds_read_b128 v[178:181], v230 offset:3072
	ds_read_b128 v[182:185], v231
	ds_read_b128 v[186:189], v231 offset:1024
	ds_read_b128 v[190:193], v231 offset:2048
	ds_read_b128 v[194:197], v231 offset:3072
	ds_read_b128 v[198:201], v163
	ds_read_b128 v[202:205], v163 offset:1024
	ds_read_b128 v[206:209], v163 offset:2048
	ds_read_b128 v[210:213], v163 offset:3072
	ds_read_b128 v[214:217], v163 offset:4096
	ds_read_b128 v[218:221], v163 offset:5120
	ds_read_b128 v[222:225], v163 offset:6144
	ds_read_b128 v[226:229], v163 offset:7168
	s_waitcnt vmcnt(8)
	s_waitcnt lgkmcnt(0)
	s_setprio 1
	s_barrier
	v_mfma_f32_16x16x32_bf16 v[122:125], v[166:169], v[198:201], 0
	v_mfma_f32_16x16x32_bf16 v[118:121], v[174:177], v[198:201], 0
	v_mfma_f32_16x16x32_bf16 v[110:113], v[166:169], v[206:209], 0
	v_mfma_f32_16x16x32_bf16 v[102:105], v[174:177], v[206:209], 0
	v_mfma_f32_16x16x32_bf16 v[94:97], v[166:169], v[214:217], 0
	v_mfma_f32_16x16x32_bf16 v[86:89], v[174:177], v[214:217], 0
	v_mfma_f32_16x16x32_bf16 v[78:81], v[166:169], v[222:225], 0
	v_mfma_f32_16x16x32_bf16 v[70:73], v[174:177], v[222:225], 0
	v_mfma_f32_16x16x32_bf16 v[122:125], v[170:173], v[202:205], v[122:125]
	v_mfma_f32_16x16x32_bf16 v[118:121], v[178:181], v[202:205], v[118:121]
	v_mfma_f32_16x16x32_bf16 v[110:113], v[170:173], v[210:213], v[110:113]
	v_mfma_f32_16x16x32_bf16 v[102:105], v[178:181], v[210:213], v[102:105]
	v_mfma_f32_16x16x32_bf16 v[94:97], v[170:173], v[218:221], v[94:97]
	v_mfma_f32_16x16x32_bf16 v[86:89], v[178:181], v[218:221], v[86:89]
	v_mfma_f32_16x16x32_bf16 v[78:81], v[170:173], v[226:229], v[78:81]
	v_mfma_f32_16x16x32_bf16 v[70:73], v[178:181], v[226:229], v[70:73]
	v_mfma_f32_16x16x32_bf16 v[126:129], v[182:185], v[198:201], 0
	v_mfma_f32_16x16x32_bf16 v[114:117], v[190:193], v[198:201], 0
	v_mfma_f32_16x16x32_bf16 v[106:109], v[182:185], v[206:209], 0
	v_mfma_f32_16x16x32_bf16 v[98:101], v[190:193], v[206:209], 0
	v_mfma_f32_16x16x32_bf16 v[90:93], v[182:185], v[214:217], 0
	v_mfma_f32_16x16x32_bf16 v[82:85], v[190:193], v[214:217], 0
	v_mfma_f32_16x16x32_bf16 v[74:77], v[182:185], v[222:225], 0
	v_mfma_f32_16x16x32_bf16 v[66:69], v[190:193], v[222:225], 0
	v_mfma_f32_16x16x32_bf16 v[126:129], v[186:189], v[202:205], v[126:129]
	v_mfma_f32_16x16x32_bf16 v[114:117], v[194:197], v[202:205], v[114:117]
	v_mfma_f32_16x16x32_bf16 v[106:109], v[186:189], v[210:213], v[106:109]
	v_mfma_f32_16x16x32_bf16 v[98:101], v[194:197], v[210:213], v[98:101]
	v_mfma_f32_16x16x32_bf16 v[90:93], v[186:189], v[218:221], v[90:93]
	v_mfma_f32_16x16x32_bf16 v[82:85], v[194:197], v[218:221], v[82:85]
	v_mfma_f32_16x16x32_bf16 v[74:77], v[186:189], v[226:229], v[74:77]
	v_mfma_f32_16x16x32_bf16 v[66:69], v[194:197], v[226:229], v[66:69]
	s_barrier
	s_setprio 0
	s_add_u32 s98, s96, 0xb0000
	s_addc_u32 s99, s97, 0
	s_add_i32 s8, s69, s54
	s_mov_b32 m0, s8
	ds_read_b128 v[198:201], v163 offset:16384
	global_load_lds_dwordx4 v132, s[96:97]
	s_add_i32 m0, s8, 0x2000
	s_add_i32 s8, s72, s54
	global_load_lds_dwordx4 v136, s[96:97]
	s_mov_b32 m0, s8
	ds_read_b128 v[202:205], v163 offset:17408
	global_load_lds_dwordx4 v132, s[98:99]
	s_add_i32 m0, s8, 0x2000
	ds_read_b128 v[206:209], v163 offset:18432
	global_load_lds_dwordx4 v136, s[98:99]
	s_mov_b32 m0, s55
	ds_read_b128 v[210:213], v163 offset:19456
	global_load_lds_dwordx4 v130, s[94:95]
	s_mov_b32 m0, s56
	ds_read_b128 v[214:217], v163 offset:20480
	global_load_lds_dwordx4 v134, s[94:95]
	ds_read_b128 v[218:221], v163 offset:21504
	ds_read_b128 v[222:225], v163 offset:22528
	ds_read_b128 v[226:229], v163 offset:23552
	s_waitcnt vmcnt(8)
	s_waitcnt lgkmcnt(0)
	s_setprio 1
	s_barrier
	v_mfma_f32_16x16x32_bf16 v[62:65], v[166:169], v[198:201], 0
	v_mfma_f32_16x16x32_bf16 v[54:57], v[174:177], v[198:201], 0
	v_mfma_f32_16x16x32_bf16 v[46:49], v[166:169], v[206:209], 0
	v_mfma_f32_16x16x32_bf16 v[38:41], v[174:177], v[206:209], 0
	v_mfma_f32_16x16x32_bf16 v[30:33], v[166:169], v[214:217], 0
	v_mfma_f32_16x16x32_bf16 v[22:25], v[174:177], v[214:217], 0
	v_mfma_f32_16x16x32_bf16 v[14:17], v[166:169], v[222:225], 0
	v_mfma_f32_16x16x32_bf16 v[6:9], v[174:177], v[222:225], 0
	v_mfma_f32_16x16x32_bf16 v[62:65], v[170:173], v[202:205], v[62:65]
	v_mfma_f32_16x16x32_bf16 v[54:57], v[178:181], v[202:205], v[54:57]
	v_mfma_f32_16x16x32_bf16 v[46:49], v[170:173], v[210:213], v[46:49]
	v_mfma_f32_16x16x32_bf16 v[38:41], v[178:181], v[210:213], v[38:41]
	v_mfma_f32_16x16x32_bf16 v[30:33], v[170:173], v[218:221], v[30:33]
	v_mfma_f32_16x16x32_bf16 v[22:25], v[178:181], v[218:221], v[22:25]
	v_mfma_f32_16x16x32_bf16 v[14:17], v[170:173], v[226:229], v[14:17]
	v_mfma_f32_16x16x32_bf16 v[6:9], v[178:181], v[226:229], v[6:9]
	v_mfma_f32_16x16x32_bf16 v[58:61], v[182:185], v[198:201], 0
	v_mfma_f32_16x16x32_bf16 v[50:53], v[190:193], v[198:201], 0
	v_mfma_f32_16x16x32_bf16 v[42:45], v[182:185], v[206:209], 0
	v_mfma_f32_16x16x32_bf16 v[34:37], v[190:193], v[206:209], 0
	v_mfma_f32_16x16x32_bf16 v[26:29], v[182:185], v[214:217], 0
	v_mfma_f32_16x16x32_bf16 v[18:21], v[190:193], v[214:217], 0
	v_mfma_f32_16x16x32_bf16 v[10:13], v[182:185], v[222:225], 0
	v_mfma_f32_16x16x32_bf16 v[2:5], v[190:193], v[222:225], 0
	v_mfma_f32_16x16x32_bf16 v[58:61], v[186:189], v[202:205], v[58:61]
	v_mfma_f32_16x16x32_bf16 v[50:53], v[194:197], v[202:205], v[50:53]
	v_mfma_f32_16x16x32_bf16 v[42:45], v[186:189], v[210:213], v[42:45]
	v_mfma_f32_16x16x32_bf16 v[34:37], v[194:197], v[210:213], v[34:37]
	v_mfma_f32_16x16x32_bf16 v[26:29], v[186:189], v[218:221], v[26:29]
	v_mfma_f32_16x16x32_bf16 v[18:21], v[194:197], v[218:221], v[18:21]
	v_mfma_f32_16x16x32_bf16 v[10:13], v[186:189], v[226:229], v[10:13]
	v_mfma_f32_16x16x32_bf16 v[2:5], v[194:197], v[226:229], v[2:5]
	s_barrier
	s_setprio 0
	s_add_u32 s98, s94, 0xb0000
	s_addc_u32 s99, s95, 0
	s_add_i32 s8, 0, 0x18000
	s_add_i32 s50, 0, 0x1c000
	s_mov_b32 m0, s57
	ds_read_b128 v[166:169], v232
	global_load_lds_dwordx4 v130, s[98:99]
	s_mov_b32 m0, s58
	ds_read_b128 v[170:173], v232 offset:1024
	global_load_lds_dwordx4 v134, s[98:99]
	ds_read_b128 v[174:177], v232 offset:2048
	ds_read_b128 v[178:181], v232 offset:3072
	ds_read_b128 v[182:185], v233
	ds_read_b128 v[186:189], v233 offset:1024
	ds_read_b128 v[190:193], v233 offset:2048
	ds_read_b128 v[194:197], v233 offset:3072
	ds_read_b128 v[198:201], v163 offset:32768
	ds_read_b128 v[202:205], v163 offset:33792
	ds_read_b128 v[206:209], v163 offset:34816
	ds_read_b128 v[210:213], v163 offset:35840
	ds_read_b128 v[214:217], v163 offset:36864
	ds_read_b128 v[218:221], v163 offset:37888
	ds_read_b128 v[222:225], v163 offset:38912
	ds_read_b128 v[226:229], v163 offset:39936
	s_waitcnt vmcnt(8)
	s_waitcnt lgkmcnt(0)
	s_setprio 1
	s_barrier
	v_mfma_f32_16x16x32_bf16 v[122:125], v[166:169], v[198:201], v[122:125]
	v_mfma_f32_16x16x32_bf16 v[118:121], v[174:177], v[198:201], v[118:121]
	v_mfma_f32_16x16x32_bf16 v[110:113], v[166:169], v[206:209], v[110:113]
	v_mfma_f32_16x16x32_bf16 v[102:105], v[174:177], v[206:209], v[102:105]
	v_mfma_f32_16x16x32_bf16 v[94:97], v[166:169], v[214:217], v[94:97]
	v_mfma_f32_16x16x32_bf16 v[86:89], v[174:177], v[214:217], v[86:89]
	v_mfma_f32_16x16x32_bf16 v[78:81], v[166:169], v[222:225], v[78:81]
	v_mfma_f32_16x16x32_bf16 v[70:73], v[174:177], v[222:225], v[70:73]
	v_mfma_f32_16x16x32_bf16 v[122:125], v[170:173], v[202:205], v[122:125]
	v_mfma_f32_16x16x32_bf16 v[118:121], v[178:181], v[202:205], v[118:121]
	v_mfma_f32_16x16x32_bf16 v[110:113], v[170:173], v[210:213], v[110:113]
	v_mfma_f32_16x16x32_bf16 v[102:105], v[178:181], v[210:213], v[102:105]
	v_mfma_f32_16x16x32_bf16 v[94:97], v[170:173], v[218:221], v[94:97]
	v_mfma_f32_16x16x32_bf16 v[86:89], v[178:181], v[218:221], v[86:89]
	v_mfma_f32_16x16x32_bf16 v[78:81], v[170:173], v[226:229], v[78:81]
	v_mfma_f32_16x16x32_bf16 v[70:73], v[178:181], v[226:229], v[70:73]
	v_mfma_f32_16x16x32_bf16 v[126:129], v[182:185], v[198:201], v[126:129]
	v_mfma_f32_16x16x32_bf16 v[114:117], v[190:193], v[198:201], v[114:117]
	v_mfma_f32_16x16x32_bf16 v[106:109], v[182:185], v[206:209], v[106:109]
	v_mfma_f32_16x16x32_bf16 v[98:101], v[190:193], v[206:209], v[98:101]
	v_mfma_f32_16x16x32_bf16 v[90:93], v[182:185], v[214:217], v[90:93]
	v_mfma_f32_16x16x32_bf16 v[82:85], v[190:193], v[214:217], v[82:85]
	v_mfma_f32_16x16x32_bf16 v[74:77], v[182:185], v[222:225], v[74:77]
	v_mfma_f32_16x16x32_bf16 v[66:69], v[190:193], v[222:225], v[66:69]
	v_mfma_f32_16x16x32_bf16 v[126:129], v[186:189], v[202:205], v[126:129]
	v_mfma_f32_16x16x32_bf16 v[114:117], v[194:197], v[202:205], v[114:117]
	v_mfma_f32_16x16x32_bf16 v[106:109], v[186:189], v[210:213], v[106:109]
	v_mfma_f32_16x16x32_bf16 v[98:101], v[194:197], v[210:213], v[98:101]
	v_mfma_f32_16x16x32_bf16 v[90:93], v[186:189], v[218:221], v[90:93]
	v_mfma_f32_16x16x32_bf16 v[82:85], v[194:197], v[218:221], v[82:85]
	v_mfma_f32_16x16x32_bf16 v[74:77], v[186:189], v[226:229], v[74:77]
	v_mfma_f32_16x16x32_bf16 v[66:69], v[194:197], v[226:229], v[66:69]
	s_barrier
	s_setprio 0
	s_add_u32 s96, s96, 0x80
	s_addc_u32 s97, s97, 0
	s_add_u32 s98, s96, 0xb0000
	s_addc_u32 s99, s97, 0
	s_add_u32 s94, s94, 0x80
	s_addc_u32 s95, s95, 0
	s_add_i32 s8, s8, s54
	s_mov_b32 m0, s8
	ds_read_b128 v[198:201], v163 offset:49152
	global_load_lds_dwordx4 v132, s[96:97]
	s_add_i32 m0, s8, 0x2000
	s_add_i32 s8, s50, s54
	global_load_lds_dwordx4 v136, s[96:97]
	s_mov_b32 m0, s8
	ds_read_b128 v[202:205], v163 offset:50176
	global_load_lds_dwordx4 v132, s[98:99]
	s_add_i32 m0, s8, 0x2000
	ds_read_b128 v[206:209], v163 offset:51200
	global_load_lds_dwordx4 v136, s[98:99]
	s_mov_b32 m0, s64
	ds_read_b128 v[210:213], v163 offset:52224
	global_load_lds_dwordx4 v130, s[94:95]
	s_mov_b32 m0, s65
	ds_read_b128 v[214:217], v163 offset:53248
	global_load_lds_dwordx4 v134, s[94:95]
	ds_read_b128 v[218:221], v163 offset:54272
	ds_read_b128 v[222:225], v163 offset:55296
	ds_read_b128 v[226:229], v163 offset:56320
	s_waitcnt vmcnt(8)
	s_waitcnt lgkmcnt(0)
	s_setprio 1
	s_barrier
	v_mfma_f32_16x16x32_bf16 v[62:65], v[166:169], v[198:201], v[62:65]
	v_mfma_f32_16x16x32_bf16 v[54:57], v[174:177], v[198:201], v[54:57]
	v_mfma_f32_16x16x32_bf16 v[46:49], v[166:169], v[206:209], v[46:49]
	v_mfma_f32_16x16x32_bf16 v[38:41], v[174:177], v[206:209], v[38:41]
	v_mfma_f32_16x16x32_bf16 v[30:33], v[166:169], v[214:217], v[30:33]
	v_mfma_f32_16x16x32_bf16 v[22:25], v[174:177], v[214:217], v[22:25]
	v_mfma_f32_16x16x32_bf16 v[14:17], v[166:169], v[222:225], v[14:17]
	v_mfma_f32_16x16x32_bf16 v[6:9], v[174:177], v[222:225], v[6:9]
	v_mfma_f32_16x16x32_bf16 v[62:65], v[170:173], v[202:205], v[62:65]
	v_mfma_f32_16x16x32_bf16 v[54:57], v[178:181], v[202:205], v[54:57]
	v_mfma_f32_16x16x32_bf16 v[46:49], v[170:173], v[210:213], v[46:49]
	v_mfma_f32_16x16x32_bf16 v[38:41], v[178:181], v[210:213], v[38:41]
	v_mfma_f32_16x16x32_bf16 v[30:33], v[170:173], v[218:221], v[30:33]
	v_mfma_f32_16x16x32_bf16 v[22:25], v[178:181], v[218:221], v[22:25]
	v_mfma_f32_16x16x32_bf16 v[14:17], v[170:173], v[226:229], v[14:17]
	v_mfma_f32_16x16x32_bf16 v[6:9], v[178:181], v[226:229], v[6:9]
	v_mfma_f32_16x16x32_bf16 v[58:61], v[182:185], v[198:201], v[58:61]
	v_mfma_f32_16x16x32_bf16 v[50:53], v[190:193], v[198:201], v[50:53]
	v_mfma_f32_16x16x32_bf16 v[42:45], v[182:185], v[206:209], v[42:45]
	v_mfma_f32_16x16x32_bf16 v[34:37], v[190:193], v[206:209], v[34:37]
	v_mfma_f32_16x16x32_bf16 v[26:29], v[182:185], v[214:217], v[26:29]
	v_mfma_f32_16x16x32_bf16 v[18:21], v[190:193], v[214:217], v[18:21]
	v_mfma_f32_16x16x32_bf16 v[10:13], v[182:185], v[222:225], v[10:13]
	v_mfma_f32_16x16x32_bf16 v[2:5], v[190:193], v[222:225], v[2:5]
	v_mfma_f32_16x16x32_bf16 v[58:61], v[186:189], v[202:205], v[58:61]
	v_mfma_f32_16x16x32_bf16 v[50:53], v[194:197], v[202:205], v[50:53]
	v_mfma_f32_16x16x32_bf16 v[42:45], v[186:189], v[210:213], v[42:45]
	v_mfma_f32_16x16x32_bf16 v[34:37], v[194:197], v[210:213], v[34:37]
	v_mfma_f32_16x16x32_bf16 v[26:29], v[186:189], v[218:221], v[26:29]
	v_mfma_f32_16x16x32_bf16 v[18:21], v[194:197], v[218:221], v[18:21]
	v_mfma_f32_16x16x32_bf16 v[10:13], v[186:189], v[226:229], v[10:13]
	v_mfma_f32_16x16x32_bf16 v[2:5], v[194:197], v[226:229], v[2:5]
	s_barrier
	s_setprio 0
	s_mov_b32 s8, s9
	s_add_u32 s88, s88, 0x100
	s_addc_u32 s89, s89, 0
	s_add_u32 s86, s86, 0x100
	s_addc_u32 s87, s87, 0
	s_cmp_ge_i32 s9, s101
	s_cbranch_scc1 .Lmy_kexit_1
.LBB0_310:
	s_add_u32 s98, s86, 0x100
	s_addc_u32 s99, s87, 0
	s_cmp_eq_u32 s8, s100
	s_cselect_b64 s[94:95], s[90:91], s[98:99]
	s_cselect_b64 s[96:97], s[92:93], s[88:89]
	s_add_i32 s9, s8, 2
	s_add_i32 m0, s55, 0xc000
	ds_read_b128 v[166:169], v230
	global_load_lds_dwordx4 v144, s[86:87]
	s_add_i32 m0, s55, 0xe000
	ds_read_b128 v[170:173], v230 offset:1024
	global_load_lds_dwordx4 v142, s[86:87]
	ds_read_b128 v[174:177], v230 offset:2048
	ds_read_b128 v[178:181], v230 offset:3072
	ds_read_b128 v[182:185], v231
	ds_read_b128 v[186:189], v231 offset:1024
	ds_read_b128 v[190:193], v231 offset:2048
	ds_read_b128 v[194:197], v231 offset:3072
	ds_read_b128 v[198:201], v163
	ds_read_b128 v[202:205], v163 offset:1024
	ds_read_b128 v[206:209], v163 offset:2048
	ds_read_b128 v[210:213], v163 offset:3072
	ds_read_b128 v[214:217], v163 offset:4096
	ds_read_b128 v[218:221], v163 offset:5120
	ds_read_b128 v[222:225], v163 offset:6144
	ds_read_b128 v[226:229], v163 offset:7168
	s_waitcnt vmcnt(8)
	s_waitcnt lgkmcnt(0)
	s_setprio 1
	s_barrier
	v_mfma_f32_16x16x32_bf16 v[122:125], v[166:169], v[198:201], v[122:125]
	v_mfma_f32_16x16x32_bf16 v[118:121], v[174:177], v[198:201], v[118:121]
	v_mfma_f32_16x16x32_bf16 v[110:113], v[166:169], v[206:209], v[110:113]
	v_mfma_f32_16x16x32_bf16 v[102:105], v[174:177], v[206:209], v[102:105]
	v_mfma_f32_16x16x32_bf16 v[94:97], v[166:169], v[214:217], v[94:97]
	v_mfma_f32_16x16x32_bf16 v[86:89], v[174:177], v[214:217], v[86:89]
	v_mfma_f32_16x16x32_bf16 v[78:81], v[166:169], v[222:225], v[78:81]
	v_mfma_f32_16x16x32_bf16 v[70:73], v[174:177], v[222:225], v[70:73]
	v_mfma_f32_16x16x32_bf16 v[122:125], v[170:173], v[202:205], v[122:125]
	v_mfma_f32_16x16x32_bf16 v[118:121], v[178:181], v[202:205], v[118:121]
	v_mfma_f32_16x16x32_bf16 v[110:113], v[170:173], v[210:213], v[110:113]
	v_mfma_f32_16x16x32_bf16 v[102:105], v[178:181], v[210:213], v[102:105]
	v_mfma_f32_16x16x32_bf16 v[94:97], v[170:173], v[218:221], v[94:97]
	v_mfma_f32_16x16x32_bf16 v[86:89], v[178:181], v[218:221], v[86:89]
	v_mfma_f32_16x16x32_bf16 v[78:81], v[170:173], v[226:229], v[78:81]
	v_mfma_f32_16x16x32_bf16 v[70:73], v[178:181], v[226:229], v[70:73]
	v_mfma_f32_16x16x32_bf16 v[126:129], v[182:185], v[198:201], v[126:129]
	v_mfma_f32_16x16x32_bf16 v[114:117], v[190:193], v[198:201], v[114:117]
	v_mfma_f32_16x16x32_bf16 v[106:109], v[182:185], v[206:209], v[106:109]
	v_mfma_f32_16x16x32_bf16 v[98:101], v[190:193], v[206:209], v[98:101]
	v_mfma_f32_16x16x32_bf16 v[90:93], v[182:185], v[214:217], v[90:93]
	v_mfma_f32_16x16x32_bf16 v[82:85], v[190:193], v[214:217], v[82:85]
	v_mfma_f32_16x16x32_bf16 v[74:77], v[182:185], v[222:225], v[74:77]
	v_mfma_f32_16x16x32_bf16 v[66:69], v[190:193], v[222:225], v[66:69]
	v_mfma_f32_16x16x32_bf16 v[126:129], v[186:189], v[202:205], v[126:129]
	v_mfma_f32_16x16x32_bf16 v[114:117], v[194:197], v[202:205], v[114:117]
	v_mfma_f32_16x16x32_bf16 v[106:109], v[186:189], v[210:213], v[106:109]
	v_mfma_f32_16x16x32_bf16 v[98:101], v[194:197], v[210:213], v[98:101]
	v_mfma_f32_16x16x32_bf16 v[90:93], v[186:189], v[218:221], v[90:93]
	v_mfma_f32_16x16x32_bf16 v[82:85], v[194:197], v[218:221], v[82:85]
	v_mfma_f32_16x16x32_bf16 v[74:77], v[186:189], v[226:229], v[74:77]
	v_mfma_f32_16x16x32_bf16 v[66:69], v[194:197], v[226:229], v[66:69]
	s_barrier
	s_setprio 0
	s_add_u32 s98, s96, 0xb0000
	s_addc_u32 s99, s97, 0
	s_add_i32 s8, s69, s54
	s_mov_b32 m0, s8
	ds_read_b128 v[198:201], v163 offset:16384
	global_load_lds_dwordx4 v132, s[96:97]
	s_add_i32 m0, s8, 0x2000
	s_add_i32 s8, s72, s54
	global_load_lds_dwordx4 v136, s[96:97]
	s_mov_b32 m0, s8
	ds_read_b128 v[202:205], v163 offset:17408
	global_load_lds_dwordx4 v132, s[98:99]
	s_add_i32 m0, s8, 0x2000
	ds_read_b128 v[206:209], v163 offset:18432
	global_load_lds_dwordx4 v136, s[98:99]
	s_mov_b32 m0, s55
	ds_read_b128 v[210:213], v163 offset:19456
	global_load_lds_dwordx4 v130, s[94:95]
	s_mov_b32 m0, s56
	ds_read_b128 v[214:217], v163 offset:20480
	global_load_lds_dwordx4 v134, s[94:95]
	ds_read_b128 v[218:221], v163 offset:21504
	ds_read_b128 v[222:225], v163 offset:22528
	ds_read_b128 v[226:229], v163 offset:23552
	s_waitcnt vmcnt(8)
	s_waitcnt lgkmcnt(0)
	s_setprio 1
	s_barrier
	v_mfma_f32_16x16x32_bf16 v[62:65], v[166:169], v[198:201], v[62:65]
	v_mfma_f32_16x16x32_bf16 v[54:57], v[174:177], v[198:201], v[54:57]
	v_mfma_f32_16x16x32_bf16 v[46:49], v[166:169], v[206:209], v[46:49]
	v_mfma_f32_16x16x32_bf16 v[38:41], v[174:177], v[206:209], v[38:41]
	v_mfma_f32_16x16x32_bf16 v[30:33], v[166:169], v[214:217], v[30:33]
	v_mfma_f32_16x16x32_bf16 v[22:25], v[174:177], v[214:217], v[22:25]
	v_mfma_f32_16x16x32_bf16 v[14:17], v[166:169], v[222:225], v[14:17]
	v_mfma_f32_16x16x32_bf16 v[6:9], v[174:177], v[222:225], v[6:9]
	v_mfma_f32_16x16x32_bf16 v[62:65], v[170:173], v[202:205], v[62:65]
	v_mfma_f32_16x16x32_bf16 v[54:57], v[178:181], v[202:205], v[54:57]
	v_mfma_f32_16x16x32_bf16 v[46:49], v[170:173], v[210:213], v[46:49]
	v_mfma_f32_16x16x32_bf16 v[38:41], v[178:181], v[210:213], v[38:41]
	v_mfma_f32_16x16x32_bf16 v[30:33], v[170:173], v[218:221], v[30:33]
	v_mfma_f32_16x16x32_bf16 v[22:25], v[178:181], v[218:221], v[22:25]
	v_mfma_f32_16x16x32_bf16 v[14:17], v[170:173], v[226:229], v[14:17]
	v_mfma_f32_16x16x32_bf16 v[6:9], v[178:181], v[226:229], v[6:9]
	v_mfma_f32_16x16x32_bf16 v[58:61], v[182:185], v[198:201], v[58:61]
	v_mfma_f32_16x16x32_bf16 v[50:53], v[190:193], v[198:201], v[50:53]
	v_mfma_f32_16x16x32_bf16 v[42:45], v[182:185], v[206:209], v[42:45]
	v_mfma_f32_16x16x32_bf16 v[34:37], v[190:193], v[206:209], v[34:37]
	v_mfma_f32_16x16x32_bf16 v[26:29], v[182:185], v[214:217], v[26:29]
	v_mfma_f32_16x16x32_bf16 v[18:21], v[190:193], v[214:217], v[18:21]
	v_mfma_f32_16x16x32_bf16 v[10:13], v[182:185], v[222:225], v[10:13]
	v_mfma_f32_16x16x32_bf16 v[2:5], v[190:193], v[222:225], v[2:5]
	v_mfma_f32_16x16x32_bf16 v[58:61], v[186:189], v[202:205], v[58:61]
	v_mfma_f32_16x16x32_bf16 v[50:53], v[194:197], v[202:205], v[50:53]
	v_mfma_f32_16x16x32_bf16 v[42:45], v[186:189], v[210:213], v[42:45]
	v_mfma_f32_16x16x32_bf16 v[34:37], v[194:197], v[210:213], v[34:37]
	v_mfma_f32_16x16x32_bf16 v[26:29], v[186:189], v[218:221], v[26:29]
	v_mfma_f32_16x16x32_bf16 v[18:21], v[194:197], v[218:221], v[18:21]
	v_mfma_f32_16x16x32_bf16 v[10:13], v[186:189], v[226:229], v[10:13]
	v_mfma_f32_16x16x32_bf16 v[2:5], v[194:197], v[226:229], v[2:5]
	s_barrier
	s_setprio 0
	s_add_u32 s98, s94, 0xb0000
	s_addc_u32 s99, s95, 0
	s_add_i32 s8, 0, 0x18000
	s_add_i32 s50, 0, 0x1c000
	s_mov_b32 m0, s57
	ds_read_b128 v[166:169], v232
	global_load_lds_dwordx4 v130, s[98:99]
	s_mov_b32 m0, s58
	ds_read_b128 v[170:173], v232 offset:1024
	global_load_lds_dwordx4 v134, s[98:99]
	ds_read_b128 v[174:177], v232 offset:2048
	ds_read_b128 v[178:181], v232 offset:3072
	ds_read_b128 v[182:185], v233
	ds_read_b128 v[186:189], v233 offset:1024
	ds_read_b128 v[190:193], v233 offset:2048
	ds_read_b128 v[194:197], v233 offset:3072
	ds_read_b128 v[198:201], v163 offset:32768
	ds_read_b128 v[202:205], v163 offset:33792
	ds_read_b128 v[206:209], v163 offset:34816
	ds_read_b128 v[210:213], v163 offset:35840
	ds_read_b128 v[214:217], v163 offset:36864
	ds_read_b128 v[218:221], v163 offset:37888
	ds_read_b128 v[222:225], v163 offset:38912
	ds_read_b128 v[226:229], v163 offset:39936
	s_waitcnt vmcnt(8)
	s_waitcnt lgkmcnt(0)
	s_setprio 1
	s_barrier
	v_mfma_f32_16x16x32_bf16 v[122:125], v[166:169], v[198:201], v[122:125]
	v_mfma_f32_16x16x32_bf16 v[118:121], v[174:177], v[198:201], v[118:121]
	v_mfma_f32_16x16x32_bf16 v[110:113], v[166:169], v[206:209], v[110:113]
	v_mfma_f32_16x16x32_bf16 v[102:105], v[174:177], v[206:209], v[102:105]
	v_mfma_f32_16x16x32_bf16 v[94:97], v[166:169], v[214:217], v[94:97]
	v_mfma_f32_16x16x32_bf16 v[86:89], v[174:177], v[214:217], v[86:89]
	v_mfma_f32_16x16x32_bf16 v[78:81], v[166:169], v[222:225], v[78:81]
	v_mfma_f32_16x16x32_bf16 v[70:73], v[174:177], v[222:225], v[70:73]
	v_mfma_f32_16x16x32_bf16 v[122:125], v[170:173], v[202:205], v[122:125]
	v_mfma_f32_16x16x32_bf16 v[118:121], v[178:181], v[202:205], v[118:121]
	v_mfma_f32_16x16x32_bf16 v[110:113], v[170:173], v[210:213], v[110:113]
	v_mfma_f32_16x16x32_bf16 v[102:105], v[178:181], v[210:213], v[102:105]
	v_mfma_f32_16x16x32_bf16 v[94:97], v[170:173], v[218:221], v[94:97]
	v_mfma_f32_16x16x32_bf16 v[86:89], v[178:181], v[218:221], v[86:89]
	v_mfma_f32_16x16x32_bf16 v[78:81], v[170:173], v[226:229], v[78:81]
	v_mfma_f32_16x16x32_bf16 v[70:73], v[178:181], v[226:229], v[70:73]
	v_mfma_f32_16x16x32_bf16 v[126:129], v[182:185], v[198:201], v[126:129]
	v_mfma_f32_16x16x32_bf16 v[114:117], v[190:193], v[198:201], v[114:117]
	v_mfma_f32_16x16x32_bf16 v[106:109], v[182:185], v[206:209], v[106:109]
	v_mfma_f32_16x16x32_bf16 v[98:101], v[190:193], v[206:209], v[98:101]
	v_mfma_f32_16x16x32_bf16 v[90:93], v[182:185], v[214:217], v[90:93]
	v_mfma_f32_16x16x32_bf16 v[82:85], v[190:193], v[214:217], v[82:85]
	v_mfma_f32_16x16x32_bf16 v[74:77], v[182:185], v[222:225], v[74:77]
	v_mfma_f32_16x16x32_bf16 v[66:69], v[190:193], v[222:225], v[66:69]
	v_mfma_f32_16x16x32_bf16 v[126:129], v[186:189], v[202:205], v[126:129]
	v_mfma_f32_16x16x32_bf16 v[114:117], v[194:197], v[202:205], v[114:117]
	v_mfma_f32_16x16x32_bf16 v[106:109], v[186:189], v[210:213], v[106:109]
	v_mfma_f32_16x16x32_bf16 v[98:101], v[194:197], v[210:213], v[98:101]
	v_mfma_f32_16x16x32_bf16 v[90:93], v[186:189], v[218:221], v[90:93]
	v_mfma_f32_16x16x32_bf16 v[82:85], v[194:197], v[218:221], v[82:85]
	v_mfma_f32_16x16x32_bf16 v[74:77], v[186:189], v[226:229], v[74:77]
	v_mfma_f32_16x16x32_bf16 v[66:69], v[194:197], v[226:229], v[66:69]
	s_barrier
	s_setprio 0
	s_add_u32 s96, s96, 0x80
	s_addc_u32 s97, s97, 0
	s_add_u32 s98, s96, 0xb0000
	s_addc_u32 s99, s97, 0
	s_add_u32 s94, s94, 0x80
	s_addc_u32 s95, s95, 0
	s_add_i32 s8, s8, s54
	s_mov_b32 m0, s8
	ds_read_b128 v[198:201], v163 offset:49152
	global_load_lds_dwordx4 v132, s[96:97]
	s_add_i32 m0, s8, 0x2000
	s_add_i32 s8, s50, s54
	global_load_lds_dwordx4 v136, s[96:97]
	s_mov_b32 m0, s8
	ds_read_b128 v[202:205], v163 offset:50176
	global_load_lds_dwordx4 v132, s[98:99]
	s_add_i32 m0, s8, 0x2000
	ds_read_b128 v[206:209], v163 offset:51200
	global_load_lds_dwordx4 v136, s[98:99]
	s_mov_b32 m0, s64
	ds_read_b128 v[210:213], v163 offset:52224
	global_load_lds_dwordx4 v130, s[94:95]
	s_mov_b32 m0, s65
	ds_read_b128 v[214:217], v163 offset:53248
	global_load_lds_dwordx4 v134, s[94:95]
	ds_read_b128 v[218:221], v163 offset:54272
	ds_read_b128 v[222:225], v163 offset:55296
	ds_read_b128 v[226:229], v163 offset:56320
	s_waitcnt vmcnt(8)
	s_waitcnt lgkmcnt(0)
	s_setprio 1
	s_barrier
	v_mfma_f32_16x16x32_bf16 v[62:65], v[166:169], v[198:201], v[62:65]
	v_mfma_f32_16x16x32_bf16 v[54:57], v[174:177], v[198:201], v[54:57]
	v_mfma_f32_16x16x32_bf16 v[46:49], v[166:169], v[206:209], v[46:49]
	v_mfma_f32_16x16x32_bf16 v[38:41], v[174:177], v[206:209], v[38:41]
	v_mfma_f32_16x16x32_bf16 v[30:33], v[166:169], v[214:217], v[30:33]
	v_mfma_f32_16x16x32_bf16 v[22:25], v[174:177], v[214:217], v[22:25]
	v_mfma_f32_16x16x32_bf16 v[14:17], v[166:169], v[222:225], v[14:17]
	v_mfma_f32_16x16x32_bf16 v[6:9], v[174:177], v[222:225], v[6:9]
	v_mfma_f32_16x16x32_bf16 v[62:65], v[170:173], v[202:205], v[62:65]
	v_mfma_f32_16x16x32_bf16 v[54:57], v[178:181], v[202:205], v[54:57]
	v_mfma_f32_16x16x32_bf16 v[46:49], v[170:173], v[210:213], v[46:49]
	v_mfma_f32_16x16x32_bf16 v[38:41], v[178:181], v[210:213], v[38:41]
	v_mfma_f32_16x16x32_bf16 v[30:33], v[170:173], v[218:221], v[30:33]
	v_mfma_f32_16x16x32_bf16 v[22:25], v[178:181], v[218:221], v[22:25]
	v_mfma_f32_16x16x32_bf16 v[14:17], v[170:173], v[226:229], v[14:17]
	v_mfma_f32_16x16x32_bf16 v[6:9], v[178:181], v[226:229], v[6:9]
	v_mfma_f32_16x16x32_bf16 v[58:61], v[182:185], v[198:201], v[58:61]
	v_mfma_f32_16x16x32_bf16 v[50:53], v[190:193], v[198:201], v[50:53]
	v_mfma_f32_16x16x32_bf16 v[42:45], v[182:185], v[206:209], v[42:45]
	v_mfma_f32_16x16x32_bf16 v[34:37], v[190:193], v[206:209], v[34:37]
	v_mfma_f32_16x16x32_bf16 v[26:29], v[182:185], v[214:217], v[26:29]
	v_mfma_f32_16x16x32_bf16 v[18:21], v[190:193], v[214:217], v[18:21]
	v_mfma_f32_16x16x32_bf16 v[10:13], v[182:185], v[222:225], v[10:13]
	v_mfma_f32_16x16x32_bf16 v[2:5], v[190:193], v[222:225], v[2:5]
	v_mfma_f32_16x16x32_bf16 v[58:61], v[186:189], v[202:205], v[58:61]
	v_mfma_f32_16x16x32_bf16 v[50:53], v[194:197], v[202:205], v[50:53]
	v_mfma_f32_16x16x32_bf16 v[42:45], v[186:189], v[210:213], v[42:45]
	v_mfma_f32_16x16x32_bf16 v[34:37], v[194:197], v[210:213], v[34:37]
	v_mfma_f32_16x16x32_bf16 v[26:29], v[186:189], v[218:221], v[26:29]
	v_mfma_f32_16x16x32_bf16 v[18:21], v[194:197], v[218:221], v[18:21]
	v_mfma_f32_16x16x32_bf16 v[10:13], v[186:189], v[226:229], v[10:13]
	v_mfma_f32_16x16x32_bf16 v[2:5], v[194:197], v[226:229], v[2:5]
	s_barrier
	s_setprio 0
	s_mov_b32 s8, s9
	s_add_u32 s88, s88, 0x100
	s_addc_u32 s89, s89, 0
	s_add_u32 s86, s86, 0x100
	s_addc_u32 s87, s87, 0
	s_cmp_ge_i32 s9, s101
	s_cbranch_scc0 .LBB0_310

.Lmy_nb_2:
	s_nop 0
	v_readfirstlane_b32 s86, v154
	v_readfirstlane_b32 s87, v155
	v_readfirstlane_b32 s88, v152
	v_readfirstlane_b32 s89, v153
	v_readfirstlane_b32 s90, v148
	v_readfirstlane_b32 s91, v149
	v_readfirstlane_b32 s92, v150
	v_readfirstlane_b32 s93, v151
	v_readfirstlane_b32 s100, v138
	v_readfirstlane_b32 s101, v141
	v_add_u32_e32 v230, s77, v160
	v_add_u32_e32 v231, s78, v160
	v_add_u32_e32 v232, 0x18000, v160
	v_add_u32_e32 v233, 0x1c000, v160
	s_add_u32 s98, s86, 0xfffc0080
	s_addc_u32 s99, s87, -1
	s_cmp_eq_u32 s7, s100
	s_cselect_b64 s[94:95], s[90:91], s[98:99]
	s_cselect_b64 s[96:97], s[92:93], s[88:89]
	s_add_i32 s45, s7, 2
	s_add_i32 m0, s49, 0xc000
	ds_read_b128 v[156:159], v230
	global_load_lds_dwordx4 v144, s[86:87]
	s_add_i32 m0, s49, 0xe000
	ds_read_b128 v[166:169], v230 offset:1024
	global_load_lds_dwordx4 v142, s[86:87]
	ds_read_b128 v[170:173], v230 offset:2048
	ds_read_b128 v[174:177], v230 offset:3072
	ds_read_b128 v[178:181], v231
	ds_read_b128 v[182:185], v231 offset:1024
	ds_read_b128 v[186:189], v231 offset:2048
	ds_read_b128 v[190:193], v231 offset:3072
	ds_read_b128 v[194:197], v163
	ds_read_b128 v[198:201], v163 offset:1024
	ds_read_b128 v[202:205], v163 offset:2048
	ds_read_b128 v[206:209], v163 offset:3072
	ds_read_b128 v[210:213], v163 offset:4096
	ds_read_b128 v[214:217], v163 offset:5120
	ds_read_b128 v[218:221], v163 offset:6144
	ds_read_b128 v[222:225], v163 offset:7168
	s_waitcnt vmcnt(8)
	s_waitcnt lgkmcnt(0)
	s_setprio 1
	s_barrier
	v_mfma_f32_16x16x32_bf16 v[122:125], v[156:159], v[194:197], 0
	v_mfma_f32_16x16x32_bf16 v[118:121], v[170:173], v[194:197], 0
	v_mfma_f32_16x16x32_bf16 v[110:113], v[156:159], v[202:205], 0
	v_mfma_f32_16x16x32_bf16 v[102:105], v[170:173], v[202:205], 0
	v_mfma_f32_16x16x32_bf16 v[94:97], v[156:159], v[210:213], 0
	v_mfma_f32_16x16x32_bf16 v[86:89], v[170:173], v[210:213], 0
	v_mfma_f32_16x16x32_bf16 v[78:81], v[156:159], v[218:221], 0
	v_mfma_f32_16x16x32_bf16 v[70:73], v[170:173], v[218:221], 0
	v_mfma_f32_16x16x32_bf16 v[122:125], v[166:169], v[198:201], v[122:125]
	v_mfma_f32_16x16x32_bf16 v[118:121], v[174:177], v[198:201], v[118:121]
	v_mfma_f32_16x16x32_bf16 v[110:113], v[166:169], v[206:209], v[110:113]
	v_mfma_f32_16x16x32_bf16 v[102:105], v[174:177], v[206:209], v[102:105]
	v_mfma_f32_16x16x32_bf16 v[94:97], v[166:169], v[214:217], v[94:97]
	v_mfma_f32_16x16x32_bf16 v[86:89], v[174:177], v[214:217], v[86:89]
	v_mfma_f32_16x16x32_bf16 v[78:81], v[166:169], v[222:225], v[78:81]
	v_mfma_f32_16x16x32_bf16 v[70:73], v[174:177], v[222:225], v[70:73]
	v_mfma_f32_16x16x32_bf16 v[126:129], v[178:181], v[194:197], 0
	v_mfma_f32_16x16x32_bf16 v[114:117], v[186:189], v[194:197], 0
	v_mfma_f32_16x16x32_bf16 v[106:109], v[178:181], v[202:205], 0
	v_mfma_f32_16x16x32_bf16 v[98:101], v[186:189], v[202:205], 0
	v_mfma_f32_16x16x32_bf16 v[90:93], v[178:181], v[210:213], 0
	v_mfma_f32_16x16x32_bf16 v[82:85], v[186:189], v[210:213], 0
	v_mfma_f32_16x16x32_bf16 v[74:77], v[178:181], v[218:221], 0
	v_mfma_f32_16x16x32_bf16 v[66:69], v[186:189], v[218:221], 0
	v_mfma_f32_16x16x32_bf16 v[126:129], v[182:185], v[198:201], v[126:129]
	v_mfma_f32_16x16x32_bf16 v[114:117], v[190:193], v[198:201], v[114:117]
	v_mfma_f32_16x16x32_bf16 v[106:109], v[182:185], v[206:209], v[106:109]
	v_mfma_f32_16x16x32_bf16 v[98:101], v[190:193], v[206:209], v[98:101]
	v_mfma_f32_16x16x32_bf16 v[90:93], v[182:185], v[214:217], v[90:93]
	v_mfma_f32_16x16x32_bf16 v[82:85], v[190:193], v[214:217], v[82:85]
	v_mfma_f32_16x16x32_bf16 v[74:77], v[182:185], v[222:225], v[74:77]
	v_mfma_f32_16x16x32_bf16 v[66:69], v[190:193], v[222:225], v[66:69]
	s_barrier
	s_setprio 0
	s_add_u32 s98, s96, 0x40000
	s_addc_u32 s99, s97, 0
	s_add_i32 s7, s77, s25
	s_mov_b32 m0, s7
	ds_read_b128 v[194:197], v163 offset:16384
	global_load_lds_dwordx4 v132, s[96:97]
	s_add_i32 m0, s7, 0x2000
	s_add_i32 s7, s78, s25
	global_load_lds_dwordx4 v136, s[96:97]
	s_mov_b32 m0, s7
	ds_read_b128 v[198:201], v163 offset:17408
	global_load_lds_dwordx4 v132, s[98:99]
	s_add_i32 m0, s7, 0x2000
	ds_read_b128 v[202:205], v163 offset:18432
	global_load_lds_dwordx4 v136, s[98:99]
	s_mov_b32 m0, s49
	ds_read_b128 v[206:209], v163 offset:19456
	global_load_lds_dwordx4 v130, s[94:95]
	s_mov_b32 m0, s58
	ds_read_b128 v[210:213], v163 offset:20480
	global_load_lds_dwordx4 v134, s[94:95]
	ds_read_b128 v[214:217], v163 offset:21504
	ds_read_b128 v[218:221], v163 offset:22528
	ds_read_b128 v[222:225], v163 offset:23552
	s_waitcnt vmcnt(8)
	s_waitcnt lgkmcnt(0)
	s_setprio 1
	s_barrier
	v_mfma_f32_16x16x32_bf16 v[62:65], v[156:159], v[194:197], 0
	v_mfma_f32_16x16x32_bf16 v[54:57], v[170:173], v[194:197], 0
	v_mfma_f32_16x16x32_bf16 v[46:49], v[156:159], v[202:205], 0
	v_mfma_f32_16x16x32_bf16 v[38:41], v[170:173], v[202:205], 0
	v_mfma_f32_16x16x32_bf16 v[30:33], v[156:159], v[210:213], 0
	v_mfma_f32_16x16x32_bf16 v[22:25], v[170:173], v[210:213], 0
	v_mfma_f32_16x16x32_bf16 v[14:17], v[156:159], v[218:221], 0
	v_mfma_f32_16x16x32_bf16 v[6:9], v[170:173], v[218:221], 0
	v_mfma_f32_16x16x32_bf16 v[62:65], v[166:169], v[198:201], v[62:65]
	v_mfma_f32_16x16x32_bf16 v[54:57], v[174:177], v[198:201], v[54:57]
	v_mfma_f32_16x16x32_bf16 v[46:49], v[166:169], v[206:209], v[46:49]
	v_mfma_f32_16x16x32_bf16 v[38:41], v[174:177], v[206:209], v[38:41]
	v_mfma_f32_16x16x32_bf16 v[30:33], v[166:169], v[214:217], v[30:33]
	v_mfma_f32_16x16x32_bf16 v[22:25], v[174:177], v[214:217], v[22:25]
	v_mfma_f32_16x16x32_bf16 v[14:17], v[166:169], v[222:225], v[14:17]
	v_mfma_f32_16x16x32_bf16 v[6:9], v[174:177], v[222:225], v[6:9]
	v_mfma_f32_16x16x32_bf16 v[58:61], v[178:181], v[194:197], 0
	v_mfma_f32_16x16x32_bf16 v[50:53], v[186:189], v[194:197], 0
	v_mfma_f32_16x16x32_bf16 v[42:45], v[178:181], v[202:205], 0
	v_mfma_f32_16x16x32_bf16 v[34:37], v[186:189], v[202:205], 0
	v_mfma_f32_16x16x32_bf16 v[26:29], v[178:181], v[210:213], 0
	v_mfma_f32_16x16x32_bf16 v[18:21], v[186:189], v[210:213], 0
	v_mfma_f32_16x16x32_bf16 v[10:13], v[178:181], v[218:221], 0
	v_mfma_f32_16x16x32_bf16 v[2:5], v[186:189], v[218:221], 0
	v_mfma_f32_16x16x32_bf16 v[58:61], v[182:185], v[198:201], v[58:61]
	v_mfma_f32_16x16x32_bf16 v[50:53], v[190:193], v[198:201], v[50:53]
	v_mfma_f32_16x16x32_bf16 v[42:45], v[182:185], v[206:209], v[42:45]
	v_mfma_f32_16x16x32_bf16 v[34:37], v[190:193], v[206:209], v[34:37]
	v_mfma_f32_16x16x32_bf16 v[26:29], v[182:185], v[214:217], v[26:29]
	v_mfma_f32_16x16x32_bf16 v[18:21], v[190:193], v[214:217], v[18:21]
	v_mfma_f32_16x16x32_bf16 v[10:13], v[182:185], v[222:225], v[10:13]
	v_mfma_f32_16x16x32_bf16 v[2:5], v[190:193], v[222:225], v[2:5]
	s_barrier
	s_setprio 0
	s_add_u32 s98, s94, 0x40000
	s_addc_u32 s99, s95, 0
	s_add_i32 s7, 0, 0x18000
	s_add_i32 s47, 0, 0x1c000
	s_mov_b32 m0, s59
	ds_read_b128 v[156:159], v232
	global_load_lds_dwordx4 v130, s[98:99]
	s_mov_b32 m0, s60
	ds_read_b128 v[166:169], v232 offset:1024
	global_load_lds_dwordx4 v134, s[98:99]
	ds_read_b128 v[170:173], v232 offset:2048
	ds_read_b128 v[174:177], v232 offset:3072
	ds_read_b128 v[178:181], v233
	ds_read_b128 v[182:185], v233 offset:1024
	ds_read_b128 v[186:189], v233 offset:2048
	ds_read_b128 v[190:193], v233 offset:3072
	ds_read_b128 v[194:197], v163 offset:32768
	ds_read_b128 v[198:201], v163 offset:33792
	ds_read_b128 v[202:205], v163 offset:34816
	ds_read_b128 v[206:209], v163 offset:35840
	ds_read_b128 v[210:213], v163 offset:36864
	ds_read_b128 v[214:217], v163 offset:37888
	ds_read_b128 v[218:221], v163 offset:38912
	ds_read_b128 v[222:225], v163 offset:39936
	s_waitcnt vmcnt(8)
	s_waitcnt lgkmcnt(0)
	s_setprio 1
	s_barrier
	v_mfma_f32_16x16x32_bf16 v[122:125], v[156:159], v[194:197], v[122:125]
	v_mfma_f32_16x16x32_bf16 v[118:121], v[170:173], v[194:197], v[118:121]
	v_mfma_f32_16x16x32_bf16 v[110:113], v[156:159], v[202:205], v[110:113]
	v_mfma_f32_16x16x32_bf16 v[102:105], v[170:173], v[202:205], v[102:105]
	v_mfma_f32_16x16x32_bf16 v[94:97], v[156:159], v[210:213], v[94:97]
	v_mfma_f32_16x16x32_bf16 v[86:89], v[170:173], v[210:213], v[86:89]
	v_mfma_f32_16x16x32_bf16 v[78:81], v[156:159], v[218:221], v[78:81]
	v_mfma_f32_16x16x32_bf16 v[70:73], v[170:173], v[218:221], v[70:73]
	v_mfma_f32_16x16x32_bf16 v[122:125], v[166:169], v[198:201], v[122:125]
	v_mfma_f32_16x16x32_bf16 v[118:121], v[174:177], v[198:201], v[118:121]
	v_mfma_f32_16x16x32_bf16 v[110:113], v[166:169], v[206:209], v[110:113]
	v_mfma_f32_16x16x32_bf16 v[102:105], v[174:177], v[206:209], v[102:105]
	v_mfma_f32_16x16x32_bf16 v[94:97], v[166:169], v[214:217], v[94:97]
	v_mfma_f32_16x16x32_bf16 v[86:89], v[174:177], v[214:217], v[86:89]
	v_mfma_f32_16x16x32_bf16 v[78:81], v[166:169], v[222:225], v[78:81]
	v_mfma_f32_16x16x32_bf16 v[70:73], v[174:177], v[222:225], v[70:73]
	v_mfma_f32_16x16x32_bf16 v[126:129], v[178:181], v[194:197], v[126:129]
	v_mfma_f32_16x16x32_bf16 v[114:117], v[186:189], v[194:197], v[114:117]
	v_mfma_f32_16x16x32_bf16 v[106:109], v[178:181], v[202:205], v[106:109]
	v_mfma_f32_16x16x32_bf16 v[98:101], v[186:189], v[202:205], v[98:101]
	v_mfma_f32_16x16x32_bf16 v[90:93], v[178:181], v[210:213], v[90:93]
	v_mfma_f32_16x16x32_bf16 v[82:85], v[186:189], v[210:213], v[82:85]
	v_mfma_f32_16x16x32_bf16 v[74:77], v[178:181], v[218:221], v[74:77]
	v_mfma_f32_16x16x32_bf16 v[66:69], v[186:189], v[218:221], v[66:69]
	v_mfma_f32_16x16x32_bf16 v[126:129], v[182:185], v[198:201], v[126:129]
	v_mfma_f32_16x16x32_bf16 v[114:117], v[190:193], v[198:201], v[114:117]
	v_mfma_f32_16x16x32_bf16 v[106:109], v[182:185], v[206:209], v[106:109]
	v_mfma_f32_16x16x32_bf16 v[98:101], v[190:193], v[206:209], v[98:101]
	v_mfma_f32_16x16x32_bf16 v[90:93], v[182:185], v[214:217], v[90:93]
	v_mfma_f32_16x16x32_bf16 v[82:85], v[190:193], v[214:217], v[82:85]
	v_mfma_f32_16x16x32_bf16 v[74:77], v[182:185], v[222:225], v[74:77]
	v_mfma_f32_16x16x32_bf16 v[66:69], v[190:193], v[222:225], v[66:69]
	s_barrier
	s_setprio 0
	s_add_u32 s96, s96, 0x80
	s_addc_u32 s97, s97, 0
	s_add_u32 s98, s96, 0x40000
	s_addc_u32 s99, s97, 0
	s_add_u32 s94, s94, 0x80
	s_addc_u32 s95, s95, 0
	s_add_i32 s7, s7, s25
	s_mov_b32 m0, s7
	ds_read_b128 v[194:197], v163 offset:49152
	global_load_lds_dwordx4 v132, s[96:97]
	s_add_i32 m0, s7, 0x2000
	s_add_i32 s7, s47, s25
	global_load_lds_dwordx4 v136, s[96:97]
	s_mov_b32 m0, s7
	ds_read_b128 v[198:201], v163 offset:50176
	global_load_lds_dwordx4 v132, s[98:99]
	s_add_i32 m0, s7, 0x2000
	ds_read_b128 v[202:205], v163 offset:51200
	global_load_lds_dwordx4 v136, s[98:99]
	s_mov_b32 m0, s66
	ds_read_b128 v[206:209], v163 offset:52224
	global_load_lds_dwordx4 v130, s[94:95]
	s_mov_b32 m0, s67
	ds_read_b128 v[210:213], v163 offset:53248
	global_load_lds_dwordx4 v134, s[94:95]
	ds_read_b128 v[214:217], v163 offset:54272
	ds_read_b128 v[218:221], v163 offset:55296
	ds_read_b128 v[222:225], v163 offset:56320
	s_waitcnt vmcnt(8)
	s_waitcnt lgkmcnt(0)
	s_setprio 1
	s_barrier
	v_mfma_f32_16x16x32_bf16 v[62:65], v[156:159], v[194:197], v[62:65]
	v_mfma_f32_16x16x32_bf16 v[54:57], v[170:173], v[194:197], v[54:57]
	v_mfma_f32_16x16x32_bf16 v[46:49], v[156:159], v[202:205], v[46:49]
	v_mfma_f32_16x16x32_bf16 v[38:41], v[170:173], v[202:205], v[38:41]
	v_mfma_f32_16x16x32_bf16 v[30:33], v[156:159], v[210:213], v[30:33]
	v_mfma_f32_16x16x32_bf16 v[22:25], v[170:173], v[210:213], v[22:25]
	v_mfma_f32_16x16x32_bf16 v[14:17], v[156:159], v[218:221], v[14:17]
	v_mfma_f32_16x16x32_bf16 v[6:9], v[170:173], v[218:221], v[6:9]
	v_mfma_f32_16x16x32_bf16 v[62:65], v[166:169], v[198:201], v[62:65]
	v_mfma_f32_16x16x32_bf16 v[54:57], v[174:177], v[198:201], v[54:57]
	v_mfma_f32_16x16x32_bf16 v[46:49], v[166:169], v[206:209], v[46:49]
	v_mfma_f32_16x16x32_bf16 v[38:41], v[174:177], v[206:209], v[38:41]
	v_mfma_f32_16x16x32_bf16 v[30:33], v[166:169], v[214:217], v[30:33]
	v_mfma_f32_16x16x32_bf16 v[22:25], v[174:177], v[214:217], v[22:25]
	v_mfma_f32_16x16x32_bf16 v[14:17], v[166:169], v[222:225], v[14:17]
	v_mfma_f32_16x16x32_bf16 v[6:9], v[174:177], v[222:225], v[6:9]
	v_mfma_f32_16x16x32_bf16 v[58:61], v[178:181], v[194:197], v[58:61]
	v_mfma_f32_16x16x32_bf16 v[50:53], v[186:189], v[194:197], v[50:53]
	v_mfma_f32_16x16x32_bf16 v[42:45], v[178:181], v[202:205], v[42:45]
	v_mfma_f32_16x16x32_bf16 v[34:37], v[186:189], v[202:205], v[34:37]
	v_mfma_f32_16x16x32_bf16 v[26:29], v[178:181], v[210:213], v[26:29]
	v_mfma_f32_16x16x32_bf16 v[18:21], v[186:189], v[210:213], v[18:21]
	v_mfma_f32_16x16x32_bf16 v[10:13], v[178:181], v[218:221], v[10:13]
	v_mfma_f32_16x16x32_bf16 v[2:5], v[186:189], v[218:221], v[2:5]
	v_mfma_f32_16x16x32_bf16 v[58:61], v[182:185], v[198:201], v[58:61]
	v_mfma_f32_16x16x32_bf16 v[50:53], v[190:193], v[198:201], v[50:53]
	v_mfma_f32_16x16x32_bf16 v[42:45], v[182:185], v[206:209], v[42:45]
	v_mfma_f32_16x16x32_bf16 v[34:37], v[190:193], v[206:209], v[34:37]
	v_mfma_f32_16x16x32_bf16 v[26:29], v[182:185], v[214:217], v[26:29]
	v_mfma_f32_16x16x32_bf16 v[18:21], v[190:193], v[214:217], v[18:21]
	v_mfma_f32_16x16x32_bf16 v[10:13], v[182:185], v[222:225], v[10:13]
	v_mfma_f32_16x16x32_bf16 v[2:5], v[190:193], v[222:225], v[2:5]
	s_barrier
	s_setprio 0
	s_mov_b32 s7, s45
	s_add_u32 s88, s88, 0x100
	s_addc_u32 s89, s89, 0
	s_add_u32 s86, s86, 0x100
	s_addc_u32 s87, s87, 0
	s_cmp_ge_i32 s45, s101
	s_cbranch_scc1 .Lmy_kexit_2
.LBB0_499:
	s_add_u32 s98, s86, 0xfffc0080
	s_addc_u32 s99, s87, -1
	s_cmp_eq_u32 s7, s100
	s_cselect_b64 s[94:95], s[90:91], s[98:99]
	s_cselect_b64 s[96:97], s[92:93], s[88:89]
	s_add_i32 s45, s7, 2
	s_add_i32 m0, s49, 0xc000
	ds_read_b128 v[156:159], v230
	global_load_lds_dwordx4 v144, s[86:87]
	s_add_i32 m0, s49, 0xe000
	ds_read_b128 v[166:169], v230 offset:1024
	global_load_lds_dwordx4 v142, s[86:87]
	ds_read_b128 v[170:173], v230 offset:2048
	ds_read_b128 v[174:177], v230 offset:3072
	ds_read_b128 v[178:181], v231
	ds_read_b128 v[182:185], v231 offset:1024
	ds_read_b128 v[186:189], v231 offset:2048
	ds_read_b128 v[190:193], v231 offset:3072
	ds_read_b128 v[194:197], v163
	ds_read_b128 v[198:201], v163 offset:1024
	ds_read_b128 v[202:205], v163 offset:2048
	ds_read_b128 v[206:209], v163 offset:3072
	ds_read_b128 v[210:213], v163 offset:4096
	ds_read_b128 v[214:217], v163 offset:5120
	ds_read_b128 v[218:221], v163 offset:6144
	ds_read_b128 v[222:225], v163 offset:7168
	s_waitcnt vmcnt(8)
	s_waitcnt lgkmcnt(0)
	s_setprio 1
	s_barrier
	v_mfma_f32_16x16x32_bf16 v[122:125], v[156:159], v[194:197], v[122:125]
	v_mfma_f32_16x16x32_bf16 v[118:121], v[170:173], v[194:197], v[118:121]
	v_mfma_f32_16x16x32_bf16 v[110:113], v[156:159], v[202:205], v[110:113]
	v_mfma_f32_16x16x32_bf16 v[102:105], v[170:173], v[202:205], v[102:105]
	v_mfma_f32_16x16x32_bf16 v[94:97], v[156:159], v[210:213], v[94:97]
	v_mfma_f32_16x16x32_bf16 v[86:89], v[170:173], v[210:213], v[86:89]
	v_mfma_f32_16x16x32_bf16 v[78:81], v[156:159], v[218:221], v[78:81]
	v_mfma_f32_16x16x32_bf16 v[70:73], v[170:173], v[218:221], v[70:73]
	v_mfma_f32_16x16x32_bf16 v[122:125], v[166:169], v[198:201], v[122:125]
	v_mfma_f32_16x16x32_bf16 v[118:121], v[174:177], v[198:201], v[118:121]
	v_mfma_f32_16x16x32_bf16 v[110:113], v[166:169], v[206:209], v[110:113]
	v_mfma_f32_16x16x32_bf16 v[102:105], v[174:177], v[206:209], v[102:105]
	v_mfma_f32_16x16x32_bf16 v[94:97], v[166:169], v[214:217], v[94:97]
	v_mfma_f32_16x16x32_bf16 v[86:89], v[174:177], v[214:217], v[86:89]
	v_mfma_f32_16x16x32_bf16 v[78:81], v[166:169], v[222:225], v[78:81]
	v_mfma_f32_16x16x32_bf16 v[70:73], v[174:177], v[222:225], v[70:73]
	v_mfma_f32_16x16x32_bf16 v[126:129], v[178:181], v[194:197], v[126:129]
	v_mfma_f32_16x16x32_bf16 v[114:117], v[186:189], v[194:197], v[114:117]
	v_mfma_f32_16x16x32_bf16 v[106:109], v[178:181], v[202:205], v[106:109]
	v_mfma_f32_16x16x32_bf16 v[98:101], v[186:189], v[202:205], v[98:101]
	v_mfma_f32_16x16x32_bf16 v[90:93], v[178:181], v[210:213], v[90:93]
	v_mfma_f32_16x16x32_bf16 v[82:85], v[186:189], v[210:213], v[82:85]
	v_mfma_f32_16x16x32_bf16 v[74:77], v[178:181], v[218:221], v[74:77]
	v_mfma_f32_16x16x32_bf16 v[66:69], v[186:189], v[218:221], v[66:69]
	v_mfma_f32_16x16x32_bf16 v[126:129], v[182:185], v[198:201], v[126:129]
	v_mfma_f32_16x16x32_bf16 v[114:117], v[190:193], v[198:201], v[114:117]
	v_mfma_f32_16x16x32_bf16 v[106:109], v[182:185], v[206:209], v[106:109]
	v_mfma_f32_16x16x32_bf16 v[98:101], v[190:193], v[206:209], v[98:101]
	v_mfma_f32_16x16x32_bf16 v[90:93], v[182:185], v[214:217], v[90:93]
	v_mfma_f32_16x16x32_bf16 v[82:85], v[190:193], v[214:217], v[82:85]
	v_mfma_f32_16x16x32_bf16 v[74:77], v[182:185], v[222:225], v[74:77]
	v_mfma_f32_16x16x32_bf16 v[66:69], v[190:193], v[222:225], v[66:69]
	s_barrier
	s_setprio 0
	s_add_u32 s98, s96, 0x40000
	s_addc_u32 s99, s97, 0
	s_add_i32 s7, s77, s25
	s_mov_b32 m0, s7
	ds_read_b128 v[194:197], v163 offset:16384
	global_load_lds_dwordx4 v132, s[96:97]
	s_add_i32 m0, s7, 0x2000
	s_add_i32 s7, s78, s25
	global_load_lds_dwordx4 v136, s[96:97]
	s_mov_b32 m0, s7
	ds_read_b128 v[198:201], v163 offset:17408
	global_load_lds_dwordx4 v132, s[98:99]
	s_add_i32 m0, s7, 0x2000
	ds_read_b128 v[202:205], v163 offset:18432
	global_load_lds_dwordx4 v136, s[98:99]
	s_mov_b32 m0, s49
	ds_read_b128 v[206:209], v163 offset:19456
	global_load_lds_dwordx4 v130, s[94:95]
	s_mov_b32 m0, s58
	ds_read_b128 v[210:213], v163 offset:20480
	global_load_lds_dwordx4 v134, s[94:95]
	ds_read_b128 v[214:217], v163 offset:21504
	ds_read_b128 v[218:221], v163 offset:22528
	ds_read_b128 v[222:225], v163 offset:23552
	s_waitcnt vmcnt(8)
	s_waitcnt lgkmcnt(0)
	s_setprio 1
	s_barrier
	v_mfma_f32_16x16x32_bf16 v[62:65], v[156:159], v[194:197], v[62:65]
	v_mfma_f32_16x16x32_bf16 v[54:57], v[170:173], v[194:197], v[54:57]
	v_mfma_f32_16x16x32_bf16 v[46:49], v[156:159], v[202:205], v[46:49]
	v_mfma_f32_16x16x32_bf16 v[38:41], v[170:173], v[202:205], v[38:41]
	v_mfma_f32_16x16x32_bf16 v[30:33], v[156:159], v[210:213], v[30:33]
	v_mfma_f32_16x16x32_bf16 v[22:25], v[170:173], v[210:213], v[22:25]
	v_mfma_f32_16x16x32_bf16 v[14:17], v[156:159], v[218:221], v[14:17]
	v_mfma_f32_16x16x32_bf16 v[6:9], v[170:173], v[218:221], v[6:9]
	v_mfma_f32_16x16x32_bf16 v[62:65], v[166:169], v[198:201], v[62:65]
	v_mfma_f32_16x16x32_bf16 v[54:57], v[174:177], v[198:201], v[54:57]
	v_mfma_f32_16x16x32_bf16 v[46:49], v[166:169], v[206:209], v[46:49]
	v_mfma_f32_16x16x32_bf16 v[38:41], v[174:177], v[206:209], v[38:41]
	v_mfma_f32_16x16x32_bf16 v[30:33], v[166:169], v[214:217], v[30:33]
	v_mfma_f32_16x16x32_bf16 v[22:25], v[174:177], v[214:217], v[22:25]
	v_mfma_f32_16x16x32_bf16 v[14:17], v[166:169], v[222:225], v[14:17]
	v_mfma_f32_16x16x32_bf16 v[6:9], v[174:177], v[222:225], v[6:9]
	v_mfma_f32_16x16x32_bf16 v[58:61], v[178:181], v[194:197], v[58:61]
	v_mfma_f32_16x16x32_bf16 v[50:53], v[186:189], v[194:197], v[50:53]
	v_mfma_f32_16x16x32_bf16 v[42:45], v[178:181], v[202:205], v[42:45]
	v_mfma_f32_16x16x32_bf16 v[34:37], v[186:189], v[202:205], v[34:37]
	v_mfma_f32_16x16x32_bf16 v[26:29], v[178:181], v[210:213], v[26:29]
	v_mfma_f32_16x16x32_bf16 v[18:21], v[186:189], v[210:213], v[18:21]
	v_mfma_f32_16x16x32_bf16 v[10:13], v[178:181], v[218:221], v[10:13]
	v_mfma_f32_16x16x32_bf16 v[2:5], v[186:189], v[218:221], v[2:5]
	v_mfma_f32_16x16x32_bf16 v[58:61], v[182:185], v[198:201], v[58:61]
	v_mfma_f32_16x16x32_bf16 v[50:53], v[190:193], v[198:201], v[50:53]
	v_mfma_f32_16x16x32_bf16 v[42:45], v[182:185], v[206:209], v[42:45]
	v_mfma_f32_16x16x32_bf16 v[34:37], v[190:193], v[206:209], v[34:37]
	v_mfma_f32_16x16x32_bf16 v[26:29], v[182:185], v[214:217], v[26:29]
	v_mfma_f32_16x16x32_bf16 v[18:21], v[190:193], v[214:217], v[18:21]
	v_mfma_f32_16x16x32_bf16 v[10:13], v[182:185], v[222:225], v[10:13]
	v_mfma_f32_16x16x32_bf16 v[2:5], v[190:193], v[222:225], v[2:5]
	s_barrier
	s_setprio 0
	s_add_u32 s98, s94, 0x40000
	s_addc_u32 s99, s95, 0
	s_add_i32 s7, 0, 0x18000
	s_add_i32 s47, 0, 0x1c000
	s_mov_b32 m0, s59
	ds_read_b128 v[156:159], v232
	global_load_lds_dwordx4 v130, s[98:99]
	s_mov_b32 m0, s60
	ds_read_b128 v[166:169], v232 offset:1024
	global_load_lds_dwordx4 v134, s[98:99]
	ds_read_b128 v[170:173], v232 offset:2048
	ds_read_b128 v[174:177], v232 offset:3072
	ds_read_b128 v[178:181], v233
	ds_read_b128 v[182:185], v233 offset:1024
	ds_read_b128 v[186:189], v233 offset:2048
	ds_read_b128 v[190:193], v233 offset:3072
	ds_read_b128 v[194:197], v163 offset:32768
	ds_read_b128 v[198:201], v163 offset:33792
	ds_read_b128 v[202:205], v163 offset:34816
	ds_read_b128 v[206:209], v163 offset:35840
	ds_read_b128 v[210:213], v163 offset:36864
	ds_read_b128 v[214:217], v163 offset:37888
	ds_read_b128 v[218:221], v163 offset:38912
	ds_read_b128 v[222:225], v163 offset:39936
	s_waitcnt vmcnt(8)
	s_waitcnt lgkmcnt(0)
	s_setprio 1
	s_barrier
	v_mfma_f32_16x16x32_bf16 v[122:125], v[156:159], v[194:197], v[122:125]
	v_mfma_f32_16x16x32_bf16 v[118:121], v[170:173], v[194:197], v[118:121]
	v_mfma_f32_16x16x32_bf16 v[110:113], v[156:159], v[202:205], v[110:113]
	v_mfma_f32_16x16x32_bf16 v[102:105], v[170:173], v[202:205], v[102:105]
	v_mfma_f32_16x16x32_bf16 v[94:97], v[156:159], v[210:213], v[94:97]
	v_mfma_f32_16x16x32_bf16 v[86:89], v[170:173], v[210:213], v[86:89]
	v_mfma_f32_16x16x32_bf16 v[78:81], v[156:159], v[218:221], v[78:81]
	v_mfma_f32_16x16x32_bf16 v[70:73], v[170:173], v[218:221], v[70:73]
	v_mfma_f32_16x16x32_bf16 v[122:125], v[166:169], v[198:201], v[122:125]
	v_mfma_f32_16x16x32_bf16 v[118:121], v[174:177], v[198:201], v[118:121]
	v_mfma_f32_16x16x32_bf16 v[110:113], v[166:169], v[206:209], v[110:113]
	v_mfma_f32_16x16x32_bf16 v[102:105], v[174:177], v[206:209], v[102:105]
	v_mfma_f32_16x16x32_bf16 v[94:97], v[166:169], v[214:217], v[94:97]
	v_mfma_f32_16x16x32_bf16 v[86:89], v[174:177], v[214:217], v[86:89]
	v_mfma_f32_16x16x32_bf16 v[78:81], v[166:169], v[222:225], v[78:81]
	v_mfma_f32_16x16x32_bf16 v[70:73], v[174:177], v[222:225], v[70:73]
	v_mfma_f32_16x16x32_bf16 v[126:129], v[178:181], v[194:197], v[126:129]
	v_mfma_f32_16x16x32_bf16 v[114:117], v[186:189], v[194:197], v[114:117]
	v_mfma_f32_16x16x32_bf16 v[106:109], v[178:181], v[202:205], v[106:109]
	v_mfma_f32_16x16x32_bf16 v[98:101], v[186:189], v[202:205], v[98:101]
	v_mfma_f32_16x16x32_bf16 v[90:93], v[178:181], v[210:213], v[90:93]
	v_mfma_f32_16x16x32_bf16 v[82:85], v[186:189], v[210:213], v[82:85]
	v_mfma_f32_16x16x32_bf16 v[74:77], v[178:181], v[218:221], v[74:77]
	v_mfma_f32_16x16x32_bf16 v[66:69], v[186:189], v[218:221], v[66:69]
	v_mfma_f32_16x16x32_bf16 v[126:129], v[182:185], v[198:201], v[126:129]
	v_mfma_f32_16x16x32_bf16 v[114:117], v[190:193], v[198:201], v[114:117]
	v_mfma_f32_16x16x32_bf16 v[106:109], v[182:185], v[206:209], v[106:109]
	v_mfma_f32_16x16x32_bf16 v[98:101], v[190:193], v[206:209], v[98:101]
	v_mfma_f32_16x16x32_bf16 v[90:93], v[182:185], v[214:217], v[90:93]
	v_mfma_f32_16x16x32_bf16 v[82:85], v[190:193], v[214:217], v[82:85]
	v_mfma_f32_16x16x32_bf16 v[74:77], v[182:185], v[222:225], v[74:77]
	v_mfma_f32_16x16x32_bf16 v[66:69], v[190:193], v[222:225], v[66:69]
	s_barrier
	s_setprio 0
	s_add_u32 s96, s96, 0x80
	s_addc_u32 s97, s97, 0
	s_add_u32 s98, s96, 0x40000
	s_addc_u32 s99, s97, 0
	s_add_u32 s94, s94, 0x80
	s_addc_u32 s95, s95, 0
	s_add_i32 s7, s7, s25
	s_mov_b32 m0, s7
	ds_read_b128 v[194:197], v163 offset:49152
	global_load_lds_dwordx4 v132, s[96:97]
	s_add_i32 m0, s7, 0x2000
	s_add_i32 s7, s47, s25
	global_load_lds_dwordx4 v136, s[96:97]
	s_mov_b32 m0, s7
	ds_read_b128 v[198:201], v163 offset:50176
	global_load_lds_dwordx4 v132, s[98:99]
	s_add_i32 m0, s7, 0x2000
	ds_read_b128 v[202:205], v163 offset:51200
	global_load_lds_dwordx4 v136, s[98:99]
	s_mov_b32 m0, s66
	ds_read_b128 v[206:209], v163 offset:52224
	global_load_lds_dwordx4 v130, s[94:95]
	s_mov_b32 m0, s67
	ds_read_b128 v[210:213], v163 offset:53248
	global_load_lds_dwordx4 v134, s[94:95]
	ds_read_b128 v[214:217], v163 offset:54272
	ds_read_b128 v[218:221], v163 offset:55296
	ds_read_b128 v[222:225], v163 offset:56320
	s_waitcnt vmcnt(8)
	s_waitcnt lgkmcnt(0)
	s_setprio 1
	s_barrier
	v_mfma_f32_16x16x32_bf16 v[62:65], v[156:159], v[194:197], v[62:65]
	v_mfma_f32_16x16x32_bf16 v[54:57], v[170:173], v[194:197], v[54:57]
	v_mfma_f32_16x16x32_bf16 v[46:49], v[156:159], v[202:205], v[46:49]
	v_mfma_f32_16x16x32_bf16 v[38:41], v[170:173], v[202:205], v[38:41]
	v_mfma_f32_16x16x32_bf16 v[30:33], v[156:159], v[210:213], v[30:33]
	v_mfma_f32_16x16x32_bf16 v[22:25], v[170:173], v[210:213], v[22:25]
	v_mfma_f32_16x16x32_bf16 v[14:17], v[156:159], v[218:221], v[14:17]
	v_mfma_f32_16x16x32_bf16 v[6:9], v[170:173], v[218:221], v[6:9]
	v_mfma_f32_16x16x32_bf16 v[62:65], v[166:169], v[198:201], v[62:65]
	v_mfma_f32_16x16x32_bf16 v[54:57], v[174:177], v[198:201], v[54:57]
	v_mfma_f32_16x16x32_bf16 v[46:49], v[166:169], v[206:209], v[46:49]
	v_mfma_f32_16x16x32_bf16 v[38:41], v[174:177], v[206:209], v[38:41]
	v_mfma_f32_16x16x32_bf16 v[30:33], v[166:169], v[214:217], v[30:33]
	v_mfma_f32_16x16x32_bf16 v[22:25], v[174:177], v[214:217], v[22:25]
	v_mfma_f32_16x16x32_bf16 v[14:17], v[166:169], v[222:225], v[14:17]
	v_mfma_f32_16x16x32_bf16 v[6:9], v[174:177], v[222:225], v[6:9]
	v_mfma_f32_16x16x32_bf16 v[58:61], v[178:181], v[194:197], v[58:61]
	v_mfma_f32_16x16x32_bf16 v[50:53], v[186:189], v[194:197], v[50:53]
	v_mfma_f32_16x16x32_bf16 v[42:45], v[178:181], v[202:205], v[42:45]
	v_mfma_f32_16x16x32_bf16 v[34:37], v[186:189], v[202:205], v[34:37]
	v_mfma_f32_16x16x32_bf16 v[26:29], v[178:181], v[210:213], v[26:29]
	v_mfma_f32_16x16x32_bf16 v[18:21], v[186:189], v[210:213], v[18:21]
	v_mfma_f32_16x16x32_bf16 v[10:13], v[178:181], v[218:221], v[10:13]
	v_mfma_f32_16x16x32_bf16 v[2:5], v[186:189], v[218:221], v[2:5]
	v_mfma_f32_16x16x32_bf16 v[58:61], v[182:185], v[198:201], v[58:61]
	v_mfma_f32_16x16x32_bf16 v[50:53], v[190:193], v[198:201], v[50:53]
	v_mfma_f32_16x16x32_bf16 v[42:45], v[182:185], v[206:209], v[42:45]
	v_mfma_f32_16x16x32_bf16 v[34:37], v[190:193], v[206:209], v[34:37]
	v_mfma_f32_16x16x32_bf16 v[26:29], v[182:185], v[214:217], v[26:29]
	v_mfma_f32_16x16x32_bf16 v[18:21], v[190:193], v[214:217], v[18:21]
	v_mfma_f32_16x16x32_bf16 v[10:13], v[182:185], v[222:225], v[10:13]
	v_mfma_f32_16x16x32_bf16 v[2:5], v[190:193], v[222:225], v[2:5]
	s_barrier
	s_setprio 0
	s_mov_b32 s7, s45
	s_add_u32 s88, s88, 0x100
	s_addc_u32 s89, s89, 0
	s_add_u32 s86, s86, 0x100
	s_addc_u32 s87, s87, 0
	s_cmp_ge_i32 s45, s101
	s_cbranch_scc0 .LBB0_499

.Lmy_nb_3:
	s_nop 0
	v_readfirstlane_b32 s86, v152
	v_readfirstlane_b32 s87, v153
	v_readfirstlane_b32 s88, v150
	v_readfirstlane_b32 s89, v151
	v_readfirstlane_b32 s90, v146
	v_readfirstlane_b32 s91, v147
	v_readfirstlane_b32 s92, v148
	v_readfirstlane_b32 s93, v149
	v_readfirstlane_b32 s100, v154
	v_readfirstlane_b32 s101, v138
	v_add_u32_e32 v230, s76, v141
	v_add_u32_e32 v231, s77, v141
	v_add_u32_e32 v232, 0x18000, v141
	v_add_u32_e32 v233, 0x1c000, v141
	s_add_u32 s98, s86, 0xfffc0080
	s_addc_u32 s99, s87, -1
	s_cmp_eq_u32 s7, s100
	s_cselect_b64 s[94:95], s[90:91], s[98:99]
	s_cselect_b64 s[96:97], s[92:93], s[88:89]
	s_add_i32 s45, s7, 2
	s_add_i32 m0, s49, 0xc000
	ds_read_b128 v[164:167], v230
	global_load_lds_dwordx4 v144, s[86:87]
	s_add_i32 m0, s49, 0xe000
	ds_read_b128 v[168:171], v230 offset:1024
	global_load_lds_dwordx4 v142, s[86:87]
	ds_read_b128 v[172:175], v230 offset:2048
	ds_read_b128 v[176:179], v230 offset:3072
	ds_read_b128 v[180:183], v231
	ds_read_b128 v[184:187], v231 offset:1024
	ds_read_b128 v[188:191], v231 offset:2048
	ds_read_b128 v[192:195], v231 offset:3072
	ds_read_b128 v[196:199], v160
	ds_read_b128 v[200:203], v160 offset:1024
	ds_read_b128 v[204:207], v160 offset:2048
	ds_read_b128 v[208:211], v160 offset:3072
	ds_read_b128 v[212:215], v160 offset:4096
	ds_read_b128 v[216:219], v160 offset:5120
	ds_read_b128 v[220:223], v160 offset:6144
	ds_read_b128 v[224:227], v160 offset:7168
	s_waitcnt vmcnt(8)
	s_waitcnt lgkmcnt(0)
	s_setprio 1
	s_barrier
	v_mfma_f32_16x16x32_bf16 v[122:125], v[164:167], v[196:199], 0
	v_mfma_f32_16x16x32_bf16 v[118:121], v[172:175], v[196:199], 0
	v_mfma_f32_16x16x32_bf16 v[110:113], v[164:167], v[204:207], 0
	v_mfma_f32_16x16x32_bf16 v[102:105], v[172:175], v[204:207], 0
	v_mfma_f32_16x16x32_bf16 v[94:97], v[164:167], v[212:215], 0
	v_mfma_f32_16x16x32_bf16 v[86:89], v[172:175], v[212:215], 0
	v_mfma_f32_16x16x32_bf16 v[78:81], v[164:167], v[220:223], 0
	v_mfma_f32_16x16x32_bf16 v[70:73], v[172:175], v[220:223], 0
	v_mfma_f32_16x16x32_bf16 v[122:125], v[168:171], v[200:203], v[122:125]
	v_mfma_f32_16x16x32_bf16 v[118:121], v[176:179], v[200:203], v[118:121]
	v_mfma_f32_16x16x32_bf16 v[110:113], v[168:171], v[208:211], v[110:113]
	v_mfma_f32_16x16x32_bf16 v[102:105], v[176:179], v[208:211], v[102:105]
	v_mfma_f32_16x16x32_bf16 v[94:97], v[168:171], v[216:219], v[94:97]
	v_mfma_f32_16x16x32_bf16 v[86:89], v[176:179], v[216:219], v[86:89]
	v_mfma_f32_16x16x32_bf16 v[78:81], v[168:171], v[224:227], v[78:81]
	v_mfma_f32_16x16x32_bf16 v[70:73], v[176:179], v[224:227], v[70:73]
	v_mfma_f32_16x16x32_bf16 v[126:129], v[180:183], v[196:199], 0
	v_mfma_f32_16x16x32_bf16 v[114:117], v[188:191], v[196:199], 0
	v_mfma_f32_16x16x32_bf16 v[106:109], v[180:183], v[204:207], 0
	v_mfma_f32_16x16x32_bf16 v[98:101], v[188:191], v[204:207], 0
	v_mfma_f32_16x16x32_bf16 v[90:93], v[180:183], v[212:215], 0
	v_mfma_f32_16x16x32_bf16 v[82:85], v[188:191], v[212:215], 0
	v_mfma_f32_16x16x32_bf16 v[74:77], v[180:183], v[220:223], 0
	v_mfma_f32_16x16x32_bf16 v[66:69], v[188:191], v[220:223], 0
	v_mfma_f32_16x16x32_bf16 v[126:129], v[184:187], v[200:203], v[126:129]
	v_mfma_f32_16x16x32_bf16 v[114:117], v[192:195], v[200:203], v[114:117]
	v_mfma_f32_16x16x32_bf16 v[106:109], v[184:187], v[208:211], v[106:109]
	v_mfma_f32_16x16x32_bf16 v[98:101], v[192:195], v[208:211], v[98:101]
	v_mfma_f32_16x16x32_bf16 v[90:93], v[184:187], v[216:219], v[90:93]
	v_mfma_f32_16x16x32_bf16 v[82:85], v[192:195], v[216:219], v[82:85]
	v_mfma_f32_16x16x32_bf16 v[74:77], v[184:187], v[224:227], v[74:77]
	v_mfma_f32_16x16x32_bf16 v[66:69], v[192:195], v[224:227], v[66:69]
	s_barrier
	s_setprio 0
	s_add_u32 s98, s96, 0x40000
	s_addc_u32 s99, s97, 0
	s_add_i32 s7, s76, s25
	s_mov_b32 m0, s7
	ds_read_b128 v[196:199], v160 offset:16384
	global_load_lds_dwordx4 v132, s[96:97]
	s_add_i32 m0, s7, 0x2000
	s_add_i32 s7, s77, s25
	global_load_lds_dwordx4 v136, s[96:97]
	s_mov_b32 m0, s7
	ds_read_b128 v[200:203], v160 offset:17408
	global_load_lds_dwordx4 v132, s[98:99]
	s_add_i32 m0, s7, 0x2000
	ds_read_b128 v[204:207], v160 offset:18432
	global_load_lds_dwordx4 v136, s[98:99]
	s_mov_b32 m0, s49
	ds_read_b128 v[208:211], v160 offset:19456
	global_load_lds_dwordx4 v130, s[94:95]
	s_mov_b32 m0, s58
	ds_read_b128 v[212:215], v160 offset:20480
	global_load_lds_dwordx4 v134, s[94:95]
	ds_read_b128 v[216:219], v160 offset:21504
	ds_read_b128 v[220:223], v160 offset:22528
	ds_read_b128 v[224:227], v160 offset:23552
	s_waitcnt vmcnt(8)
	s_waitcnt lgkmcnt(0)
	s_setprio 1
	s_barrier
	v_mfma_f32_16x16x32_bf16 v[62:65], v[164:167], v[196:199], 0
	v_mfma_f32_16x16x32_bf16 v[54:57], v[172:175], v[196:199], 0
	v_mfma_f32_16x16x32_bf16 v[46:49], v[164:167], v[204:207], 0
	v_mfma_f32_16x16x32_bf16 v[38:41], v[172:175], v[204:207], 0
	v_mfma_f32_16x16x32_bf16 v[30:33], v[164:167], v[212:215], 0
	v_mfma_f32_16x16x32_bf16 v[22:25], v[172:175], v[212:215], 0
	v_mfma_f32_16x16x32_bf16 v[14:17], v[164:167], v[220:223], 0
	v_mfma_f32_16x16x32_bf16 v[6:9], v[172:175], v[220:223], 0
	v_mfma_f32_16x16x32_bf16 v[62:65], v[168:171], v[200:203], v[62:65]
	v_mfma_f32_16x16x32_bf16 v[54:57], v[176:179], v[200:203], v[54:57]
	v_mfma_f32_16x16x32_bf16 v[46:49], v[168:171], v[208:211], v[46:49]
	v_mfma_f32_16x16x32_bf16 v[38:41], v[176:179], v[208:211], v[38:41]
	v_mfma_f32_16x16x32_bf16 v[30:33], v[168:171], v[216:219], v[30:33]
	v_mfma_f32_16x16x32_bf16 v[22:25], v[176:179], v[216:219], v[22:25]
	v_mfma_f32_16x16x32_bf16 v[14:17], v[168:171], v[224:227], v[14:17]
	v_mfma_f32_16x16x32_bf16 v[6:9], v[176:179], v[224:227], v[6:9]
	v_mfma_f32_16x16x32_bf16 v[58:61], v[180:183], v[196:199], 0
	v_mfma_f32_16x16x32_bf16 v[50:53], v[188:191], v[196:199], 0
	v_mfma_f32_16x16x32_bf16 v[42:45], v[180:183], v[204:207], 0
	v_mfma_f32_16x16x32_bf16 v[34:37], v[188:191], v[204:207], 0
	v_mfma_f32_16x16x32_bf16 v[26:29], v[180:183], v[212:215], 0
	v_mfma_f32_16x16x32_bf16 v[18:21], v[188:191], v[212:215], 0
	v_mfma_f32_16x16x32_bf16 v[10:13], v[180:183], v[220:223], 0
	v_mfma_f32_16x16x32_bf16 v[2:5], v[188:191], v[220:223], 0
	v_mfma_f32_16x16x32_bf16 v[58:61], v[184:187], v[200:203], v[58:61]
	v_mfma_f32_16x16x32_bf16 v[50:53], v[192:195], v[200:203], v[50:53]
	v_mfma_f32_16x16x32_bf16 v[42:45], v[184:187], v[208:211], v[42:45]
	v_mfma_f32_16x16x32_bf16 v[34:37], v[192:195], v[208:211], v[34:37]
	v_mfma_f32_16x16x32_bf16 v[26:29], v[184:187], v[216:219], v[26:29]
	v_mfma_f32_16x16x32_bf16 v[18:21], v[192:195], v[216:219], v[18:21]
	v_mfma_f32_16x16x32_bf16 v[10:13], v[184:187], v[224:227], v[10:13]
	v_mfma_f32_16x16x32_bf16 v[2:5], v[192:195], v[224:227], v[2:5]
	s_barrier
	s_setprio 0
	s_add_u32 s98, s94, 0x40000
	s_addc_u32 s99, s95, 0
	s_add_i32 s7, 0, 0x18000
	s_add_i32 s47, 0, 0x1c000
	s_mov_b32 m0, s59
	ds_read_b128 v[164:167], v232
	global_load_lds_dwordx4 v130, s[98:99]
	s_mov_b32 m0, s60
	ds_read_b128 v[168:171], v232 offset:1024
	global_load_lds_dwordx4 v134, s[98:99]
	ds_read_b128 v[172:175], v232 offset:2048
	ds_read_b128 v[176:179], v232 offset:3072
	ds_read_b128 v[180:183], v233
	ds_read_b128 v[184:187], v233 offset:1024
	ds_read_b128 v[188:191], v233 offset:2048
	ds_read_b128 v[192:195], v233 offset:3072
	ds_read_b128 v[196:199], v160 offset:32768
	ds_read_b128 v[200:203], v160 offset:33792
	ds_read_b128 v[204:207], v160 offset:34816
	ds_read_b128 v[208:211], v160 offset:35840
	ds_read_b128 v[212:215], v160 offset:36864
	ds_read_b128 v[216:219], v160 offset:37888
	ds_read_b128 v[220:223], v160 offset:38912
	ds_read_b128 v[224:227], v160 offset:39936
	s_waitcnt vmcnt(8)
	s_waitcnt lgkmcnt(0)
	s_setprio 1
	s_barrier
	v_mfma_f32_16x16x32_bf16 v[122:125], v[164:167], v[196:199], v[122:125]
	v_mfma_f32_16x16x32_bf16 v[118:121], v[172:175], v[196:199], v[118:121]
	v_mfma_f32_16x16x32_bf16 v[110:113], v[164:167], v[204:207], v[110:113]
	v_mfma_f32_16x16x32_bf16 v[102:105], v[172:175], v[204:207], v[102:105]
	v_mfma_f32_16x16x32_bf16 v[94:97], v[164:167], v[212:215], v[94:97]
	v_mfma_f32_16x16x32_bf16 v[86:89], v[172:175], v[212:215], v[86:89]
	v_mfma_f32_16x16x32_bf16 v[78:81], v[164:167], v[220:223], v[78:81]
	v_mfma_f32_16x16x32_bf16 v[70:73], v[172:175], v[220:223], v[70:73]
	v_mfma_f32_16x16x32_bf16 v[122:125], v[168:171], v[200:203], v[122:125]
	v_mfma_f32_16x16x32_bf16 v[118:121], v[176:179], v[200:203], v[118:121]
	v_mfma_f32_16x16x32_bf16 v[110:113], v[168:171], v[208:211], v[110:113]
	v_mfma_f32_16x16x32_bf16 v[102:105], v[176:179], v[208:211], v[102:105]
	v_mfma_f32_16x16x32_bf16 v[94:97], v[168:171], v[216:219], v[94:97]
	v_mfma_f32_16x16x32_bf16 v[86:89], v[176:179], v[216:219], v[86:89]
	v_mfma_f32_16x16x32_bf16 v[78:81], v[168:171], v[224:227], v[78:81]
	v_mfma_f32_16x16x32_bf16 v[70:73], v[176:179], v[224:227], v[70:73]
	v_mfma_f32_16x16x32_bf16 v[126:129], v[180:183], v[196:199], v[126:129]
	v_mfma_f32_16x16x32_bf16 v[114:117], v[188:191], v[196:199], v[114:117]
	v_mfma_f32_16x16x32_bf16 v[106:109], v[180:183], v[204:207], v[106:109]
	v_mfma_f32_16x16x32_bf16 v[98:101], v[188:191], v[204:207], v[98:101]
	v_mfma_f32_16x16x32_bf16 v[90:93], v[180:183], v[212:215], v[90:93]
	v_mfma_f32_16x16x32_bf16 v[82:85], v[188:191], v[212:215], v[82:85]
	v_mfma_f32_16x16x32_bf16 v[74:77], v[180:183], v[220:223], v[74:77]
	v_mfma_f32_16x16x32_bf16 v[66:69], v[188:191], v[220:223], v[66:69]
	v_mfma_f32_16x16x32_bf16 v[126:129], v[184:187], v[200:203], v[126:129]
	v_mfma_f32_16x16x32_bf16 v[114:117], v[192:195], v[200:203], v[114:117]
	v_mfma_f32_16x16x32_bf16 v[106:109], v[184:187], v[208:211], v[106:109]
	v_mfma_f32_16x16x32_bf16 v[98:101], v[192:195], v[208:211], v[98:101]
	v_mfma_f32_16x16x32_bf16 v[90:93], v[184:187], v[216:219], v[90:93]
	v_mfma_f32_16x16x32_bf16 v[82:85], v[192:195], v[216:219], v[82:85]
	v_mfma_f32_16x16x32_bf16 v[74:77], v[184:187], v[224:227], v[74:77]
	v_mfma_f32_16x16x32_bf16 v[66:69], v[192:195], v[224:227], v[66:69]
	s_barrier
	s_setprio 0
	s_add_u32 s96, s96, 0x80
	s_addc_u32 s97, s97, 0
	s_add_u32 s98, s96, 0x40000
	s_addc_u32 s99, s97, 0
	s_add_u32 s94, s94, 0x80
	s_addc_u32 s95, s95, 0
	s_add_i32 s7, s7, s25
	s_mov_b32 m0, s7
	ds_read_b128 v[196:199], v160 offset:49152
	global_load_lds_dwordx4 v132, s[96:97]
	s_add_i32 m0, s7, 0x2000
	s_add_i32 s7, s47, s25
	global_load_lds_dwordx4 v136, s[96:97]
	s_mov_b32 m0, s7
	ds_read_b128 v[200:203], v160 offset:50176
	global_load_lds_dwordx4 v132, s[98:99]
	s_add_i32 m0, s7, 0x2000
	ds_read_b128 v[204:207], v160 offset:51200
	global_load_lds_dwordx4 v136, s[98:99]
	s_mov_b32 m0, s66
	ds_read_b128 v[208:211], v160 offset:52224
	global_load_lds_dwordx4 v130, s[94:95]
	s_mov_b32 m0, s67
	ds_read_b128 v[212:215], v160 offset:53248
	global_load_lds_dwordx4 v134, s[94:95]
	ds_read_b128 v[216:219], v160 offset:54272
	ds_read_b128 v[220:223], v160 offset:55296
	ds_read_b128 v[224:227], v160 offset:56320
	s_waitcnt vmcnt(8)
	s_waitcnt lgkmcnt(0)
	s_setprio 1
	s_barrier
	v_mfma_f32_16x16x32_bf16 v[62:65], v[164:167], v[196:199], v[62:65]
	v_mfma_f32_16x16x32_bf16 v[54:57], v[172:175], v[196:199], v[54:57]
	v_mfma_f32_16x16x32_bf16 v[46:49], v[164:167], v[204:207], v[46:49]
	v_mfma_f32_16x16x32_bf16 v[38:41], v[172:175], v[204:207], v[38:41]
	v_mfma_f32_16x16x32_bf16 v[30:33], v[164:167], v[212:215], v[30:33]
	v_mfma_f32_16x16x32_bf16 v[22:25], v[172:175], v[212:215], v[22:25]
	v_mfma_f32_16x16x32_bf16 v[14:17], v[164:167], v[220:223], v[14:17]
	v_mfma_f32_16x16x32_bf16 v[6:9], v[172:175], v[220:223], v[6:9]
	v_mfma_f32_16x16x32_bf16 v[62:65], v[168:171], v[200:203], v[62:65]
	v_mfma_f32_16x16x32_bf16 v[54:57], v[176:179], v[200:203], v[54:57]
	v_mfma_f32_16x16x32_bf16 v[46:49], v[168:171], v[208:211], v[46:49]
	v_mfma_f32_16x16x32_bf16 v[38:41], v[176:179], v[208:211], v[38:41]
	v_mfma_f32_16x16x32_bf16 v[30:33], v[168:171], v[216:219], v[30:33]
	v_mfma_f32_16x16x32_bf16 v[22:25], v[176:179], v[216:219], v[22:25]
	v_mfma_f32_16x16x32_bf16 v[14:17], v[168:171], v[224:227], v[14:17]
	v_mfma_f32_16x16x32_bf16 v[6:9], v[176:179], v[224:227], v[6:9]
	v_mfma_f32_16x16x32_bf16 v[58:61], v[180:183], v[196:199], v[58:61]
	v_mfma_f32_16x16x32_bf16 v[50:53], v[188:191], v[196:199], v[50:53]
	v_mfma_f32_16x16x32_bf16 v[42:45], v[180:183], v[204:207], v[42:45]
	v_mfma_f32_16x16x32_bf16 v[34:37], v[188:191], v[204:207], v[34:37]
	v_mfma_f32_16x16x32_bf16 v[26:29], v[180:183], v[212:215], v[26:29]
	v_mfma_f32_16x16x32_bf16 v[18:21], v[188:191], v[212:215], v[18:21]
	v_mfma_f32_16x16x32_bf16 v[10:13], v[180:183], v[220:223], v[10:13]
	v_mfma_f32_16x16x32_bf16 v[2:5], v[188:191], v[220:223], v[2:5]
	v_mfma_f32_16x16x32_bf16 v[58:61], v[184:187], v[200:203], v[58:61]
	v_mfma_f32_16x16x32_bf16 v[50:53], v[192:195], v[200:203], v[50:53]
	v_mfma_f32_16x16x32_bf16 v[42:45], v[184:187], v[208:211], v[42:45]
	v_mfma_f32_16x16x32_bf16 v[34:37], v[192:195], v[208:211], v[34:37]
	v_mfma_f32_16x16x32_bf16 v[26:29], v[184:187], v[216:219], v[26:29]
	v_mfma_f32_16x16x32_bf16 v[18:21], v[192:195], v[216:219], v[18:21]
	v_mfma_f32_16x16x32_bf16 v[10:13], v[184:187], v[224:227], v[10:13]
	v_mfma_f32_16x16x32_bf16 v[2:5], v[192:195], v[224:227], v[2:5]
	s_barrier
	s_setprio 0
	s_mov_b32 s7, s45
	s_add_u32 s88, s88, 0x100
	s_addc_u32 s89, s89, 0
	s_add_u32 s86, s86, 0x100
	s_addc_u32 s87, s87, 0
	s_cmp_ge_i32 s45, s101
	s_cbranch_scc1 .Lmy_kexit_3
.LBB0_768:
	s_add_u32 s98, s86, 0xfffc0080
	s_addc_u32 s99, s87, -1
	s_cmp_eq_u32 s7, s100
	s_cselect_b64 s[94:95], s[90:91], s[98:99]
	s_cselect_b64 s[96:97], s[92:93], s[88:89]
	s_add_i32 s45, s7, 2
	s_add_i32 m0, s49, 0xc000
	ds_read_b128 v[164:167], v230
	global_load_lds_dwordx4 v144, s[86:87]
	s_add_i32 m0, s49, 0xe000
	ds_read_b128 v[168:171], v230 offset:1024
	global_load_lds_dwordx4 v142, s[86:87]
	ds_read_b128 v[172:175], v230 offset:2048
	ds_read_b128 v[176:179], v230 offset:3072
	ds_read_b128 v[180:183], v231
	ds_read_b128 v[184:187], v231 offset:1024
	ds_read_b128 v[188:191], v231 offset:2048
	ds_read_b128 v[192:195], v231 offset:3072
	ds_read_b128 v[196:199], v160
	ds_read_b128 v[200:203], v160 offset:1024
	ds_read_b128 v[204:207], v160 offset:2048
	ds_read_b128 v[208:211], v160 offset:3072
	ds_read_b128 v[212:215], v160 offset:4096
	ds_read_b128 v[216:219], v160 offset:5120
	ds_read_b128 v[220:223], v160 offset:6144
	ds_read_b128 v[224:227], v160 offset:7168
	s_waitcnt vmcnt(8)
	s_waitcnt lgkmcnt(0)
	s_setprio 1
	s_barrier
	v_mfma_f32_16x16x32_bf16 v[122:125], v[164:167], v[196:199], v[122:125]
	v_mfma_f32_16x16x32_bf16 v[118:121], v[172:175], v[196:199], v[118:121]
	v_mfma_f32_16x16x32_bf16 v[110:113], v[164:167], v[204:207], v[110:113]
	v_mfma_f32_16x16x32_bf16 v[102:105], v[172:175], v[204:207], v[102:105]
	v_mfma_f32_16x16x32_bf16 v[94:97], v[164:167], v[212:215], v[94:97]
	v_mfma_f32_16x16x32_bf16 v[86:89], v[172:175], v[212:215], v[86:89]
	v_mfma_f32_16x16x32_bf16 v[78:81], v[164:167], v[220:223], v[78:81]
	v_mfma_f32_16x16x32_bf16 v[70:73], v[172:175], v[220:223], v[70:73]
	v_mfma_f32_16x16x32_bf16 v[122:125], v[168:171], v[200:203], v[122:125]
	v_mfma_f32_16x16x32_bf16 v[118:121], v[176:179], v[200:203], v[118:121]
	v_mfma_f32_16x16x32_bf16 v[110:113], v[168:171], v[208:211], v[110:113]
	v_mfma_f32_16x16x32_bf16 v[102:105], v[176:179], v[208:211], v[102:105]
	v_mfma_f32_16x16x32_bf16 v[94:97], v[168:171], v[216:219], v[94:97]
	v_mfma_f32_16x16x32_bf16 v[86:89], v[176:179], v[216:219], v[86:89]
	v_mfma_f32_16x16x32_bf16 v[78:81], v[168:171], v[224:227], v[78:81]
	v_mfma_f32_16x16x32_bf16 v[70:73], v[176:179], v[224:227], v[70:73]
	v_mfma_f32_16x16x32_bf16 v[126:129], v[180:183], v[196:199], v[126:129]
	v_mfma_f32_16x16x32_bf16 v[114:117], v[188:191], v[196:199], v[114:117]
	v_mfma_f32_16x16x32_bf16 v[106:109], v[180:183], v[204:207], v[106:109]
	v_mfma_f32_16x16x32_bf16 v[98:101], v[188:191], v[204:207], v[98:101]
	v_mfma_f32_16x16x32_bf16 v[90:93], v[180:183], v[212:215], v[90:93]
	v_mfma_f32_16x16x32_bf16 v[82:85], v[188:191], v[212:215], v[82:85]
	v_mfma_f32_16x16x32_bf16 v[74:77], v[180:183], v[220:223], v[74:77]
	v_mfma_f32_16x16x32_bf16 v[66:69], v[188:191], v[220:223], v[66:69]
	v_mfma_f32_16x16x32_bf16 v[126:129], v[184:187], v[200:203], v[126:129]
	v_mfma_f32_16x16x32_bf16 v[114:117], v[192:195], v[200:203], v[114:117]
	v_mfma_f32_16x16x32_bf16 v[106:109], v[184:187], v[208:211], v[106:109]
	v_mfma_f32_16x16x32_bf16 v[98:101], v[192:195], v[208:211], v[98:101]
	v_mfma_f32_16x16x32_bf16 v[90:93], v[184:187], v[216:219], v[90:93]
	v_mfma_f32_16x16x32_bf16 v[82:85], v[192:195], v[216:219], v[82:85]
	v_mfma_f32_16x16x32_bf16 v[74:77], v[184:187], v[224:227], v[74:77]
	v_mfma_f32_16x16x32_bf16 v[66:69], v[192:195], v[224:227], v[66:69]
	s_barrier
	s_setprio 0
	s_add_u32 s98, s96, 0x40000
	s_addc_u32 s99, s97, 0
	s_add_i32 s7, s76, s25
	s_mov_b32 m0, s7
	ds_read_b128 v[196:199], v160 offset:16384
	global_load_lds_dwordx4 v132, s[96:97]
	s_add_i32 m0, s7, 0x2000
	s_add_i32 s7, s77, s25
	global_load_lds_dwordx4 v136, s[96:97]
	s_mov_b32 m0, s7
	ds_read_b128 v[200:203], v160 offset:17408
	global_load_lds_dwordx4 v132, s[98:99]
	s_add_i32 m0, s7, 0x2000
	ds_read_b128 v[204:207], v160 offset:18432
	global_load_lds_dwordx4 v136, s[98:99]
	s_mov_b32 m0, s49
	ds_read_b128 v[208:211], v160 offset:19456
	global_load_lds_dwordx4 v130, s[94:95]
	s_mov_b32 m0, s58
	ds_read_b128 v[212:215], v160 offset:20480
	global_load_lds_dwordx4 v134, s[94:95]
	ds_read_b128 v[216:219], v160 offset:21504
	ds_read_b128 v[220:223], v160 offset:22528
	ds_read_b128 v[224:227], v160 offset:23552
	s_waitcnt vmcnt(8)
	s_waitcnt lgkmcnt(0)
	s_setprio 1
	s_barrier
	v_mfma_f32_16x16x32_bf16 v[62:65], v[164:167], v[196:199], v[62:65]
	v_mfma_f32_16x16x32_bf16 v[54:57], v[172:175], v[196:199], v[54:57]
	v_mfma_f32_16x16x32_bf16 v[46:49], v[164:167], v[204:207], v[46:49]
	v_mfma_f32_16x16x32_bf16 v[38:41], v[172:175], v[204:207], v[38:41]
	v_mfma_f32_16x16x32_bf16 v[30:33], v[164:167], v[212:215], v[30:33]
	v_mfma_f32_16x16x32_bf16 v[22:25], v[172:175], v[212:215], v[22:25]
	v_mfma_f32_16x16x32_bf16 v[14:17], v[164:167], v[220:223], v[14:17]
	v_mfma_f32_16x16x32_bf16 v[6:9], v[172:175], v[220:223], v[6:9]
	v_mfma_f32_16x16x32_bf16 v[62:65], v[168:171], v[200:203], v[62:65]
	v_mfma_f32_16x16x32_bf16 v[54:57], v[176:179], v[200:203], v[54:57]
	v_mfma_f32_16x16x32_bf16 v[46:49], v[168:171], v[208:211], v[46:49]
	v_mfma_f32_16x16x32_bf16 v[38:41], v[176:179], v[208:211], v[38:41]
	v_mfma_f32_16x16x32_bf16 v[30:33], v[168:171], v[216:219], v[30:33]
	v_mfma_f32_16x16x32_bf16 v[22:25], v[176:179], v[216:219], v[22:25]
	v_mfma_f32_16x16x32_bf16 v[14:17], v[168:171], v[224:227], v[14:17]
	v_mfma_f32_16x16x32_bf16 v[6:9], v[176:179], v[224:227], v[6:9]
	v_mfma_f32_16x16x32_bf16 v[58:61], v[180:183], v[196:199], v[58:61]
	v_mfma_f32_16x16x32_bf16 v[50:53], v[188:191], v[196:199], v[50:53]
	v_mfma_f32_16x16x32_bf16 v[42:45], v[180:183], v[204:207], v[42:45]
	v_mfma_f32_16x16x32_bf16 v[34:37], v[188:191], v[204:207], v[34:37]
	v_mfma_f32_16x16x32_bf16 v[26:29], v[180:183], v[212:215], v[26:29]
	v_mfma_f32_16x16x32_bf16 v[18:21], v[188:191], v[212:215], v[18:21]
	v_mfma_f32_16x16x32_bf16 v[10:13], v[180:183], v[220:223], v[10:13]
	v_mfma_f32_16x16x32_bf16 v[2:5], v[188:191], v[220:223], v[2:5]
	v_mfma_f32_16x16x32_bf16 v[58:61], v[184:187], v[200:203], v[58:61]
	v_mfma_f32_16x16x32_bf16 v[50:53], v[192:195], v[200:203], v[50:53]
	v_mfma_f32_16x16x32_bf16 v[42:45], v[184:187], v[208:211], v[42:45]
	v_mfma_f32_16x16x32_bf16 v[34:37], v[192:195], v[208:211], v[34:37]
	v_mfma_f32_16x16x32_bf16 v[26:29], v[184:187], v[216:219], v[26:29]
	v_mfma_f32_16x16x32_bf16 v[18:21], v[192:195], v[216:219], v[18:21]
	v_mfma_f32_16x16x32_bf16 v[10:13], v[184:187], v[224:227], v[10:13]
	v_mfma_f32_16x16x32_bf16 v[2:5], v[192:195], v[224:227], v[2:5]
	s_barrier
	s_setprio 0
	s_add_u32 s98, s94, 0x40000
	s_addc_u32 s99, s95, 0
	s_add_i32 s7, 0, 0x18000
	s_add_i32 s47, 0, 0x1c000
	s_mov_b32 m0, s59
	ds_read_b128 v[164:167], v232
	global_load_lds_dwordx4 v130, s[98:99]
	s_mov_b32 m0, s60
	ds_read_b128 v[168:171], v232 offset:1024
	global_load_lds_dwordx4 v134, s[98:99]
	ds_read_b128 v[172:175], v232 offset:2048
	ds_read_b128 v[176:179], v232 offset:3072
	ds_read_b128 v[180:183], v233
	ds_read_b128 v[184:187], v233 offset:1024
	ds_read_b128 v[188:191], v233 offset:2048
	ds_read_b128 v[192:195], v233 offset:3072
	ds_read_b128 v[196:199], v160 offset:32768
	ds_read_b128 v[200:203], v160 offset:33792
	ds_read_b128 v[204:207], v160 offset:34816
	ds_read_b128 v[208:211], v160 offset:35840
	ds_read_b128 v[212:215], v160 offset:36864
	ds_read_b128 v[216:219], v160 offset:37888
	ds_read_b128 v[220:223], v160 offset:38912
	ds_read_b128 v[224:227], v160 offset:39936
	s_waitcnt vmcnt(8)
	s_waitcnt lgkmcnt(0)
	s_setprio 1
	s_barrier
	v_mfma_f32_16x16x32_bf16 v[122:125], v[164:167], v[196:199], v[122:125]
	v_mfma_f32_16x16x32_bf16 v[118:121], v[172:175], v[196:199], v[118:121]
	v_mfma_f32_16x16x32_bf16 v[110:113], v[164:167], v[204:207], v[110:113]
	v_mfma_f32_16x16x32_bf16 v[102:105], v[172:175], v[204:207], v[102:105]
	v_mfma_f32_16x16x32_bf16 v[94:97], v[164:167], v[212:215], v[94:97]
	v_mfma_f32_16x16x32_bf16 v[86:89], v[172:175], v[212:215], v[86:89]
	v_mfma_f32_16x16x32_bf16 v[78:81], v[164:167], v[220:223], v[78:81]
	v_mfma_f32_16x16x32_bf16 v[70:73], v[172:175], v[220:223], v[70:73]
	v_mfma_f32_16x16x32_bf16 v[122:125], v[168:171], v[200:203], v[122:125]
	v_mfma_f32_16x16x32_bf16 v[118:121], v[176:179], v[200:203], v[118:121]
	v_mfma_f32_16x16x32_bf16 v[110:113], v[168:171], v[208:211], v[110:113]
	v_mfma_f32_16x16x32_bf16 v[102:105], v[176:179], v[208:211], v[102:105]
	v_mfma_f32_16x16x32_bf16 v[94:97], v[168:171], v[216:219], v[94:97]
	v_mfma_f32_16x16x32_bf16 v[86:89], v[176:179], v[216:219], v[86:89]
	v_mfma_f32_16x16x32_bf16 v[78:81], v[168:171], v[224:227], v[78:81]
	v_mfma_f32_16x16x32_bf16 v[70:73], v[176:179], v[224:227], v[70:73]
	v_mfma_f32_16x16x32_bf16 v[126:129], v[180:183], v[196:199], v[126:129]
	v_mfma_f32_16x16x32_bf16 v[114:117], v[188:191], v[196:199], v[114:117]
	v_mfma_f32_16x16x32_bf16 v[106:109], v[180:183], v[204:207], v[106:109]
	v_mfma_f32_16x16x32_bf16 v[98:101], v[188:191], v[204:207], v[98:101]
	v_mfma_f32_16x16x32_bf16 v[90:93], v[180:183], v[212:215], v[90:93]
	v_mfma_f32_16x16x32_bf16 v[82:85], v[188:191], v[212:215], v[82:85]
	v_mfma_f32_16x16x32_bf16 v[74:77], v[180:183], v[220:223], v[74:77]
	v_mfma_f32_16x16x32_bf16 v[66:69], v[188:191], v[220:223], v[66:69]
	v_mfma_f32_16x16x32_bf16 v[126:129], v[184:187], v[200:203], v[126:129]
	v_mfma_f32_16x16x32_bf16 v[114:117], v[192:195], v[200:203], v[114:117]
	v_mfma_f32_16x16x32_bf16 v[106:109], v[184:187], v[208:211], v[106:109]
	v_mfma_f32_16x16x32_bf16 v[98:101], v[192:195], v[208:211], v[98:101]
	v_mfma_f32_16x16x32_bf16 v[90:93], v[184:187], v[216:219], v[90:93]
	v_mfma_f32_16x16x32_bf16 v[82:85], v[192:195], v[216:219], v[82:85]
	v_mfma_f32_16x16x32_bf16 v[74:77], v[184:187], v[224:227], v[74:77]
	v_mfma_f32_16x16x32_bf16 v[66:69], v[192:195], v[224:227], v[66:69]
	s_barrier
	s_setprio 0
	s_add_u32 s96, s96, 0x80
	s_addc_u32 s97, s97, 0
	s_add_u32 s98, s96, 0x40000
	s_addc_u32 s99, s97, 0
	s_add_u32 s94, s94, 0x80
	s_addc_u32 s95, s95, 0
	s_add_i32 s7, s7, s25
	s_mov_b32 m0, s7
	ds_read_b128 v[196:199], v160 offset:49152
	global_load_lds_dwordx4 v132, s[96:97]
	s_add_i32 m0, s7, 0x2000
	s_add_i32 s7, s47, s25
	global_load_lds_dwordx4 v136, s[96:97]
	s_mov_b32 m0, s7
	ds_read_b128 v[200:203], v160 offset:50176
	global_load_lds_dwordx4 v132, s[98:99]
	s_add_i32 m0, s7, 0x2000
	ds_read_b128 v[204:207], v160 offset:51200
	global_load_lds_dwordx4 v136, s[98:99]
	s_mov_b32 m0, s66
	ds_read_b128 v[208:211], v160 offset:52224
	global_load_lds_dwordx4 v130, s[94:95]
	s_mov_b32 m0, s67
	ds_read_b128 v[212:215], v160 offset:53248
	global_load_lds_dwordx4 v134, s[94:95]
	ds_read_b128 v[216:219], v160 offset:54272
	ds_read_b128 v[220:223], v160 offset:55296
	ds_read_b128 v[224:227], v160 offset:56320
	s_waitcnt vmcnt(8)
	s_waitcnt lgkmcnt(0)
	s_setprio 1
	s_barrier
	v_mfma_f32_16x16x32_bf16 v[62:65], v[164:167], v[196:199], v[62:65]
	v_mfma_f32_16x16x32_bf16 v[54:57], v[172:175], v[196:199], v[54:57]
	v_mfma_f32_16x16x32_bf16 v[46:49], v[164:167], v[204:207], v[46:49]
	v_mfma_f32_16x16x32_bf16 v[38:41], v[172:175], v[204:207], v[38:41]
	v_mfma_f32_16x16x32_bf16 v[30:33], v[164:167], v[212:215], v[30:33]
	v_mfma_f32_16x16x32_bf16 v[22:25], v[172:175], v[212:215], v[22:25]
	v_mfma_f32_16x16x32_bf16 v[14:17], v[164:167], v[220:223], v[14:17]
	v_mfma_f32_16x16x32_bf16 v[6:9], v[172:175], v[220:223], v[6:9]
	v_mfma_f32_16x16x32_bf16 v[62:65], v[168:171], v[200:203], v[62:65]
	v_mfma_f32_16x16x32_bf16 v[54:57], v[176:179], v[200:203], v[54:57]
	v_mfma_f32_16x16x32_bf16 v[46:49], v[168:171], v[208:211], v[46:49]
	v_mfma_f32_16x16x32_bf16 v[38:41], v[176:179], v[208:211], v[38:41]
	v_mfma_f32_16x16x32_bf16 v[30:33], v[168:171], v[216:219], v[30:33]
	v_mfma_f32_16x16x32_bf16 v[22:25], v[176:179], v[216:219], v[22:25]
	v_mfma_f32_16x16x32_bf16 v[14:17], v[168:171], v[224:227], v[14:17]
	v_mfma_f32_16x16x32_bf16 v[6:9], v[176:179], v[224:227], v[6:9]
	v_mfma_f32_16x16x32_bf16 v[58:61], v[180:183], v[196:199], v[58:61]
	v_mfma_f32_16x16x32_bf16 v[50:53], v[188:191], v[196:199], v[50:53]
	v_mfma_f32_16x16x32_bf16 v[42:45], v[180:183], v[204:207], v[42:45]
	v_mfma_f32_16x16x32_bf16 v[34:37], v[188:191], v[204:207], v[34:37]
	v_mfma_f32_16x16x32_bf16 v[26:29], v[180:183], v[212:215], v[26:29]
	v_mfma_f32_16x16x32_bf16 v[18:21], v[188:191], v[212:215], v[18:21]
	v_mfma_f32_16x16x32_bf16 v[10:13], v[180:183], v[220:223], v[10:13]
	v_mfma_f32_16x16x32_bf16 v[2:5], v[188:191], v[220:223], v[2:5]
	v_mfma_f32_16x16x32_bf16 v[58:61], v[184:187], v[200:203], v[58:61]
	v_mfma_f32_16x16x32_bf16 v[50:53], v[192:195], v[200:203], v[50:53]
	v_mfma_f32_16x16x32_bf16 v[42:45], v[184:187], v[208:211], v[42:45]
	v_mfma_f32_16x16x32_bf16 v[34:37], v[192:195], v[208:211], v[34:37]
	v_mfma_f32_16x16x32_bf16 v[26:29], v[184:187], v[216:219], v[26:29]
	v_mfma_f32_16x16x32_bf16 v[18:21], v[192:195], v[216:219], v[18:21]
	v_mfma_f32_16x16x32_bf16 v[10:13], v[184:187], v[224:227], v[10:13]
	v_mfma_f32_16x16x32_bf16 v[2:5], v[192:195], v[224:227], v[2:5]
	s_barrier
	s_setprio 0
	s_mov_b32 s7, s45
	s_add_u32 s88, s88, 0x100
	s_addc_u32 s89, s89, 0
	s_add_u32 s86, s86, 0x100
	s_addc_u32 s87, s87, 0
	s_cmp_ge_i32 s45, s101
	s_cbranch_scc0 .LBB0_768

.Lmy_nb_4:
	s_nop 0
	v_readfirstlane_b32 s86, v152
	v_readfirstlane_b32 s87, v153
	v_readfirstlane_b32 s88, v150
	v_readfirstlane_b32 s89, v151
	v_readfirstlane_b32 s90, v146
	v_readfirstlane_b32 s91, v147
	v_readfirstlane_b32 s92, v148
	v_readfirstlane_b32 s93, v149
	v_readfirstlane_b32 s100, v154
	v_readfirstlane_b32 s101, v138
	v_add_u32_e32 v230, s74, v141
	v_add_u32_e32 v231, s75, v141
	v_add_u32_e32 v232, 0x18000, v141
	v_add_u32_e32 v233, 0x1c000, v141
	s_add_u32 s98, s86, 0xfffc0080
	s_addc_u32 s99, s87, -1
	s_cmp_eq_u32 s7, s100
	s_cselect_b64 s[94:95], s[90:91], s[98:99]
	s_cselect_b64 s[96:97], s[92:93], s[88:89]
	s_add_i32 s47, s7, 2
	s_mov_b32 m0, s76
	ds_read_b128 v[164:167], v230
	global_load_lds_dwordx4 v144, s[86:87]
	s_mov_b32 m0, s77
	ds_read_b128 v[168:171], v230 offset:1024
	global_load_lds_dwordx4 v142, s[86:87]
	ds_read_b128 v[172:175], v230 offset:2048
	ds_read_b128 v[176:179], v230 offset:3072
	ds_read_b128 v[180:183], v231
	ds_read_b128 v[184:187], v231 offset:1024
	ds_read_b128 v[188:191], v231 offset:2048
	ds_read_b128 v[192:195], v231 offset:3072
	ds_read_b128 v[196:199], v160
	ds_read_b128 v[200:203], v160 offset:1024
	ds_read_b128 v[204:207], v160 offset:2048
	ds_read_b128 v[208:211], v160 offset:3072
	ds_read_b128 v[212:215], v160 offset:4096
	ds_read_b128 v[216:219], v160 offset:5120
	ds_read_b128 v[220:223], v160 offset:6144
	ds_read_b128 v[224:227], v160 offset:7168
	s_waitcnt vmcnt(8)
	s_waitcnt lgkmcnt(0)
	s_setprio 1
	s_barrier
	v_mfma_f32_16x16x32_bf16 v[122:125], v[164:167], v[196:199], 0
	v_mfma_f32_16x16x32_bf16 v[118:121], v[172:175], v[196:199], 0
	v_mfma_f32_16x16x32_bf16 v[110:113], v[164:167], v[204:207], 0
	v_mfma_f32_16x16x32_bf16 v[102:105], v[172:175], v[204:207], 0
	v_mfma_f32_16x16x32_bf16 v[94:97], v[164:167], v[212:215], 0
	v_mfma_f32_16x16x32_bf16 v[86:89], v[172:175], v[212:215], 0
	v_mfma_f32_16x16x32_bf16 v[78:81], v[164:167], v[220:223], 0
	v_mfma_f32_16x16x32_bf16 v[70:73], v[172:175], v[220:223], 0
	v_mfma_f32_16x16x32_bf16 v[122:125], v[168:171], v[200:203], v[122:125]
	v_mfma_f32_16x16x32_bf16 v[118:121], v[176:179], v[200:203], v[118:121]
	v_mfma_f32_16x16x32_bf16 v[110:113], v[168:171], v[208:211], v[110:113]
	v_mfma_f32_16x16x32_bf16 v[102:105], v[176:179], v[208:211], v[102:105]
	v_mfma_f32_16x16x32_bf16 v[94:97], v[168:171], v[216:219], v[94:97]
	v_mfma_f32_16x16x32_bf16 v[86:89], v[176:179], v[216:219], v[86:89]
	v_mfma_f32_16x16x32_bf16 v[78:81], v[168:171], v[224:227], v[78:81]
	v_mfma_f32_16x16x32_bf16 v[70:73], v[176:179], v[224:227], v[70:73]
	v_mfma_f32_16x16x32_bf16 v[126:129], v[180:183], v[196:199], 0
	v_mfma_f32_16x16x32_bf16 v[114:117], v[188:191], v[196:199], 0
	v_mfma_f32_16x16x32_bf16 v[106:109], v[180:183], v[204:207], 0
	v_mfma_f32_16x16x32_bf16 v[98:101], v[188:191], v[204:207], 0
	v_mfma_f32_16x16x32_bf16 v[90:93], v[180:183], v[212:215], 0
	v_mfma_f32_16x16x32_bf16 v[82:85], v[188:191], v[212:215], 0
	v_mfma_f32_16x16x32_bf16 v[74:77], v[180:183], v[220:223], 0
	v_mfma_f32_16x16x32_bf16 v[66:69], v[188:191], v[220:223], 0
	v_mfma_f32_16x16x32_bf16 v[126:129], v[184:187], v[200:203], v[126:129]
	v_mfma_f32_16x16x32_bf16 v[114:117], v[192:195], v[200:203], v[114:117]
	v_mfma_f32_16x16x32_bf16 v[106:109], v[184:187], v[208:211], v[106:109]
	v_mfma_f32_16x16x32_bf16 v[98:101], v[192:195], v[208:211], v[98:101]
	v_mfma_f32_16x16x32_bf16 v[90:93], v[184:187], v[216:219], v[90:93]
	v_mfma_f32_16x16x32_bf16 v[82:85], v[192:195], v[216:219], v[82:85]
	v_mfma_f32_16x16x32_bf16 v[74:77], v[184:187], v[224:227], v[74:77]
	v_mfma_f32_16x16x32_bf16 v[66:69], v[192:195], v[224:227], v[66:69]
	s_barrier
	s_setprio 0
	s_add_u32 s98, s96, 0x40000
	s_addc_u32 s99, s97, 0
	s_mov_b32 m0, s78
	ds_read_b128 v[196:199], v160 offset:16384
	global_load_lds_dwordx4 v132, s[96:97]
	s_mov_b32 m0, s79
	s_add_i32 s7, s75, s29
	global_load_lds_dwordx4 v136, s[96:97]
	s_mov_b32 m0, s7
	ds_read_b128 v[200:203], v160 offset:17408
	global_load_lds_dwordx4 v132, s[98:99]
	s_add_i32 m0, s7, 0x2000
	ds_read_b128 v[204:207], v160 offset:18432
	global_load_lds_dwordx4 v136, s[98:99]
	s_mov_b32 m0, s51
	ds_read_b128 v[208:211], v160 offset:19456
	global_load_lds_dwordx4 v130, s[94:95]
	s_mov_b32 m0, s60
	ds_read_b128 v[212:215], v160 offset:20480
	global_load_lds_dwordx4 v134, s[94:95]
	ds_read_b128 v[216:219], v160 offset:21504
	ds_read_b128 v[220:223], v160 offset:22528
	ds_read_b128 v[224:227], v160 offset:23552
	s_waitcnt vmcnt(8)
	s_waitcnt lgkmcnt(0)
	s_setprio 1
	s_barrier
	v_mfma_f32_16x16x32_bf16 v[62:65], v[164:167], v[196:199], 0
	v_mfma_f32_16x16x32_bf16 v[54:57], v[172:175], v[196:199], 0
	v_mfma_f32_16x16x32_bf16 v[46:49], v[164:167], v[204:207], 0
	v_mfma_f32_16x16x32_bf16 v[38:41], v[172:175], v[204:207], 0
	v_mfma_f32_16x16x32_bf16 v[30:33], v[164:167], v[212:215], 0
	v_mfma_f32_16x16x32_bf16 v[22:25], v[172:175], v[212:215], 0
	v_mfma_f32_16x16x32_bf16 v[14:17], v[164:167], v[220:223], 0
	v_mfma_f32_16x16x32_bf16 v[6:9], v[172:175], v[220:223], 0
	v_mfma_f32_16x16x32_bf16 v[62:65], v[168:171], v[200:203], v[62:65]
	v_mfma_f32_16x16x32_bf16 v[54:57], v[176:179], v[200:203], v[54:57]
	v_mfma_f32_16x16x32_bf16 v[46:49], v[168:171], v[208:211], v[46:49]
	v_mfma_f32_16x16x32_bf16 v[38:41], v[176:179], v[208:211], v[38:41]
	v_mfma_f32_16x16x32_bf16 v[30:33], v[168:171], v[216:219], v[30:33]
	v_mfma_f32_16x16x32_bf16 v[22:25], v[176:179], v[216:219], v[22:25]
	v_mfma_f32_16x16x32_bf16 v[14:17], v[168:171], v[224:227], v[14:17]
	v_mfma_f32_16x16x32_bf16 v[6:9], v[176:179], v[224:227], v[6:9]
	v_mfma_f32_16x16x32_bf16 v[58:61], v[180:183], v[196:199], 0
	v_mfma_f32_16x16x32_bf16 v[50:53], v[188:191], v[196:199], 0
	v_mfma_f32_16x16x32_bf16 v[42:45], v[180:183], v[204:207], 0
	v_mfma_f32_16x16x32_bf16 v[34:37], v[188:191], v[204:207], 0
	v_mfma_f32_16x16x32_bf16 v[26:29], v[180:183], v[212:215], 0
	v_mfma_f32_16x16x32_bf16 v[18:21], v[188:191], v[212:215], 0
	v_mfma_f32_16x16x32_bf16 v[10:13], v[180:183], v[220:223], 0
	v_mfma_f32_16x16x32_bf16 v[2:5], v[188:191], v[220:223], 0
	v_mfma_f32_16x16x32_bf16 v[58:61], v[184:187], v[200:203], v[58:61]
	v_mfma_f32_16x16x32_bf16 v[50:53], v[192:195], v[200:203], v[50:53]
	v_mfma_f32_16x16x32_bf16 v[42:45], v[184:187], v[208:211], v[42:45]
	v_mfma_f32_16x16x32_bf16 v[34:37], v[192:195], v[208:211], v[34:37]
	v_mfma_f32_16x16x32_bf16 v[26:29], v[184:187], v[216:219], v[26:29]
	v_mfma_f32_16x16x32_bf16 v[18:21], v[192:195], v[216:219], v[18:21]
	v_mfma_f32_16x16x32_bf16 v[10:13], v[184:187], v[224:227], v[10:13]
	v_mfma_f32_16x16x32_bf16 v[2:5], v[192:195], v[224:227], v[2:5]
	s_barrier
	s_setprio 0
	s_add_u32 s98, s94, 0x40000
	s_addc_u32 s99, s95, 0
	s_add_i32 s7, 0, 0x18000
	s_add_i32 s49, 0, 0x1c000
	s_mov_b32 m0, s61
	ds_read_b128 v[164:167], v232
	global_load_lds_dwordx4 v130, s[98:99]
	s_mov_b32 m0, s62
	ds_read_b128 v[168:171], v232 offset:1024
	global_load_lds_dwordx4 v134, s[98:99]
	ds_read_b128 v[172:175], v232 offset:2048
	ds_read_b128 v[176:179], v232 offset:3072
	ds_read_b128 v[180:183], v233
	ds_read_b128 v[184:187], v233 offset:1024
	ds_read_b128 v[188:191], v233 offset:2048
	ds_read_b128 v[192:195], v233 offset:3072
	ds_read_b128 v[196:199], v160 offset:32768
	ds_read_b128 v[200:203], v160 offset:33792
	ds_read_b128 v[204:207], v160 offset:34816
	ds_read_b128 v[208:211], v160 offset:35840
	ds_read_b128 v[212:215], v160 offset:36864
	ds_read_b128 v[216:219], v160 offset:37888
	ds_read_b128 v[220:223], v160 offset:38912
	ds_read_b128 v[224:227], v160 offset:39936
	s_waitcnt vmcnt(8)
	s_waitcnt lgkmcnt(0)
	s_setprio 1
	s_barrier
	v_mfma_f32_16x16x32_bf16 v[122:125], v[164:167], v[196:199], v[122:125]
	v_mfma_f32_16x16x32_bf16 v[118:121], v[172:175], v[196:199], v[118:121]
	v_mfma_f32_16x16x32_bf16 v[110:113], v[164:167], v[204:207], v[110:113]
	v_mfma_f32_16x16x32_bf16 v[102:105], v[172:175], v[204:207], v[102:105]
	v_mfma_f32_16x16x32_bf16 v[94:97], v[164:167], v[212:215], v[94:97]
	v_mfma_f32_16x16x32_bf16 v[86:89], v[172:175], v[212:215], v[86:89]
	v_mfma_f32_16x16x32_bf16 v[78:81], v[164:167], v[220:223], v[78:81]
	v_mfma_f32_16x16x32_bf16 v[70:73], v[172:175], v[220:223], v[70:73]
	v_mfma_f32_16x16x32_bf16 v[122:125], v[168:171], v[200:203], v[122:125]
	v_mfma_f32_16x16x32_bf16 v[118:121], v[176:179], v[200:203], v[118:121]
	v_mfma_f32_16x16x32_bf16 v[110:113], v[168:171], v[208:211], v[110:113]
	v_mfma_f32_16x16x32_bf16 v[102:105], v[176:179], v[208:211], v[102:105]
	v_mfma_f32_16x16x32_bf16 v[94:97], v[168:171], v[216:219], v[94:97]
	v_mfma_f32_16x16x32_bf16 v[86:89], v[176:179], v[216:219], v[86:89]
	v_mfma_f32_16x16x32_bf16 v[78:81], v[168:171], v[224:227], v[78:81]
	v_mfma_f32_16x16x32_bf16 v[70:73], v[176:179], v[224:227], v[70:73]
	v_mfma_f32_16x16x32_bf16 v[126:129], v[180:183], v[196:199], v[126:129]
	v_mfma_f32_16x16x32_bf16 v[114:117], v[188:191], v[196:199], v[114:117]
	v_mfma_f32_16x16x32_bf16 v[106:109], v[180:183], v[204:207], v[106:109]
	v_mfma_f32_16x16x32_bf16 v[98:101], v[188:191], v[204:207], v[98:101]
	v_mfma_f32_16x16x32_bf16 v[90:93], v[180:183], v[212:215], v[90:93]
	v_mfma_f32_16x16x32_bf16 v[82:85], v[188:191], v[212:215], v[82:85]
	v_mfma_f32_16x16x32_bf16 v[74:77], v[180:183], v[220:223], v[74:77]
	v_mfma_f32_16x16x32_bf16 v[66:69], v[188:191], v[220:223], v[66:69]
	v_mfma_f32_16x16x32_bf16 v[126:129], v[184:187], v[200:203], v[126:129]
	v_mfma_f32_16x16x32_bf16 v[114:117], v[192:195], v[200:203], v[114:117]
	v_mfma_f32_16x16x32_bf16 v[106:109], v[184:187], v[208:211], v[106:109]
	v_mfma_f32_16x16x32_bf16 v[98:101], v[192:195], v[208:211], v[98:101]
	v_mfma_f32_16x16x32_bf16 v[90:93], v[184:187], v[216:219], v[90:93]
	v_mfma_f32_16x16x32_bf16 v[82:85], v[192:195], v[216:219], v[82:85]
	v_mfma_f32_16x16x32_bf16 v[74:77], v[184:187], v[224:227], v[74:77]
	v_mfma_f32_16x16x32_bf16 v[66:69], v[192:195], v[224:227], v[66:69]
	s_barrier
	s_setprio 0
	s_add_u32 s96, s96, 0x80
	s_addc_u32 s97, s97, 0
	s_add_u32 s98, s96, 0x40000
	s_addc_u32 s99, s97, 0
	s_add_u32 s94, s94, 0x80
	s_addc_u32 s95, s95, 0
	s_add_i32 s7, s7, s29
	s_mov_b32 m0, s7
	ds_read_b128 v[196:199], v160 offset:49152
	global_load_lds_dwordx4 v132, s[96:97]
	s_add_i32 m0, s7, 0x2000
	s_add_i32 s7, s49, s29
	global_load_lds_dwordx4 v136, s[96:97]
	s_mov_b32 m0, s7
	ds_read_b128 v[200:203], v160 offset:50176
	global_load_lds_dwordx4 v132, s[98:99]
	s_add_i32 m0, s7, 0x2000
	ds_read_b128 v[204:207], v160 offset:51200
	global_load_lds_dwordx4 v136, s[98:99]
	s_mov_b32 m0, s63
	ds_read_b128 v[208:211], v160 offset:52224
	global_load_lds_dwordx4 v130, s[94:95]
	s_mov_b32 m0, s64
	ds_read_b128 v[212:215], v160 offset:53248
	global_load_lds_dwordx4 v134, s[94:95]
	ds_read_b128 v[216:219], v160 offset:54272
	ds_read_b128 v[220:223], v160 offset:55296
	ds_read_b128 v[224:227], v160 offset:56320
	s_waitcnt vmcnt(8)
	s_waitcnt lgkmcnt(0)
	s_setprio 1
	s_barrier
	v_mfma_f32_16x16x32_bf16 v[62:65], v[164:167], v[196:199], v[62:65]
	v_mfma_f32_16x16x32_bf16 v[54:57], v[172:175], v[196:199], v[54:57]
	v_mfma_f32_16x16x32_bf16 v[46:49], v[164:167], v[204:207], v[46:49]
	v_mfma_f32_16x16x32_bf16 v[38:41], v[172:175], v[204:207], v[38:41]
	v_mfma_f32_16x16x32_bf16 v[30:33], v[164:167], v[212:215], v[30:33]
	v_mfma_f32_16x16x32_bf16 v[22:25], v[172:175], v[212:215], v[22:25]
	v_mfma_f32_16x16x32_bf16 v[14:17], v[164:167], v[220:223], v[14:17]
	v_mfma_f32_16x16x32_bf16 v[6:9], v[172:175], v[220:223], v[6:9]
	v_mfma_f32_16x16x32_bf16 v[62:65], v[168:171], v[200:203], v[62:65]
	v_mfma_f32_16x16x32_bf16 v[54:57], v[176:179], v[200:203], v[54:57]
	v_mfma_f32_16x16x32_bf16 v[46:49], v[168:171], v[208:211], v[46:49]
	v_mfma_f32_16x16x32_bf16 v[38:41], v[176:179], v[208:211], v[38:41]
	v_mfma_f32_16x16x32_bf16 v[30:33], v[168:171], v[216:219], v[30:33]
	v_mfma_f32_16x16x32_bf16 v[22:25], v[176:179], v[216:219], v[22:25]
	v_mfma_f32_16x16x32_bf16 v[14:17], v[168:171], v[224:227], v[14:17]
	v_mfma_f32_16x16x32_bf16 v[6:9], v[176:179], v[224:227], v[6:9]
	v_mfma_f32_16x16x32_bf16 v[58:61], v[180:183], v[196:199], v[58:61]
	v_mfma_f32_16x16x32_bf16 v[50:53], v[188:191], v[196:199], v[50:53]
	v_mfma_f32_16x16x32_bf16 v[42:45], v[180:183], v[204:207], v[42:45]
	v_mfma_f32_16x16x32_bf16 v[34:37], v[188:191], v[204:207], v[34:37]
	v_mfma_f32_16x16x32_bf16 v[26:29], v[180:183], v[212:215], v[26:29]
	v_mfma_f32_16x16x32_bf16 v[18:21], v[188:191], v[212:215], v[18:21]
	v_mfma_f32_16x16x32_bf16 v[10:13], v[180:183], v[220:223], v[10:13]
	v_mfma_f32_16x16x32_bf16 v[2:5], v[188:191], v[220:223], v[2:5]
	v_mfma_f32_16x16x32_bf16 v[58:61], v[184:187], v[200:203], v[58:61]
	v_mfma_f32_16x16x32_bf16 v[50:53], v[192:195], v[200:203], v[50:53]
	v_mfma_f32_16x16x32_bf16 v[42:45], v[184:187], v[208:211], v[42:45]
	v_mfma_f32_16x16x32_bf16 v[34:37], v[192:195], v[208:211], v[34:37]
	v_mfma_f32_16x16x32_bf16 v[26:29], v[184:187], v[216:219], v[26:29]
	v_mfma_f32_16x16x32_bf16 v[18:21], v[192:195], v[216:219], v[18:21]
	v_mfma_f32_16x16x32_bf16 v[10:13], v[184:187], v[224:227], v[10:13]
	v_mfma_f32_16x16x32_bf16 v[2:5], v[192:195], v[224:227], v[2:5]
	s_barrier
	s_setprio 0
	s_mov_b32 s7, s47
	s_add_u32 s88, s88, 0x100
	s_addc_u32 s89, s89, 0
	s_add_u32 s86, s86, 0x100
	s_addc_u32 s87, s87, 0
	s_cmp_ge_i32 s47, s101
	s_cbranch_scc1 .Lmy_kexit_4
.LBB0_949:
	s_add_u32 s98, s86, 0xfffc0080
	s_addc_u32 s99, s87, -1
	s_cmp_eq_u32 s7, s100
	s_cselect_b64 s[94:95], s[90:91], s[98:99]
	s_cselect_b64 s[96:97], s[92:93], s[88:89]
	s_add_i32 s47, s7, 2
	s_mov_b32 m0, s76
	ds_read_b128 v[164:167], v230
	global_load_lds_dwordx4 v144, s[86:87]
	s_mov_b32 m0, s77
	ds_read_b128 v[168:171], v230 offset:1024
	global_load_lds_dwordx4 v142, s[86:87]
	ds_read_b128 v[172:175], v230 offset:2048
	ds_read_b128 v[176:179], v230 offset:3072
	ds_read_b128 v[180:183], v231
	ds_read_b128 v[184:187], v231 offset:1024
	ds_read_b128 v[188:191], v231 offset:2048
	ds_read_b128 v[192:195], v231 offset:3072
	ds_read_b128 v[196:199], v160
	ds_read_b128 v[200:203], v160 offset:1024
	ds_read_b128 v[204:207], v160 offset:2048
	ds_read_b128 v[208:211], v160 offset:3072
	ds_read_b128 v[212:215], v160 offset:4096
	ds_read_b128 v[216:219], v160 offset:5120
	ds_read_b128 v[220:223], v160 offset:6144
	ds_read_b128 v[224:227], v160 offset:7168
	s_waitcnt vmcnt(8)
	s_waitcnt lgkmcnt(0)
	s_setprio 1
	s_barrier
	v_mfma_f32_16x16x32_bf16 v[122:125], v[164:167], v[196:199], v[122:125]
	v_mfma_f32_16x16x32_bf16 v[118:121], v[172:175], v[196:199], v[118:121]
	v_mfma_f32_16x16x32_bf16 v[110:113], v[164:167], v[204:207], v[110:113]
	v_mfma_f32_16x16x32_bf16 v[102:105], v[172:175], v[204:207], v[102:105]
	v_mfma_f32_16x16x32_bf16 v[94:97], v[164:167], v[212:215], v[94:97]
	v_mfma_f32_16x16x32_bf16 v[86:89], v[172:175], v[212:215], v[86:89]
	v_mfma_f32_16x16x32_bf16 v[78:81], v[164:167], v[220:223], v[78:81]
	v_mfma_f32_16x16x32_bf16 v[70:73], v[172:175], v[220:223], v[70:73]
	v_mfma_f32_16x16x32_bf16 v[122:125], v[168:171], v[200:203], v[122:125]
	v_mfma_f32_16x16x32_bf16 v[118:121], v[176:179], v[200:203], v[118:121]
	v_mfma_f32_16x16x32_bf16 v[110:113], v[168:171], v[208:211], v[110:113]
	v_mfma_f32_16x16x32_bf16 v[102:105], v[176:179], v[208:211], v[102:105]
	v_mfma_f32_16x16x32_bf16 v[94:97], v[168:171], v[216:219], v[94:97]
	v_mfma_f32_16x16x32_bf16 v[86:89], v[176:179], v[216:219], v[86:89]
	v_mfma_f32_16x16x32_bf16 v[78:81], v[168:171], v[224:227], v[78:81]
	v_mfma_f32_16x16x32_bf16 v[70:73], v[176:179], v[224:227], v[70:73]
	v_mfma_f32_16x16x32_bf16 v[126:129], v[180:183], v[196:199], v[126:129]
	v_mfma_f32_16x16x32_bf16 v[114:117], v[188:191], v[196:199], v[114:117]
	v_mfma_f32_16x16x32_bf16 v[106:109], v[180:183], v[204:207], v[106:109]
	v_mfma_f32_16x16x32_bf16 v[98:101], v[188:191], v[204:207], v[98:101]
	v_mfma_f32_16x16x32_bf16 v[90:93], v[180:183], v[212:215], v[90:93]
	v_mfma_f32_16x16x32_bf16 v[82:85], v[188:191], v[212:215], v[82:85]
	v_mfma_f32_16x16x32_bf16 v[74:77], v[180:183], v[220:223], v[74:77]
	v_mfma_f32_16x16x32_bf16 v[66:69], v[188:191], v[220:223], v[66:69]
	v_mfma_f32_16x16x32_bf16 v[126:129], v[184:187], v[200:203], v[126:129]
	v_mfma_f32_16x16x32_bf16 v[114:117], v[192:195], v[200:203], v[114:117]
	v_mfma_f32_16x16x32_bf16 v[106:109], v[184:187], v[208:211], v[106:109]
	v_mfma_f32_16x16x32_bf16 v[98:101], v[192:195], v[208:211], v[98:101]
	v_mfma_f32_16x16x32_bf16 v[90:93], v[184:187], v[216:219], v[90:93]
	v_mfma_f32_16x16x32_bf16 v[82:85], v[192:195], v[216:219], v[82:85]
	v_mfma_f32_16x16x32_bf16 v[74:77], v[184:187], v[224:227], v[74:77]
	v_mfma_f32_16x16x32_bf16 v[66:69], v[192:195], v[224:227], v[66:69]
	s_barrier
	s_setprio 0
	s_add_u32 s98, s96, 0x40000
	s_addc_u32 s99, s97, 0
	s_mov_b32 m0, s78
	ds_read_b128 v[196:199], v160 offset:16384
	global_load_lds_dwordx4 v132, s[96:97]
	s_mov_b32 m0, s79
	s_add_i32 s7, s75, s29
	global_load_lds_dwordx4 v136, s[96:97]
	s_mov_b32 m0, s7
	ds_read_b128 v[200:203], v160 offset:17408
	global_load_lds_dwordx4 v132, s[98:99]
	s_add_i32 m0, s7, 0x2000
	ds_read_b128 v[204:207], v160 offset:18432
	global_load_lds_dwordx4 v136, s[98:99]
	s_mov_b32 m0, s51
	ds_read_b128 v[208:211], v160 offset:19456
	global_load_lds_dwordx4 v130, s[94:95]
	s_mov_b32 m0, s60
	ds_read_b128 v[212:215], v160 offset:20480
	global_load_lds_dwordx4 v134, s[94:95]
	ds_read_b128 v[216:219], v160 offset:21504
	ds_read_b128 v[220:223], v160 offset:22528
	ds_read_b128 v[224:227], v160 offset:23552
	s_waitcnt vmcnt(8)
	s_waitcnt lgkmcnt(0)
	s_setprio 1
	s_barrier
	v_mfma_f32_16x16x32_bf16 v[62:65], v[164:167], v[196:199], v[62:65]
	v_mfma_f32_16x16x32_bf16 v[54:57], v[172:175], v[196:199], v[54:57]
	v_mfma_f32_16x16x32_bf16 v[46:49], v[164:167], v[204:207], v[46:49]
	v_mfma_f32_16x16x32_bf16 v[38:41], v[172:175], v[204:207], v[38:41]
	v_mfma_f32_16x16x32_bf16 v[30:33], v[164:167], v[212:215], v[30:33]
	v_mfma_f32_16x16x32_bf16 v[22:25], v[172:175], v[212:215], v[22:25]
	v_mfma_f32_16x16x32_bf16 v[14:17], v[164:167], v[220:223], v[14:17]
	v_mfma_f32_16x16x32_bf16 v[6:9], v[172:175], v[220:223], v[6:9]
	v_mfma_f32_16x16x32_bf16 v[62:65], v[168:171], v[200:203], v[62:65]
	v_mfma_f32_16x16x32_bf16 v[54:57], v[176:179], v[200:203], v[54:57]
	v_mfma_f32_16x16x32_bf16 v[46:49], v[168:171], v[208:211], v[46:49]
	v_mfma_f32_16x16x32_bf16 v[38:41], v[176:179], v[208:211], v[38:41]
	v_mfma_f32_16x16x32_bf16 v[30:33], v[168:171], v[216:219], v[30:33]
	v_mfma_f32_16x16x32_bf16 v[22:25], v[176:179], v[216:219], v[22:25]
	v_mfma_f32_16x16x32_bf16 v[14:17], v[168:171], v[224:227], v[14:17]
	v_mfma_f32_16x16x32_bf16 v[6:9], v[176:179], v[224:227], v[6:9]
	v_mfma_f32_16x16x32_bf16 v[58:61], v[180:183], v[196:199], v[58:61]
	v_mfma_f32_16x16x32_bf16 v[50:53], v[188:191], v[196:199], v[50:53]
	v_mfma_f32_16x16x32_bf16 v[42:45], v[180:183], v[204:207], v[42:45]
	v_mfma_f32_16x16x32_bf16 v[34:37], v[188:191], v[204:207], v[34:37]
	v_mfma_f32_16x16x32_bf16 v[26:29], v[180:183], v[212:215], v[26:29]
	v_mfma_f32_16x16x32_bf16 v[18:21], v[188:191], v[212:215], v[18:21]
	v_mfma_f32_16x16x32_bf16 v[10:13], v[180:183], v[220:223], v[10:13]
	v_mfma_f32_16x16x32_bf16 v[2:5], v[188:191], v[220:223], v[2:5]
	v_mfma_f32_16x16x32_bf16 v[58:61], v[184:187], v[200:203], v[58:61]
	v_mfma_f32_16x16x32_bf16 v[50:53], v[192:195], v[200:203], v[50:53]
	v_mfma_f32_16x16x32_bf16 v[42:45], v[184:187], v[208:211], v[42:45]
	v_mfma_f32_16x16x32_bf16 v[34:37], v[192:195], v[208:211], v[34:37]
	v_mfma_f32_16x16x32_bf16 v[26:29], v[184:187], v[216:219], v[26:29]
	v_mfma_f32_16x16x32_bf16 v[18:21], v[192:195], v[216:219], v[18:21]
	v_mfma_f32_16x16x32_bf16 v[10:13], v[184:187], v[224:227], v[10:13]
	v_mfma_f32_16x16x32_bf16 v[2:5], v[192:195], v[224:227], v[2:5]
	s_barrier
	s_setprio 0
	s_add_u32 s98, s94, 0x40000
	s_addc_u32 s99, s95, 0
	s_add_i32 s7, 0, 0x18000
	s_add_i32 s49, 0, 0x1c000
	s_mov_b32 m0, s61
	ds_read_b128 v[164:167], v232
	global_load_lds_dwordx4 v130, s[98:99]
	s_mov_b32 m0, s62
	ds_read_b128 v[168:171], v232 offset:1024
	global_load_lds_dwordx4 v134, s[98:99]
	ds_read_b128 v[172:175], v232 offset:2048
	ds_read_b128 v[176:179], v232 offset:3072
	ds_read_b128 v[180:183], v233
	ds_read_b128 v[184:187], v233 offset:1024
	ds_read_b128 v[188:191], v233 offset:2048
	ds_read_b128 v[192:195], v233 offset:3072
	ds_read_b128 v[196:199], v160 offset:32768
	ds_read_b128 v[200:203], v160 offset:33792
	ds_read_b128 v[204:207], v160 offset:34816
	ds_read_b128 v[208:211], v160 offset:35840
	ds_read_b128 v[212:215], v160 offset:36864
	ds_read_b128 v[216:219], v160 offset:37888
	ds_read_b128 v[220:223], v160 offset:38912
	ds_read_b128 v[224:227], v160 offset:39936
	s_waitcnt vmcnt(8)
	s_waitcnt lgkmcnt(0)
	s_setprio 1
	s_barrier
	v_mfma_f32_16x16x32_bf16 v[122:125], v[164:167], v[196:199], v[122:125]
	v_mfma_f32_16x16x32_bf16 v[118:121], v[172:175], v[196:199], v[118:121]
	v_mfma_f32_16x16x32_bf16 v[110:113], v[164:167], v[204:207], v[110:113]
	v_mfma_f32_16x16x32_bf16 v[102:105], v[172:175], v[204:207], v[102:105]
	v_mfma_f32_16x16x32_bf16 v[94:97], v[164:167], v[212:215], v[94:97]
	v_mfma_f32_16x16x32_bf16 v[86:89], v[172:175], v[212:215], v[86:89]
	v_mfma_f32_16x16x32_bf16 v[78:81], v[164:167], v[220:223], v[78:81]
	v_mfma_f32_16x16x32_bf16 v[70:73], v[172:175], v[220:223], v[70:73]
	v_mfma_f32_16x16x32_bf16 v[122:125], v[168:171], v[200:203], v[122:125]
	v_mfma_f32_16x16x32_bf16 v[118:121], v[176:179], v[200:203], v[118:121]
	v_mfma_f32_16x16x32_bf16 v[110:113], v[168:171], v[208:211], v[110:113]
	v_mfma_f32_16x16x32_bf16 v[102:105], v[176:179], v[208:211], v[102:105]
	v_mfma_f32_16x16x32_bf16 v[94:97], v[168:171], v[216:219], v[94:97]
	v_mfma_f32_16x16x32_bf16 v[86:89], v[176:179], v[216:219], v[86:89]
	v_mfma_f32_16x16x32_bf16 v[78:81], v[168:171], v[224:227], v[78:81]
	v_mfma_f32_16x16x32_bf16 v[70:73], v[176:179], v[224:227], v[70:73]
	v_mfma_f32_16x16x32_bf16 v[126:129], v[180:183], v[196:199], v[126:129]
	v_mfma_f32_16x16x32_bf16 v[114:117], v[188:191], v[196:199], v[114:117]
	v_mfma_f32_16x16x32_bf16 v[106:109], v[180:183], v[204:207], v[106:109]
	v_mfma_f32_16x16x32_bf16 v[98:101], v[188:191], v[204:207], v[98:101]
	v_mfma_f32_16x16x32_bf16 v[90:93], v[180:183], v[212:215], v[90:93]
	v_mfma_f32_16x16x32_bf16 v[82:85], v[188:191], v[212:215], v[82:85]
	v_mfma_f32_16x16x32_bf16 v[74:77], v[180:183], v[220:223], v[74:77]
	v_mfma_f32_16x16x32_bf16 v[66:69], v[188:191], v[220:223], v[66:69]
	v_mfma_f32_16x16x32_bf16 v[126:129], v[184:187], v[200:203], v[126:129]
	v_mfma_f32_16x16x32_bf16 v[114:117], v[192:195], v[200:203], v[114:117]
	v_mfma_f32_16x16x32_bf16 v[106:109], v[184:187], v[208:211], v[106:109]
	v_mfma_f32_16x16x32_bf16 v[98:101], v[192:195], v[208:211], v[98:101]
	v_mfma_f32_16x16x32_bf16 v[90:93], v[184:187], v[216:219], v[90:93]
	v_mfma_f32_16x16x32_bf16 v[82:85], v[192:195], v[216:219], v[82:85]
	v_mfma_f32_16x16x32_bf16 v[74:77], v[184:187], v[224:227], v[74:77]
	v_mfma_f32_16x16x32_bf16 v[66:69], v[192:195], v[224:227], v[66:69]
	s_barrier
	s_setprio 0
	s_add_u32 s96, s96, 0x80
	s_addc_u32 s97, s97, 0
	s_add_u32 s98, s96, 0x40000
	s_addc_u32 s99, s97, 0
	s_add_u32 s94, s94, 0x80
	s_addc_u32 s95, s95, 0
	s_add_i32 s7, s7, s29
	s_mov_b32 m0, s7
	ds_read_b128 v[196:199], v160 offset:49152
	global_load_lds_dwordx4 v132, s[96:97]
	s_add_i32 m0, s7, 0x2000
	s_add_i32 s7, s49, s29
	global_load_lds_dwordx4 v136, s[96:97]
	s_mov_b32 m0, s7
	ds_read_b128 v[200:203], v160 offset:50176
	global_load_lds_dwordx4 v132, s[98:99]
	s_add_i32 m0, s7, 0x2000
	ds_read_b128 v[204:207], v160 offset:51200
	global_load_lds_dwordx4 v136, s[98:99]
	s_mov_b32 m0, s63
	ds_read_b128 v[208:211], v160 offset:52224
	global_load_lds_dwordx4 v130, s[94:95]
	s_mov_b32 m0, s64
	ds_read_b128 v[212:215], v160 offset:53248
	global_load_lds_dwordx4 v134, s[94:95]
	ds_read_b128 v[216:219], v160 offset:54272
	ds_read_b128 v[220:223], v160 offset:55296
	ds_read_b128 v[224:227], v160 offset:56320
	s_waitcnt vmcnt(8)
	s_waitcnt lgkmcnt(0)
	s_setprio 1
	s_barrier
	v_mfma_f32_16x16x32_bf16 v[62:65], v[164:167], v[196:199], v[62:65]
	v_mfma_f32_16x16x32_bf16 v[54:57], v[172:175], v[196:199], v[54:57]
	v_mfma_f32_16x16x32_bf16 v[46:49], v[164:167], v[204:207], v[46:49]
	v_mfma_f32_16x16x32_bf16 v[38:41], v[172:175], v[204:207], v[38:41]
	v_mfma_f32_16x16x32_bf16 v[30:33], v[164:167], v[212:215], v[30:33]
	v_mfma_f32_16x16x32_bf16 v[22:25], v[172:175], v[212:215], v[22:25]
	v_mfma_f32_16x16x32_bf16 v[14:17], v[164:167], v[220:223], v[14:17]
	v_mfma_f32_16x16x32_bf16 v[6:9], v[172:175], v[220:223], v[6:9]
	v_mfma_f32_16x16x32_bf16 v[62:65], v[168:171], v[200:203], v[62:65]
	v_mfma_f32_16x16x32_bf16 v[54:57], v[176:179], v[200:203], v[54:57]
	v_mfma_f32_16x16x32_bf16 v[46:49], v[168:171], v[208:211], v[46:49]
	v_mfma_f32_16x16x32_bf16 v[38:41], v[176:179], v[208:211], v[38:41]
	v_mfma_f32_16x16x32_bf16 v[30:33], v[168:171], v[216:219], v[30:33]
	v_mfma_f32_16x16x32_bf16 v[22:25], v[176:179], v[216:219], v[22:25]
	v_mfma_f32_16x16x32_bf16 v[14:17], v[168:171], v[224:227], v[14:17]
	v_mfma_f32_16x16x32_bf16 v[6:9], v[176:179], v[224:227], v[6:9]
	v_mfma_f32_16x16x32_bf16 v[58:61], v[180:183], v[196:199], v[58:61]
	v_mfma_f32_16x16x32_bf16 v[50:53], v[188:191], v[196:199], v[50:53]
	v_mfma_f32_16x16x32_bf16 v[42:45], v[180:183], v[204:207], v[42:45]
	v_mfma_f32_16x16x32_bf16 v[34:37], v[188:191], v[204:207], v[34:37]
	v_mfma_f32_16x16x32_bf16 v[26:29], v[180:183], v[212:215], v[26:29]
	v_mfma_f32_16x16x32_bf16 v[18:21], v[188:191], v[212:215], v[18:21]
	v_mfma_f32_16x16x32_bf16 v[10:13], v[180:183], v[220:223], v[10:13]
	v_mfma_f32_16x16x32_bf16 v[2:5], v[188:191], v[220:223], v[2:5]
	v_mfma_f32_16x16x32_bf16 v[58:61], v[184:187], v[200:203], v[58:61]
	v_mfma_f32_16x16x32_bf16 v[50:53], v[192:195], v[200:203], v[50:53]
	v_mfma_f32_16x16x32_bf16 v[42:45], v[184:187], v[208:211], v[42:45]
	v_mfma_f32_16x16x32_bf16 v[34:37], v[192:195], v[208:211], v[34:37]
	v_mfma_f32_16x16x32_bf16 v[26:29], v[184:187], v[216:219], v[26:29]
	v_mfma_f32_16x16x32_bf16 v[18:21], v[192:195], v[216:219], v[18:21]
	v_mfma_f32_16x16x32_bf16 v[10:13], v[184:187], v[224:227], v[10:13]
	v_mfma_f32_16x16x32_bf16 v[2:5], v[192:195], v[224:227], v[2:5]
	s_barrier
	s_setprio 0
	s_mov_b32 s7, s47
	s_add_u32 s88, s88, 0x100
	s_addc_u32 s89, s89, 0
	s_add_u32 s86, s86, 0x100
	s_addc_u32 s87, s87, 0
	s_cmp_ge_i32 s47, s101
	s_cbranch_scc0 .LBB0_949

.Lmy_nb_5:
	s_nop 0
	v_readfirstlane_b32 s86, v150
	v_readfirstlane_b32 s87, v151
	v_readfirstlane_b32 s88, v152
	v_readfirstlane_b32 s89, v153
	v_readfirstlane_b32 s90, v146
	v_readfirstlane_b32 s91, v147
	v_readfirstlane_b32 s92, v148
	v_readfirstlane_b32 s93, v149
	v_readfirstlane_b32 s100, v138
	v_readfirstlane_b32 s101, v156
	v_add_u32_e32 v230, s67, v141
	v_add_u32_e32 v231, s68, v141
	v_add_u32_e32 v232, 0x18000, v141
	v_add_u32_e32 v233, 0x1c000, v141
	s_add_u32 s98, s86, 0x100
	s_addc_u32 s99, s87, 0
	s_cmp_eq_u32 s6, s100
	s_cselect_b64 s[94:95], s[90:91], s[98:99]
	s_cselect_b64 s[96:97], s[92:93], s[88:89]
	s_add_i32 s7, s6, 2
	s_add_i32 m0, s46, 0xc000
	ds_read_b128 v[164:167], v230
	global_load_lds_dwordx4 v144, s[86:87]
	s_add_i32 m0, s46, 0xe000
	ds_read_b128 v[168:171], v230 offset:1024
	global_load_lds_dwordx4 v142, s[86:87]
	ds_read_b128 v[172:175], v230 offset:2048
	ds_read_b128 v[176:179], v230 offset:3072
	ds_read_b128 v[180:183], v231
	ds_read_b128 v[184:187], v231 offset:1024
	ds_read_b128 v[188:191], v231 offset:2048
	ds_read_b128 v[192:195], v231 offset:3072
	ds_read_b128 v[196:199], v160
	ds_read_b128 v[200:203], v160 offset:1024
	ds_read_b128 v[204:207], v160 offset:2048
	ds_read_b128 v[208:211], v160 offset:3072
	ds_read_b128 v[212:215], v160 offset:4096
	ds_read_b128 v[216:219], v160 offset:5120
	ds_read_b128 v[220:223], v160 offset:6144
	ds_read_b128 v[224:227], v160 offset:7168
	s_waitcnt vmcnt(8)
	s_waitcnt lgkmcnt(0)
	s_setprio 1
	s_barrier
	v_mfma_f32_16x16x32_bf16 v[122:125], v[164:167], v[196:199], 0
	v_mfma_f32_16x16x32_bf16 v[118:121], v[172:175], v[196:199], 0
	v_mfma_f32_16x16x32_bf16 v[110:113], v[164:167], v[204:207], 0
	v_mfma_f32_16x16x32_bf16 v[102:105], v[172:175], v[204:207], 0
	v_mfma_f32_16x16x32_bf16 v[94:97], v[164:167], v[212:215], 0
	v_mfma_f32_16x16x32_bf16 v[86:89], v[172:175], v[212:215], 0
	v_mfma_f32_16x16x32_bf16 v[78:81], v[164:167], v[220:223], 0
	v_mfma_f32_16x16x32_bf16 v[70:73], v[172:175], v[220:223], 0
	v_mfma_f32_16x16x32_bf16 v[122:125], v[168:171], v[200:203], v[122:125]
	v_mfma_f32_16x16x32_bf16 v[118:121], v[176:179], v[200:203], v[118:121]
	v_mfma_f32_16x16x32_bf16 v[110:113], v[168:171], v[208:211], v[110:113]
	v_mfma_f32_16x16x32_bf16 v[102:105], v[176:179], v[208:211], v[102:105]
	v_mfma_f32_16x16x32_bf16 v[94:97], v[168:171], v[216:219], v[94:97]
	v_mfma_f32_16x16x32_bf16 v[86:89], v[176:179], v[216:219], v[86:89]
	v_mfma_f32_16x16x32_bf16 v[78:81], v[168:171], v[224:227], v[78:81]
	v_mfma_f32_16x16x32_bf16 v[70:73], v[176:179], v[224:227], v[70:73]
	v_mfma_f32_16x16x32_bf16 v[126:129], v[180:183], v[196:199], 0
	v_mfma_f32_16x16x32_bf16 v[114:117], v[188:191], v[196:199], 0
	v_mfma_f32_16x16x32_bf16 v[106:109], v[180:183], v[204:207], 0
	v_mfma_f32_16x16x32_bf16 v[98:101], v[188:191], v[204:207], 0
	v_mfma_f32_16x16x32_bf16 v[90:93], v[180:183], v[212:215], 0
	v_mfma_f32_16x16x32_bf16 v[82:85], v[188:191], v[212:215], 0
	v_mfma_f32_16x16x32_bf16 v[74:77], v[180:183], v[220:223], 0
	v_mfma_f32_16x16x32_bf16 v[66:69], v[188:191], v[220:223], 0
	v_mfma_f32_16x16x32_bf16 v[126:129], v[184:187], v[200:203], v[126:129]
	v_mfma_f32_16x16x32_bf16 v[114:117], v[192:195], v[200:203], v[114:117]
	v_mfma_f32_16x16x32_bf16 v[106:109], v[184:187], v[208:211], v[106:109]
	v_mfma_f32_16x16x32_bf16 v[98:101], v[192:195], v[208:211], v[98:101]
	v_mfma_f32_16x16x32_bf16 v[90:93], v[184:187], v[216:219], v[90:93]
	v_mfma_f32_16x16x32_bf16 v[82:85], v[192:195], v[216:219], v[82:85]
	v_mfma_f32_16x16x32_bf16 v[74:77], v[184:187], v[224:227], v[74:77]
	v_mfma_f32_16x16x32_bf16 v[66:69], v[192:195], v[224:227], v[66:69]
	s_barrier
	s_setprio 0
	s_add_u32 s98, s96, 0xb0000
	s_addc_u32 s99, s97, 0
	s_add_i32 s6, s67, s23
	s_mov_b32 m0, s6
	ds_read_b128 v[196:199], v160 offset:16384
	global_load_lds_dwordx4 v132, s[96:97]
	s_add_i32 m0, s6, 0x2000
	s_add_i32 s6, s68, s23
	global_load_lds_dwordx4 v136, s[96:97]
	s_mov_b32 m0, s6
	ds_read_b128 v[200:203], v160 offset:17408
	global_load_lds_dwordx4 v132, s[98:99]
	s_add_i32 m0, s6, 0x2000
	ds_read_b128 v[204:207], v160 offset:18432
	global_load_lds_dwordx4 v136, s[98:99]
	s_mov_b32 m0, s46
	ds_read_b128 v[208:211], v160 offset:19456
	global_load_lds_dwordx4 v130, s[94:95]
	s_mov_b32 m0, s47
	ds_read_b128 v[212:215], v160 offset:20480
	global_load_lds_dwordx4 v134, s[94:95]
	ds_read_b128 v[216:219], v160 offset:21504
	ds_read_b128 v[220:223], v160 offset:22528
	ds_read_b128 v[224:227], v160 offset:23552
	s_waitcnt vmcnt(8)
	s_waitcnt lgkmcnt(0)
	s_setprio 1
	s_barrier
	v_mfma_f32_16x16x32_bf16 v[62:65], v[164:167], v[196:199], 0
	v_mfma_f32_16x16x32_bf16 v[54:57], v[172:175], v[196:199], 0
	v_mfma_f32_16x16x32_bf16 v[46:49], v[164:167], v[204:207], 0
	v_mfma_f32_16x16x32_bf16 v[38:41], v[172:175], v[204:207], 0
	v_mfma_f32_16x16x32_bf16 v[30:33], v[164:167], v[212:215], 0
	v_mfma_f32_16x16x32_bf16 v[22:25], v[172:175], v[212:215], 0
	v_mfma_f32_16x16x32_bf16 v[14:17], v[164:167], v[220:223], 0
	v_mfma_f32_16x16x32_bf16 v[6:9], v[172:175], v[220:223], 0
	v_mfma_f32_16x16x32_bf16 v[62:65], v[168:171], v[200:203], v[62:65]
	v_mfma_f32_16x16x32_bf16 v[54:57], v[176:179], v[200:203], v[54:57]
	v_mfma_f32_16x16x32_bf16 v[46:49], v[168:171], v[208:211], v[46:49]
	v_mfma_f32_16x16x32_bf16 v[38:41], v[176:179], v[208:211], v[38:41]
	v_mfma_f32_16x16x32_bf16 v[30:33], v[168:171], v[216:219], v[30:33]
	v_mfma_f32_16x16x32_bf16 v[22:25], v[176:179], v[216:219], v[22:25]
	v_mfma_f32_16x16x32_bf16 v[14:17], v[168:171], v[224:227], v[14:17]
	v_mfma_f32_16x16x32_bf16 v[6:9], v[176:179], v[224:227], v[6:9]
	v_mfma_f32_16x16x32_bf16 v[58:61], v[180:183], v[196:199], 0
	v_mfma_f32_16x16x32_bf16 v[50:53], v[188:191], v[196:199], 0
	v_mfma_f32_16x16x32_bf16 v[42:45], v[180:183], v[204:207], 0
	v_mfma_f32_16x16x32_bf16 v[34:37], v[188:191], v[204:207], 0
	v_mfma_f32_16x16x32_bf16 v[26:29], v[180:183], v[212:215], 0
	v_mfma_f32_16x16x32_bf16 v[18:21], v[188:191], v[212:215], 0
	v_mfma_f32_16x16x32_bf16 v[10:13], v[180:183], v[220:223], 0
	v_mfma_f32_16x16x32_bf16 v[2:5], v[188:191], v[220:223], 0
	v_mfma_f32_16x16x32_bf16 v[58:61], v[184:187], v[200:203], v[58:61]
	v_mfma_f32_16x16x32_bf16 v[50:53], v[192:195], v[200:203], v[50:53]
	v_mfma_f32_16x16x32_bf16 v[42:45], v[184:187], v[208:211], v[42:45]
	v_mfma_f32_16x16x32_bf16 v[34:37], v[192:195], v[208:211], v[34:37]
	v_mfma_f32_16x16x32_bf16 v[26:29], v[184:187], v[216:219], v[26:29]
	v_mfma_f32_16x16x32_bf16 v[18:21], v[192:195], v[216:219], v[18:21]
	v_mfma_f32_16x16x32_bf16 v[10:13], v[184:187], v[224:227], v[10:13]
	v_mfma_f32_16x16x32_bf16 v[2:5], v[192:195], v[224:227], v[2:5]
	s_barrier
	s_setprio 0
	s_add_u32 s98, s94, 0xb0000
	s_addc_u32 s99, s95, 0
	s_add_i32 s6, 0, 0x18000
	s_add_i32 s29, 0, 0x1c000
	s_mov_b32 m0, s48
	ds_read_b128 v[164:167], v232
	global_load_lds_dwordx4 v130, s[98:99]
	s_mov_b32 m0, s49
	ds_read_b128 v[168:171], v232 offset:1024
	global_load_lds_dwordx4 v134, s[98:99]
	ds_read_b128 v[172:175], v232 offset:2048
	ds_read_b128 v[176:179], v232 offset:3072
	ds_read_b128 v[180:183], v233
	ds_read_b128 v[184:187], v233 offset:1024
	ds_read_b128 v[188:191], v233 offset:2048
	ds_read_b128 v[192:195], v233 offset:3072
	ds_read_b128 v[196:199], v160 offset:32768
	ds_read_b128 v[200:203], v160 offset:33792
	ds_read_b128 v[204:207], v160 offset:34816
	ds_read_b128 v[208:211], v160 offset:35840
	ds_read_b128 v[212:215], v160 offset:36864
	ds_read_b128 v[216:219], v160 offset:37888
	ds_read_b128 v[220:223], v160 offset:38912
	ds_read_b128 v[224:227], v160 offset:39936
	s_waitcnt vmcnt(8)
	s_waitcnt lgkmcnt(0)
	s_setprio 1
	s_barrier
	v_mfma_f32_16x16x32_bf16 v[122:125], v[164:167], v[196:199], v[122:125]
	v_mfma_f32_16x16x32_bf16 v[118:121], v[172:175], v[196:199], v[118:121]
	v_mfma_f32_16x16x32_bf16 v[110:113], v[164:167], v[204:207], v[110:113]
	v_mfma_f32_16x16x32_bf16 v[102:105], v[172:175], v[204:207], v[102:105]
	v_mfma_f32_16x16x32_bf16 v[94:97], v[164:167], v[212:215], v[94:97]
	v_mfma_f32_16x16x32_bf16 v[86:89], v[172:175], v[212:215], v[86:89]
	v_mfma_f32_16x16x32_bf16 v[78:81], v[164:167], v[220:223], v[78:81]
	v_mfma_f32_16x16x32_bf16 v[70:73], v[172:175], v[220:223], v[70:73]
	v_mfma_f32_16x16x32_bf16 v[122:125], v[168:171], v[200:203], v[122:125]
	v_mfma_f32_16x16x32_bf16 v[118:121], v[176:179], v[200:203], v[118:121]
	v_mfma_f32_16x16x32_bf16 v[110:113], v[168:171], v[208:211], v[110:113]
	v_mfma_f32_16x16x32_bf16 v[102:105], v[176:179], v[208:211], v[102:105]
	v_mfma_f32_16x16x32_bf16 v[94:97], v[168:171], v[216:219], v[94:97]
	v_mfma_f32_16x16x32_bf16 v[86:89], v[176:179], v[216:219], v[86:89]
	v_mfma_f32_16x16x32_bf16 v[78:81], v[168:171], v[224:227], v[78:81]
	v_mfma_f32_16x16x32_bf16 v[70:73], v[176:179], v[224:227], v[70:73]
	v_mfma_f32_16x16x32_bf16 v[126:129], v[180:183], v[196:199], v[126:129]
	v_mfma_f32_16x16x32_bf16 v[114:117], v[188:191], v[196:199], v[114:117]
	v_mfma_f32_16x16x32_bf16 v[106:109], v[180:183], v[204:207], v[106:109]
	v_mfma_f32_16x16x32_bf16 v[98:101], v[188:191], v[204:207], v[98:101]
	v_mfma_f32_16x16x32_bf16 v[90:93], v[180:183], v[212:215], v[90:93]
	v_mfma_f32_16x16x32_bf16 v[82:85], v[188:191], v[212:215], v[82:85]
	v_mfma_f32_16x16x32_bf16 v[74:77], v[180:183], v[220:223], v[74:77]
	v_mfma_f32_16x16x32_bf16 v[66:69], v[188:191], v[220:223], v[66:69]
	v_mfma_f32_16x16x32_bf16 v[126:129], v[184:187], v[200:203], v[126:129]
	v_mfma_f32_16x16x32_bf16 v[114:117], v[192:195], v[200:203], v[114:117]
	v_mfma_f32_16x16x32_bf16 v[106:109], v[184:187], v[208:211], v[106:109]
	v_mfma_f32_16x16x32_bf16 v[98:101], v[192:195], v[208:211], v[98:101]
	v_mfma_f32_16x16x32_bf16 v[90:93], v[184:187], v[216:219], v[90:93]
	v_mfma_f32_16x16x32_bf16 v[82:85], v[192:195], v[216:219], v[82:85]
	v_mfma_f32_16x16x32_bf16 v[74:77], v[184:187], v[224:227], v[74:77]
	v_mfma_f32_16x16x32_bf16 v[66:69], v[192:195], v[224:227], v[66:69]
	s_barrier
	s_setprio 0
	s_add_u32 s96, s96, 0x80
	s_addc_u32 s97, s97, 0
	s_add_u32 s98, s96, 0xb0000
	s_addc_u32 s99, s97, 0
	s_add_u32 s94, s94, 0x80
	s_addc_u32 s95, s95, 0
	s_add_i32 s6, s6, s23
	s_mov_b32 m0, s6
	ds_read_b128 v[196:199], v160 offset:49152
	global_load_lds_dwordx4 v132, s[96:97]
	s_add_i32 m0, s6, 0x2000
	s_add_i32 s6, s29, s23
	global_load_lds_dwordx4 v136, s[96:97]
	s_mov_b32 m0, s6
	ds_read_b128 v[200:203], v160 offset:50176
	global_load_lds_dwordx4 v132, s[98:99]
	s_add_i32 m0, s6, 0x2000
	ds_read_b128 v[204:207], v160 offset:51200
	global_load_lds_dwordx4 v136, s[98:99]
	s_mov_b32 m0, s59
	ds_read_b128 v[208:211], v160 offset:52224
	global_load_lds_dwordx4 v130, s[94:95]
	s_mov_b32 m0, s60
	ds_read_b128 v[212:215], v160 offset:53248
	global_load_lds_dwordx4 v134, s[94:95]
	ds_read_b128 v[216:219], v160 offset:54272
	ds_read_b128 v[220:223], v160 offset:55296
	ds_read_b128 v[224:227], v160 offset:56320
	s_waitcnt vmcnt(8)
	s_waitcnt lgkmcnt(0)
	s_setprio 1
	s_barrier
	v_mfma_f32_16x16x32_bf16 v[62:65], v[164:167], v[196:199], v[62:65]
	v_mfma_f32_16x16x32_bf16 v[54:57], v[172:175], v[196:199], v[54:57]
	v_mfma_f32_16x16x32_bf16 v[46:49], v[164:167], v[204:207], v[46:49]
	v_mfma_f32_16x16x32_bf16 v[38:41], v[172:175], v[204:207], v[38:41]
	v_mfma_f32_16x16x32_bf16 v[30:33], v[164:167], v[212:215], v[30:33]
	v_mfma_f32_16x16x32_bf16 v[22:25], v[172:175], v[212:215], v[22:25]
	v_mfma_f32_16x16x32_bf16 v[14:17], v[164:167], v[220:223], v[14:17]
	v_mfma_f32_16x16x32_bf16 v[6:9], v[172:175], v[220:223], v[6:9]
	v_mfma_f32_16x16x32_bf16 v[62:65], v[168:171], v[200:203], v[62:65]
	v_mfma_f32_16x16x32_bf16 v[54:57], v[176:179], v[200:203], v[54:57]
	v_mfma_f32_16x16x32_bf16 v[46:49], v[168:171], v[208:211], v[46:49]
	v_mfma_f32_16x16x32_bf16 v[38:41], v[176:179], v[208:211], v[38:41]
	v_mfma_f32_16x16x32_bf16 v[30:33], v[168:171], v[216:219], v[30:33]
	v_mfma_f32_16x16x32_bf16 v[22:25], v[176:179], v[216:219], v[22:25]
	v_mfma_f32_16x16x32_bf16 v[14:17], v[168:171], v[224:227], v[14:17]
	v_mfma_f32_16x16x32_bf16 v[6:9], v[176:179], v[224:227], v[6:9]
	v_mfma_f32_16x16x32_bf16 v[58:61], v[180:183], v[196:199], v[58:61]
	v_mfma_f32_16x16x32_bf16 v[50:53], v[188:191], v[196:199], v[50:53]
	v_mfma_f32_16x16x32_bf16 v[42:45], v[180:183], v[204:207], v[42:45]
	v_mfma_f32_16x16x32_bf16 v[34:37], v[188:191], v[204:207], v[34:37]
	v_mfma_f32_16x16x32_bf16 v[26:29], v[180:183], v[212:215], v[26:29]
	v_mfma_f32_16x16x32_bf16 v[18:21], v[188:191], v[212:215], v[18:21]
	v_mfma_f32_16x16x32_bf16 v[10:13], v[180:183], v[220:223], v[10:13]
	v_mfma_f32_16x16x32_bf16 v[2:5], v[188:191], v[220:223], v[2:5]
	v_mfma_f32_16x16x32_bf16 v[58:61], v[184:187], v[200:203], v[58:61]
	v_mfma_f32_16x16x32_bf16 v[50:53], v[192:195], v[200:203], v[50:53]
	v_mfma_f32_16x16x32_bf16 v[42:45], v[184:187], v[208:211], v[42:45]
	v_mfma_f32_16x16x32_bf16 v[34:37], v[192:195], v[208:211], v[34:37]
	v_mfma_f32_16x16x32_bf16 v[26:29], v[184:187], v[216:219], v[26:29]
	v_mfma_f32_16x16x32_bf16 v[18:21], v[192:195], v[216:219], v[18:21]
	v_mfma_f32_16x16x32_bf16 v[10:13], v[184:187], v[224:227], v[10:13]
	v_mfma_f32_16x16x32_bf16 v[2:5], v[192:195], v[224:227], v[2:5]
	s_barrier
	s_setprio 0
	s_mov_b32 s6, s7
	s_add_u32 s88, s88, 0x100
	s_addc_u32 s89, s89, 0
	s_add_u32 s86, s86, 0x100
	s_addc_u32 s87, s87, 0
	s_cmp_ge_i32 s7, s101
	s_cbranch_scc1 .Lmy_kexit_5
.LBB0_1080:
	s_add_u32 s98, s86, 0x100
	s_addc_u32 s99, s87, 0
	s_cmp_eq_u32 s6, s100
	s_cselect_b64 s[94:95], s[90:91], s[98:99]
	s_cselect_b64 s[96:97], s[92:93], s[88:89]
	s_add_i32 s7, s6, 2
	s_add_i32 m0, s46, 0xc000
	ds_read_b128 v[164:167], v230
	global_load_lds_dwordx4 v144, s[86:87]
	s_add_i32 m0, s46, 0xe000
	ds_read_b128 v[168:171], v230 offset:1024
	global_load_lds_dwordx4 v142, s[86:87]
	ds_read_b128 v[172:175], v230 offset:2048
	ds_read_b128 v[176:179], v230 offset:3072
	ds_read_b128 v[180:183], v231
	ds_read_b128 v[184:187], v231 offset:1024
	ds_read_b128 v[188:191], v231 offset:2048
	ds_read_b128 v[192:195], v231 offset:3072
	ds_read_b128 v[196:199], v160
	ds_read_b128 v[200:203], v160 offset:1024
	ds_read_b128 v[204:207], v160 offset:2048
	ds_read_b128 v[208:211], v160 offset:3072
	ds_read_b128 v[212:215], v160 offset:4096
	ds_read_b128 v[216:219], v160 offset:5120
	ds_read_b128 v[220:223], v160 offset:6144
	ds_read_b128 v[224:227], v160 offset:7168
	s_waitcnt vmcnt(8)
	s_waitcnt lgkmcnt(0)
	s_setprio 1
	s_barrier
	v_mfma_f32_16x16x32_bf16 v[122:125], v[164:167], v[196:199], v[122:125]
	v_mfma_f32_16x16x32_bf16 v[118:121], v[172:175], v[196:199], v[118:121]
	v_mfma_f32_16x16x32_bf16 v[110:113], v[164:167], v[204:207], v[110:113]
	v_mfma_f32_16x16x32_bf16 v[102:105], v[172:175], v[204:207], v[102:105]
	v_mfma_f32_16x16x32_bf16 v[94:97], v[164:167], v[212:215], v[94:97]
	v_mfma_f32_16x16x32_bf16 v[86:89], v[172:175], v[212:215], v[86:89]
	v_mfma_f32_16x16x32_bf16 v[78:81], v[164:167], v[220:223], v[78:81]
	v_mfma_f32_16x16x32_bf16 v[70:73], v[172:175], v[220:223], v[70:73]
	v_mfma_f32_16x16x32_bf16 v[122:125], v[168:171], v[200:203], v[122:125]
	v_mfma_f32_16x16x32_bf16 v[118:121], v[176:179], v[200:203], v[118:121]
	v_mfma_f32_16x16x32_bf16 v[110:113], v[168:171], v[208:211], v[110:113]
	v_mfma_f32_16x16x32_bf16 v[102:105], v[176:179], v[208:211], v[102:105]
	v_mfma_f32_16x16x32_bf16 v[94:97], v[168:171], v[216:219], v[94:97]
	v_mfma_f32_16x16x32_bf16 v[86:89], v[176:179], v[216:219], v[86:89]
	v_mfma_f32_16x16x32_bf16 v[78:81], v[168:171], v[224:227], v[78:81]
	v_mfma_f32_16x16x32_bf16 v[70:73], v[176:179], v[224:227], v[70:73]
	v_mfma_f32_16x16x32_bf16 v[126:129], v[180:183], v[196:199], v[126:129]
	v_mfma_f32_16x16x32_bf16 v[114:117], v[188:191], v[196:199], v[114:117]
	v_mfma_f32_16x16x32_bf16 v[106:109], v[180:183], v[204:207], v[106:109]
	v_mfma_f32_16x16x32_bf16 v[98:101], v[188:191], v[204:207], v[98:101]
	v_mfma_f32_16x16x32_bf16 v[90:93], v[180:183], v[212:215], v[90:93]
	v_mfma_f32_16x16x32_bf16 v[82:85], v[188:191], v[212:215], v[82:85]
	v_mfma_f32_16x16x32_bf16 v[74:77], v[180:183], v[220:223], v[74:77]
	v_mfma_f32_16x16x32_bf16 v[66:69], v[188:191], v[220:223], v[66:69]
	v_mfma_f32_16x16x32_bf16 v[126:129], v[184:187], v[200:203], v[126:129]
	v_mfma_f32_16x16x32_bf16 v[114:117], v[192:195], v[200:203], v[114:117]
	v_mfma_f32_16x16x32_bf16 v[106:109], v[184:187], v[208:211], v[106:109]
	v_mfma_f32_16x16x32_bf16 v[98:101], v[192:195], v[208:211], v[98:101]
	v_mfma_f32_16x16x32_bf16 v[90:93], v[184:187], v[216:219], v[90:93]
	v_mfma_f32_16x16x32_bf16 v[82:85], v[192:195], v[216:219], v[82:85]
	v_mfma_f32_16x16x32_bf16 v[74:77], v[184:187], v[224:227], v[74:77]
	v_mfma_f32_16x16x32_bf16 v[66:69], v[192:195], v[224:227], v[66:69]
	s_barrier
	s_setprio 0
	s_add_u32 s98, s96, 0xb0000
	s_addc_u32 s99, s97, 0
	s_add_i32 s6, s67, s23
	s_mov_b32 m0, s6
	ds_read_b128 v[196:199], v160 offset:16384
	global_load_lds_dwordx4 v132, s[96:97]
	s_add_i32 m0, s6, 0x2000
	s_add_i32 s6, s68, s23
	global_load_lds_dwordx4 v136, s[96:97]
	s_mov_b32 m0, s6
	ds_read_b128 v[200:203], v160 offset:17408
	global_load_lds_dwordx4 v132, s[98:99]
	s_add_i32 m0, s6, 0x2000
	ds_read_b128 v[204:207], v160 offset:18432
	global_load_lds_dwordx4 v136, s[98:99]
	s_mov_b32 m0, s46
	ds_read_b128 v[208:211], v160 offset:19456
	global_load_lds_dwordx4 v130, s[94:95]
	s_mov_b32 m0, s47
	ds_read_b128 v[212:215], v160 offset:20480
	global_load_lds_dwordx4 v134, s[94:95]
	ds_read_b128 v[216:219], v160 offset:21504
	ds_read_b128 v[220:223], v160 offset:22528
	ds_read_b128 v[224:227], v160 offset:23552
	s_waitcnt vmcnt(8)
	s_waitcnt lgkmcnt(0)
	s_setprio 1
	s_barrier
	v_mfma_f32_16x16x32_bf16 v[62:65], v[164:167], v[196:199], v[62:65]
	v_mfma_f32_16x16x32_bf16 v[54:57], v[172:175], v[196:199], v[54:57]
	v_mfma_f32_16x16x32_bf16 v[46:49], v[164:167], v[204:207], v[46:49]
	v_mfma_f32_16x16x32_bf16 v[38:41], v[172:175], v[204:207], v[38:41]
	v_mfma_f32_16x16x32_bf16 v[30:33], v[164:167], v[212:215], v[30:33]
	v_mfma_f32_16x16x32_bf16 v[22:25], v[172:175], v[212:215], v[22:25]
	v_mfma_f32_16x16x32_bf16 v[14:17], v[164:167], v[220:223], v[14:17]
	v_mfma_f32_16x16x32_bf16 v[6:9], v[172:175], v[220:223], v[6:9]
	v_mfma_f32_16x16x32_bf16 v[62:65], v[168:171], v[200:203], v[62:65]
	v_mfma_f32_16x16x32_bf16 v[54:57], v[176:179], v[200:203], v[54:57]
	v_mfma_f32_16x16x32_bf16 v[46:49], v[168:171], v[208:211], v[46:49]
	v_mfma_f32_16x16x32_bf16 v[38:41], v[176:179], v[208:211], v[38:41]
	v_mfma_f32_16x16x32_bf16 v[30:33], v[168:171], v[216:219], v[30:33]
	v_mfma_f32_16x16x32_bf16 v[22:25], v[176:179], v[216:219], v[22:25]
	v_mfma_f32_16x16x32_bf16 v[14:17], v[168:171], v[224:227], v[14:17]
	v_mfma_f32_16x16x32_bf16 v[6:9], v[176:179], v[224:227], v[6:9]
	v_mfma_f32_16x16x32_bf16 v[58:61], v[180:183], v[196:199], v[58:61]
	v_mfma_f32_16x16x32_bf16 v[50:53], v[188:191], v[196:199], v[50:53]
	v_mfma_f32_16x16x32_bf16 v[42:45], v[180:183], v[204:207], v[42:45]
	v_mfma_f32_16x16x32_bf16 v[34:37], v[188:191], v[204:207], v[34:37]
	v_mfma_f32_16x16x32_bf16 v[26:29], v[180:183], v[212:215], v[26:29]
	v_mfma_f32_16x16x32_bf16 v[18:21], v[188:191], v[212:215], v[18:21]
	v_mfma_f32_16x16x32_bf16 v[10:13], v[180:183], v[220:223], v[10:13]
	v_mfma_f32_16x16x32_bf16 v[2:5], v[188:191], v[220:223], v[2:5]
	v_mfma_f32_16x16x32_bf16 v[58:61], v[184:187], v[200:203], v[58:61]
	v_mfma_f32_16x16x32_bf16 v[50:53], v[192:195], v[200:203], v[50:53]
	v_mfma_f32_16x16x32_bf16 v[42:45], v[184:187], v[208:211], v[42:45]
	v_mfma_f32_16x16x32_bf16 v[34:37], v[192:195], v[208:211], v[34:37]
	v_mfma_f32_16x16x32_bf16 v[26:29], v[184:187], v[216:219], v[26:29]
	v_mfma_f32_16x16x32_bf16 v[18:21], v[192:195], v[216:219], v[18:21]
	v_mfma_f32_16x16x32_bf16 v[10:13], v[184:187], v[224:227], v[10:13]
	v_mfma_f32_16x16x32_bf16 v[2:5], v[192:195], v[224:227], v[2:5]
	s_barrier
	s_setprio 0
	s_add_u32 s98, s94, 0xb0000
	s_addc_u32 s99, s95, 0
	s_add_i32 s6, 0, 0x18000
	s_add_i32 s29, 0, 0x1c000
	s_mov_b32 m0, s48
	ds_read_b128 v[164:167], v232
	global_load_lds_dwordx4 v130, s[98:99]
	s_mov_b32 m0, s49
	ds_read_b128 v[168:171], v232 offset:1024
	global_load_lds_dwordx4 v134, s[98:99]
	ds_read_b128 v[172:175], v232 offset:2048
	ds_read_b128 v[176:179], v232 offset:3072
	ds_read_b128 v[180:183], v233
	ds_read_b128 v[184:187], v233 offset:1024
	ds_read_b128 v[188:191], v233 offset:2048
	ds_read_b128 v[192:195], v233 offset:3072
	ds_read_b128 v[196:199], v160 offset:32768
	ds_read_b128 v[200:203], v160 offset:33792
	ds_read_b128 v[204:207], v160 offset:34816
	ds_read_b128 v[208:211], v160 offset:35840
	ds_read_b128 v[212:215], v160 offset:36864
	ds_read_b128 v[216:219], v160 offset:37888
	ds_read_b128 v[220:223], v160 offset:38912
	ds_read_b128 v[224:227], v160 offset:39936
	s_waitcnt vmcnt(8)
	s_waitcnt lgkmcnt(0)
	s_setprio 1
	s_barrier
	v_mfma_f32_16x16x32_bf16 v[122:125], v[164:167], v[196:199], v[122:125]
	v_mfma_f32_16x16x32_bf16 v[118:121], v[172:175], v[196:199], v[118:121]
	v_mfma_f32_16x16x32_bf16 v[110:113], v[164:167], v[204:207], v[110:113]
	v_mfma_f32_16x16x32_bf16 v[102:105], v[172:175], v[204:207], v[102:105]
	v_mfma_f32_16x16x32_bf16 v[94:97], v[164:167], v[212:215], v[94:97]
	v_mfma_f32_16x16x32_bf16 v[86:89], v[172:175], v[212:215], v[86:89]
	v_mfma_f32_16x16x32_bf16 v[78:81], v[164:167], v[220:223], v[78:81]
	v_mfma_f32_16x16x32_bf16 v[70:73], v[172:175], v[220:223], v[70:73]
	v_mfma_f32_16x16x32_bf16 v[122:125], v[168:171], v[200:203], v[122:125]
	v_mfma_f32_16x16x32_bf16 v[118:121], v[176:179], v[200:203], v[118:121]
	v_mfma_f32_16x16x32_bf16 v[110:113], v[168:171], v[208:211], v[110:113]
	v_mfma_f32_16x16x32_bf16 v[102:105], v[176:179], v[208:211], v[102:105]
	v_mfma_f32_16x16x32_bf16 v[94:97], v[168:171], v[216:219], v[94:97]
	v_mfma_f32_16x16x32_bf16 v[86:89], v[176:179], v[216:219], v[86:89]
	v_mfma_f32_16x16x32_bf16 v[78:81], v[168:171], v[224:227], v[78:81]
	v_mfma_f32_16x16x32_bf16 v[70:73], v[176:179], v[224:227], v[70:73]
	v_mfma_f32_16x16x32_bf16 v[126:129], v[180:183], v[196:199], v[126:129]
	v_mfma_f32_16x16x32_bf16 v[114:117], v[188:191], v[196:199], v[114:117]
	v_mfma_f32_16x16x32_bf16 v[106:109], v[180:183], v[204:207], v[106:109]
	v_mfma_f32_16x16x32_bf16 v[98:101], v[188:191], v[204:207], v[98:101]
	v_mfma_f32_16x16x32_bf16 v[90:93], v[180:183], v[212:215], v[90:93]
	v_mfma_f32_16x16x32_bf16 v[82:85], v[188:191], v[212:215], v[82:85]
	v_mfma_f32_16x16x32_bf16 v[74:77], v[180:183], v[220:223], v[74:77]
	v_mfma_f32_16x16x32_bf16 v[66:69], v[188:191], v[220:223], v[66:69]
	v_mfma_f32_16x16x32_bf16 v[126:129], v[184:187], v[200:203], v[126:129]
	v_mfma_f32_16x16x32_bf16 v[114:117], v[192:195], v[200:203], v[114:117]
	v_mfma_f32_16x16x32_bf16 v[106:109], v[184:187], v[208:211], v[106:109]
	v_mfma_f32_16x16x32_bf16 v[98:101], v[192:195], v[208:211], v[98:101]
	v_mfma_f32_16x16x32_bf16 v[90:93], v[184:187], v[216:219], v[90:93]
	v_mfma_f32_16x16x32_bf16 v[82:85], v[192:195], v[216:219], v[82:85]
	v_mfma_f32_16x16x32_bf16 v[74:77], v[184:187], v[224:227], v[74:77]
	v_mfma_f32_16x16x32_bf16 v[66:69], v[192:195], v[224:227], v[66:69]
	s_barrier
	s_setprio 0
	s_add_u32 s96, s96, 0x80
	s_addc_u32 s97, s97, 0
	s_add_u32 s98, s96, 0xb0000
	s_addc_u32 s99, s97, 0
	s_add_u32 s94, s94, 0x80
	s_addc_u32 s95, s95, 0
	s_add_i32 s6, s6, s23
	s_mov_b32 m0, s6
	ds_read_b128 v[196:199], v160 offset:49152
	global_load_lds_dwordx4 v132, s[96:97]
	s_add_i32 m0, s6, 0x2000
	s_add_i32 s6, s29, s23
	global_load_lds_dwordx4 v136, s[96:97]
	s_mov_b32 m0, s6
	ds_read_b128 v[200:203], v160 offset:50176
	global_load_lds_dwordx4 v132, s[98:99]
	s_add_i32 m0, s6, 0x2000
	ds_read_b128 v[204:207], v160 offset:51200
	global_load_lds_dwordx4 v136, s[98:99]
	s_mov_b32 m0, s59
	ds_read_b128 v[208:211], v160 offset:52224
	global_load_lds_dwordx4 v130, s[94:95]
	s_mov_b32 m0, s60
	ds_read_b128 v[212:215], v160 offset:53248
	global_load_lds_dwordx4 v134, s[94:95]
	ds_read_b128 v[216:219], v160 offset:54272
	ds_read_b128 v[220:223], v160 offset:55296
	ds_read_b128 v[224:227], v160 offset:56320
	s_waitcnt vmcnt(8)
	s_waitcnt lgkmcnt(0)
	s_setprio 1
	s_barrier
	v_mfma_f32_16x16x32_bf16 v[62:65], v[164:167], v[196:199], v[62:65]
	v_mfma_f32_16x16x32_bf16 v[54:57], v[172:175], v[196:199], v[54:57]
	v_mfma_f32_16x16x32_bf16 v[46:49], v[164:167], v[204:207], v[46:49]
	v_mfma_f32_16x16x32_bf16 v[38:41], v[172:175], v[204:207], v[38:41]
	v_mfma_f32_16x16x32_bf16 v[30:33], v[164:167], v[212:215], v[30:33]
	v_mfma_f32_16x16x32_bf16 v[22:25], v[172:175], v[212:215], v[22:25]
	v_mfma_f32_16x16x32_bf16 v[14:17], v[164:167], v[220:223], v[14:17]
	v_mfma_f32_16x16x32_bf16 v[6:9], v[172:175], v[220:223], v[6:9]
	v_mfma_f32_16x16x32_bf16 v[62:65], v[168:171], v[200:203], v[62:65]
	v_mfma_f32_16x16x32_bf16 v[54:57], v[176:179], v[200:203], v[54:57]
	v_mfma_f32_16x16x32_bf16 v[46:49], v[168:171], v[208:211], v[46:49]
	v_mfma_f32_16x16x32_bf16 v[38:41], v[176:179], v[208:211], v[38:41]
	v_mfma_f32_16x16x32_bf16 v[30:33], v[168:171], v[216:219], v[30:33]
	v_mfma_f32_16x16x32_bf16 v[22:25], v[176:179], v[216:219], v[22:25]
	v_mfma_f32_16x16x32_bf16 v[14:17], v[168:171], v[224:227], v[14:17]
	v_mfma_f32_16x16x32_bf16 v[6:9], v[176:179], v[224:227], v[6:9]
	v_mfma_f32_16x16x32_bf16 v[58:61], v[180:183], v[196:199], v[58:61]
	v_mfma_f32_16x16x32_bf16 v[50:53], v[188:191], v[196:199], v[50:53]
	v_mfma_f32_16x16x32_bf16 v[42:45], v[180:183], v[204:207], v[42:45]
	v_mfma_f32_16x16x32_bf16 v[34:37], v[188:191], v[204:207], v[34:37]
	v_mfma_f32_16x16x32_bf16 v[26:29], v[180:183], v[212:215], v[26:29]
	v_mfma_f32_16x16x32_bf16 v[18:21], v[188:191], v[212:215], v[18:21]
	v_mfma_f32_16x16x32_bf16 v[10:13], v[180:183], v[220:223], v[10:13]
	v_mfma_f32_16x16x32_bf16 v[2:5], v[188:191], v[220:223], v[2:5]
	v_mfma_f32_16x16x32_bf16 v[58:61], v[184:187], v[200:203], v[58:61]
	v_mfma_f32_16x16x32_bf16 v[50:53], v[192:195], v[200:203], v[50:53]
	v_mfma_f32_16x16x32_bf16 v[42:45], v[184:187], v[208:211], v[42:45]
	v_mfma_f32_16x16x32_bf16 v[34:37], v[192:195], v[208:211], v[34:37]
	v_mfma_f32_16x16x32_bf16 v[26:29], v[184:187], v[216:219], v[26:29]
	v_mfma_f32_16x16x32_bf16 v[18:21], v[192:195], v[216:219], v[18:21]
	v_mfma_f32_16x16x32_bf16 v[10:13], v[184:187], v[224:227], v[10:13]
	v_mfma_f32_16x16x32_bf16 v[2:5], v[192:195], v[224:227], v[2:5]
	s_barrier
	s_setprio 0
	s_mov_b32 s6, s7
	s_add_u32 s88, s88, 0x100
	s_addc_u32 s89, s89, 0
	s_add_u32 s86, s86, 0x100
	s_addc_u32 s87, s87, 0
	s_cmp_ge_i32 s7, s101
	s_cbranch_scc0 .LBB0_1080

.Lmy_nb_7:
	s_nop 0
	v_readfirstlane_b32 s86, v150
	v_readfirstlane_b32 s87, v151
	v_readfirstlane_b32 s88, v152
	v_readfirstlane_b32 s89, v153
	v_readfirstlane_b32 s90, v146
	v_readfirstlane_b32 s91, v147
	v_readfirstlane_b32 s92, v148
	v_readfirstlane_b32 s93, v149
	v_readfirstlane_b32 s100, v138
	v_readfirstlane_b32 s101, v156
	v_add_u32_e32 v230, s67, v141
	v_add_u32_e32 v231, s70, v141
	v_add_u32_e32 v232, 0x18000, v141
	v_add_u32_e32 v233, 0x1c000, v141
	s_add_u32 s98, s86, 0x100
	s_addc_u32 s99, s87, 0
	s_cmp_eq_u32 s6, s100
	s_cselect_b64 s[94:95], s[90:91], s[98:99]
	s_cselect_b64 s[96:97], s[92:93], s[88:89]
	s_add_i32 s7, s6, 2
	s_add_i32 m0, s46, 0xc000
	ds_read_b128 v[164:167], v230
	global_load_lds_dwordx4 v144, s[86:87]
	s_add_i32 m0, s46, 0xe000
	ds_read_b128 v[168:171], v230 offset:1024
	global_load_lds_dwordx4 v142, s[86:87]
	ds_read_b128 v[172:175], v230 offset:2048
	ds_read_b128 v[176:179], v230 offset:3072
	ds_read_b128 v[180:183], v231
	ds_read_b128 v[184:187], v231 offset:1024
	ds_read_b128 v[188:191], v231 offset:2048
	ds_read_b128 v[192:195], v231 offset:3072
	ds_read_b128 v[196:199], v160
	ds_read_b128 v[200:203], v160 offset:1024
	ds_read_b128 v[204:207], v160 offset:2048
	ds_read_b128 v[208:211], v160 offset:3072
	ds_read_b128 v[212:215], v160 offset:4096
	ds_read_b128 v[216:219], v160 offset:5120
	ds_read_b128 v[220:223], v160 offset:6144
	ds_read_b128 v[224:227], v160 offset:7168
	s_waitcnt vmcnt(8)
	s_waitcnt lgkmcnt(0)
	s_setprio 1
	s_barrier
	v_mfma_f32_16x16x32_bf16 v[122:125], v[164:167], v[196:199], 0
	v_mfma_f32_16x16x32_bf16 v[118:121], v[172:175], v[196:199], 0
	v_mfma_f32_16x16x32_bf16 v[110:113], v[164:167], v[204:207], 0
	v_mfma_f32_16x16x32_bf16 v[102:105], v[172:175], v[204:207], 0
	v_mfma_f32_16x16x32_bf16 v[94:97], v[164:167], v[212:215], 0
	v_mfma_f32_16x16x32_bf16 v[86:89], v[172:175], v[212:215], 0
	v_mfma_f32_16x16x32_bf16 v[78:81], v[164:167], v[220:223], 0
	v_mfma_f32_16x16x32_bf16 v[70:73], v[172:175], v[220:223], 0
	v_mfma_f32_16x16x32_bf16 v[122:125], v[168:171], v[200:203], v[122:125]
	v_mfma_f32_16x16x32_bf16 v[118:121], v[176:179], v[200:203], v[118:121]
	v_mfma_f32_16x16x32_bf16 v[110:113], v[168:171], v[208:211], v[110:113]
	v_mfma_f32_16x16x32_bf16 v[102:105], v[176:179], v[208:211], v[102:105]
	v_mfma_f32_16x16x32_bf16 v[94:97], v[168:171], v[216:219], v[94:97]
	v_mfma_f32_16x16x32_bf16 v[86:89], v[176:179], v[216:219], v[86:89]
	v_mfma_f32_16x16x32_bf16 v[78:81], v[168:171], v[224:227], v[78:81]
	v_mfma_f32_16x16x32_bf16 v[70:73], v[176:179], v[224:227], v[70:73]
	v_mfma_f32_16x16x32_bf16 v[126:129], v[180:183], v[196:199], 0
	v_mfma_f32_16x16x32_bf16 v[114:117], v[188:191], v[196:199], 0
	v_mfma_f32_16x16x32_bf16 v[106:109], v[180:183], v[204:207], 0
	v_mfma_f32_16x16x32_bf16 v[98:101], v[188:191], v[204:207], 0
	v_mfma_f32_16x16x32_bf16 v[90:93], v[180:183], v[212:215], 0
	v_mfma_f32_16x16x32_bf16 v[82:85], v[188:191], v[212:215], 0
	v_mfma_f32_16x16x32_bf16 v[74:77], v[180:183], v[220:223], 0
	v_mfma_f32_16x16x32_bf16 v[66:69], v[188:191], v[220:223], 0
	v_mfma_f32_16x16x32_bf16 v[126:129], v[184:187], v[200:203], v[126:129]
	v_mfma_f32_16x16x32_bf16 v[114:117], v[192:195], v[200:203], v[114:117]
	v_mfma_f32_16x16x32_bf16 v[106:109], v[184:187], v[208:211], v[106:109]
	v_mfma_f32_16x16x32_bf16 v[98:101], v[192:195], v[208:211], v[98:101]
	v_mfma_f32_16x16x32_bf16 v[90:93], v[184:187], v[216:219], v[90:93]
	v_mfma_f32_16x16x32_bf16 v[82:85], v[192:195], v[216:219], v[82:85]
	v_mfma_f32_16x16x32_bf16 v[74:77], v[184:187], v[224:227], v[74:77]
	v_mfma_f32_16x16x32_bf16 v[66:69], v[192:195], v[224:227], v[66:69]
	s_barrier
	s_setprio 0
	s_add_u32 s98, s96, 0xb0000
	s_addc_u32 s99, s97, 0
	s_add_i32 s6, s67, s23
	s_mov_b32 m0, s6
	ds_read_b128 v[196:199], v160 offset:16384
	global_load_lds_dwordx4 v132, s[96:97]
	s_add_i32 m0, s6, 0x2000
	s_add_i32 s6, s70, s23
	global_load_lds_dwordx4 v136, s[96:97]
	s_mov_b32 m0, s6
	ds_read_b128 v[200:203], v160 offset:17408
	global_load_lds_dwordx4 v132, s[98:99]
	s_add_i32 m0, s6, 0x2000
	ds_read_b128 v[204:207], v160 offset:18432
	global_load_lds_dwordx4 v136, s[98:99]
	s_mov_b32 m0, s46
	ds_read_b128 v[208:211], v160 offset:19456
	global_load_lds_dwordx4 v130, s[94:95]
	s_mov_b32 m0, s47
	ds_read_b128 v[212:215], v160 offset:20480
	global_load_lds_dwordx4 v134, s[94:95]
	ds_read_b128 v[216:219], v160 offset:21504
	ds_read_b128 v[220:223], v160 offset:22528
	ds_read_b128 v[224:227], v160 offset:23552
	s_waitcnt vmcnt(8)
	s_waitcnt lgkmcnt(0)
	s_setprio 1
	s_barrier
	v_mfma_f32_16x16x32_bf16 v[62:65], v[164:167], v[196:199], 0
	v_mfma_f32_16x16x32_bf16 v[54:57], v[172:175], v[196:199], 0
	v_mfma_f32_16x16x32_bf16 v[46:49], v[164:167], v[204:207], 0
	v_mfma_f32_16x16x32_bf16 v[38:41], v[172:175], v[204:207], 0
	v_mfma_f32_16x16x32_bf16 v[30:33], v[164:167], v[212:215], 0
	v_mfma_f32_16x16x32_bf16 v[22:25], v[172:175], v[212:215], 0
	v_mfma_f32_16x16x32_bf16 v[14:17], v[164:167], v[220:223], 0
	v_mfma_f32_16x16x32_bf16 v[6:9], v[172:175], v[220:223], 0
	v_mfma_f32_16x16x32_bf16 v[62:65], v[168:171], v[200:203], v[62:65]
	v_mfma_f32_16x16x32_bf16 v[54:57], v[176:179], v[200:203], v[54:57]
	v_mfma_f32_16x16x32_bf16 v[46:49], v[168:171], v[208:211], v[46:49]
	v_mfma_f32_16x16x32_bf16 v[38:41], v[176:179], v[208:211], v[38:41]
	v_mfma_f32_16x16x32_bf16 v[30:33], v[168:171], v[216:219], v[30:33]
	v_mfma_f32_16x16x32_bf16 v[22:25], v[176:179], v[216:219], v[22:25]
	v_mfma_f32_16x16x32_bf16 v[14:17], v[168:171], v[224:227], v[14:17]
	v_mfma_f32_16x16x32_bf16 v[6:9], v[176:179], v[224:227], v[6:9]
	v_mfma_f32_16x16x32_bf16 v[58:61], v[180:183], v[196:199], 0
	v_mfma_f32_16x16x32_bf16 v[50:53], v[188:191], v[196:199], 0
	v_mfma_f32_16x16x32_bf16 v[42:45], v[180:183], v[204:207], 0
	v_mfma_f32_16x16x32_bf16 v[34:37], v[188:191], v[204:207], 0
	v_mfma_f32_16x16x32_bf16 v[26:29], v[180:183], v[212:215], 0
	v_mfma_f32_16x16x32_bf16 v[18:21], v[188:191], v[212:215], 0
	v_mfma_f32_16x16x32_bf16 v[10:13], v[180:183], v[220:223], 0
	v_mfma_f32_16x16x32_bf16 v[2:5], v[188:191], v[220:223], 0
	v_mfma_f32_16x16x32_bf16 v[58:61], v[184:187], v[200:203], v[58:61]
	v_mfma_f32_16x16x32_bf16 v[50:53], v[192:195], v[200:203], v[50:53]
	v_mfma_f32_16x16x32_bf16 v[42:45], v[184:187], v[208:211], v[42:45]
	v_mfma_f32_16x16x32_bf16 v[34:37], v[192:195], v[208:211], v[34:37]
	v_mfma_f32_16x16x32_bf16 v[26:29], v[184:187], v[216:219], v[26:29]
	v_mfma_f32_16x16x32_bf16 v[18:21], v[192:195], v[216:219], v[18:21]
	v_mfma_f32_16x16x32_bf16 v[10:13], v[184:187], v[224:227], v[10:13]
	v_mfma_f32_16x16x32_bf16 v[2:5], v[192:195], v[224:227], v[2:5]
	s_barrier
	s_setprio 0
	s_add_u32 s98, s94, 0xb0000
	s_addc_u32 s99, s95, 0
	s_add_i32 s6, 0, 0x18000
	s_add_i32 s29, 0, 0x1c000
	s_mov_b32 m0, s48
	ds_read_b128 v[164:167], v232
	global_load_lds_dwordx4 v130, s[98:99]
	s_mov_b32 m0, s49
	ds_read_b128 v[168:171], v232 offset:1024
	global_load_lds_dwordx4 v134, s[98:99]
	ds_read_b128 v[172:175], v232 offset:2048
	ds_read_b128 v[176:179], v232 offset:3072
	ds_read_b128 v[180:183], v233
	ds_read_b128 v[184:187], v233 offset:1024
	ds_read_b128 v[188:191], v233 offset:2048
	ds_read_b128 v[192:195], v233 offset:3072
	ds_read_b128 v[196:199], v160 offset:32768
	ds_read_b128 v[200:203], v160 offset:33792
	ds_read_b128 v[204:207], v160 offset:34816
	ds_read_b128 v[208:211], v160 offset:35840
	ds_read_b128 v[212:215], v160 offset:36864
	ds_read_b128 v[216:219], v160 offset:37888
	ds_read_b128 v[220:223], v160 offset:38912
	ds_read_b128 v[224:227], v160 offset:39936
	s_waitcnt vmcnt(8)
	s_waitcnt lgkmcnt(0)
	s_setprio 1
	s_barrier
	v_mfma_f32_16x16x32_bf16 v[122:125], v[164:167], v[196:199], v[122:125]
	v_mfma_f32_16x16x32_bf16 v[118:121], v[172:175], v[196:199], v[118:121]
	v_mfma_f32_16x16x32_bf16 v[110:113], v[164:167], v[204:207], v[110:113]
	v_mfma_f32_16x16x32_bf16 v[102:105], v[172:175], v[204:207], v[102:105]
	v_mfma_f32_16x16x32_bf16 v[94:97], v[164:167], v[212:215], v[94:97]
	v_mfma_f32_16x16x32_bf16 v[86:89], v[172:175], v[212:215], v[86:89]
	v_mfma_f32_16x16x32_bf16 v[78:81], v[164:167], v[220:223], v[78:81]
	v_mfma_f32_16x16x32_bf16 v[70:73], v[172:175], v[220:223], v[70:73]
	v_mfma_f32_16x16x32_bf16 v[122:125], v[168:171], v[200:203], v[122:125]
	v_mfma_f32_16x16x32_bf16 v[118:121], v[176:179], v[200:203], v[118:121]
	v_mfma_f32_16x16x32_bf16 v[110:113], v[168:171], v[208:211], v[110:113]
	v_mfma_f32_16x16x32_bf16 v[102:105], v[176:179], v[208:211], v[102:105]
	v_mfma_f32_16x16x32_bf16 v[94:97], v[168:171], v[216:219], v[94:97]
	v_mfma_f32_16x16x32_bf16 v[86:89], v[176:179], v[216:219], v[86:89]
	v_mfma_f32_16x16x32_bf16 v[78:81], v[168:171], v[224:227], v[78:81]
	v_mfma_f32_16x16x32_bf16 v[70:73], v[176:179], v[224:227], v[70:73]
	v_mfma_f32_16x16x32_bf16 v[126:129], v[180:183], v[196:199], v[126:129]
	v_mfma_f32_16x16x32_bf16 v[114:117], v[188:191], v[196:199], v[114:117]
	v_mfma_f32_16x16x32_bf16 v[106:109], v[180:183], v[204:207], v[106:109]
	v_mfma_f32_16x16x32_bf16 v[98:101], v[188:191], v[204:207], v[98:101]
	v_mfma_f32_16x16x32_bf16 v[90:93], v[180:183], v[212:215], v[90:93]
	v_mfma_f32_16x16x32_bf16 v[82:85], v[188:191], v[212:215], v[82:85]
	v_mfma_f32_16x16x32_bf16 v[74:77], v[180:183], v[220:223], v[74:77]
	v_mfma_f32_16x16x32_bf16 v[66:69], v[188:191], v[220:223], v[66:69]
	v_mfma_f32_16x16x32_bf16 v[126:129], v[184:187], v[200:203], v[126:129]
	v_mfma_f32_16x16x32_bf16 v[114:117], v[192:195], v[200:203], v[114:117]
	v_mfma_f32_16x16x32_bf16 v[106:109], v[184:187], v[208:211], v[106:109]
	v_mfma_f32_16x16x32_bf16 v[98:101], v[192:195], v[208:211], v[98:101]
	v_mfma_f32_16x16x32_bf16 v[90:93], v[184:187], v[216:219], v[90:93]
	v_mfma_f32_16x16x32_bf16 v[82:85], v[192:195], v[216:219], v[82:85]
	v_mfma_f32_16x16x32_bf16 v[74:77], v[184:187], v[224:227], v[74:77]
	v_mfma_f32_16x16x32_bf16 v[66:69], v[192:195], v[224:227], v[66:69]
	s_barrier
	s_setprio 0
	s_add_u32 s96, s96, 0x80
	s_addc_u32 s97, s97, 0
	s_add_u32 s98, s96, 0xb0000
	s_addc_u32 s99, s97, 0
	s_add_u32 s94, s94, 0x80
	s_addc_u32 s95, s95, 0
	s_add_i32 s6, s6, s23
	s_mov_b32 m0, s6
	ds_read_b128 v[196:199], v160 offset:49152
	global_load_lds_dwordx4 v132, s[96:97]
	s_add_i32 m0, s6, 0x2000
	s_add_i32 s6, s29, s23
	global_load_lds_dwordx4 v136, s[96:97]
	s_mov_b32 m0, s6
	ds_read_b128 v[200:203], v160 offset:50176
	global_load_lds_dwordx4 v132, s[98:99]
	s_add_i32 m0, s6, 0x2000
	ds_read_b128 v[204:207], v160 offset:51200
	global_load_lds_dwordx4 v136, s[98:99]
	s_mov_b32 m0, s59
	ds_read_b128 v[208:211], v160 offset:52224
	global_load_lds_dwordx4 v130, s[94:95]
	s_mov_b32 m0, s60
	ds_read_b128 v[212:215], v160 offset:53248
	global_load_lds_dwordx4 v134, s[94:95]
	ds_read_b128 v[216:219], v160 offset:54272
	ds_read_b128 v[220:223], v160 offset:55296
	ds_read_b128 v[224:227], v160 offset:56320
	s_waitcnt vmcnt(8)
	s_waitcnt lgkmcnt(0)
	s_setprio 1
	s_barrier
	v_mfma_f32_16x16x32_bf16 v[62:65], v[164:167], v[196:199], v[62:65]
	v_mfma_f32_16x16x32_bf16 v[54:57], v[172:175], v[196:199], v[54:57]
	v_mfma_f32_16x16x32_bf16 v[46:49], v[164:167], v[204:207], v[46:49]
	v_mfma_f32_16x16x32_bf16 v[38:41], v[172:175], v[204:207], v[38:41]
	v_mfma_f32_16x16x32_bf16 v[30:33], v[164:167], v[212:215], v[30:33]
	v_mfma_f32_16x16x32_bf16 v[22:25], v[172:175], v[212:215], v[22:25]
	v_mfma_f32_16x16x32_bf16 v[14:17], v[164:167], v[220:223], v[14:17]
	v_mfma_f32_16x16x32_bf16 v[6:9], v[172:175], v[220:223], v[6:9]
	v_mfma_f32_16x16x32_bf16 v[62:65], v[168:171], v[200:203], v[62:65]
	v_mfma_f32_16x16x32_bf16 v[54:57], v[176:179], v[200:203], v[54:57]
	v_mfma_f32_16x16x32_bf16 v[46:49], v[168:171], v[208:211], v[46:49]
	v_mfma_f32_16x16x32_bf16 v[38:41], v[176:179], v[208:211], v[38:41]
	v_mfma_f32_16x16x32_bf16 v[30:33], v[168:171], v[216:219], v[30:33]
	v_mfma_f32_16x16x32_bf16 v[22:25], v[176:179], v[216:219], v[22:25]
	v_mfma_f32_16x16x32_bf16 v[14:17], v[168:171], v[224:227], v[14:17]
	v_mfma_f32_16x16x32_bf16 v[6:9], v[176:179], v[224:227], v[6:9]
	v_mfma_f32_16x16x32_bf16 v[58:61], v[180:183], v[196:199], v[58:61]
	v_mfma_f32_16x16x32_bf16 v[50:53], v[188:191], v[196:199], v[50:53]
	v_mfma_f32_16x16x32_bf16 v[42:45], v[180:183], v[204:207], v[42:45]
	v_mfma_f32_16x16x32_bf16 v[34:37], v[188:191], v[204:207], v[34:37]
	v_mfma_f32_16x16x32_bf16 v[26:29], v[180:183], v[212:215], v[26:29]
	v_mfma_f32_16x16x32_bf16 v[18:21], v[188:191], v[212:215], v[18:21]
	v_mfma_f32_16x16x32_bf16 v[10:13], v[180:183], v[220:223], v[10:13]
	v_mfma_f32_16x16x32_bf16 v[2:5], v[188:191], v[220:223], v[2:5]
	v_mfma_f32_16x16x32_bf16 v[58:61], v[184:187], v[200:203], v[58:61]
	v_mfma_f32_16x16x32_bf16 v[50:53], v[192:195], v[200:203], v[50:53]
	v_mfma_f32_16x16x32_bf16 v[42:45], v[184:187], v[208:211], v[42:45]
	v_mfma_f32_16x16x32_bf16 v[34:37], v[192:195], v[208:211], v[34:37]
	v_mfma_f32_16x16x32_bf16 v[26:29], v[184:187], v[216:219], v[26:29]
	v_mfma_f32_16x16x32_bf16 v[18:21], v[192:195], v[216:219], v[18:21]
	v_mfma_f32_16x16x32_bf16 v[10:13], v[184:187], v[224:227], v[10:13]
	v_mfma_f32_16x16x32_bf16 v[2:5], v[192:195], v[224:227], v[2:5]
	s_barrier
	s_setprio 0
	s_mov_b32 s6, s7
	s_add_u32 s88, s88, 0x100
	s_addc_u32 s89, s89, 0
	s_add_u32 s86, s86, 0x100
	s_addc_u32 s87, s87, 0
	s_cmp_ge_i32 s7, s101
	s_cbranch_scc1 .Lmy_kexit_7
.LBB0_1392:
	s_add_u32 s98, s86, 0x100
	s_addc_u32 s99, s87, 0
	s_cmp_eq_u32 s6, s100
	s_cselect_b64 s[94:95], s[90:91], s[98:99]
	s_cselect_b64 s[96:97], s[92:93], s[88:89]
	s_add_i32 s7, s6, 2
	s_add_i32 m0, s46, 0xc000
	ds_read_b128 v[164:167], v230
	global_load_lds_dwordx4 v144, s[86:87]
	s_add_i32 m0, s46, 0xe000
	ds_read_b128 v[168:171], v230 offset:1024
	global_load_lds_dwordx4 v142, s[86:87]
	ds_read_b128 v[172:175], v230 offset:2048
	ds_read_b128 v[176:179], v230 offset:3072
	ds_read_b128 v[180:183], v231
	ds_read_b128 v[184:187], v231 offset:1024
	ds_read_b128 v[188:191], v231 offset:2048
	ds_read_b128 v[192:195], v231 offset:3072
	ds_read_b128 v[196:199], v160
	ds_read_b128 v[200:203], v160 offset:1024
	ds_read_b128 v[204:207], v160 offset:2048
	ds_read_b128 v[208:211], v160 offset:3072
	ds_read_b128 v[212:215], v160 offset:4096
	ds_read_b128 v[216:219], v160 offset:5120
	ds_read_b128 v[220:223], v160 offset:6144
	ds_read_b128 v[224:227], v160 offset:7168
	s_waitcnt vmcnt(8)
	s_waitcnt lgkmcnt(0)
	s_setprio 1
	s_barrier
	v_mfma_f32_16x16x32_bf16 v[122:125], v[164:167], v[196:199], v[122:125]
	v_mfma_f32_16x16x32_bf16 v[118:121], v[172:175], v[196:199], v[118:121]
	v_mfma_f32_16x16x32_bf16 v[110:113], v[164:167], v[204:207], v[110:113]
	v_mfma_f32_16x16x32_bf16 v[102:105], v[172:175], v[204:207], v[102:105]
	v_mfma_f32_16x16x32_bf16 v[94:97], v[164:167], v[212:215], v[94:97]
	v_mfma_f32_16x16x32_bf16 v[86:89], v[172:175], v[212:215], v[86:89]
	v_mfma_f32_16x16x32_bf16 v[78:81], v[164:167], v[220:223], v[78:81]
	v_mfma_f32_16x16x32_bf16 v[70:73], v[172:175], v[220:223], v[70:73]
	v_mfma_f32_16x16x32_bf16 v[122:125], v[168:171], v[200:203], v[122:125]
	v_mfma_f32_16x16x32_bf16 v[118:121], v[176:179], v[200:203], v[118:121]
	v_mfma_f32_16x16x32_bf16 v[110:113], v[168:171], v[208:211], v[110:113]
	v_mfma_f32_16x16x32_bf16 v[102:105], v[176:179], v[208:211], v[102:105]
	v_mfma_f32_16x16x32_bf16 v[94:97], v[168:171], v[216:219], v[94:97]
	v_mfma_f32_16x16x32_bf16 v[86:89], v[176:179], v[216:219], v[86:89]
	v_mfma_f32_16x16x32_bf16 v[78:81], v[168:171], v[224:227], v[78:81]
	v_mfma_f32_16x16x32_bf16 v[70:73], v[176:179], v[224:227], v[70:73]
	v_mfma_f32_16x16x32_bf16 v[126:129], v[180:183], v[196:199], v[126:129]
	v_mfma_f32_16x16x32_bf16 v[114:117], v[188:191], v[196:199], v[114:117]
	v_mfma_f32_16x16x32_bf16 v[106:109], v[180:183], v[204:207], v[106:109]
	v_mfma_f32_16x16x32_bf16 v[98:101], v[188:191], v[204:207], v[98:101]
	v_mfma_f32_16x16x32_bf16 v[90:93], v[180:183], v[212:215], v[90:93]
	v_mfma_f32_16x16x32_bf16 v[82:85], v[188:191], v[212:215], v[82:85]
	v_mfma_f32_16x16x32_bf16 v[74:77], v[180:183], v[220:223], v[74:77]
	v_mfma_f32_16x16x32_bf16 v[66:69], v[188:191], v[220:223], v[66:69]
	v_mfma_f32_16x16x32_bf16 v[126:129], v[184:187], v[200:203], v[126:129]
	v_mfma_f32_16x16x32_bf16 v[114:117], v[192:195], v[200:203], v[114:117]
	v_mfma_f32_16x16x32_bf16 v[106:109], v[184:187], v[208:211], v[106:109]
	v_mfma_f32_16x16x32_bf16 v[98:101], v[192:195], v[208:211], v[98:101]
	v_mfma_f32_16x16x32_bf16 v[90:93], v[184:187], v[216:219], v[90:93]
	v_mfma_f32_16x16x32_bf16 v[82:85], v[192:195], v[216:219], v[82:85]
	v_mfma_f32_16x16x32_bf16 v[74:77], v[184:187], v[224:227], v[74:77]
	v_mfma_f32_16x16x32_bf16 v[66:69], v[192:195], v[224:227], v[66:69]
	s_barrier
	s_setprio 0
	s_add_u32 s98, s96, 0xb0000
	s_addc_u32 s99, s97, 0
	s_add_i32 s6, s67, s23
	s_mov_b32 m0, s6
	ds_read_b128 v[196:199], v160 offset:16384
	global_load_lds_dwordx4 v132, s[96:97]
	s_add_i32 m0, s6, 0x2000
	s_add_i32 s6, s70, s23
	global_load_lds_dwordx4 v136, s[96:97]
	s_mov_b32 m0, s6
	ds_read_b128 v[200:203], v160 offset:17408
	global_load_lds_dwordx4 v132, s[98:99]
	s_add_i32 m0, s6, 0x2000
	ds_read_b128 v[204:207], v160 offset:18432
	global_load_lds_dwordx4 v136, s[98:99]
	s_mov_b32 m0, s46
	ds_read_b128 v[208:211], v160 offset:19456
	global_load_lds_dwordx4 v130, s[94:95]
	s_mov_b32 m0, s47
	ds_read_b128 v[212:215], v160 offset:20480
	global_load_lds_dwordx4 v134, s[94:95]
	ds_read_b128 v[216:219], v160 offset:21504
	ds_read_b128 v[220:223], v160 offset:22528
	ds_read_b128 v[224:227], v160 offset:23552
	s_waitcnt vmcnt(8)
	s_waitcnt lgkmcnt(0)
	s_setprio 1
	s_barrier
	v_mfma_f32_16x16x32_bf16 v[62:65], v[164:167], v[196:199], v[62:65]
	v_mfma_f32_16x16x32_bf16 v[54:57], v[172:175], v[196:199], v[54:57]
	v_mfma_f32_16x16x32_bf16 v[46:49], v[164:167], v[204:207], v[46:49]
	v_mfma_f32_16x16x32_bf16 v[38:41], v[172:175], v[204:207], v[38:41]
	v_mfma_f32_16x16x32_bf16 v[30:33], v[164:167], v[212:215], v[30:33]
	v_mfma_f32_16x16x32_bf16 v[22:25], v[172:175], v[212:215], v[22:25]
	v_mfma_f32_16x16x32_bf16 v[14:17], v[164:167], v[220:223], v[14:17]
	v_mfma_f32_16x16x32_bf16 v[6:9], v[172:175], v[220:223], v[6:9]
	v_mfma_f32_16x16x32_bf16 v[62:65], v[168:171], v[200:203], v[62:65]
	v_mfma_f32_16x16x32_bf16 v[54:57], v[176:179], v[200:203], v[54:57]
	v_mfma_f32_16x16x32_bf16 v[46:49], v[168:171], v[208:211], v[46:49]
	v_mfma_f32_16x16x32_bf16 v[38:41], v[176:179], v[208:211], v[38:41]
	v_mfma_f32_16x16x32_bf16 v[30:33], v[168:171], v[216:219], v[30:33]
	v_mfma_f32_16x16x32_bf16 v[22:25], v[176:179], v[216:219], v[22:25]
	v_mfma_f32_16x16x32_bf16 v[14:17], v[168:171], v[224:227], v[14:17]
	v_mfma_f32_16x16x32_bf16 v[6:9], v[176:179], v[224:227], v[6:9]
	v_mfma_f32_16x16x32_bf16 v[58:61], v[180:183], v[196:199], v[58:61]
	v_mfma_f32_16x16x32_bf16 v[50:53], v[188:191], v[196:199], v[50:53]
	v_mfma_f32_16x16x32_bf16 v[42:45], v[180:183], v[204:207], v[42:45]
	v_mfma_f32_16x16x32_bf16 v[34:37], v[188:191], v[204:207], v[34:37]
	v_mfma_f32_16x16x32_bf16 v[26:29], v[180:183], v[212:215], v[26:29]
	v_mfma_f32_16x16x32_bf16 v[18:21], v[188:191], v[212:215], v[18:21]
	v_mfma_f32_16x16x32_bf16 v[10:13], v[180:183], v[220:223], v[10:13]
	v_mfma_f32_16x16x32_bf16 v[2:5], v[188:191], v[220:223], v[2:5]
	v_mfma_f32_16x16x32_bf16 v[58:61], v[184:187], v[200:203], v[58:61]
	v_mfma_f32_16x16x32_bf16 v[50:53], v[192:195], v[200:203], v[50:53]
	v_mfma_f32_16x16x32_bf16 v[42:45], v[184:187], v[208:211], v[42:45]
	v_mfma_f32_16x16x32_bf16 v[34:37], v[192:195], v[208:211], v[34:37]
	v_mfma_f32_16x16x32_bf16 v[26:29], v[184:187], v[216:219], v[26:29]
	v_mfma_f32_16x16x32_bf16 v[18:21], v[192:195], v[216:219], v[18:21]
	v_mfma_f32_16x16x32_bf16 v[10:13], v[184:187], v[224:227], v[10:13]
	v_mfma_f32_16x16x32_bf16 v[2:5], v[192:195], v[224:227], v[2:5]
	s_barrier
	s_setprio 0
	s_add_u32 s98, s94, 0xb0000
	s_addc_u32 s99, s95, 0
	s_add_i32 s6, 0, 0x18000
	s_add_i32 s29, 0, 0x1c000
	s_mov_b32 m0, s48
	ds_read_b128 v[164:167], v232
	global_load_lds_dwordx4 v130, s[98:99]
	s_mov_b32 m0, s49
	ds_read_b128 v[168:171], v232 offset:1024
	global_load_lds_dwordx4 v134, s[98:99]
	ds_read_b128 v[172:175], v232 offset:2048
	ds_read_b128 v[176:179], v232 offset:3072
	ds_read_b128 v[180:183], v233
	ds_read_b128 v[184:187], v233 offset:1024
	ds_read_b128 v[188:191], v233 offset:2048
	ds_read_b128 v[192:195], v233 offset:3072
	ds_read_b128 v[196:199], v160 offset:32768
	ds_read_b128 v[200:203], v160 offset:33792
	ds_read_b128 v[204:207], v160 offset:34816
	ds_read_b128 v[208:211], v160 offset:35840
	ds_read_b128 v[212:215], v160 offset:36864
	ds_read_b128 v[216:219], v160 offset:37888
	ds_read_b128 v[220:223], v160 offset:38912
	ds_read_b128 v[224:227], v160 offset:39936
	s_waitcnt vmcnt(8)
	s_waitcnt lgkmcnt(0)
	s_setprio 1
	s_barrier
	v_mfma_f32_16x16x32_bf16 v[122:125], v[164:167], v[196:199], v[122:125]
	v_mfma_f32_16x16x32_bf16 v[118:121], v[172:175], v[196:199], v[118:121]
	v_mfma_f32_16x16x32_bf16 v[110:113], v[164:167], v[204:207], v[110:113]
	v_mfma_f32_16x16x32_bf16 v[102:105], v[172:175], v[204:207], v[102:105]
	v_mfma_f32_16x16x32_bf16 v[94:97], v[164:167], v[212:215], v[94:97]
	v_mfma_f32_16x16x32_bf16 v[86:89], v[172:175], v[212:215], v[86:89]
	v_mfma_f32_16x16x32_bf16 v[78:81], v[164:167], v[220:223], v[78:81]
	v_mfma_f32_16x16x32_bf16 v[70:73], v[172:175], v[220:223], v[70:73]
	v_mfma_f32_16x16x32_bf16 v[122:125], v[168:171], v[200:203], v[122:125]
	v_mfma_f32_16x16x32_bf16 v[118:121], v[176:179], v[200:203], v[118:121]
	v_mfma_f32_16x16x32_bf16 v[110:113], v[168:171], v[208:211], v[110:113]
	v_mfma_f32_16x16x32_bf16 v[102:105], v[176:179], v[208:211], v[102:105]
	v_mfma_f32_16x16x32_bf16 v[94:97], v[168:171], v[216:219], v[94:97]
	v_mfma_f32_16x16x32_bf16 v[86:89], v[176:179], v[216:219], v[86:89]
	v_mfma_f32_16x16x32_bf16 v[78:81], v[168:171], v[224:227], v[78:81]
	v_mfma_f32_16x16x32_bf16 v[70:73], v[176:179], v[224:227], v[70:73]
	v_mfma_f32_16x16x32_bf16 v[126:129], v[180:183], v[196:199], v[126:129]
	v_mfma_f32_16x16x32_bf16 v[114:117], v[188:191], v[196:199], v[114:117]
	v_mfma_f32_16x16x32_bf16 v[106:109], v[180:183], v[204:207], v[106:109]
	v_mfma_f32_16x16x32_bf16 v[98:101], v[188:191], v[204:207], v[98:101]
	v_mfma_f32_16x16x32_bf16 v[90:93], v[180:183], v[212:215], v[90:93]
	v_mfma_f32_16x16x32_bf16 v[82:85], v[188:191], v[212:215], v[82:85]
	v_mfma_f32_16x16x32_bf16 v[74:77], v[180:183], v[220:223], v[74:77]
	v_mfma_f32_16x16x32_bf16 v[66:69], v[188:191], v[220:223], v[66:69]
	v_mfma_f32_16x16x32_bf16 v[126:129], v[184:187], v[200:203], v[126:129]
	v_mfma_f32_16x16x32_bf16 v[114:117], v[192:195], v[200:203], v[114:117]
	v_mfma_f32_16x16x32_bf16 v[106:109], v[184:187], v[208:211], v[106:109]
	v_mfma_f32_16x16x32_bf16 v[98:101], v[192:195], v[208:211], v[98:101]
	v_mfma_f32_16x16x32_bf16 v[90:93], v[184:187], v[216:219], v[90:93]
	v_mfma_f32_16x16x32_bf16 v[82:85], v[192:195], v[216:219], v[82:85]
	v_mfma_f32_16x16x32_bf16 v[74:77], v[184:187], v[224:227], v[74:77]
	v_mfma_f32_16x16x32_bf16 v[66:69], v[192:195], v[224:227], v[66:69]
	s_barrier
	s_setprio 0
	s_add_u32 s96, s96, 0x80
	s_addc_u32 s97, s97, 0
	s_add_u32 s98, s96, 0xb0000
	s_addc_u32 s99, s97, 0
	s_add_u32 s94, s94, 0x80
	s_addc_u32 s95, s95, 0
	s_add_i32 s6, s6, s23
	s_mov_b32 m0, s6
	ds_read_b128 v[196:199], v160 offset:49152
	global_load_lds_dwordx4 v132, s[96:97]
	s_add_i32 m0, s6, 0x2000
	s_add_i32 s6, s29, s23
	global_load_lds_dwordx4 v136, s[96:97]
	s_mov_b32 m0, s6
	ds_read_b128 v[200:203], v160 offset:50176
	global_load_lds_dwordx4 v132, s[98:99]
	s_add_i32 m0, s6, 0x2000
	ds_read_b128 v[204:207], v160 offset:51200
	global_load_lds_dwordx4 v136, s[98:99]
	s_mov_b32 m0, s59
	ds_read_b128 v[208:211], v160 offset:52224
	global_load_lds_dwordx4 v130, s[94:95]
	s_mov_b32 m0, s60
	ds_read_b128 v[212:215], v160 offset:53248
	global_load_lds_dwordx4 v134, s[94:95]
	ds_read_b128 v[216:219], v160 offset:54272
	ds_read_b128 v[220:223], v160 offset:55296
	ds_read_b128 v[224:227], v160 offset:56320
	s_waitcnt vmcnt(8)
	s_waitcnt lgkmcnt(0)
	s_setprio 1
	s_barrier
	v_mfma_f32_16x16x32_bf16 v[62:65], v[164:167], v[196:199], v[62:65]
	v_mfma_f32_16x16x32_bf16 v[54:57], v[172:175], v[196:199], v[54:57]
	v_mfma_f32_16x16x32_bf16 v[46:49], v[164:167], v[204:207], v[46:49]
	v_mfma_f32_16x16x32_bf16 v[38:41], v[172:175], v[204:207], v[38:41]
	v_mfma_f32_16x16x32_bf16 v[30:33], v[164:167], v[212:215], v[30:33]
	v_mfma_f32_16x16x32_bf16 v[22:25], v[172:175], v[212:215], v[22:25]
	v_mfma_f32_16x16x32_bf16 v[14:17], v[164:167], v[220:223], v[14:17]
	v_mfma_f32_16x16x32_bf16 v[6:9], v[172:175], v[220:223], v[6:9]
	v_mfma_f32_16x16x32_bf16 v[62:65], v[168:171], v[200:203], v[62:65]
	v_mfma_f32_16x16x32_bf16 v[54:57], v[176:179], v[200:203], v[54:57]
	v_mfma_f32_16x16x32_bf16 v[46:49], v[168:171], v[208:211], v[46:49]
	v_mfma_f32_16x16x32_bf16 v[38:41], v[176:179], v[208:211], v[38:41]
	v_mfma_f32_16x16x32_bf16 v[30:33], v[168:171], v[216:219], v[30:33]
	v_mfma_f32_16x16x32_bf16 v[22:25], v[176:179], v[216:219], v[22:25]
	v_mfma_f32_16x16x32_bf16 v[14:17], v[168:171], v[224:227], v[14:17]
	v_mfma_f32_16x16x32_bf16 v[6:9], v[176:179], v[224:227], v[6:9]
	v_mfma_f32_16x16x32_bf16 v[58:61], v[180:183], v[196:199], v[58:61]
	v_mfma_f32_16x16x32_bf16 v[50:53], v[188:191], v[196:199], v[50:53]
	v_mfma_f32_16x16x32_bf16 v[42:45], v[180:183], v[204:207], v[42:45]
	v_mfma_f32_16x16x32_bf16 v[34:37], v[188:191], v[204:207], v[34:37]
	v_mfma_f32_16x16x32_bf16 v[26:29], v[180:183], v[212:215], v[26:29]
	v_mfma_f32_16x16x32_bf16 v[18:21], v[188:191], v[212:215], v[18:21]
	v_mfma_f32_16x16x32_bf16 v[10:13], v[180:183], v[220:223], v[10:13]
	v_mfma_f32_16x16x32_bf16 v[2:5], v[188:191], v[220:223], v[2:5]
	v_mfma_f32_16x16x32_bf16 v[58:61], v[184:187], v[200:203], v[58:61]
	v_mfma_f32_16x16x32_bf16 v[50:53], v[192:195], v[200:203], v[50:53]
	v_mfma_f32_16x16x32_bf16 v[42:45], v[184:187], v[208:211], v[42:45]
	v_mfma_f32_16x16x32_bf16 v[34:37], v[192:195], v[208:211], v[34:37]
	v_mfma_f32_16x16x32_bf16 v[26:29], v[184:187], v[216:219], v[26:29]
	v_mfma_f32_16x16x32_bf16 v[18:21], v[192:195], v[216:219], v[18:21]
	v_mfma_f32_16x16x32_bf16 v[10:13], v[184:187], v[224:227], v[10:13]
	v_mfma_f32_16x16x32_bf16 v[2:5], v[192:195], v[224:227], v[2:5]
	s_barrier
	s_setprio 0
	s_mov_b32 s6, s7
	s_add_u32 s88, s88, 0x100
	s_addc_u32 s89, s89, 0
	s_add_u32 s86, s86, 0x100
	s_addc_u32 s87, s87, 0
	s_cmp_ge_i32 s7, s101
	s_cbranch_scc0 .LBB0_1392

.Lmy_nb_8:
	s_nop 0
	v_readfirstlane_b32 s86, v154
	v_readfirstlane_b32 s87, v155
	v_readfirstlane_b32 s88, v152
	v_readfirstlane_b32 s89, v153
	v_readfirstlane_b32 s90, v148
	v_readfirstlane_b32 s91, v149
	v_readfirstlane_b32 s92, v150
	v_readfirstlane_b32 s93, v151
	v_readfirstlane_b32 s100, v138
	v_readfirstlane_b32 s101, v141
	v_add_u32_e32 v230, s71, v160
	v_add_u32_e32 v231, s72, v160
	v_add_u32_e32 v232, 0x18000, v160
	v_add_u32_e32 v233, 0x1c000, v160
	s_add_u32 s98, s86, 0xfffc0080
	s_addc_u32 s99, s87, -1
	s_cmp_eq_u32 s7, s100
	s_cselect_b64 s[94:95], s[90:91], s[98:99]
	s_cselect_b64 s[96:97], s[92:93], s[88:89]
	s_add_i32 s47, s7, 2
	s_mov_b32 m0, s74
	ds_read_b128 v[156:159], v230
	global_load_lds_dwordx4 v144, s[86:87]
	s_mov_b32 m0, s75
	ds_read_b128 v[166:169], v230 offset:1024
	global_load_lds_dwordx4 v142, s[86:87]
	ds_read_b128 v[170:173], v230 offset:2048
	ds_read_b128 v[174:177], v230 offset:3072
	ds_read_b128 v[178:181], v231
	ds_read_b128 v[182:185], v231 offset:1024
	ds_read_b128 v[186:189], v231 offset:2048
	ds_read_b128 v[190:193], v231 offset:3072
	ds_read_b128 v[194:197], v163
	ds_read_b128 v[198:201], v163 offset:1024
	ds_read_b128 v[202:205], v163 offset:2048
	ds_read_b128 v[206:209], v163 offset:3072
	ds_read_b128 v[210:213], v163 offset:4096
	ds_read_b128 v[214:217], v163 offset:5120
	ds_read_b128 v[218:221], v163 offset:6144
	ds_read_b128 v[222:225], v163 offset:7168
	s_waitcnt vmcnt(8)
	s_waitcnt lgkmcnt(0)
	s_setprio 1
	s_barrier
	v_mfma_f32_16x16x32_bf16 v[122:125], v[156:159], v[194:197], 0
	v_mfma_f32_16x16x32_bf16 v[118:121], v[170:173], v[194:197], 0
	v_mfma_f32_16x16x32_bf16 v[110:113], v[156:159], v[202:205], 0
	v_mfma_f32_16x16x32_bf16 v[102:105], v[170:173], v[202:205], 0
	v_mfma_f32_16x16x32_bf16 v[94:97], v[156:159], v[210:213], 0
	v_mfma_f32_16x16x32_bf16 v[86:89], v[170:173], v[210:213], 0
	v_mfma_f32_16x16x32_bf16 v[78:81], v[156:159], v[218:221], 0
	v_mfma_f32_16x16x32_bf16 v[70:73], v[170:173], v[218:221], 0
	v_mfma_f32_16x16x32_bf16 v[122:125], v[166:169], v[198:201], v[122:125]
	v_mfma_f32_16x16x32_bf16 v[118:121], v[174:177], v[198:201], v[118:121]
	v_mfma_f32_16x16x32_bf16 v[110:113], v[166:169], v[206:209], v[110:113]
	v_mfma_f32_16x16x32_bf16 v[102:105], v[174:177], v[206:209], v[102:105]
	v_mfma_f32_16x16x32_bf16 v[94:97], v[166:169], v[214:217], v[94:97]
	v_mfma_f32_16x16x32_bf16 v[86:89], v[174:177], v[214:217], v[86:89]
	v_mfma_f32_16x16x32_bf16 v[78:81], v[166:169], v[222:225], v[78:81]
	v_mfma_f32_16x16x32_bf16 v[70:73], v[174:177], v[222:225], v[70:73]
	v_mfma_f32_16x16x32_bf16 v[126:129], v[178:181], v[194:197], 0
	v_mfma_f32_16x16x32_bf16 v[114:117], v[186:189], v[194:197], 0
	v_mfma_f32_16x16x32_bf16 v[106:109], v[178:181], v[202:205], 0
	v_mfma_f32_16x16x32_bf16 v[98:101], v[186:189], v[202:205], 0
	v_mfma_f32_16x16x32_bf16 v[90:93], v[178:181], v[210:213], 0
	v_mfma_f32_16x16x32_bf16 v[82:85], v[186:189], v[210:213], 0
	v_mfma_f32_16x16x32_bf16 v[74:77], v[178:181], v[218:221], 0
	v_mfma_f32_16x16x32_bf16 v[66:69], v[186:189], v[218:221], 0
	v_mfma_f32_16x16x32_bf16 v[126:129], v[182:185], v[198:201], v[126:129]
	v_mfma_f32_16x16x32_bf16 v[114:117], v[190:193], v[198:201], v[114:117]
	v_mfma_f32_16x16x32_bf16 v[106:109], v[182:185], v[206:209], v[106:109]
	v_mfma_f32_16x16x32_bf16 v[98:101], v[190:193], v[206:209], v[98:101]
	v_mfma_f32_16x16x32_bf16 v[90:93], v[182:185], v[214:217], v[90:93]
	v_mfma_f32_16x16x32_bf16 v[82:85], v[190:193], v[214:217], v[82:85]
	v_mfma_f32_16x16x32_bf16 v[74:77], v[182:185], v[222:225], v[74:77]
	v_mfma_f32_16x16x32_bf16 v[66:69], v[190:193], v[222:225], v[66:69]
	s_barrier
	s_setprio 0
	s_add_u32 s98, s96, 0x40000
	s_addc_u32 s99, s97, 0
	s_add_i32 s7, s71, s29
	s_mov_b32 m0, s7
	ds_read_b128 v[194:197], v163 offset:16384
	global_load_lds_dwordx4 v132, s[96:97]
	s_add_i32 m0, s7, 0x2000
	s_add_i32 s7, s72, s29
	global_load_lds_dwordx4 v136, s[96:97]
	s_mov_b32 m0, s7
	ds_read_b128 v[198:201], v163 offset:17408
	global_load_lds_dwordx4 v132, s[98:99]
	s_add_i32 m0, s7, 0x2000
	ds_read_b128 v[202:205], v163 offset:18432
	global_load_lds_dwordx4 v136, s[98:99]
	s_mov_b32 m0, s51
	ds_read_b128 v[206:209], v163 offset:19456
	global_load_lds_dwordx4 v130, s[94:95]
	s_mov_b32 m0, s60
	ds_read_b128 v[210:213], v163 offset:20480
	global_load_lds_dwordx4 v134, s[94:95]
	ds_read_b128 v[214:217], v163 offset:21504
	ds_read_b128 v[218:221], v163 offset:22528
	ds_read_b128 v[222:225], v163 offset:23552
	s_waitcnt vmcnt(8)
	s_waitcnt lgkmcnt(0)
	s_setprio 1
	s_barrier
	v_mfma_f32_16x16x32_bf16 v[62:65], v[156:159], v[194:197], 0
	v_mfma_f32_16x16x32_bf16 v[54:57], v[170:173], v[194:197], 0
	v_mfma_f32_16x16x32_bf16 v[46:49], v[156:159], v[202:205], 0
	v_mfma_f32_16x16x32_bf16 v[38:41], v[170:173], v[202:205], 0
	v_mfma_f32_16x16x32_bf16 v[30:33], v[156:159], v[210:213], 0
	v_mfma_f32_16x16x32_bf16 v[22:25], v[170:173], v[210:213], 0
	v_mfma_f32_16x16x32_bf16 v[14:17], v[156:159], v[218:221], 0
	v_mfma_f32_16x16x32_bf16 v[6:9], v[170:173], v[218:221], 0
	v_mfma_f32_16x16x32_bf16 v[62:65], v[166:169], v[198:201], v[62:65]
	v_mfma_f32_16x16x32_bf16 v[54:57], v[174:177], v[198:201], v[54:57]
	v_mfma_f32_16x16x32_bf16 v[46:49], v[166:169], v[206:209], v[46:49]
	v_mfma_f32_16x16x32_bf16 v[38:41], v[174:177], v[206:209], v[38:41]
	v_mfma_f32_16x16x32_bf16 v[30:33], v[166:169], v[214:217], v[30:33]
	v_mfma_f32_16x16x32_bf16 v[22:25], v[174:177], v[214:217], v[22:25]
	v_mfma_f32_16x16x32_bf16 v[14:17], v[166:169], v[222:225], v[14:17]
	v_mfma_f32_16x16x32_bf16 v[6:9], v[174:177], v[222:225], v[6:9]
	v_mfma_f32_16x16x32_bf16 v[58:61], v[178:181], v[194:197], 0
	v_mfma_f32_16x16x32_bf16 v[50:53], v[186:189], v[194:197], 0
	v_mfma_f32_16x16x32_bf16 v[42:45], v[178:181], v[202:205], 0
	v_mfma_f32_16x16x32_bf16 v[34:37], v[186:189], v[202:205], 0
	v_mfma_f32_16x16x32_bf16 v[26:29], v[178:181], v[210:213], 0
	v_mfma_f32_16x16x32_bf16 v[18:21], v[186:189], v[210:213], 0
	v_mfma_f32_16x16x32_bf16 v[10:13], v[178:181], v[218:221], 0
	v_mfma_f32_16x16x32_bf16 v[2:5], v[186:189], v[218:221], 0
	v_mfma_f32_16x16x32_bf16 v[58:61], v[182:185], v[198:201], v[58:61]
	v_mfma_f32_16x16x32_bf16 v[50:53], v[190:193], v[198:201], v[50:53]
	v_mfma_f32_16x16x32_bf16 v[42:45], v[182:185], v[206:209], v[42:45]
	v_mfma_f32_16x16x32_bf16 v[34:37], v[190:193], v[206:209], v[34:37]
	v_mfma_f32_16x16x32_bf16 v[26:29], v[182:185], v[214:217], v[26:29]
	v_mfma_f32_16x16x32_bf16 v[18:21], v[190:193], v[214:217], v[18:21]
	v_mfma_f32_16x16x32_bf16 v[10:13], v[182:185], v[222:225], v[10:13]
	v_mfma_f32_16x16x32_bf16 v[2:5], v[190:193], v[222:225], v[2:5]
	s_barrier
	s_setprio 0
	s_add_u32 s98, s94, 0x40000
	s_addc_u32 s99, s95, 0
	s_add_i32 s7, 0, 0x18000
	s_add_i32 s49, 0, 0x1c000
	s_mov_b32 m0, s61
	ds_read_b128 v[156:159], v232
	global_load_lds_dwordx4 v130, s[98:99]
	s_mov_b32 m0, s62
	ds_read_b128 v[166:169], v232 offset:1024
	global_load_lds_dwordx4 v134, s[98:99]
	ds_read_b128 v[170:173], v232 offset:2048
	ds_read_b128 v[174:177], v232 offset:3072
	ds_read_b128 v[178:181], v233
	ds_read_b128 v[182:185], v233 offset:1024
	ds_read_b128 v[186:189], v233 offset:2048
	ds_read_b128 v[190:193], v233 offset:3072
	ds_read_b128 v[194:197], v163 offset:32768
	ds_read_b128 v[198:201], v163 offset:33792
	ds_read_b128 v[202:205], v163 offset:34816
	ds_read_b128 v[206:209], v163 offset:35840
	ds_read_b128 v[210:213], v163 offset:36864
	ds_read_b128 v[214:217], v163 offset:37888
	ds_read_b128 v[218:221], v163 offset:38912
	ds_read_b128 v[222:225], v163 offset:39936
	s_waitcnt vmcnt(8)
	s_waitcnt lgkmcnt(0)
	s_setprio 1
	s_barrier
	v_mfma_f32_16x16x32_bf16 v[122:125], v[156:159], v[194:197], v[122:125]
	v_mfma_f32_16x16x32_bf16 v[118:121], v[170:173], v[194:197], v[118:121]
	v_mfma_f32_16x16x32_bf16 v[110:113], v[156:159], v[202:205], v[110:113]
	v_mfma_f32_16x16x32_bf16 v[102:105], v[170:173], v[202:205], v[102:105]
	v_mfma_f32_16x16x32_bf16 v[94:97], v[156:159], v[210:213], v[94:97]
	v_mfma_f32_16x16x32_bf16 v[86:89], v[170:173], v[210:213], v[86:89]
	v_mfma_f32_16x16x32_bf16 v[78:81], v[156:159], v[218:221], v[78:81]
	v_mfma_f32_16x16x32_bf16 v[70:73], v[170:173], v[218:221], v[70:73]
	v_mfma_f32_16x16x32_bf16 v[122:125], v[166:169], v[198:201], v[122:125]
	v_mfma_f32_16x16x32_bf16 v[118:121], v[174:177], v[198:201], v[118:121]
	v_mfma_f32_16x16x32_bf16 v[110:113], v[166:169], v[206:209], v[110:113]
	v_mfma_f32_16x16x32_bf16 v[102:105], v[174:177], v[206:209], v[102:105]
	v_mfma_f32_16x16x32_bf16 v[94:97], v[166:169], v[214:217], v[94:97]
	v_mfma_f32_16x16x32_bf16 v[86:89], v[174:177], v[214:217], v[86:89]
	v_mfma_f32_16x16x32_bf16 v[78:81], v[166:169], v[222:225], v[78:81]
	v_mfma_f32_16x16x32_bf16 v[70:73], v[174:177], v[222:225], v[70:73]
	v_mfma_f32_16x16x32_bf16 v[126:129], v[178:181], v[194:197], v[126:129]
	v_mfma_f32_16x16x32_bf16 v[114:117], v[186:189], v[194:197], v[114:117]
	v_mfma_f32_16x16x32_bf16 v[106:109], v[178:181], v[202:205], v[106:109]
	v_mfma_f32_16x16x32_bf16 v[98:101], v[186:189], v[202:205], v[98:101]
	v_mfma_f32_16x16x32_bf16 v[90:93], v[178:181], v[210:213], v[90:93]
	v_mfma_f32_16x16x32_bf16 v[82:85], v[186:189], v[210:213], v[82:85]
	v_mfma_f32_16x16x32_bf16 v[74:77], v[178:181], v[218:221], v[74:77]
	v_mfma_f32_16x16x32_bf16 v[66:69], v[186:189], v[218:221], v[66:69]
	v_mfma_f32_16x16x32_bf16 v[126:129], v[182:185], v[198:201], v[126:129]
	v_mfma_f32_16x16x32_bf16 v[114:117], v[190:193], v[198:201], v[114:117]
	v_mfma_f32_16x16x32_bf16 v[106:109], v[182:185], v[206:209], v[106:109]
	v_mfma_f32_16x16x32_bf16 v[98:101], v[190:193], v[206:209], v[98:101]
	v_mfma_f32_16x16x32_bf16 v[90:93], v[182:185], v[214:217], v[90:93]
	v_mfma_f32_16x16x32_bf16 v[82:85], v[190:193], v[214:217], v[82:85]
	v_mfma_f32_16x16x32_bf16 v[74:77], v[182:185], v[222:225], v[74:77]
	v_mfma_f32_16x16x32_bf16 v[66:69], v[190:193], v[222:225], v[66:69]
	s_barrier
	s_setprio 0
	s_add_u32 s96, s96, 0x80
	s_addc_u32 s97, s97, 0
	s_add_u32 s98, s96, 0x40000
	s_addc_u32 s99, s97, 0
	s_add_u32 s94, s94, 0x80
	s_addc_u32 s95, s95, 0
	s_add_i32 s7, s7, s29
	s_mov_b32 m0, s7
	ds_read_b128 v[194:197], v163 offset:49152
	global_load_lds_dwordx4 v132, s[96:97]
	s_add_i32 m0, s7, 0x2000
	s_add_i32 s7, s49, s29
	global_load_lds_dwordx4 v136, s[96:97]
	s_mov_b32 m0, s7
	ds_read_b128 v[198:201], v163 offset:50176
	global_load_lds_dwordx4 v132, s[98:99]
	s_add_i32 m0, s7, 0x2000
	ds_read_b128 v[202:205], v163 offset:51200
	global_load_lds_dwordx4 v136, s[98:99]
	s_mov_b32 m0, s63
	ds_read_b128 v[206:209], v163 offset:52224
	global_load_lds_dwordx4 v130, s[94:95]
	s_mov_b32 m0, s64
	ds_read_b128 v[210:213], v163 offset:53248
	global_load_lds_dwordx4 v134, s[94:95]
	ds_read_b128 v[214:217], v163 offset:54272
	ds_read_b128 v[218:221], v163 offset:55296
	ds_read_b128 v[222:225], v163 offset:56320
	s_waitcnt vmcnt(8)
	s_waitcnt lgkmcnt(0)
	s_setprio 1
	s_barrier
	v_mfma_f32_16x16x32_bf16 v[62:65], v[156:159], v[194:197], v[62:65]
	v_mfma_f32_16x16x32_bf16 v[54:57], v[170:173], v[194:197], v[54:57]
	v_mfma_f32_16x16x32_bf16 v[46:49], v[156:159], v[202:205], v[46:49]
	v_mfma_f32_16x16x32_bf16 v[38:41], v[170:173], v[202:205], v[38:41]
	v_mfma_f32_16x16x32_bf16 v[30:33], v[156:159], v[210:213], v[30:33]
	v_mfma_f32_16x16x32_bf16 v[22:25], v[170:173], v[210:213], v[22:25]
	v_mfma_f32_16x16x32_bf16 v[14:17], v[156:159], v[218:221], v[14:17]
	v_mfma_f32_16x16x32_bf16 v[6:9], v[170:173], v[218:221], v[6:9]
	v_mfma_f32_16x16x32_bf16 v[62:65], v[166:169], v[198:201], v[62:65]
	v_mfma_f32_16x16x32_bf16 v[54:57], v[174:177], v[198:201], v[54:57]
	v_mfma_f32_16x16x32_bf16 v[46:49], v[166:169], v[206:209], v[46:49]
	v_mfma_f32_16x16x32_bf16 v[38:41], v[174:177], v[206:209], v[38:41]
	v_mfma_f32_16x16x32_bf16 v[30:33], v[166:169], v[214:217], v[30:33]
	v_mfma_f32_16x16x32_bf16 v[22:25], v[174:177], v[214:217], v[22:25]
	v_mfma_f32_16x16x32_bf16 v[14:17], v[166:169], v[222:225], v[14:17]
	v_mfma_f32_16x16x32_bf16 v[6:9], v[174:177], v[222:225], v[6:9]
	v_mfma_f32_16x16x32_bf16 v[58:61], v[178:181], v[194:197], v[58:61]
	v_mfma_f32_16x16x32_bf16 v[50:53], v[186:189], v[194:197], v[50:53]
	v_mfma_f32_16x16x32_bf16 v[42:45], v[178:181], v[202:205], v[42:45]
	v_mfma_f32_16x16x32_bf16 v[34:37], v[186:189], v[202:205], v[34:37]
	v_mfma_f32_16x16x32_bf16 v[26:29], v[178:181], v[210:213], v[26:29]
	v_mfma_f32_16x16x32_bf16 v[18:21], v[186:189], v[210:213], v[18:21]
	v_mfma_f32_16x16x32_bf16 v[10:13], v[178:181], v[218:221], v[10:13]
	v_mfma_f32_16x16x32_bf16 v[2:5], v[186:189], v[218:221], v[2:5]
	v_mfma_f32_16x16x32_bf16 v[58:61], v[182:185], v[198:201], v[58:61]
	v_mfma_f32_16x16x32_bf16 v[50:53], v[190:193], v[198:201], v[50:53]
	v_mfma_f32_16x16x32_bf16 v[42:45], v[182:185], v[206:209], v[42:45]
	v_mfma_f32_16x16x32_bf16 v[34:37], v[190:193], v[206:209], v[34:37]
	v_mfma_f32_16x16x32_bf16 v[26:29], v[182:185], v[214:217], v[26:29]
	v_mfma_f32_16x16x32_bf16 v[18:21], v[190:193], v[214:217], v[18:21]
	v_mfma_f32_16x16x32_bf16 v[10:13], v[182:185], v[222:225], v[10:13]
	v_mfma_f32_16x16x32_bf16 v[2:5], v[190:193], v[222:225], v[2:5]
	s_barrier
	s_setprio 0
	s_mov_b32 s7, s47
	s_add_u32 s88, s88, 0x100
	s_addc_u32 s89, s89, 0
	s_add_u32 s86, s86, 0x100
	s_addc_u32 s87, s87, 0
	s_cmp_ge_i32 s47, s101
	s_cbranch_scc1 .Lmy_kexit_8
.LBB0_1573:
	s_add_u32 s98, s86, 0xfffc0080
	s_addc_u32 s99, s87, -1
	s_cmp_eq_u32 s7, s100
	s_cselect_b64 s[94:95], s[90:91], s[98:99]
	s_cselect_b64 s[96:97], s[92:93], s[88:89]
	s_add_i32 s47, s7, 2
	s_mov_b32 m0, s74
	ds_read_b128 v[156:159], v230
	global_load_lds_dwordx4 v144, s[86:87]
	s_mov_b32 m0, s75
	ds_read_b128 v[166:169], v230 offset:1024
	global_load_lds_dwordx4 v142, s[86:87]
	ds_read_b128 v[170:173], v230 offset:2048
	ds_read_b128 v[174:177], v230 offset:3072
	ds_read_b128 v[178:181], v231
	ds_read_b128 v[182:185], v231 offset:1024
	ds_read_b128 v[186:189], v231 offset:2048
	ds_read_b128 v[190:193], v231 offset:3072
	ds_read_b128 v[194:197], v163
	ds_read_b128 v[198:201], v163 offset:1024
	ds_read_b128 v[202:205], v163 offset:2048
	ds_read_b128 v[206:209], v163 offset:3072
	ds_read_b128 v[210:213], v163 offset:4096
	ds_read_b128 v[214:217], v163 offset:5120
	ds_read_b128 v[218:221], v163 offset:6144
	ds_read_b128 v[222:225], v163 offset:7168
	s_waitcnt vmcnt(8)
	s_waitcnt lgkmcnt(0)
	s_setprio 1
	s_barrier
	v_mfma_f32_16x16x32_bf16 v[122:125], v[156:159], v[194:197], v[122:125]
	v_mfma_f32_16x16x32_bf16 v[118:121], v[170:173], v[194:197], v[118:121]
	v_mfma_f32_16x16x32_bf16 v[110:113], v[156:159], v[202:205], v[110:113]
	v_mfma_f32_16x16x32_bf16 v[102:105], v[170:173], v[202:205], v[102:105]
	v_mfma_f32_16x16x32_bf16 v[94:97], v[156:159], v[210:213], v[94:97]
	v_mfma_f32_16x16x32_bf16 v[86:89], v[170:173], v[210:213], v[86:89]
	v_mfma_f32_16x16x32_bf16 v[78:81], v[156:159], v[218:221], v[78:81]
	v_mfma_f32_16x16x32_bf16 v[70:73], v[170:173], v[218:221], v[70:73]
	v_mfma_f32_16x16x32_bf16 v[122:125], v[166:169], v[198:201], v[122:125]
	v_mfma_f32_16x16x32_bf16 v[118:121], v[174:177], v[198:201], v[118:121]
	v_mfma_f32_16x16x32_bf16 v[110:113], v[166:169], v[206:209], v[110:113]
	v_mfma_f32_16x16x32_bf16 v[102:105], v[174:177], v[206:209], v[102:105]
	v_mfma_f32_16x16x32_bf16 v[94:97], v[166:169], v[214:217], v[94:97]
	v_mfma_f32_16x16x32_bf16 v[86:89], v[174:177], v[214:217], v[86:89]
	v_mfma_f32_16x16x32_bf16 v[78:81], v[166:169], v[222:225], v[78:81]
	v_mfma_f32_16x16x32_bf16 v[70:73], v[174:177], v[222:225], v[70:73]
	v_mfma_f32_16x16x32_bf16 v[126:129], v[178:181], v[194:197], v[126:129]
	v_mfma_f32_16x16x32_bf16 v[114:117], v[186:189], v[194:197], v[114:117]
	v_mfma_f32_16x16x32_bf16 v[106:109], v[178:181], v[202:205], v[106:109]
	v_mfma_f32_16x16x32_bf16 v[98:101], v[186:189], v[202:205], v[98:101]
	v_mfma_f32_16x16x32_bf16 v[90:93], v[178:181], v[210:213], v[90:93]
	v_mfma_f32_16x16x32_bf16 v[82:85], v[186:189], v[210:213], v[82:85]
	v_mfma_f32_16x16x32_bf16 v[74:77], v[178:181], v[218:221], v[74:77]
	v_mfma_f32_16x16x32_bf16 v[66:69], v[186:189], v[218:221], v[66:69]
	v_mfma_f32_16x16x32_bf16 v[126:129], v[182:185], v[198:201], v[126:129]
	v_mfma_f32_16x16x32_bf16 v[114:117], v[190:193], v[198:201], v[114:117]
	v_mfma_f32_16x16x32_bf16 v[106:109], v[182:185], v[206:209], v[106:109]
	v_mfma_f32_16x16x32_bf16 v[98:101], v[190:193], v[206:209], v[98:101]
	v_mfma_f32_16x16x32_bf16 v[90:93], v[182:185], v[214:217], v[90:93]
	v_mfma_f32_16x16x32_bf16 v[82:85], v[190:193], v[214:217], v[82:85]
	v_mfma_f32_16x16x32_bf16 v[74:77], v[182:185], v[222:225], v[74:77]
	v_mfma_f32_16x16x32_bf16 v[66:69], v[190:193], v[222:225], v[66:69]
	s_barrier
	s_setprio 0
	s_add_u32 s98, s96, 0x40000
	s_addc_u32 s99, s97, 0
	s_add_i32 s7, s71, s29
	s_mov_b32 m0, s7
	ds_read_b128 v[194:197], v163 offset:16384
	global_load_lds_dwordx4 v132, s[96:97]
	s_add_i32 m0, s7, 0x2000
	s_add_i32 s7, s72, s29
	global_load_lds_dwordx4 v136, s[96:97]
	s_mov_b32 m0, s7
	ds_read_b128 v[198:201], v163 offset:17408
	global_load_lds_dwordx4 v132, s[98:99]
	s_add_i32 m0, s7, 0x2000
	ds_read_b128 v[202:205], v163 offset:18432
	global_load_lds_dwordx4 v136, s[98:99]
	s_mov_b32 m0, s51
	ds_read_b128 v[206:209], v163 offset:19456
	global_load_lds_dwordx4 v130, s[94:95]
	s_mov_b32 m0, s60
	ds_read_b128 v[210:213], v163 offset:20480
	global_load_lds_dwordx4 v134, s[94:95]
	ds_read_b128 v[214:217], v163 offset:21504
	ds_read_b128 v[218:221], v163 offset:22528
	ds_read_b128 v[222:225], v163 offset:23552
	s_waitcnt vmcnt(8)
	s_waitcnt lgkmcnt(0)
	s_setprio 1
	s_barrier
	v_mfma_f32_16x16x32_bf16 v[62:65], v[156:159], v[194:197], v[62:65]
	v_mfma_f32_16x16x32_bf16 v[54:57], v[170:173], v[194:197], v[54:57]
	v_mfma_f32_16x16x32_bf16 v[46:49], v[156:159], v[202:205], v[46:49]
	v_mfma_f32_16x16x32_bf16 v[38:41], v[170:173], v[202:205], v[38:41]
	v_mfma_f32_16x16x32_bf16 v[30:33], v[156:159], v[210:213], v[30:33]
	v_mfma_f32_16x16x32_bf16 v[22:25], v[170:173], v[210:213], v[22:25]
	v_mfma_f32_16x16x32_bf16 v[14:17], v[156:159], v[218:221], v[14:17]
	v_mfma_f32_16x16x32_bf16 v[6:9], v[170:173], v[218:221], v[6:9]
	v_mfma_f32_16x16x32_bf16 v[62:65], v[166:169], v[198:201], v[62:65]
	v_mfma_f32_16x16x32_bf16 v[54:57], v[174:177], v[198:201], v[54:57]
	v_mfma_f32_16x16x32_bf16 v[46:49], v[166:169], v[206:209], v[46:49]
	v_mfma_f32_16x16x32_bf16 v[38:41], v[174:177], v[206:209], v[38:41]
	v_mfma_f32_16x16x32_bf16 v[30:33], v[166:169], v[214:217], v[30:33]
	v_mfma_f32_16x16x32_bf16 v[22:25], v[174:177], v[214:217], v[22:25]
	v_mfma_f32_16x16x32_bf16 v[14:17], v[166:169], v[222:225], v[14:17]
	v_mfma_f32_16x16x32_bf16 v[6:9], v[174:177], v[222:225], v[6:9]
	v_mfma_f32_16x16x32_bf16 v[58:61], v[178:181], v[194:197], v[58:61]
	v_mfma_f32_16x16x32_bf16 v[50:53], v[186:189], v[194:197], v[50:53]
	v_mfma_f32_16x16x32_bf16 v[42:45], v[178:181], v[202:205], v[42:45]
	v_mfma_f32_16x16x32_bf16 v[34:37], v[186:189], v[202:205], v[34:37]
	v_mfma_f32_16x16x32_bf16 v[26:29], v[178:181], v[210:213], v[26:29]
	v_mfma_f32_16x16x32_bf16 v[18:21], v[186:189], v[210:213], v[18:21]
	v_mfma_f32_16x16x32_bf16 v[10:13], v[178:181], v[218:221], v[10:13]
	v_mfma_f32_16x16x32_bf16 v[2:5], v[186:189], v[218:221], v[2:5]
	v_mfma_f32_16x16x32_bf16 v[58:61], v[182:185], v[198:201], v[58:61]
	v_mfma_f32_16x16x32_bf16 v[50:53], v[190:193], v[198:201], v[50:53]
	v_mfma_f32_16x16x32_bf16 v[42:45], v[182:185], v[206:209], v[42:45]
	v_mfma_f32_16x16x32_bf16 v[34:37], v[190:193], v[206:209], v[34:37]
	v_mfma_f32_16x16x32_bf16 v[26:29], v[182:185], v[214:217], v[26:29]
	v_mfma_f32_16x16x32_bf16 v[18:21], v[190:193], v[214:217], v[18:21]
	v_mfma_f32_16x16x32_bf16 v[10:13], v[182:185], v[222:225], v[10:13]
	v_mfma_f32_16x16x32_bf16 v[2:5], v[190:193], v[222:225], v[2:5]
	s_barrier
	s_setprio 0
	s_add_u32 s98, s94, 0x40000
	s_addc_u32 s99, s95, 0
	s_add_i32 s7, 0, 0x18000
	s_add_i32 s49, 0, 0x1c000
	s_mov_b32 m0, s61
	ds_read_b128 v[156:159], v232
	global_load_lds_dwordx4 v130, s[98:99]
	s_mov_b32 m0, s62
	ds_read_b128 v[166:169], v232 offset:1024
	global_load_lds_dwordx4 v134, s[98:99]
	ds_read_b128 v[170:173], v232 offset:2048
	ds_read_b128 v[174:177], v232 offset:3072
	ds_read_b128 v[178:181], v233
	ds_read_b128 v[182:185], v233 offset:1024
	ds_read_b128 v[186:189], v233 offset:2048
	ds_read_b128 v[190:193], v233 offset:3072
	ds_read_b128 v[194:197], v163 offset:32768
	ds_read_b128 v[198:201], v163 offset:33792
	ds_read_b128 v[202:205], v163 offset:34816
	ds_read_b128 v[206:209], v163 offset:35840
	ds_read_b128 v[210:213], v163 offset:36864
	ds_read_b128 v[214:217], v163 offset:37888
	ds_read_b128 v[218:221], v163 offset:38912
	ds_read_b128 v[222:225], v163 offset:39936
	s_waitcnt vmcnt(8)
	s_waitcnt lgkmcnt(0)
	s_setprio 1
	s_barrier
	v_mfma_f32_16x16x32_bf16 v[122:125], v[156:159], v[194:197], v[122:125]
	v_mfma_f32_16x16x32_bf16 v[118:121], v[170:173], v[194:197], v[118:121]
	v_mfma_f32_16x16x32_bf16 v[110:113], v[156:159], v[202:205], v[110:113]
	v_mfma_f32_16x16x32_bf16 v[102:105], v[170:173], v[202:205], v[102:105]
	v_mfma_f32_16x16x32_bf16 v[94:97], v[156:159], v[210:213], v[94:97]
	v_mfma_f32_16x16x32_bf16 v[86:89], v[170:173], v[210:213], v[86:89]
	v_mfma_f32_16x16x32_bf16 v[78:81], v[156:159], v[218:221], v[78:81]
	v_mfma_f32_16x16x32_bf16 v[70:73], v[170:173], v[218:221], v[70:73]
	v_mfma_f32_16x16x32_bf16 v[122:125], v[166:169], v[198:201], v[122:125]
	v_mfma_f32_16x16x32_bf16 v[118:121], v[174:177], v[198:201], v[118:121]
	v_mfma_f32_16x16x32_bf16 v[110:113], v[166:169], v[206:209], v[110:113]
	v_mfma_f32_16x16x32_bf16 v[102:105], v[174:177], v[206:209], v[102:105]
	v_mfma_f32_16x16x32_bf16 v[94:97], v[166:169], v[214:217], v[94:97]
	v_mfma_f32_16x16x32_bf16 v[86:89], v[174:177], v[214:217], v[86:89]
	v_mfma_f32_16x16x32_bf16 v[78:81], v[166:169], v[222:225], v[78:81]
	v_mfma_f32_16x16x32_bf16 v[70:73], v[174:177], v[222:225], v[70:73]
	v_mfma_f32_16x16x32_bf16 v[126:129], v[178:181], v[194:197], v[126:129]
	v_mfma_f32_16x16x32_bf16 v[114:117], v[186:189], v[194:197], v[114:117]
	v_mfma_f32_16x16x32_bf16 v[106:109], v[178:181], v[202:205], v[106:109]
	v_mfma_f32_16x16x32_bf16 v[98:101], v[186:189], v[202:205], v[98:101]
	v_mfma_f32_16x16x32_bf16 v[90:93], v[178:181], v[210:213], v[90:93]
	v_mfma_f32_16x16x32_bf16 v[82:85], v[186:189], v[210:213], v[82:85]
	v_mfma_f32_16x16x32_bf16 v[74:77], v[178:181], v[218:221], v[74:77]
	v_mfma_f32_16x16x32_bf16 v[66:69], v[186:189], v[218:221], v[66:69]
	v_mfma_f32_16x16x32_bf16 v[126:129], v[182:185], v[198:201], v[126:129]
	v_mfma_f32_16x16x32_bf16 v[114:117], v[190:193], v[198:201], v[114:117]
	v_mfma_f32_16x16x32_bf16 v[106:109], v[182:185], v[206:209], v[106:109]
	v_mfma_f32_16x16x32_bf16 v[98:101], v[190:193], v[206:209], v[98:101]
	v_mfma_f32_16x16x32_bf16 v[90:93], v[182:185], v[214:217], v[90:93]
	v_mfma_f32_16x16x32_bf16 v[82:85], v[190:193], v[214:217], v[82:85]
	v_mfma_f32_16x16x32_bf16 v[74:77], v[182:185], v[222:225], v[74:77]
	v_mfma_f32_16x16x32_bf16 v[66:69], v[190:193], v[222:225], v[66:69]
	s_barrier
	s_setprio 0
	s_add_u32 s96, s96, 0x80
	s_addc_u32 s97, s97, 0
	s_add_u32 s98, s96, 0x40000
	s_addc_u32 s99, s97, 0
	s_add_u32 s94, s94, 0x80
	s_addc_u32 s95, s95, 0
	s_add_i32 s7, s7, s29
	s_mov_b32 m0, s7
	ds_read_b128 v[194:197], v163 offset:49152
	global_load_lds_dwordx4 v132, s[96:97]
	s_add_i32 m0, s7, 0x2000
	s_add_i32 s7, s49, s29
	global_load_lds_dwordx4 v136, s[96:97]
	s_mov_b32 m0, s7
	ds_read_b128 v[198:201], v163 offset:50176
	global_load_lds_dwordx4 v132, s[98:99]
	s_add_i32 m0, s7, 0x2000
	ds_read_b128 v[202:205], v163 offset:51200
	global_load_lds_dwordx4 v136, s[98:99]
	s_mov_b32 m0, s63
	ds_read_b128 v[206:209], v163 offset:52224
	global_load_lds_dwordx4 v130, s[94:95]
	s_mov_b32 m0, s64
	ds_read_b128 v[210:213], v163 offset:53248
	global_load_lds_dwordx4 v134, s[94:95]
	ds_read_b128 v[214:217], v163 offset:54272
	ds_read_b128 v[218:221], v163 offset:55296
	ds_read_b128 v[222:225], v163 offset:56320
	s_waitcnt vmcnt(8)
	s_waitcnt lgkmcnt(0)
	s_setprio 1
	s_barrier
	v_mfma_f32_16x16x32_bf16 v[62:65], v[156:159], v[194:197], v[62:65]
	v_mfma_f32_16x16x32_bf16 v[54:57], v[170:173], v[194:197], v[54:57]
	v_mfma_f32_16x16x32_bf16 v[46:49], v[156:159], v[202:205], v[46:49]
	v_mfma_f32_16x16x32_bf16 v[38:41], v[170:173], v[202:205], v[38:41]
	v_mfma_f32_16x16x32_bf16 v[30:33], v[156:159], v[210:213], v[30:33]
	v_mfma_f32_16x16x32_bf16 v[22:25], v[170:173], v[210:213], v[22:25]
	v_mfma_f32_16x16x32_bf16 v[14:17], v[156:159], v[218:221], v[14:17]
	v_mfma_f32_16x16x32_bf16 v[6:9], v[170:173], v[218:221], v[6:9]
	v_mfma_f32_16x16x32_bf16 v[62:65], v[166:169], v[198:201], v[62:65]
	v_mfma_f32_16x16x32_bf16 v[54:57], v[174:177], v[198:201], v[54:57]
	v_mfma_f32_16x16x32_bf16 v[46:49], v[166:169], v[206:209], v[46:49]
	v_mfma_f32_16x16x32_bf16 v[38:41], v[174:177], v[206:209], v[38:41]
	v_mfma_f32_16x16x32_bf16 v[30:33], v[166:169], v[214:217], v[30:33]
	v_mfma_f32_16x16x32_bf16 v[22:25], v[174:177], v[214:217], v[22:25]
	v_mfma_f32_16x16x32_bf16 v[14:17], v[166:169], v[222:225], v[14:17]
	v_mfma_f32_16x16x32_bf16 v[6:9], v[174:177], v[222:225], v[6:9]
	v_mfma_f32_16x16x32_bf16 v[58:61], v[178:181], v[194:197], v[58:61]
	v_mfma_f32_16x16x32_bf16 v[50:53], v[186:189], v[194:197], v[50:53]
	v_mfma_f32_16x16x32_bf16 v[42:45], v[178:181], v[202:205], v[42:45]
	v_mfma_f32_16x16x32_bf16 v[34:37], v[186:189], v[202:205], v[34:37]
	v_mfma_f32_16x16x32_bf16 v[26:29], v[178:181], v[210:213], v[26:29]
	v_mfma_f32_16x16x32_bf16 v[18:21], v[186:189], v[210:213], v[18:21]
	v_mfma_f32_16x16x32_bf16 v[10:13], v[178:181], v[218:221], v[10:13]
	v_mfma_f32_16x16x32_bf16 v[2:5], v[186:189], v[218:221], v[2:5]
	v_mfma_f32_16x16x32_bf16 v[58:61], v[182:185], v[198:201], v[58:61]
	v_mfma_f32_16x16x32_bf16 v[50:53], v[190:193], v[198:201], v[50:53]
	v_mfma_f32_16x16x32_bf16 v[42:45], v[182:185], v[206:209], v[42:45]
	v_mfma_f32_16x16x32_bf16 v[34:37], v[190:193], v[206:209], v[34:37]
	v_mfma_f32_16x16x32_bf16 v[26:29], v[182:185], v[214:217], v[26:29]
	v_mfma_f32_16x16x32_bf16 v[18:21], v[190:193], v[214:217], v[18:21]
	v_mfma_f32_16x16x32_bf16 v[10:13], v[182:185], v[222:225], v[10:13]
	v_mfma_f32_16x16x32_bf16 v[2:5], v[190:193], v[222:225], v[2:5]
	s_barrier
	s_setprio 0
	s_mov_b32 s7, s47
	s_add_u32 s88, s88, 0x100
	s_addc_u32 s89, s89, 0
	s_add_u32 s86, s86, 0x100
	s_addc_u32 s87, s87, 0
	s_cmp_ge_i32 s47, s101
	s_cbranch_scc0 .LBB0_1573

.Lmy_nb_9:
	s_nop 0
	v_readfirstlane_b32 s86, v152
	v_readfirstlane_b32 s87, v153
	v_readfirstlane_b32 s88, v150
	v_readfirstlane_b32 s89, v151
	v_readfirstlane_b32 s90, v146
	v_readfirstlane_b32 s91, v147
	v_readfirstlane_b32 s92, v148
	v_readfirstlane_b32 s93, v149
	v_readfirstlane_b32 s100, v154
	v_readfirstlane_b32 s101, v138
	v_add_u32_e32 v230, s74, v141
	v_add_u32_e32 v231, s75, v141
	v_add_u32_e32 v232, 0x18000, v141
	v_add_u32_e32 v233, 0x1c000, v141
	s_add_u32 s98, s86, 0xfffc0080
	s_addc_u32 s99, s87, -1
	s_cmp_eq_u32 s5, s100
	s_cselect_b64 s[94:95], s[90:91], s[98:99]
	s_cselect_b64 s[96:97], s[92:93], s[88:89]
	s_add_i32 s29, s5, 2
	s_add_i32 m0, s47, 0xc000
	ds_read_b128 v[164:167], v230
	global_load_lds_dwordx4 v144, s[86:87]
	s_add_i32 m0, s47, 0xe000
	ds_read_b128 v[168:171], v230 offset:1024
	global_load_lds_dwordx4 v142, s[86:87]
	ds_read_b128 v[172:175], v230 offset:2048
	ds_read_b128 v[176:179], v230 offset:3072
	ds_read_b128 v[180:183], v231
	ds_read_b128 v[184:187], v231 offset:1024
	ds_read_b128 v[188:191], v231 offset:2048
	ds_read_b128 v[192:195], v231 offset:3072
	ds_read_b128 v[196:199], v160
	ds_read_b128 v[200:203], v160 offset:1024
	ds_read_b128 v[204:207], v160 offset:2048
	ds_read_b128 v[208:211], v160 offset:3072
	ds_read_b128 v[212:215], v160 offset:4096
	ds_read_b128 v[216:219], v160 offset:5120
	ds_read_b128 v[220:223], v160 offset:6144
	ds_read_b128 v[224:227], v160 offset:7168
	s_waitcnt vmcnt(8)
	s_waitcnt lgkmcnt(0)
	s_setprio 1
	s_barrier
	v_mfma_f32_16x16x32_bf16 v[122:125], v[164:167], v[196:199], 0
	v_mfma_f32_16x16x32_bf16 v[118:121], v[172:175], v[196:199], 0
	v_mfma_f32_16x16x32_bf16 v[110:113], v[164:167], v[204:207], 0
	v_mfma_f32_16x16x32_bf16 v[102:105], v[172:175], v[204:207], 0
	v_mfma_f32_16x16x32_bf16 v[94:97], v[164:167], v[212:215], 0
	v_mfma_f32_16x16x32_bf16 v[86:89], v[172:175], v[212:215], 0
	v_mfma_f32_16x16x32_bf16 v[78:81], v[164:167], v[220:223], 0
	v_mfma_f32_16x16x32_bf16 v[70:73], v[172:175], v[220:223], 0
	v_mfma_f32_16x16x32_bf16 v[122:125], v[168:171], v[200:203], v[122:125]
	v_mfma_f32_16x16x32_bf16 v[118:121], v[176:179], v[200:203], v[118:121]
	v_mfma_f32_16x16x32_bf16 v[110:113], v[168:171], v[208:211], v[110:113]
	v_mfma_f32_16x16x32_bf16 v[102:105], v[176:179], v[208:211], v[102:105]
	v_mfma_f32_16x16x32_bf16 v[94:97], v[168:171], v[216:219], v[94:97]
	v_mfma_f32_16x16x32_bf16 v[86:89], v[176:179], v[216:219], v[86:89]
	v_mfma_f32_16x16x32_bf16 v[78:81], v[168:171], v[224:227], v[78:81]
	v_mfma_f32_16x16x32_bf16 v[70:73], v[176:179], v[224:227], v[70:73]
	v_mfma_f32_16x16x32_bf16 v[126:129], v[180:183], v[196:199], 0
	v_mfma_f32_16x16x32_bf16 v[114:117], v[188:191], v[196:199], 0
	v_mfma_f32_16x16x32_bf16 v[106:109], v[180:183], v[204:207], 0
	v_mfma_f32_16x16x32_bf16 v[98:101], v[188:191], v[204:207], 0
	v_mfma_f32_16x16x32_bf16 v[90:93], v[180:183], v[212:215], 0
	v_mfma_f32_16x16x32_bf16 v[82:85], v[188:191], v[212:215], 0
	v_mfma_f32_16x16x32_bf16 v[74:77], v[180:183], v[220:223], 0
	v_mfma_f32_16x16x32_bf16 v[66:69], v[188:191], v[220:223], 0
	v_mfma_f32_16x16x32_bf16 v[126:129], v[184:187], v[200:203], v[126:129]
	v_mfma_f32_16x16x32_bf16 v[114:117], v[192:195], v[200:203], v[114:117]
	v_mfma_f32_16x16x32_bf16 v[106:109], v[184:187], v[208:211], v[106:109]
	v_mfma_f32_16x16x32_bf16 v[98:101], v[192:195], v[208:211], v[98:101]
	v_mfma_f32_16x16x32_bf16 v[90:93], v[184:187], v[216:219], v[90:93]
	v_mfma_f32_16x16x32_bf16 v[82:85], v[192:195], v[216:219], v[82:85]
	v_mfma_f32_16x16x32_bf16 v[74:77], v[184:187], v[224:227], v[74:77]
	v_mfma_f32_16x16x32_bf16 v[66:69], v[192:195], v[224:227], v[66:69]
	s_barrier
	s_setprio 0
	s_add_u32 s98, s96, 0x40000
	s_addc_u32 s99, s97, 0
	s_add_i32 s5, s74, s23
	s_mov_b32 m0, s5
	ds_read_b128 v[196:199], v160 offset:16384
	global_load_lds_dwordx4 v132, s[96:97]
	s_add_i32 m0, s5, 0x2000
	s_add_i32 s5, s75, s23
	global_load_lds_dwordx4 v136, s[96:97]
	s_mov_b32 m0, s5
	ds_read_b128 v[200:203], v160 offset:17408
	global_load_lds_dwordx4 v132, s[98:99]
	s_add_i32 m0, s5, 0x2000
	ds_read_b128 v[204:207], v160 offset:18432
	global_load_lds_dwordx4 v136, s[98:99]
	s_mov_b32 m0, s47
	ds_read_b128 v[208:211], v160 offset:19456
	global_load_lds_dwordx4 v130, s[94:95]
	s_mov_b32 m0, s56
	ds_read_b128 v[212:215], v160 offset:20480
	global_load_lds_dwordx4 v134, s[94:95]
	ds_read_b128 v[216:219], v160 offset:21504
	ds_read_b128 v[220:223], v160 offset:22528
	ds_read_b128 v[224:227], v160 offset:23552
	s_waitcnt vmcnt(8)
	s_waitcnt lgkmcnt(0)
	s_setprio 1
	s_barrier
	v_mfma_f32_16x16x32_bf16 v[62:65], v[164:167], v[196:199], 0
	v_mfma_f32_16x16x32_bf16 v[54:57], v[172:175], v[196:199], 0
	v_mfma_f32_16x16x32_bf16 v[46:49], v[164:167], v[204:207], 0
	v_mfma_f32_16x16x32_bf16 v[38:41], v[172:175], v[204:207], 0
	v_mfma_f32_16x16x32_bf16 v[30:33], v[164:167], v[212:215], 0
	v_mfma_f32_16x16x32_bf16 v[22:25], v[172:175], v[212:215], 0
	v_mfma_f32_16x16x32_bf16 v[14:17], v[164:167], v[220:223], 0
	v_mfma_f32_16x16x32_bf16 v[6:9], v[172:175], v[220:223], 0
	v_mfma_f32_16x16x32_bf16 v[62:65], v[168:171], v[200:203], v[62:65]
	v_mfma_f32_16x16x32_bf16 v[54:57], v[176:179], v[200:203], v[54:57]
	v_mfma_f32_16x16x32_bf16 v[46:49], v[168:171], v[208:211], v[46:49]
	v_mfma_f32_16x16x32_bf16 v[38:41], v[176:179], v[208:211], v[38:41]
	v_mfma_f32_16x16x32_bf16 v[30:33], v[168:171], v[216:219], v[30:33]
	v_mfma_f32_16x16x32_bf16 v[22:25], v[176:179], v[216:219], v[22:25]
	v_mfma_f32_16x16x32_bf16 v[14:17], v[168:171], v[224:227], v[14:17]
	v_mfma_f32_16x16x32_bf16 v[6:9], v[176:179], v[224:227], v[6:9]
	v_mfma_f32_16x16x32_bf16 v[58:61], v[180:183], v[196:199], 0
	v_mfma_f32_16x16x32_bf16 v[50:53], v[188:191], v[196:199], 0
	v_mfma_f32_16x16x32_bf16 v[42:45], v[180:183], v[204:207], 0
	v_mfma_f32_16x16x32_bf16 v[34:37], v[188:191], v[204:207], 0
	v_mfma_f32_16x16x32_bf16 v[26:29], v[180:183], v[212:215], 0
	v_mfma_f32_16x16x32_bf16 v[18:21], v[188:191], v[212:215], 0
	v_mfma_f32_16x16x32_bf16 v[10:13], v[180:183], v[220:223], 0
	v_mfma_f32_16x16x32_bf16 v[2:5], v[188:191], v[220:223], 0
	v_mfma_f32_16x16x32_bf16 v[58:61], v[184:187], v[200:203], v[58:61]
	v_mfma_f32_16x16x32_bf16 v[50:53], v[192:195], v[200:203], v[50:53]
	v_mfma_f32_16x16x32_bf16 v[42:45], v[184:187], v[208:211], v[42:45]
	v_mfma_f32_16x16x32_bf16 v[34:37], v[192:195], v[208:211], v[34:37]
	v_mfma_f32_16x16x32_bf16 v[26:29], v[184:187], v[216:219], v[26:29]
	v_mfma_f32_16x16x32_bf16 v[18:21], v[192:195], v[216:219], v[18:21]
	v_mfma_f32_16x16x32_bf16 v[10:13], v[184:187], v[224:227], v[10:13]
	v_mfma_f32_16x16x32_bf16 v[2:5], v[192:195], v[224:227], v[2:5]
	s_barrier
	s_setprio 0
	s_add_u32 s98, s94, 0x40000
	s_addc_u32 s99, s95, 0
	s_add_i32 s5, 0, 0x18000
	s_add_i32 s45, 0, 0x1c000
	s_mov_b32 m0, s57
	ds_read_b128 v[164:167], v232
	global_load_lds_dwordx4 v130, s[98:99]
	s_mov_b32 m0, s58
	ds_read_b128 v[168:171], v232 offset:1024
	global_load_lds_dwordx4 v134, s[98:99]
	ds_read_b128 v[172:175], v232 offset:2048
	ds_read_b128 v[176:179], v232 offset:3072
	ds_read_b128 v[180:183], v233
	ds_read_b128 v[184:187], v233 offset:1024
	ds_read_b128 v[188:191], v233 offset:2048
	ds_read_b128 v[192:195], v233 offset:3072
	ds_read_b128 v[196:199], v160 offset:32768
	ds_read_b128 v[200:203], v160 offset:33792
	ds_read_b128 v[204:207], v160 offset:34816
	ds_read_b128 v[208:211], v160 offset:35840
	ds_read_b128 v[212:215], v160 offset:36864
	ds_read_b128 v[216:219], v160 offset:37888
	ds_read_b128 v[220:223], v160 offset:38912
	ds_read_b128 v[224:227], v160 offset:39936
	s_waitcnt vmcnt(8)
	s_waitcnt lgkmcnt(0)
	s_setprio 1
	s_barrier
	v_mfma_f32_16x16x32_bf16 v[122:125], v[164:167], v[196:199], v[122:125]
	v_mfma_f32_16x16x32_bf16 v[118:121], v[172:175], v[196:199], v[118:121]
	v_mfma_f32_16x16x32_bf16 v[110:113], v[164:167], v[204:207], v[110:113]
	v_mfma_f32_16x16x32_bf16 v[102:105], v[172:175], v[204:207], v[102:105]
	v_mfma_f32_16x16x32_bf16 v[94:97], v[164:167], v[212:215], v[94:97]
	v_mfma_f32_16x16x32_bf16 v[86:89], v[172:175], v[212:215], v[86:89]
	v_mfma_f32_16x16x32_bf16 v[78:81], v[164:167], v[220:223], v[78:81]
	v_mfma_f32_16x16x32_bf16 v[70:73], v[172:175], v[220:223], v[70:73]
	v_mfma_f32_16x16x32_bf16 v[122:125], v[168:171], v[200:203], v[122:125]
	v_mfma_f32_16x16x32_bf16 v[118:121], v[176:179], v[200:203], v[118:121]
	v_mfma_f32_16x16x32_bf16 v[110:113], v[168:171], v[208:211], v[110:113]
	v_mfma_f32_16x16x32_bf16 v[102:105], v[176:179], v[208:211], v[102:105]
	v_mfma_f32_16x16x32_bf16 v[94:97], v[168:171], v[216:219], v[94:97]
	v_mfma_f32_16x16x32_bf16 v[86:89], v[176:179], v[216:219], v[86:89]
	v_mfma_f32_16x16x32_bf16 v[78:81], v[168:171], v[224:227], v[78:81]
	v_mfma_f32_16x16x32_bf16 v[70:73], v[176:179], v[224:227], v[70:73]
	v_mfma_f32_16x16x32_bf16 v[126:129], v[180:183], v[196:199], v[126:129]
	v_mfma_f32_16x16x32_bf16 v[114:117], v[188:191], v[196:199], v[114:117]
	v_mfma_f32_16x16x32_bf16 v[106:109], v[180:183], v[204:207], v[106:109]
	v_mfma_f32_16x16x32_bf16 v[98:101], v[188:191], v[204:207], v[98:101]
	v_mfma_f32_16x16x32_bf16 v[90:93], v[180:183], v[212:215], v[90:93]
	v_mfma_f32_16x16x32_bf16 v[82:85], v[188:191], v[212:215], v[82:85]
	v_mfma_f32_16x16x32_bf16 v[74:77], v[180:183], v[220:223], v[74:77]
	v_mfma_f32_16x16x32_bf16 v[66:69], v[188:191], v[220:223], v[66:69]
	v_mfma_f32_16x16x32_bf16 v[126:129], v[184:187], v[200:203], v[126:129]
	v_mfma_f32_16x16x32_bf16 v[114:117], v[192:195], v[200:203], v[114:117]
	v_mfma_f32_16x16x32_bf16 v[106:109], v[184:187], v[208:211], v[106:109]
	v_mfma_f32_16x16x32_bf16 v[98:101], v[192:195], v[208:211], v[98:101]
	v_mfma_f32_16x16x32_bf16 v[90:93], v[184:187], v[216:219], v[90:93]
	v_mfma_f32_16x16x32_bf16 v[82:85], v[192:195], v[216:219], v[82:85]
	v_mfma_f32_16x16x32_bf16 v[74:77], v[184:187], v[224:227], v[74:77]
	v_mfma_f32_16x16x32_bf16 v[66:69], v[192:195], v[224:227], v[66:69]
	s_barrier
	s_setprio 0
	s_add_u32 s96, s96, 0x80
	s_addc_u32 s97, s97, 0
	s_add_u32 s98, s96, 0x40000
	s_addc_u32 s99, s97, 0
	s_add_u32 s94, s94, 0x80
	s_addc_u32 s95, s95, 0
	s_add_i32 s5, s5, s23
	s_mov_b32 m0, s5
	ds_read_b128 v[196:199], v160 offset:49152
	global_load_lds_dwordx4 v132, s[96:97]
	s_add_i32 m0, s5, 0x2000
	s_add_i32 s5, s45, s23
	global_load_lds_dwordx4 v136, s[96:97]
	s_mov_b32 m0, s5
	ds_read_b128 v[200:203], v160 offset:50176
	global_load_lds_dwordx4 v132, s[98:99]
	s_add_i32 m0, s5, 0x2000
	ds_read_b128 v[204:207], v160 offset:51200
	global_load_lds_dwordx4 v136, s[98:99]
	s_mov_b32 m0, s64
	ds_read_b128 v[208:211], v160 offset:52224
	global_load_lds_dwordx4 v130, s[94:95]
	s_mov_b32 m0, s65
	ds_read_b128 v[212:215], v160 offset:53248
	global_load_lds_dwordx4 v134, s[94:95]
	ds_read_b128 v[216:219], v160 offset:54272
	ds_read_b128 v[220:223], v160 offset:55296
	ds_read_b128 v[224:227], v160 offset:56320
	s_waitcnt vmcnt(8)
	s_waitcnt lgkmcnt(0)
	s_setprio 1
	s_barrier
	v_mfma_f32_16x16x32_bf16 v[62:65], v[164:167], v[196:199], v[62:65]
	v_mfma_f32_16x16x32_bf16 v[54:57], v[172:175], v[196:199], v[54:57]
	v_mfma_f32_16x16x32_bf16 v[46:49], v[164:167], v[204:207], v[46:49]
	v_mfma_f32_16x16x32_bf16 v[38:41], v[172:175], v[204:207], v[38:41]
	v_mfma_f32_16x16x32_bf16 v[30:33], v[164:167], v[212:215], v[30:33]
	v_mfma_f32_16x16x32_bf16 v[22:25], v[172:175], v[212:215], v[22:25]
	v_mfma_f32_16x16x32_bf16 v[14:17], v[164:167], v[220:223], v[14:17]
	v_mfma_f32_16x16x32_bf16 v[6:9], v[172:175], v[220:223], v[6:9]
	v_mfma_f32_16x16x32_bf16 v[62:65], v[168:171], v[200:203], v[62:65]
	v_mfma_f32_16x16x32_bf16 v[54:57], v[176:179], v[200:203], v[54:57]
	v_mfma_f32_16x16x32_bf16 v[46:49], v[168:171], v[208:211], v[46:49]
	v_mfma_f32_16x16x32_bf16 v[38:41], v[176:179], v[208:211], v[38:41]
	v_mfma_f32_16x16x32_bf16 v[30:33], v[168:171], v[216:219], v[30:33]
	v_mfma_f32_16x16x32_bf16 v[22:25], v[176:179], v[216:219], v[22:25]
	v_mfma_f32_16x16x32_bf16 v[14:17], v[168:171], v[224:227], v[14:17]
	v_mfma_f32_16x16x32_bf16 v[6:9], v[176:179], v[224:227], v[6:9]
	v_mfma_f32_16x16x32_bf16 v[58:61], v[180:183], v[196:199], v[58:61]
	v_mfma_f32_16x16x32_bf16 v[50:53], v[188:191], v[196:199], v[50:53]
	v_mfma_f32_16x16x32_bf16 v[42:45], v[180:183], v[204:207], v[42:45]
	v_mfma_f32_16x16x32_bf16 v[34:37], v[188:191], v[204:207], v[34:37]
	v_mfma_f32_16x16x32_bf16 v[26:29], v[180:183], v[212:215], v[26:29]
	v_mfma_f32_16x16x32_bf16 v[18:21], v[188:191], v[212:215], v[18:21]
	v_mfma_f32_16x16x32_bf16 v[10:13], v[180:183], v[220:223], v[10:13]
	v_mfma_f32_16x16x32_bf16 v[2:5], v[188:191], v[220:223], v[2:5]
	v_mfma_f32_16x16x32_bf16 v[58:61], v[184:187], v[200:203], v[58:61]
	v_mfma_f32_16x16x32_bf16 v[50:53], v[192:195], v[200:203], v[50:53]
	v_mfma_f32_16x16x32_bf16 v[42:45], v[184:187], v[208:211], v[42:45]
	v_mfma_f32_16x16x32_bf16 v[34:37], v[192:195], v[208:211], v[34:37]
	v_mfma_f32_16x16x32_bf16 v[26:29], v[184:187], v[216:219], v[26:29]
	v_mfma_f32_16x16x32_bf16 v[18:21], v[192:195], v[216:219], v[18:21]
	v_mfma_f32_16x16x32_bf16 v[10:13], v[184:187], v[224:227], v[10:13]
	v_mfma_f32_16x16x32_bf16 v[2:5], v[192:195], v[224:227], v[2:5]
	s_barrier
	s_setprio 0
	s_mov_b32 s5, s29
	s_add_u32 s88, s88, 0x100
	s_addc_u32 s89, s89, 0
	s_add_u32 s86, s86, 0x100
	s_addc_u32 s87, s87, 0
	s_cmp_ge_i32 s29, s101
	s_cbranch_scc1 .Lmy_kexit_9
.LBB0_1763:
	s_add_u32 s98, s86, 0xfffc0080
	s_addc_u32 s99, s87, -1
	s_cmp_eq_u32 s5, s100
	s_cselect_b64 s[94:95], s[90:91], s[98:99]
	s_cselect_b64 s[96:97], s[92:93], s[88:89]
	s_add_i32 s29, s5, 2
	s_add_i32 m0, s47, 0xc000
	ds_read_b128 v[164:167], v230
	global_load_lds_dwordx4 v144, s[86:87]
	s_add_i32 m0, s47, 0xe000
	ds_read_b128 v[168:171], v230 offset:1024
	global_load_lds_dwordx4 v142, s[86:87]
	ds_read_b128 v[172:175], v230 offset:2048
	ds_read_b128 v[176:179], v230 offset:3072
	ds_read_b128 v[180:183], v231
	ds_read_b128 v[184:187], v231 offset:1024
	ds_read_b128 v[188:191], v231 offset:2048
	ds_read_b128 v[192:195], v231 offset:3072
	ds_read_b128 v[196:199], v160
	ds_read_b128 v[200:203], v160 offset:1024
	ds_read_b128 v[204:207], v160 offset:2048
	ds_read_b128 v[208:211], v160 offset:3072
	ds_read_b128 v[212:215], v160 offset:4096
	ds_read_b128 v[216:219], v160 offset:5120
	ds_read_b128 v[220:223], v160 offset:6144
	ds_read_b128 v[224:227], v160 offset:7168
	s_waitcnt vmcnt(8)
	s_waitcnt lgkmcnt(0)
	s_setprio 1
	s_barrier
	v_mfma_f32_16x16x32_bf16 v[122:125], v[164:167], v[196:199], v[122:125]
	v_mfma_f32_16x16x32_bf16 v[118:121], v[172:175], v[196:199], v[118:121]
	v_mfma_f32_16x16x32_bf16 v[110:113], v[164:167], v[204:207], v[110:113]
	v_mfma_f32_16x16x32_bf16 v[102:105], v[172:175], v[204:207], v[102:105]
	v_mfma_f32_16x16x32_bf16 v[94:97], v[164:167], v[212:215], v[94:97]
	v_mfma_f32_16x16x32_bf16 v[86:89], v[172:175], v[212:215], v[86:89]
	v_mfma_f32_16x16x32_bf16 v[78:81], v[164:167], v[220:223], v[78:81]
	v_mfma_f32_16x16x32_bf16 v[70:73], v[172:175], v[220:223], v[70:73]
	v_mfma_f32_16x16x32_bf16 v[122:125], v[168:171], v[200:203], v[122:125]
	v_mfma_f32_16x16x32_bf16 v[118:121], v[176:179], v[200:203], v[118:121]
	v_mfma_f32_16x16x32_bf16 v[110:113], v[168:171], v[208:211], v[110:113]
	v_mfma_f32_16x16x32_bf16 v[102:105], v[176:179], v[208:211], v[102:105]
	v_mfma_f32_16x16x32_bf16 v[94:97], v[168:171], v[216:219], v[94:97]
	v_mfma_f32_16x16x32_bf16 v[86:89], v[176:179], v[216:219], v[86:89]
	v_mfma_f32_16x16x32_bf16 v[78:81], v[168:171], v[224:227], v[78:81]
	v_mfma_f32_16x16x32_bf16 v[70:73], v[176:179], v[224:227], v[70:73]
	v_mfma_f32_16x16x32_bf16 v[126:129], v[180:183], v[196:199], v[126:129]
	v_mfma_f32_16x16x32_bf16 v[114:117], v[188:191], v[196:199], v[114:117]
	v_mfma_f32_16x16x32_bf16 v[106:109], v[180:183], v[204:207], v[106:109]
	v_mfma_f32_16x16x32_bf16 v[98:101], v[188:191], v[204:207], v[98:101]
	v_mfma_f32_16x16x32_bf16 v[90:93], v[180:183], v[212:215], v[90:93]
	v_mfma_f32_16x16x32_bf16 v[82:85], v[188:191], v[212:215], v[82:85]
	v_mfma_f32_16x16x32_bf16 v[74:77], v[180:183], v[220:223], v[74:77]
	v_mfma_f32_16x16x32_bf16 v[66:69], v[188:191], v[220:223], v[66:69]
	v_mfma_f32_16x16x32_bf16 v[126:129], v[184:187], v[200:203], v[126:129]
	v_mfma_f32_16x16x32_bf16 v[114:117], v[192:195], v[200:203], v[114:117]
	v_mfma_f32_16x16x32_bf16 v[106:109], v[184:187], v[208:211], v[106:109]
	v_mfma_f32_16x16x32_bf16 v[98:101], v[192:195], v[208:211], v[98:101]
	v_mfma_f32_16x16x32_bf16 v[90:93], v[184:187], v[216:219], v[90:93]
	v_mfma_f32_16x16x32_bf16 v[82:85], v[192:195], v[216:219], v[82:85]
	v_mfma_f32_16x16x32_bf16 v[74:77], v[184:187], v[224:227], v[74:77]
	v_mfma_f32_16x16x32_bf16 v[66:69], v[192:195], v[224:227], v[66:69]
	s_barrier
	s_setprio 0
	s_add_u32 s98, s96, 0x40000
	s_addc_u32 s99, s97, 0
	s_add_i32 s5, s74, s23
	s_mov_b32 m0, s5
	ds_read_b128 v[196:199], v160 offset:16384
	global_load_lds_dwordx4 v132, s[96:97]
	s_add_i32 m0, s5, 0x2000
	s_add_i32 s5, s75, s23
	global_load_lds_dwordx4 v136, s[96:97]
	s_mov_b32 m0, s5
	ds_read_b128 v[200:203], v160 offset:17408
	global_load_lds_dwordx4 v132, s[98:99]
	s_add_i32 m0, s5, 0x2000
	ds_read_b128 v[204:207], v160 offset:18432
	global_load_lds_dwordx4 v136, s[98:99]
	s_mov_b32 m0, s47
	ds_read_b128 v[208:211], v160 offset:19456
	global_load_lds_dwordx4 v130, s[94:95]
	s_mov_b32 m0, s56
	ds_read_b128 v[212:215], v160 offset:20480
	global_load_lds_dwordx4 v134, s[94:95]
	ds_read_b128 v[216:219], v160 offset:21504
	ds_read_b128 v[220:223], v160 offset:22528
	ds_read_b128 v[224:227], v160 offset:23552
	s_waitcnt vmcnt(8)
	s_waitcnt lgkmcnt(0)
	s_setprio 1
	s_barrier
	v_mfma_f32_16x16x32_bf16 v[62:65], v[164:167], v[196:199], v[62:65]
	v_mfma_f32_16x16x32_bf16 v[54:57], v[172:175], v[196:199], v[54:57]
	v_mfma_f32_16x16x32_bf16 v[46:49], v[164:167], v[204:207], v[46:49]
	v_mfma_f32_16x16x32_bf16 v[38:41], v[172:175], v[204:207], v[38:41]
	v_mfma_f32_16x16x32_bf16 v[30:33], v[164:167], v[212:215], v[30:33]
	v_mfma_f32_16x16x32_bf16 v[22:25], v[172:175], v[212:215], v[22:25]
	v_mfma_f32_16x16x32_bf16 v[14:17], v[164:167], v[220:223], v[14:17]
	v_mfma_f32_16x16x32_bf16 v[6:9], v[172:175], v[220:223], v[6:9]
	v_mfma_f32_16x16x32_bf16 v[62:65], v[168:171], v[200:203], v[62:65]
	v_mfma_f32_16x16x32_bf16 v[54:57], v[176:179], v[200:203], v[54:57]
	v_mfma_f32_16x16x32_bf16 v[46:49], v[168:171], v[208:211], v[46:49]
	v_mfma_f32_16x16x32_bf16 v[38:41], v[176:179], v[208:211], v[38:41]
	v_mfma_f32_16x16x32_bf16 v[30:33], v[168:171], v[216:219], v[30:33]
	v_mfma_f32_16x16x32_bf16 v[22:25], v[176:179], v[216:219], v[22:25]
	v_mfma_f32_16x16x32_bf16 v[14:17], v[168:171], v[224:227], v[14:17]
	v_mfma_f32_16x16x32_bf16 v[6:9], v[176:179], v[224:227], v[6:9]
	v_mfma_f32_16x16x32_bf16 v[58:61], v[180:183], v[196:199], v[58:61]
	v_mfma_f32_16x16x32_bf16 v[50:53], v[188:191], v[196:199], v[50:53]
	v_mfma_f32_16x16x32_bf16 v[42:45], v[180:183], v[204:207], v[42:45]
	v_mfma_f32_16x16x32_bf16 v[34:37], v[188:191], v[204:207], v[34:37]
	v_mfma_f32_16x16x32_bf16 v[26:29], v[180:183], v[212:215], v[26:29]
	v_mfma_f32_16x16x32_bf16 v[18:21], v[188:191], v[212:215], v[18:21]
	v_mfma_f32_16x16x32_bf16 v[10:13], v[180:183], v[220:223], v[10:13]
	v_mfma_f32_16x16x32_bf16 v[2:5], v[188:191], v[220:223], v[2:5]
	v_mfma_f32_16x16x32_bf16 v[58:61], v[184:187], v[200:203], v[58:61]
	v_mfma_f32_16x16x32_bf16 v[50:53], v[192:195], v[200:203], v[50:53]
	v_mfma_f32_16x16x32_bf16 v[42:45], v[184:187], v[208:211], v[42:45]
	v_mfma_f32_16x16x32_bf16 v[34:37], v[192:195], v[208:211], v[34:37]
	v_mfma_f32_16x16x32_bf16 v[26:29], v[184:187], v[216:219], v[26:29]
	v_mfma_f32_16x16x32_bf16 v[18:21], v[192:195], v[216:219], v[18:21]
	v_mfma_f32_16x16x32_bf16 v[10:13], v[184:187], v[224:227], v[10:13]
	v_mfma_f32_16x16x32_bf16 v[2:5], v[192:195], v[224:227], v[2:5]
	s_barrier
	s_setprio 0
	s_add_u32 s98, s94, 0x40000
	s_addc_u32 s99, s95, 0
	s_add_i32 s5, 0, 0x18000
	s_add_i32 s45, 0, 0x1c000
	s_mov_b32 m0, s57
	ds_read_b128 v[164:167], v232
	global_load_lds_dwordx4 v130, s[98:99]
	s_mov_b32 m0, s58
	ds_read_b128 v[168:171], v232 offset:1024
	global_load_lds_dwordx4 v134, s[98:99]
	ds_read_b128 v[172:175], v232 offset:2048
	ds_read_b128 v[176:179], v232 offset:3072
	ds_read_b128 v[180:183], v233
	ds_read_b128 v[184:187], v233 offset:1024
	ds_read_b128 v[188:191], v233 offset:2048
	ds_read_b128 v[192:195], v233 offset:3072
	ds_read_b128 v[196:199], v160 offset:32768
	ds_read_b128 v[200:203], v160 offset:33792
	ds_read_b128 v[204:207], v160 offset:34816
	ds_read_b128 v[208:211], v160 offset:35840
	ds_read_b128 v[212:215], v160 offset:36864
	ds_read_b128 v[216:219], v160 offset:37888
	ds_read_b128 v[220:223], v160 offset:38912
	ds_read_b128 v[224:227], v160 offset:39936
	s_waitcnt vmcnt(8)
	s_waitcnt lgkmcnt(0)
	s_setprio 1
	s_barrier
	v_mfma_f32_16x16x32_bf16 v[122:125], v[164:167], v[196:199], v[122:125]
	v_mfma_f32_16x16x32_bf16 v[118:121], v[172:175], v[196:199], v[118:121]
	v_mfma_f32_16x16x32_bf16 v[110:113], v[164:167], v[204:207], v[110:113]
	v_mfma_f32_16x16x32_bf16 v[102:105], v[172:175], v[204:207], v[102:105]
	v_mfma_f32_16x16x32_bf16 v[94:97], v[164:167], v[212:215], v[94:97]
	v_mfma_f32_16x16x32_bf16 v[86:89], v[172:175], v[212:215], v[86:89]
	v_mfma_f32_16x16x32_bf16 v[78:81], v[164:167], v[220:223], v[78:81]
	v_mfma_f32_16x16x32_bf16 v[70:73], v[172:175], v[220:223], v[70:73]
	v_mfma_f32_16x16x32_bf16 v[122:125], v[168:171], v[200:203], v[122:125]
	v_mfma_f32_16x16x32_bf16 v[118:121], v[176:179], v[200:203], v[118:121]
	v_mfma_f32_16x16x32_bf16 v[110:113], v[168:171], v[208:211], v[110:113]
	v_mfma_f32_16x16x32_bf16 v[102:105], v[176:179], v[208:211], v[102:105]
	v_mfma_f32_16x16x32_bf16 v[94:97], v[168:171], v[216:219], v[94:97]
	v_mfma_f32_16x16x32_bf16 v[86:89], v[176:179], v[216:219], v[86:89]
	v_mfma_f32_16x16x32_bf16 v[78:81], v[168:171], v[224:227], v[78:81]
	v_mfma_f32_16x16x32_bf16 v[70:73], v[176:179], v[224:227], v[70:73]
	v_mfma_f32_16x16x32_bf16 v[126:129], v[180:183], v[196:199], v[126:129]
	v_mfma_f32_16x16x32_bf16 v[114:117], v[188:191], v[196:199], v[114:117]
	v_mfma_f32_16x16x32_bf16 v[106:109], v[180:183], v[204:207], v[106:109]
	v_mfma_f32_16x16x32_bf16 v[98:101], v[188:191], v[204:207], v[98:101]
	v_mfma_f32_16x16x32_bf16 v[90:93], v[180:183], v[212:215], v[90:93]
	v_mfma_f32_16x16x32_bf16 v[82:85], v[188:191], v[212:215], v[82:85]
	v_mfma_f32_16x16x32_bf16 v[74:77], v[180:183], v[220:223], v[74:77]
	v_mfma_f32_16x16x32_bf16 v[66:69], v[188:191], v[220:223], v[66:69]
	v_mfma_f32_16x16x32_bf16 v[126:129], v[184:187], v[200:203], v[126:129]
	v_mfma_f32_16x16x32_bf16 v[114:117], v[192:195], v[200:203], v[114:117]
	v_mfma_f32_16x16x32_bf16 v[106:109], v[184:187], v[208:211], v[106:109]
	v_mfma_f32_16x16x32_bf16 v[98:101], v[192:195], v[208:211], v[98:101]
	v_mfma_f32_16x16x32_bf16 v[90:93], v[184:187], v[216:219], v[90:93]
	v_mfma_f32_16x16x32_bf16 v[82:85], v[192:195], v[216:219], v[82:85]
	v_mfma_f32_16x16x32_bf16 v[74:77], v[184:187], v[224:227], v[74:77]
	v_mfma_f32_16x16x32_bf16 v[66:69], v[192:195], v[224:227], v[66:69]
	s_barrier
	s_setprio 0
	s_add_u32 s96, s96, 0x80
	s_addc_u32 s97, s97, 0
	s_add_u32 s98, s96, 0x40000
	s_addc_u32 s99, s97, 0
	s_add_u32 s94, s94, 0x80
	s_addc_u32 s95, s95, 0
	s_add_i32 s5, s5, s23
	s_mov_b32 m0, s5
	ds_read_b128 v[196:199], v160 offset:49152
	global_load_lds_dwordx4 v132, s[96:97]
	s_add_i32 m0, s5, 0x2000
	s_add_i32 s5, s45, s23
	global_load_lds_dwordx4 v136, s[96:97]
	s_mov_b32 m0, s5
	ds_read_b128 v[200:203], v160 offset:50176
	global_load_lds_dwordx4 v132, s[98:99]
	s_add_i32 m0, s5, 0x2000
	ds_read_b128 v[204:207], v160 offset:51200
	global_load_lds_dwordx4 v136, s[98:99]
	s_mov_b32 m0, s64
	ds_read_b128 v[208:211], v160 offset:52224
	global_load_lds_dwordx4 v130, s[94:95]
	s_mov_b32 m0, s65
	ds_read_b128 v[212:215], v160 offset:53248
	global_load_lds_dwordx4 v134, s[94:95]
	ds_read_b128 v[216:219], v160 offset:54272
	ds_read_b128 v[220:223], v160 offset:55296
	ds_read_b128 v[224:227], v160 offset:56320
	s_waitcnt vmcnt(8)
	s_waitcnt lgkmcnt(0)
	s_setprio 1
	s_barrier
	v_mfma_f32_16x16x32_bf16 v[62:65], v[164:167], v[196:199], v[62:65]
	v_mfma_f32_16x16x32_bf16 v[54:57], v[172:175], v[196:199], v[54:57]
	v_mfma_f32_16x16x32_bf16 v[46:49], v[164:167], v[204:207], v[46:49]
	v_mfma_f32_16x16x32_bf16 v[38:41], v[172:175], v[204:207], v[38:41]
	v_mfma_f32_16x16x32_bf16 v[30:33], v[164:167], v[212:215], v[30:33]
	v_mfma_f32_16x16x32_bf16 v[22:25], v[172:175], v[212:215], v[22:25]
	v_mfma_f32_16x16x32_bf16 v[14:17], v[164:167], v[220:223], v[14:17]
	v_mfma_f32_16x16x32_bf16 v[6:9], v[172:175], v[220:223], v[6:9]
	v_mfma_f32_16x16x32_bf16 v[62:65], v[168:171], v[200:203], v[62:65]
	v_mfma_f32_16x16x32_bf16 v[54:57], v[176:179], v[200:203], v[54:57]
	v_mfma_f32_16x16x32_bf16 v[46:49], v[168:171], v[208:211], v[46:49]
	v_mfma_f32_16x16x32_bf16 v[38:41], v[176:179], v[208:211], v[38:41]
	v_mfma_f32_16x16x32_bf16 v[30:33], v[168:171], v[216:219], v[30:33]
	v_mfma_f32_16x16x32_bf16 v[22:25], v[176:179], v[216:219], v[22:25]
	v_mfma_f32_16x16x32_bf16 v[14:17], v[168:171], v[224:227], v[14:17]
	v_mfma_f32_16x16x32_bf16 v[6:9], v[176:179], v[224:227], v[6:9]
	v_mfma_f32_16x16x32_bf16 v[58:61], v[180:183], v[196:199], v[58:61]
	v_mfma_f32_16x16x32_bf16 v[50:53], v[188:191], v[196:199], v[50:53]
	v_mfma_f32_16x16x32_bf16 v[42:45], v[180:183], v[204:207], v[42:45]
	v_mfma_f32_16x16x32_bf16 v[34:37], v[188:191], v[204:207], v[34:37]
	v_mfma_f32_16x16x32_bf16 v[26:29], v[180:183], v[212:215], v[26:29]
	v_mfma_f32_16x16x32_bf16 v[18:21], v[188:191], v[212:215], v[18:21]
	v_mfma_f32_16x16x32_bf16 v[10:13], v[180:183], v[220:223], v[10:13]
	v_mfma_f32_16x16x32_bf16 v[2:5], v[188:191], v[220:223], v[2:5]
	v_mfma_f32_16x16x32_bf16 v[58:61], v[184:187], v[200:203], v[58:61]
	v_mfma_f32_16x16x32_bf16 v[50:53], v[192:195], v[200:203], v[50:53]
	v_mfma_f32_16x16x32_bf16 v[42:45], v[184:187], v[208:211], v[42:45]
	v_mfma_f32_16x16x32_bf16 v[34:37], v[192:195], v[208:211], v[34:37]
	v_mfma_f32_16x16x32_bf16 v[26:29], v[184:187], v[216:219], v[26:29]
	v_mfma_f32_16x16x32_bf16 v[18:21], v[192:195], v[216:219], v[18:21]
	v_mfma_f32_16x16x32_bf16 v[10:13], v[184:187], v[224:227], v[10:13]
	v_mfma_f32_16x16x32_bf16 v[2:5], v[192:195], v[224:227], v[2:5]
	s_barrier
	s_setprio 0
	s_mov_b32 s5, s29
	s_add_u32 s88, s88, 0x100
	s_addc_u32 s89, s89, 0
	s_add_u32 s86, s86, 0x100
	s_addc_u32 s87, s87, 0
	s_cmp_ge_i32 s29, s101
	s_cbranch_scc0 .LBB0_1763

.Lmy_nb_10:
	s_nop 0
	v_readfirstlane_b32 s86, v152
	v_readfirstlane_b32 s87, v153
	v_readfirstlane_b32 s88, v150
	v_readfirstlane_b32 s89, v151
	v_readfirstlane_b32 s90, v146
	v_readfirstlane_b32 s91, v147
	v_readfirstlane_b32 s92, v148
	v_readfirstlane_b32 s93, v149
	v_readfirstlane_b32 s100, v154
	v_readfirstlane_b32 s101, v138
	v_add_u32_e32 v230, s72, v141
	v_add_u32_e32 v231, s73, v141
	v_add_u32_e32 v232, 0x18000, v141
	v_add_u32_e32 v233, 0x1c000, v141
	s_add_u32 s98, s86, 0xfffc0080
	s_addc_u32 s99, s87, -1
	s_cmp_eq_u32 s5, s100
	s_cselect_b64 s[94:95], s[90:91], s[98:99]
	s_cselect_b64 s[96:97], s[92:93], s[88:89]
	s_add_i32 s45, s5, 2
	s_mov_b32 m0, s74
	ds_read_b128 v[164:167], v230
	global_load_lds_dwordx4 v144, s[86:87]
	s_mov_b32 m0, s75
	ds_read_b128 v[168:171], v230 offset:1024
	global_load_lds_dwordx4 v142, s[86:87]
	ds_read_b128 v[172:175], v230 offset:2048
	ds_read_b128 v[176:179], v230 offset:3072
	ds_read_b128 v[180:183], v231
	ds_read_b128 v[184:187], v231 offset:1024
	ds_read_b128 v[188:191], v231 offset:2048
	ds_read_b128 v[192:195], v231 offset:3072
	ds_read_b128 v[196:199], v160
	ds_read_b128 v[200:203], v160 offset:1024
	ds_read_b128 v[204:207], v160 offset:2048
	ds_read_b128 v[208:211], v160 offset:3072
	ds_read_b128 v[212:215], v160 offset:4096
	ds_read_b128 v[216:219], v160 offset:5120
	ds_read_b128 v[220:223], v160 offset:6144
	ds_read_b128 v[224:227], v160 offset:7168
	s_waitcnt vmcnt(8)
	s_waitcnt lgkmcnt(0)
	s_setprio 1
	s_barrier
	v_mfma_f32_16x16x32_bf16 v[122:125], v[164:167], v[196:199], 0
	v_mfma_f32_16x16x32_bf16 v[118:121], v[172:175], v[196:199], 0
	v_mfma_f32_16x16x32_bf16 v[110:113], v[164:167], v[204:207], 0
	v_mfma_f32_16x16x32_bf16 v[102:105], v[172:175], v[204:207], 0
	v_mfma_f32_16x16x32_bf16 v[94:97], v[164:167], v[212:215], 0
	v_mfma_f32_16x16x32_bf16 v[86:89], v[172:175], v[212:215], 0
	v_mfma_f32_16x16x32_bf16 v[78:81], v[164:167], v[220:223], 0
	v_mfma_f32_16x16x32_bf16 v[70:73], v[172:175], v[220:223], 0
	v_mfma_f32_16x16x32_bf16 v[122:125], v[168:171], v[200:203], v[122:125]
	v_mfma_f32_16x16x32_bf16 v[118:121], v[176:179], v[200:203], v[118:121]
	v_mfma_f32_16x16x32_bf16 v[110:113], v[168:171], v[208:211], v[110:113]
	v_mfma_f32_16x16x32_bf16 v[102:105], v[176:179], v[208:211], v[102:105]
	v_mfma_f32_16x16x32_bf16 v[94:97], v[168:171], v[216:219], v[94:97]
	v_mfma_f32_16x16x32_bf16 v[86:89], v[176:179], v[216:219], v[86:89]
	v_mfma_f32_16x16x32_bf16 v[78:81], v[168:171], v[224:227], v[78:81]
	v_mfma_f32_16x16x32_bf16 v[70:73], v[176:179], v[224:227], v[70:73]
	v_mfma_f32_16x16x32_bf16 v[126:129], v[180:183], v[196:199], 0
	v_mfma_f32_16x16x32_bf16 v[114:117], v[188:191], v[196:199], 0
	v_mfma_f32_16x16x32_bf16 v[106:109], v[180:183], v[204:207], 0
	v_mfma_f32_16x16x32_bf16 v[98:101], v[188:191], v[204:207], 0
	v_mfma_f32_16x16x32_bf16 v[90:93], v[180:183], v[212:215], 0
	v_mfma_f32_16x16x32_bf16 v[82:85], v[188:191], v[212:215], 0
	v_mfma_f32_16x16x32_bf16 v[74:77], v[180:183], v[220:223], 0
	v_mfma_f32_16x16x32_bf16 v[66:69], v[188:191], v[220:223], 0
	v_mfma_f32_16x16x32_bf16 v[126:129], v[184:187], v[200:203], v[126:129]
	v_mfma_f32_16x16x32_bf16 v[114:117], v[192:195], v[200:203], v[114:117]
	v_mfma_f32_16x16x32_bf16 v[106:109], v[184:187], v[208:211], v[106:109]
	v_mfma_f32_16x16x32_bf16 v[98:101], v[192:195], v[208:211], v[98:101]
	v_mfma_f32_16x16x32_bf16 v[90:93], v[184:187], v[216:219], v[90:93]
	v_mfma_f32_16x16x32_bf16 v[82:85], v[192:195], v[216:219], v[82:85]
	v_mfma_f32_16x16x32_bf16 v[74:77], v[184:187], v[224:227], v[74:77]
	v_mfma_f32_16x16x32_bf16 v[66:69], v[192:195], v[224:227], v[66:69]
	s_barrier
	s_setprio 0
	s_add_u32 s98, s96, 0x40000
	s_addc_u32 s99, s97, 0
	s_mov_b32 m0, s76
	ds_read_b128 v[196:199], v160 offset:16384
	global_load_lds_dwordx4 v132, s[96:97]
	s_mov_b32 m0, s77
	s_add_i32 s5, s73, s25
	global_load_lds_dwordx4 v136, s[96:97]
	s_mov_b32 m0, s5
	ds_read_b128 v[200:203], v160 offset:17408
	global_load_lds_dwordx4 v132, s[98:99]
	s_add_i32 m0, s5, 0x2000
	ds_read_b128 v[204:207], v160 offset:18432
	global_load_lds_dwordx4 v136, s[98:99]
	s_mov_b32 m0, s49
	ds_read_b128 v[208:211], v160 offset:19456
	global_load_lds_dwordx4 v130, s[94:95]
	s_mov_b32 m0, s58
	ds_read_b128 v[212:215], v160 offset:20480
	global_load_lds_dwordx4 v134, s[94:95]
	ds_read_b128 v[216:219], v160 offset:21504
	ds_read_b128 v[220:223], v160 offset:22528
	ds_read_b128 v[224:227], v160 offset:23552
	s_waitcnt vmcnt(8)
	s_waitcnt lgkmcnt(0)
	s_setprio 1
	s_barrier
	v_mfma_f32_16x16x32_bf16 v[62:65], v[164:167], v[196:199], 0
	v_mfma_f32_16x16x32_bf16 v[54:57], v[172:175], v[196:199], 0
	v_mfma_f32_16x16x32_bf16 v[46:49], v[164:167], v[204:207], 0
	v_mfma_f32_16x16x32_bf16 v[38:41], v[172:175], v[204:207], 0
	v_mfma_f32_16x16x32_bf16 v[30:33], v[164:167], v[212:215], 0
	v_mfma_f32_16x16x32_bf16 v[22:25], v[172:175], v[212:215], 0
	v_mfma_f32_16x16x32_bf16 v[14:17], v[164:167], v[220:223], 0
	v_mfma_f32_16x16x32_bf16 v[6:9], v[172:175], v[220:223], 0
	v_mfma_f32_16x16x32_bf16 v[62:65], v[168:171], v[200:203], v[62:65]
	v_mfma_f32_16x16x32_bf16 v[54:57], v[176:179], v[200:203], v[54:57]
	v_mfma_f32_16x16x32_bf16 v[46:49], v[168:171], v[208:211], v[46:49]
	v_mfma_f32_16x16x32_bf16 v[38:41], v[176:179], v[208:211], v[38:41]
	v_mfma_f32_16x16x32_bf16 v[30:33], v[168:171], v[216:219], v[30:33]
	v_mfma_f32_16x16x32_bf16 v[22:25], v[176:179], v[216:219], v[22:25]
	v_mfma_f32_16x16x32_bf16 v[14:17], v[168:171], v[224:227], v[14:17]
	v_mfma_f32_16x16x32_bf16 v[6:9], v[176:179], v[224:227], v[6:9]
	v_mfma_f32_16x16x32_bf16 v[58:61], v[180:183], v[196:199], 0
	v_mfma_f32_16x16x32_bf16 v[50:53], v[188:191], v[196:199], 0
	v_mfma_f32_16x16x32_bf16 v[42:45], v[180:183], v[204:207], 0
	v_mfma_f32_16x16x32_bf16 v[34:37], v[188:191], v[204:207], 0
	v_mfma_f32_16x16x32_bf16 v[26:29], v[180:183], v[212:215], 0
	v_mfma_f32_16x16x32_bf16 v[18:21], v[188:191], v[212:215], 0
	v_mfma_f32_16x16x32_bf16 v[10:13], v[180:183], v[220:223], 0
	v_mfma_f32_16x16x32_bf16 v[2:5], v[188:191], v[220:223], 0
	v_mfma_f32_16x16x32_bf16 v[58:61], v[184:187], v[200:203], v[58:61]
	v_mfma_f32_16x16x32_bf16 v[50:53], v[192:195], v[200:203], v[50:53]
	v_mfma_f32_16x16x32_bf16 v[42:45], v[184:187], v[208:211], v[42:45]
	v_mfma_f32_16x16x32_bf16 v[34:37], v[192:195], v[208:211], v[34:37]
	v_mfma_f32_16x16x32_bf16 v[26:29], v[184:187], v[216:219], v[26:29]
	v_mfma_f32_16x16x32_bf16 v[18:21], v[192:195], v[216:219], v[18:21]
	v_mfma_f32_16x16x32_bf16 v[10:13], v[184:187], v[224:227], v[10:13]
	v_mfma_f32_16x16x32_bf16 v[2:5], v[192:195], v[224:227], v[2:5]
	s_barrier
	s_setprio 0
	s_add_u32 s98, s94, 0x40000
	s_addc_u32 s99, s95, 0
	s_add_i32 s5, 0, 0x18000
	s_add_i32 s47, 0, 0x1c000
	s_mov_b32 m0, s59
	ds_read_b128 v[164:167], v232
	global_load_lds_dwordx4 v130, s[98:99]
	s_mov_b32 m0, s60
	ds_read_b128 v[168:171], v232 offset:1024
	global_load_lds_dwordx4 v134, s[98:99]
	ds_read_b128 v[172:175], v232 offset:2048
	ds_read_b128 v[176:179], v232 offset:3072
	ds_read_b128 v[180:183], v233
	ds_read_b128 v[184:187], v233 offset:1024
	ds_read_b128 v[188:191], v233 offset:2048
	ds_read_b128 v[192:195], v233 offset:3072
	ds_read_b128 v[196:199], v160 offset:32768
	ds_read_b128 v[200:203], v160 offset:33792
	ds_read_b128 v[204:207], v160 offset:34816
	ds_read_b128 v[208:211], v160 offset:35840
	ds_read_b128 v[212:215], v160 offset:36864
	ds_read_b128 v[216:219], v160 offset:37888
	ds_read_b128 v[220:223], v160 offset:38912
	ds_read_b128 v[224:227], v160 offset:39936
	s_waitcnt vmcnt(8)
	s_waitcnt lgkmcnt(0)
	s_setprio 1
	s_barrier
	v_mfma_f32_16x16x32_bf16 v[122:125], v[164:167], v[196:199], v[122:125]
	v_mfma_f32_16x16x32_bf16 v[118:121], v[172:175], v[196:199], v[118:121]
	v_mfma_f32_16x16x32_bf16 v[110:113], v[164:167], v[204:207], v[110:113]
	v_mfma_f32_16x16x32_bf16 v[102:105], v[172:175], v[204:207], v[102:105]
	v_mfma_f32_16x16x32_bf16 v[94:97], v[164:167], v[212:215], v[94:97]
	v_mfma_f32_16x16x32_bf16 v[86:89], v[172:175], v[212:215], v[86:89]
	v_mfma_f32_16x16x32_bf16 v[78:81], v[164:167], v[220:223], v[78:81]
	v_mfma_f32_16x16x32_bf16 v[70:73], v[172:175], v[220:223], v[70:73]
	v_mfma_f32_16x16x32_bf16 v[122:125], v[168:171], v[200:203], v[122:125]
	v_mfma_f32_16x16x32_bf16 v[118:121], v[176:179], v[200:203], v[118:121]
	v_mfma_f32_16x16x32_bf16 v[110:113], v[168:171], v[208:211], v[110:113]
	v_mfma_f32_16x16x32_bf16 v[102:105], v[176:179], v[208:211], v[102:105]
	v_mfma_f32_16x16x32_bf16 v[94:97], v[168:171], v[216:219], v[94:97]
	v_mfma_f32_16x16x32_bf16 v[86:89], v[176:179], v[216:219], v[86:89]
	v_mfma_f32_16x16x32_bf16 v[78:81], v[168:171], v[224:227], v[78:81]
	v_mfma_f32_16x16x32_bf16 v[70:73], v[176:179], v[224:227], v[70:73]
	v_mfma_f32_16x16x32_bf16 v[126:129], v[180:183], v[196:199], v[126:129]
	v_mfma_f32_16x16x32_bf16 v[114:117], v[188:191], v[196:199], v[114:117]
	v_mfma_f32_16x16x32_bf16 v[106:109], v[180:183], v[204:207], v[106:109]
	v_mfma_f32_16x16x32_bf16 v[98:101], v[188:191], v[204:207], v[98:101]
	v_mfma_f32_16x16x32_bf16 v[90:93], v[180:183], v[212:215], v[90:93]
	v_mfma_f32_16x16x32_bf16 v[82:85], v[188:191], v[212:215], v[82:85]
	v_mfma_f32_16x16x32_bf16 v[74:77], v[180:183], v[220:223], v[74:77]
	v_mfma_f32_16x16x32_bf16 v[66:69], v[188:191], v[220:223], v[66:69]
	v_mfma_f32_16x16x32_bf16 v[126:129], v[184:187], v[200:203], v[126:129]
	v_mfma_f32_16x16x32_bf16 v[114:117], v[192:195], v[200:203], v[114:117]
	v_mfma_f32_16x16x32_bf16 v[106:109], v[184:187], v[208:211], v[106:109]
	v_mfma_f32_16x16x32_bf16 v[98:101], v[192:195], v[208:211], v[98:101]
	v_mfma_f32_16x16x32_bf16 v[90:93], v[184:187], v[216:219], v[90:93]
	v_mfma_f32_16x16x32_bf16 v[82:85], v[192:195], v[216:219], v[82:85]
	v_mfma_f32_16x16x32_bf16 v[74:77], v[184:187], v[224:227], v[74:77]
	v_mfma_f32_16x16x32_bf16 v[66:69], v[192:195], v[224:227], v[66:69]
	s_barrier
	s_setprio 0
	s_add_u32 s96, s96, 0x80
	s_addc_u32 s97, s97, 0
	s_add_u32 s98, s96, 0x40000
	s_addc_u32 s99, s97, 0
	s_add_u32 s94, s94, 0x80
	s_addc_u32 s95, s95, 0
	s_add_i32 s5, s5, s25
	s_mov_b32 m0, s5
	ds_read_b128 v[196:199], v160 offset:49152
	global_load_lds_dwordx4 v132, s[96:97]
	s_add_i32 m0, s5, 0x2000
	s_add_i32 s5, s47, s25
	global_load_lds_dwordx4 v136, s[96:97]
	s_mov_b32 m0, s5
	ds_read_b128 v[200:203], v160 offset:50176
	global_load_lds_dwordx4 v132, s[98:99]
	s_add_i32 m0, s5, 0x2000
	ds_read_b128 v[204:207], v160 offset:51200
	global_load_lds_dwordx4 v136, s[98:99]
	s_mov_b32 m0, s61
	ds_read_b128 v[208:211], v160 offset:52224
	global_load_lds_dwordx4 v130, s[94:95]
	s_mov_b32 m0, s62
	ds_read_b128 v[212:215], v160 offset:53248
	global_load_lds_dwordx4 v134, s[94:95]
	ds_read_b128 v[216:219], v160 offset:54272
	ds_read_b128 v[220:223], v160 offset:55296
	ds_read_b128 v[224:227], v160 offset:56320
	s_waitcnt vmcnt(8)
	s_waitcnt lgkmcnt(0)
	s_setprio 1
	s_barrier
	v_mfma_f32_16x16x32_bf16 v[62:65], v[164:167], v[196:199], v[62:65]
	v_mfma_f32_16x16x32_bf16 v[54:57], v[172:175], v[196:199], v[54:57]
	v_mfma_f32_16x16x32_bf16 v[46:49], v[164:167], v[204:207], v[46:49]
	v_mfma_f32_16x16x32_bf16 v[38:41], v[172:175], v[204:207], v[38:41]
	v_mfma_f32_16x16x32_bf16 v[30:33], v[164:167], v[212:215], v[30:33]
	v_mfma_f32_16x16x32_bf16 v[22:25], v[172:175], v[212:215], v[22:25]
	v_mfma_f32_16x16x32_bf16 v[14:17], v[164:167], v[220:223], v[14:17]
	v_mfma_f32_16x16x32_bf16 v[6:9], v[172:175], v[220:223], v[6:9]
	v_mfma_f32_16x16x32_bf16 v[62:65], v[168:171], v[200:203], v[62:65]
	v_mfma_f32_16x16x32_bf16 v[54:57], v[176:179], v[200:203], v[54:57]
	v_mfma_f32_16x16x32_bf16 v[46:49], v[168:171], v[208:211], v[46:49]
	v_mfma_f32_16x16x32_bf16 v[38:41], v[176:179], v[208:211], v[38:41]
	v_mfma_f32_16x16x32_bf16 v[30:33], v[168:171], v[216:219], v[30:33]
	v_mfma_f32_16x16x32_bf16 v[22:25], v[176:179], v[216:219], v[22:25]
	v_mfma_f32_16x16x32_bf16 v[14:17], v[168:171], v[224:227], v[14:17]
	v_mfma_f32_16x16x32_bf16 v[6:9], v[176:179], v[224:227], v[6:9]
	v_mfma_f32_16x16x32_bf16 v[58:61], v[180:183], v[196:199], v[58:61]
	v_mfma_f32_16x16x32_bf16 v[50:53], v[188:191], v[196:199], v[50:53]
	v_mfma_f32_16x16x32_bf16 v[42:45], v[180:183], v[204:207], v[42:45]
	v_mfma_f32_16x16x32_bf16 v[34:37], v[188:191], v[204:207], v[34:37]
	v_mfma_f32_16x16x32_bf16 v[26:29], v[180:183], v[212:215], v[26:29]
	v_mfma_f32_16x16x32_bf16 v[18:21], v[188:191], v[212:215], v[18:21]
	v_mfma_f32_16x16x32_bf16 v[10:13], v[180:183], v[220:223], v[10:13]
	v_mfma_f32_16x16x32_bf16 v[2:5], v[188:191], v[220:223], v[2:5]
	v_mfma_f32_16x16x32_bf16 v[58:61], v[184:187], v[200:203], v[58:61]
	v_mfma_f32_16x16x32_bf16 v[50:53], v[192:195], v[200:203], v[50:53]
	v_mfma_f32_16x16x32_bf16 v[42:45], v[184:187], v[208:211], v[42:45]
	v_mfma_f32_16x16x32_bf16 v[34:37], v[192:195], v[208:211], v[34:37]
	v_mfma_f32_16x16x32_bf16 v[26:29], v[184:187], v[216:219], v[26:29]
	v_mfma_f32_16x16x32_bf16 v[18:21], v[192:195], v[216:219], v[18:21]
	v_mfma_f32_16x16x32_bf16 v[10:13], v[184:187], v[224:227], v[10:13]
	v_mfma_f32_16x16x32_bf16 v[2:5], v[192:195], v[224:227], v[2:5]
	s_barrier
	s_setprio 0
	s_mov_b32 s5, s45
	s_add_u32 s88, s88, 0x100
	s_addc_u32 s89, s89, 0
	s_add_u32 s86, s86, 0x100
	s_addc_u32 s87, s87, 0
	s_cmp_ge_i32 s45, s101
	s_cbranch_scc1 .Lmy_kexit_10
.LBB0_1944:
	s_add_u32 s98, s86, 0xfffc0080
	s_addc_u32 s99, s87, -1
	s_cmp_eq_u32 s5, s100
	s_cselect_b64 s[94:95], s[90:91], s[98:99]
	s_cselect_b64 s[96:97], s[92:93], s[88:89]
	s_add_i32 s45, s5, 2
	s_mov_b32 m0, s74
	ds_read_b128 v[164:167], v230
	global_load_lds_dwordx4 v144, s[86:87]
	s_mov_b32 m0, s75
	ds_read_b128 v[168:171], v230 offset:1024
	global_load_lds_dwordx4 v142, s[86:87]
	ds_read_b128 v[172:175], v230 offset:2048
	ds_read_b128 v[176:179], v230 offset:3072
	ds_read_b128 v[180:183], v231
	ds_read_b128 v[184:187], v231 offset:1024
	ds_read_b128 v[188:191], v231 offset:2048
	ds_read_b128 v[192:195], v231 offset:3072
	ds_read_b128 v[196:199], v160
	ds_read_b128 v[200:203], v160 offset:1024
	ds_read_b128 v[204:207], v160 offset:2048
	ds_read_b128 v[208:211], v160 offset:3072
	ds_read_b128 v[212:215], v160 offset:4096
	ds_read_b128 v[216:219], v160 offset:5120
	ds_read_b128 v[220:223], v160 offset:6144
	ds_read_b128 v[224:227], v160 offset:7168
	s_waitcnt vmcnt(8)
	s_waitcnt lgkmcnt(0)
	s_setprio 1
	s_barrier
	v_mfma_f32_16x16x32_bf16 v[122:125], v[164:167], v[196:199], v[122:125]
	v_mfma_f32_16x16x32_bf16 v[118:121], v[172:175], v[196:199], v[118:121]
	v_mfma_f32_16x16x32_bf16 v[110:113], v[164:167], v[204:207], v[110:113]
	v_mfma_f32_16x16x32_bf16 v[102:105], v[172:175], v[204:207], v[102:105]
	v_mfma_f32_16x16x32_bf16 v[94:97], v[164:167], v[212:215], v[94:97]
	v_mfma_f32_16x16x32_bf16 v[86:89], v[172:175], v[212:215], v[86:89]
	v_mfma_f32_16x16x32_bf16 v[78:81], v[164:167], v[220:223], v[78:81]
	v_mfma_f32_16x16x32_bf16 v[70:73], v[172:175], v[220:223], v[70:73]
	v_mfma_f32_16x16x32_bf16 v[122:125], v[168:171], v[200:203], v[122:125]
	v_mfma_f32_16x16x32_bf16 v[118:121], v[176:179], v[200:203], v[118:121]
	v_mfma_f32_16x16x32_bf16 v[110:113], v[168:171], v[208:211], v[110:113]
	v_mfma_f32_16x16x32_bf16 v[102:105], v[176:179], v[208:211], v[102:105]
	v_mfma_f32_16x16x32_bf16 v[94:97], v[168:171], v[216:219], v[94:97]
	v_mfma_f32_16x16x32_bf16 v[86:89], v[176:179], v[216:219], v[86:89]
	v_mfma_f32_16x16x32_bf16 v[78:81], v[168:171], v[224:227], v[78:81]
	v_mfma_f32_16x16x32_bf16 v[70:73], v[176:179], v[224:227], v[70:73]
	v_mfma_f32_16x16x32_bf16 v[126:129], v[180:183], v[196:199], v[126:129]
	v_mfma_f32_16x16x32_bf16 v[114:117], v[188:191], v[196:199], v[114:117]
	v_mfma_f32_16x16x32_bf16 v[106:109], v[180:183], v[204:207], v[106:109]
	v_mfma_f32_16x16x32_bf16 v[98:101], v[188:191], v[204:207], v[98:101]
	v_mfma_f32_16x16x32_bf16 v[90:93], v[180:183], v[212:215], v[90:93]
	v_mfma_f32_16x16x32_bf16 v[82:85], v[188:191], v[212:215], v[82:85]
	v_mfma_f32_16x16x32_bf16 v[74:77], v[180:183], v[220:223], v[74:77]
	v_mfma_f32_16x16x32_bf16 v[66:69], v[188:191], v[220:223], v[66:69]
	v_mfma_f32_16x16x32_bf16 v[126:129], v[184:187], v[200:203], v[126:129]
	v_mfma_f32_16x16x32_bf16 v[114:117], v[192:195], v[200:203], v[114:117]
	v_mfma_f32_16x16x32_bf16 v[106:109], v[184:187], v[208:211], v[106:109]
	v_mfma_f32_16x16x32_bf16 v[98:101], v[192:195], v[208:211], v[98:101]
	v_mfma_f32_16x16x32_bf16 v[90:93], v[184:187], v[216:219], v[90:93]
	v_mfma_f32_16x16x32_bf16 v[82:85], v[192:195], v[216:219], v[82:85]
	v_mfma_f32_16x16x32_bf16 v[74:77], v[184:187], v[224:227], v[74:77]
	v_mfma_f32_16x16x32_bf16 v[66:69], v[192:195], v[224:227], v[66:69]
	s_barrier
	s_setprio 0
	s_add_u32 s98, s96, 0x40000
	s_addc_u32 s99, s97, 0
	s_mov_b32 m0, s76
	ds_read_b128 v[196:199], v160 offset:16384
	global_load_lds_dwordx4 v132, s[96:97]
	s_mov_b32 m0, s77
	s_add_i32 s5, s73, s25
	global_load_lds_dwordx4 v136, s[96:97]
	s_mov_b32 m0, s5
	ds_read_b128 v[200:203], v160 offset:17408
	global_load_lds_dwordx4 v132, s[98:99]
	s_add_i32 m0, s5, 0x2000
	ds_read_b128 v[204:207], v160 offset:18432
	global_load_lds_dwordx4 v136, s[98:99]
	s_mov_b32 m0, s49
	ds_read_b128 v[208:211], v160 offset:19456
	global_load_lds_dwordx4 v130, s[94:95]
	s_mov_b32 m0, s58
	ds_read_b128 v[212:215], v160 offset:20480
	global_load_lds_dwordx4 v134, s[94:95]
	ds_read_b128 v[216:219], v160 offset:21504
	ds_read_b128 v[220:223], v160 offset:22528
	ds_read_b128 v[224:227], v160 offset:23552
	s_waitcnt vmcnt(8)
	s_waitcnt lgkmcnt(0)
	s_setprio 1
	s_barrier
	v_mfma_f32_16x16x32_bf16 v[62:65], v[164:167], v[196:199], v[62:65]
	v_mfma_f32_16x16x32_bf16 v[54:57], v[172:175], v[196:199], v[54:57]
	v_mfma_f32_16x16x32_bf16 v[46:49], v[164:167], v[204:207], v[46:49]
	v_mfma_f32_16x16x32_bf16 v[38:41], v[172:175], v[204:207], v[38:41]
	v_mfma_f32_16x16x32_bf16 v[30:33], v[164:167], v[212:215], v[30:33]
	v_mfma_f32_16x16x32_bf16 v[22:25], v[172:175], v[212:215], v[22:25]
	v_mfma_f32_16x16x32_bf16 v[14:17], v[164:167], v[220:223], v[14:17]
	v_mfma_f32_16x16x32_bf16 v[6:9], v[172:175], v[220:223], v[6:9]
	v_mfma_f32_16x16x32_bf16 v[62:65], v[168:171], v[200:203], v[62:65]
	v_mfma_f32_16x16x32_bf16 v[54:57], v[176:179], v[200:203], v[54:57]
	v_mfma_f32_16x16x32_bf16 v[46:49], v[168:171], v[208:211], v[46:49]
	v_mfma_f32_16x16x32_bf16 v[38:41], v[176:179], v[208:211], v[38:41]
	v_mfma_f32_16x16x32_bf16 v[30:33], v[168:171], v[216:219], v[30:33]
	v_mfma_f32_16x16x32_bf16 v[22:25], v[176:179], v[216:219], v[22:25]
	v_mfma_f32_16x16x32_bf16 v[14:17], v[168:171], v[224:227], v[14:17]
	v_mfma_f32_16x16x32_bf16 v[6:9], v[176:179], v[224:227], v[6:9]
	v_mfma_f32_16x16x32_bf16 v[58:61], v[180:183], v[196:199], v[58:61]
	v_mfma_f32_16x16x32_bf16 v[50:53], v[188:191], v[196:199], v[50:53]
	v_mfma_f32_16x16x32_bf16 v[42:45], v[180:183], v[204:207], v[42:45]
	v_mfma_f32_16x16x32_bf16 v[34:37], v[188:191], v[204:207], v[34:37]
	v_mfma_f32_16x16x32_bf16 v[26:29], v[180:183], v[212:215], v[26:29]
	v_mfma_f32_16x16x32_bf16 v[18:21], v[188:191], v[212:215], v[18:21]
	v_mfma_f32_16x16x32_bf16 v[10:13], v[180:183], v[220:223], v[10:13]
	v_mfma_f32_16x16x32_bf16 v[2:5], v[188:191], v[220:223], v[2:5]
	v_mfma_f32_16x16x32_bf16 v[58:61], v[184:187], v[200:203], v[58:61]
	v_mfma_f32_16x16x32_bf16 v[50:53], v[192:195], v[200:203], v[50:53]
	v_mfma_f32_16x16x32_bf16 v[42:45], v[184:187], v[208:211], v[42:45]
	v_mfma_f32_16x16x32_bf16 v[34:37], v[192:195], v[208:211], v[34:37]
	v_mfma_f32_16x16x32_bf16 v[26:29], v[184:187], v[216:219], v[26:29]
	v_mfma_f32_16x16x32_bf16 v[18:21], v[192:195], v[216:219], v[18:21]
	v_mfma_f32_16x16x32_bf16 v[10:13], v[184:187], v[224:227], v[10:13]
	v_mfma_f32_16x16x32_bf16 v[2:5], v[192:195], v[224:227], v[2:5]
	s_barrier
	s_setprio 0
	s_add_u32 s98, s94, 0x40000
	s_addc_u32 s99, s95, 0
	s_add_i32 s5, 0, 0x18000
	s_add_i32 s47, 0, 0x1c000
	s_mov_b32 m0, s59
	ds_read_b128 v[164:167], v232
	global_load_lds_dwordx4 v130, s[98:99]
	s_mov_b32 m0, s60
	ds_read_b128 v[168:171], v232 offset:1024
	global_load_lds_dwordx4 v134, s[98:99]
	ds_read_b128 v[172:175], v232 offset:2048
	ds_read_b128 v[176:179], v232 offset:3072
	ds_read_b128 v[180:183], v233
	ds_read_b128 v[184:187], v233 offset:1024
	ds_read_b128 v[188:191], v233 offset:2048
	ds_read_b128 v[192:195], v233 offset:3072
	ds_read_b128 v[196:199], v160 offset:32768
	ds_read_b128 v[200:203], v160 offset:33792
	ds_read_b128 v[204:207], v160 offset:34816
	ds_read_b128 v[208:211], v160 offset:35840
	ds_read_b128 v[212:215], v160 offset:36864
	ds_read_b128 v[216:219], v160 offset:37888
	ds_read_b128 v[220:223], v160 offset:38912
	ds_read_b128 v[224:227], v160 offset:39936
	s_waitcnt vmcnt(8)
	s_waitcnt lgkmcnt(0)
	s_setprio 1
	s_barrier
	v_mfma_f32_16x16x32_bf16 v[122:125], v[164:167], v[196:199], v[122:125]
	v_mfma_f32_16x16x32_bf16 v[118:121], v[172:175], v[196:199], v[118:121]
	v_mfma_f32_16x16x32_bf16 v[110:113], v[164:167], v[204:207], v[110:113]
	v_mfma_f32_16x16x32_bf16 v[102:105], v[172:175], v[204:207], v[102:105]
	v_mfma_f32_16x16x32_bf16 v[94:97], v[164:167], v[212:215], v[94:97]
	v_mfma_f32_16x16x32_bf16 v[86:89], v[172:175], v[212:215], v[86:89]
	v_mfma_f32_16x16x32_bf16 v[78:81], v[164:167], v[220:223], v[78:81]
	v_mfma_f32_16x16x32_bf16 v[70:73], v[172:175], v[220:223], v[70:73]
	v_mfma_f32_16x16x32_bf16 v[122:125], v[168:171], v[200:203], v[122:125]
	v_mfma_f32_16x16x32_bf16 v[118:121], v[176:179], v[200:203], v[118:121]
	v_mfma_f32_16x16x32_bf16 v[110:113], v[168:171], v[208:211], v[110:113]
	v_mfma_f32_16x16x32_bf16 v[102:105], v[176:179], v[208:211], v[102:105]
	v_mfma_f32_16x16x32_bf16 v[94:97], v[168:171], v[216:219], v[94:97]
	v_mfma_f32_16x16x32_bf16 v[86:89], v[176:179], v[216:219], v[86:89]
	v_mfma_f32_16x16x32_bf16 v[78:81], v[168:171], v[224:227], v[78:81]
	v_mfma_f32_16x16x32_bf16 v[70:73], v[176:179], v[224:227], v[70:73]
	v_mfma_f32_16x16x32_bf16 v[126:129], v[180:183], v[196:199], v[126:129]
	v_mfma_f32_16x16x32_bf16 v[114:117], v[188:191], v[196:199], v[114:117]
	v_mfma_f32_16x16x32_bf16 v[106:109], v[180:183], v[204:207], v[106:109]
	v_mfma_f32_16x16x32_bf16 v[98:101], v[188:191], v[204:207], v[98:101]
	v_mfma_f32_16x16x32_bf16 v[90:93], v[180:183], v[212:215], v[90:93]
	v_mfma_f32_16x16x32_bf16 v[82:85], v[188:191], v[212:215], v[82:85]
	v_mfma_f32_16x16x32_bf16 v[74:77], v[180:183], v[220:223], v[74:77]
	v_mfma_f32_16x16x32_bf16 v[66:69], v[188:191], v[220:223], v[66:69]
	v_mfma_f32_16x16x32_bf16 v[126:129], v[184:187], v[200:203], v[126:129]
	v_mfma_f32_16x16x32_bf16 v[114:117], v[192:195], v[200:203], v[114:117]
	v_mfma_f32_16x16x32_bf16 v[106:109], v[184:187], v[208:211], v[106:109]
	v_mfma_f32_16x16x32_bf16 v[98:101], v[192:195], v[208:211], v[98:101]
	v_mfma_f32_16x16x32_bf16 v[90:93], v[184:187], v[216:219], v[90:93]
	v_mfma_f32_16x16x32_bf16 v[82:85], v[192:195], v[216:219], v[82:85]
	v_mfma_f32_16x16x32_bf16 v[74:77], v[184:187], v[224:227], v[74:77]
	v_mfma_f32_16x16x32_bf16 v[66:69], v[192:195], v[224:227], v[66:69]
	s_barrier
	s_setprio 0
	s_add_u32 s96, s96, 0x80
	s_addc_u32 s97, s97, 0
	s_add_u32 s98, s96, 0x40000
	s_addc_u32 s99, s97, 0
	s_add_u32 s94, s94, 0x80
	s_addc_u32 s95, s95, 0
	s_add_i32 s5, s5, s25
	s_mov_b32 m0, s5
	ds_read_b128 v[196:199], v160 offset:49152
	global_load_lds_dwordx4 v132, s[96:97]
	s_add_i32 m0, s5, 0x2000
	s_add_i32 s5, s47, s25
	global_load_lds_dwordx4 v136, s[96:97]
	s_mov_b32 m0, s5
	ds_read_b128 v[200:203], v160 offset:50176
	global_load_lds_dwordx4 v132, s[98:99]
	s_add_i32 m0, s5, 0x2000
	ds_read_b128 v[204:207], v160 offset:51200
	global_load_lds_dwordx4 v136, s[98:99]
	s_mov_b32 m0, s61
	ds_read_b128 v[208:211], v160 offset:52224
	global_load_lds_dwordx4 v130, s[94:95]
	s_mov_b32 m0, s62
	ds_read_b128 v[212:215], v160 offset:53248
	global_load_lds_dwordx4 v134, s[94:95]
	ds_read_b128 v[216:219], v160 offset:54272
	ds_read_b128 v[220:223], v160 offset:55296
	ds_read_b128 v[224:227], v160 offset:56320
	s_waitcnt vmcnt(8)
	s_waitcnt lgkmcnt(0)
	s_setprio 1
	s_barrier
	v_mfma_f32_16x16x32_bf16 v[62:65], v[164:167], v[196:199], v[62:65]
	v_mfma_f32_16x16x32_bf16 v[54:57], v[172:175], v[196:199], v[54:57]
	v_mfma_f32_16x16x32_bf16 v[46:49], v[164:167], v[204:207], v[46:49]
	v_mfma_f32_16x16x32_bf16 v[38:41], v[172:175], v[204:207], v[38:41]
	v_mfma_f32_16x16x32_bf16 v[30:33], v[164:167], v[212:215], v[30:33]
	v_mfma_f32_16x16x32_bf16 v[22:25], v[172:175], v[212:215], v[22:25]
	v_mfma_f32_16x16x32_bf16 v[14:17], v[164:167], v[220:223], v[14:17]
	v_mfma_f32_16x16x32_bf16 v[6:9], v[172:175], v[220:223], v[6:9]
	v_mfma_f32_16x16x32_bf16 v[62:65], v[168:171], v[200:203], v[62:65]
	v_mfma_f32_16x16x32_bf16 v[54:57], v[176:179], v[200:203], v[54:57]
	v_mfma_f32_16x16x32_bf16 v[46:49], v[168:171], v[208:211], v[46:49]
	v_mfma_f32_16x16x32_bf16 v[38:41], v[176:179], v[208:211], v[38:41]
	v_mfma_f32_16x16x32_bf16 v[30:33], v[168:171], v[216:219], v[30:33]
	v_mfma_f32_16x16x32_bf16 v[22:25], v[176:179], v[216:219], v[22:25]
	v_mfma_f32_16x16x32_bf16 v[14:17], v[168:171], v[224:227], v[14:17]
	v_mfma_f32_16x16x32_bf16 v[6:9], v[176:179], v[224:227], v[6:9]
	v_mfma_f32_16x16x32_bf16 v[58:61], v[180:183], v[196:199], v[58:61]
	v_mfma_f32_16x16x32_bf16 v[50:53], v[188:191], v[196:199], v[50:53]
	v_mfma_f32_16x16x32_bf16 v[42:45], v[180:183], v[204:207], v[42:45]
	v_mfma_f32_16x16x32_bf16 v[34:37], v[188:191], v[204:207], v[34:37]
	v_mfma_f32_16x16x32_bf16 v[26:29], v[180:183], v[212:215], v[26:29]
	v_mfma_f32_16x16x32_bf16 v[18:21], v[188:191], v[212:215], v[18:21]
	v_mfma_f32_16x16x32_bf16 v[10:13], v[180:183], v[220:223], v[10:13]
	v_mfma_f32_16x16x32_bf16 v[2:5], v[188:191], v[220:223], v[2:5]
	v_mfma_f32_16x16x32_bf16 v[58:61], v[184:187], v[200:203], v[58:61]
	v_mfma_f32_16x16x32_bf16 v[50:53], v[192:195], v[200:203], v[50:53]
	v_mfma_f32_16x16x32_bf16 v[42:45], v[184:187], v[208:211], v[42:45]
	v_mfma_f32_16x16x32_bf16 v[34:37], v[192:195], v[208:211], v[34:37]
	v_mfma_f32_16x16x32_bf16 v[26:29], v[184:187], v[216:219], v[26:29]
	v_mfma_f32_16x16x32_bf16 v[18:21], v[192:195], v[216:219], v[18:21]
	v_mfma_f32_16x16x32_bf16 v[10:13], v[184:187], v[224:227], v[10:13]
	v_mfma_f32_16x16x32_bf16 v[2:5], v[192:195], v[224:227], v[2:5]
	s_barrier
	s_setprio 0
	s_mov_b32 s5, s45
	s_add_u32 s88, s88, 0x100
	s_addc_u32 s89, s89, 0
	s_add_u32 s86, s86, 0x100
	s_addc_u32 s87, s87, 0
	s_cmp_ge_i32 s45, s101
	s_cbranch_scc0 .LBB0_1944

.Lmy_nb_11:
	s_nop 0
	v_readfirstlane_b32 s86, v150
	v_readfirstlane_b32 s87, v151
	v_readfirstlane_b32 s88, v152
	v_readfirstlane_b32 s89, v153
	v_readfirstlane_b32 s90, v146
	v_readfirstlane_b32 s91, v147
	v_readfirstlane_b32 s92, v148
	v_readfirstlane_b32 s93, v149
	v_readfirstlane_b32 s100, v138
	v_readfirstlane_b32 s101, v156
	v_add_u32_e32 v230, s65, v141
	v_add_u32_e32 v231, s66, v141
	v_add_u32_e32 v232, 0x18000, v141
	v_add_u32_e32 v233, 0x1c000, v141
	s_add_u32 s98, s86, 0x100
	s_addc_u32 s99, s87, 0
	s_cmp_eq_u32 s4, s100
	s_cselect_b64 s[94:95], s[90:91], s[98:99]
	s_cselect_b64 s[96:97], s[92:93], s[88:89]
	s_add_i32 s5, s4, 2
	s_add_i32 m0, s44, 0xc000
	ds_read_b128 v[164:167], v230
	global_load_lds_dwordx4 v144, s[86:87]
	s_add_i32 m0, s44, 0xe000
	ds_read_b128 v[168:171], v230 offset:1024
	global_load_lds_dwordx4 v142, s[86:87]
	ds_read_b128 v[172:175], v230 offset:2048
	ds_read_b128 v[176:179], v230 offset:3072
	ds_read_b128 v[180:183], v231
	ds_read_b128 v[184:187], v231 offset:1024
	ds_read_b128 v[188:191], v231 offset:2048
	ds_read_b128 v[192:195], v231 offset:3072
	ds_read_b128 v[196:199], v160
	ds_read_b128 v[200:203], v160 offset:1024
	ds_read_b128 v[204:207], v160 offset:2048
	ds_read_b128 v[208:211], v160 offset:3072
	ds_read_b128 v[212:215], v160 offset:4096
	ds_read_b128 v[216:219], v160 offset:5120
	ds_read_b128 v[220:223], v160 offset:6144
	ds_read_b128 v[224:227], v160 offset:7168
	s_waitcnt vmcnt(8)
	s_waitcnt lgkmcnt(0)
	s_setprio 1
	s_barrier
	v_mfma_f32_16x16x32_bf16 v[122:125], v[164:167], v[196:199], 0
	v_mfma_f32_16x16x32_bf16 v[118:121], v[172:175], v[196:199], 0
	v_mfma_f32_16x16x32_bf16 v[110:113], v[164:167], v[204:207], 0
	v_mfma_f32_16x16x32_bf16 v[102:105], v[172:175], v[204:207], 0
	v_mfma_f32_16x16x32_bf16 v[94:97], v[164:167], v[212:215], 0
	v_mfma_f32_16x16x32_bf16 v[86:89], v[172:175], v[212:215], 0
	v_mfma_f32_16x16x32_bf16 v[78:81], v[164:167], v[220:223], 0
	v_mfma_f32_16x16x32_bf16 v[70:73], v[172:175], v[220:223], 0
	v_mfma_f32_16x16x32_bf16 v[122:125], v[168:171], v[200:203], v[122:125]
	v_mfma_f32_16x16x32_bf16 v[118:121], v[176:179], v[200:203], v[118:121]
	v_mfma_f32_16x16x32_bf16 v[110:113], v[168:171], v[208:211], v[110:113]
	v_mfma_f32_16x16x32_bf16 v[102:105], v[176:179], v[208:211], v[102:105]
	v_mfma_f32_16x16x32_bf16 v[94:97], v[168:171], v[216:219], v[94:97]
	v_mfma_f32_16x16x32_bf16 v[86:89], v[176:179], v[216:219], v[86:89]
	v_mfma_f32_16x16x32_bf16 v[78:81], v[168:171], v[224:227], v[78:81]
	v_mfma_f32_16x16x32_bf16 v[70:73], v[176:179], v[224:227], v[70:73]
	v_mfma_f32_16x16x32_bf16 v[126:129], v[180:183], v[196:199], 0
	v_mfma_f32_16x16x32_bf16 v[114:117], v[188:191], v[196:199], 0
	v_mfma_f32_16x16x32_bf16 v[106:109], v[180:183], v[204:207], 0
	v_mfma_f32_16x16x32_bf16 v[98:101], v[188:191], v[204:207], 0
	v_mfma_f32_16x16x32_bf16 v[90:93], v[180:183], v[212:215], 0
	v_mfma_f32_16x16x32_bf16 v[82:85], v[188:191], v[212:215], 0
	v_mfma_f32_16x16x32_bf16 v[74:77], v[180:183], v[220:223], 0
	v_mfma_f32_16x16x32_bf16 v[66:69], v[188:191], v[220:223], 0
	v_mfma_f32_16x16x32_bf16 v[126:129], v[184:187], v[200:203], v[126:129]
	v_mfma_f32_16x16x32_bf16 v[114:117], v[192:195], v[200:203], v[114:117]
	v_mfma_f32_16x16x32_bf16 v[106:109], v[184:187], v[208:211], v[106:109]
	v_mfma_f32_16x16x32_bf16 v[98:101], v[192:195], v[208:211], v[98:101]
	v_mfma_f32_16x16x32_bf16 v[90:93], v[184:187], v[216:219], v[90:93]
	v_mfma_f32_16x16x32_bf16 v[82:85], v[192:195], v[216:219], v[82:85]
	v_mfma_f32_16x16x32_bf16 v[74:77], v[184:187], v[224:227], v[74:77]
	v_mfma_f32_16x16x32_bf16 v[66:69], v[192:195], v[224:227], v[66:69]
	s_barrier
	s_setprio 0
	s_add_u32 s98, s96, 0xb0000
	s_addc_u32 s99, s97, 0
	s_add_i32 s4, s65, s21
	s_mov_b32 m0, s4
	ds_read_b128 v[196:199], v160 offset:16384
	global_load_lds_dwordx4 v132, s[96:97]
	s_add_i32 m0, s4, 0x2000
	s_add_i32 s4, s66, s21
	global_load_lds_dwordx4 v136, s[96:97]
	s_mov_b32 m0, s4
	ds_read_b128 v[200:203], v160 offset:17408
	global_load_lds_dwordx4 v132, s[98:99]
	s_add_i32 m0, s4, 0x2000
	ds_read_b128 v[204:207], v160 offset:18432
	global_load_lds_dwordx4 v136, s[98:99]
	s_mov_b32 m0, s44
	ds_read_b128 v[208:211], v160 offset:19456
	global_load_lds_dwordx4 v130, s[94:95]
	s_mov_b32 m0, s45
	ds_read_b128 v[212:215], v160 offset:20480
	global_load_lds_dwordx4 v134, s[94:95]
	ds_read_b128 v[216:219], v160 offset:21504
	ds_read_b128 v[220:223], v160 offset:22528
	ds_read_b128 v[224:227], v160 offset:23552
	s_waitcnt vmcnt(8)
	s_waitcnt lgkmcnt(0)
	s_setprio 1
	s_barrier
	v_mfma_f32_16x16x32_bf16 v[62:65], v[164:167], v[196:199], 0
	v_mfma_f32_16x16x32_bf16 v[54:57], v[172:175], v[196:199], 0
	v_mfma_f32_16x16x32_bf16 v[46:49], v[164:167], v[204:207], 0
	v_mfma_f32_16x16x32_bf16 v[38:41], v[172:175], v[204:207], 0
	v_mfma_f32_16x16x32_bf16 v[30:33], v[164:167], v[212:215], 0
	v_mfma_f32_16x16x32_bf16 v[22:25], v[172:175], v[212:215], 0
	v_mfma_f32_16x16x32_bf16 v[14:17], v[164:167], v[220:223], 0
	v_mfma_f32_16x16x32_bf16 v[6:9], v[172:175], v[220:223], 0
	v_mfma_f32_16x16x32_bf16 v[62:65], v[168:171], v[200:203], v[62:65]
	v_mfma_f32_16x16x32_bf16 v[54:57], v[176:179], v[200:203], v[54:57]
	v_mfma_f32_16x16x32_bf16 v[46:49], v[168:171], v[208:211], v[46:49]
	v_mfma_f32_16x16x32_bf16 v[38:41], v[176:179], v[208:211], v[38:41]
	v_mfma_f32_16x16x32_bf16 v[30:33], v[168:171], v[216:219], v[30:33]
	v_mfma_f32_16x16x32_bf16 v[22:25], v[176:179], v[216:219], v[22:25]
	v_mfma_f32_16x16x32_bf16 v[14:17], v[168:171], v[224:227], v[14:17]
	v_mfma_f32_16x16x32_bf16 v[6:9], v[176:179], v[224:227], v[6:9]
	v_mfma_f32_16x16x32_bf16 v[58:61], v[180:183], v[196:199], 0
	v_mfma_f32_16x16x32_bf16 v[50:53], v[188:191], v[196:199], 0
	v_mfma_f32_16x16x32_bf16 v[42:45], v[180:183], v[204:207], 0
	v_mfma_f32_16x16x32_bf16 v[34:37], v[188:191], v[204:207], 0
	v_mfma_f32_16x16x32_bf16 v[26:29], v[180:183], v[212:215], 0
	v_mfma_f32_16x16x32_bf16 v[18:21], v[188:191], v[212:215], 0
	v_mfma_f32_16x16x32_bf16 v[10:13], v[180:183], v[220:223], 0
	v_mfma_f32_16x16x32_bf16 v[2:5], v[188:191], v[220:223], 0
	v_mfma_f32_16x16x32_bf16 v[58:61], v[184:187], v[200:203], v[58:61]
	v_mfma_f32_16x16x32_bf16 v[50:53], v[192:195], v[200:203], v[50:53]
	v_mfma_f32_16x16x32_bf16 v[42:45], v[184:187], v[208:211], v[42:45]
	v_mfma_f32_16x16x32_bf16 v[34:37], v[192:195], v[208:211], v[34:37]
	v_mfma_f32_16x16x32_bf16 v[26:29], v[184:187], v[216:219], v[26:29]
	v_mfma_f32_16x16x32_bf16 v[18:21], v[192:195], v[216:219], v[18:21]
	v_mfma_f32_16x16x32_bf16 v[10:13], v[184:187], v[224:227], v[10:13]
	v_mfma_f32_16x16x32_bf16 v[2:5], v[192:195], v[224:227], v[2:5]
	s_barrier
	s_setprio 0
	s_add_u32 s98, s94, 0xb0000
	s_addc_u32 s99, s95, 0
	s_add_i32 s4, 0, 0x18000
	s_add_i32 s25, 0, 0x1c000
	s_mov_b32 m0, s46
	ds_read_b128 v[164:167], v232
	global_load_lds_dwordx4 v130, s[98:99]
	s_mov_b32 m0, s47
	ds_read_b128 v[168:171], v232 offset:1024
	global_load_lds_dwordx4 v134, s[98:99]
	ds_read_b128 v[172:175], v232 offset:2048
	ds_read_b128 v[176:179], v232 offset:3072
	ds_read_b128 v[180:183], v233
	ds_read_b128 v[184:187], v233 offset:1024
	ds_read_b128 v[188:191], v233 offset:2048
	ds_read_b128 v[192:195], v233 offset:3072
	ds_read_b128 v[196:199], v160 offset:32768
	ds_read_b128 v[200:203], v160 offset:33792
	ds_read_b128 v[204:207], v160 offset:34816
	ds_read_b128 v[208:211], v160 offset:35840
	ds_read_b128 v[212:215], v160 offset:36864
	ds_read_b128 v[216:219], v160 offset:37888
	ds_read_b128 v[220:223], v160 offset:38912
	ds_read_b128 v[224:227], v160 offset:39936
	s_waitcnt vmcnt(8)
	s_waitcnt lgkmcnt(0)
	s_setprio 1
	s_barrier
	v_mfma_f32_16x16x32_bf16 v[122:125], v[164:167], v[196:199], v[122:125]
	v_mfma_f32_16x16x32_bf16 v[118:121], v[172:175], v[196:199], v[118:121]
	v_mfma_f32_16x16x32_bf16 v[110:113], v[164:167], v[204:207], v[110:113]
	v_mfma_f32_16x16x32_bf16 v[102:105], v[172:175], v[204:207], v[102:105]
	v_mfma_f32_16x16x32_bf16 v[94:97], v[164:167], v[212:215], v[94:97]
	v_mfma_f32_16x16x32_bf16 v[86:89], v[172:175], v[212:215], v[86:89]
	v_mfma_f32_16x16x32_bf16 v[78:81], v[164:167], v[220:223], v[78:81]
	v_mfma_f32_16x16x32_bf16 v[70:73], v[172:175], v[220:223], v[70:73]
	v_mfma_f32_16x16x32_bf16 v[122:125], v[168:171], v[200:203], v[122:125]
	v_mfma_f32_16x16x32_bf16 v[118:121], v[176:179], v[200:203], v[118:121]
	v_mfma_f32_16x16x32_bf16 v[110:113], v[168:171], v[208:211], v[110:113]
	v_mfma_f32_16x16x32_bf16 v[102:105], v[176:179], v[208:211], v[102:105]
	v_mfma_f32_16x16x32_bf16 v[94:97], v[168:171], v[216:219], v[94:97]
	v_mfma_f32_16x16x32_bf16 v[86:89], v[176:179], v[216:219], v[86:89]
	v_mfma_f32_16x16x32_bf16 v[78:81], v[168:171], v[224:227], v[78:81]
	v_mfma_f32_16x16x32_bf16 v[70:73], v[176:179], v[224:227], v[70:73]
	v_mfma_f32_16x16x32_bf16 v[126:129], v[180:183], v[196:199], v[126:129]
	v_mfma_f32_16x16x32_bf16 v[114:117], v[188:191], v[196:199], v[114:117]
	v_mfma_f32_16x16x32_bf16 v[106:109], v[180:183], v[204:207], v[106:109]
	v_mfma_f32_16x16x32_bf16 v[98:101], v[188:191], v[204:207], v[98:101]
	v_mfma_f32_16x16x32_bf16 v[90:93], v[180:183], v[212:215], v[90:93]
	v_mfma_f32_16x16x32_bf16 v[82:85], v[188:191], v[212:215], v[82:85]
	v_mfma_f32_16x16x32_bf16 v[74:77], v[180:183], v[220:223], v[74:77]
	v_mfma_f32_16x16x32_bf16 v[66:69], v[188:191], v[220:223], v[66:69]
	v_mfma_f32_16x16x32_bf16 v[126:129], v[184:187], v[200:203], v[126:129]
	v_mfma_f32_16x16x32_bf16 v[114:117], v[192:195], v[200:203], v[114:117]
	v_mfma_f32_16x16x32_bf16 v[106:109], v[184:187], v[208:211], v[106:109]
	v_mfma_f32_16x16x32_bf16 v[98:101], v[192:195], v[208:211], v[98:101]
	v_mfma_f32_16x16x32_bf16 v[90:93], v[184:187], v[216:219], v[90:93]
	v_mfma_f32_16x16x32_bf16 v[82:85], v[192:195], v[216:219], v[82:85]
	v_mfma_f32_16x16x32_bf16 v[74:77], v[184:187], v[224:227], v[74:77]
	v_mfma_f32_16x16x32_bf16 v[66:69], v[192:195], v[224:227], v[66:69]
	s_barrier
	s_setprio 0
	s_add_u32 s96, s96, 0x80
	s_addc_u32 s97, s97, 0
	s_add_u32 s98, s96, 0xb0000
	s_addc_u32 s99, s97, 0
	s_add_u32 s94, s94, 0x80
	s_addc_u32 s95, s95, 0
	s_add_i32 s4, s4, s21
	s_mov_b32 m0, s4
	ds_read_b128 v[196:199], v160 offset:49152
	global_load_lds_dwordx4 v132, s[96:97]
	s_add_i32 m0, s4, 0x2000
	s_add_i32 s4, s25, s21
	global_load_lds_dwordx4 v136, s[96:97]
	s_mov_b32 m0, s4
	ds_read_b128 v[200:203], v160 offset:50176
	global_load_lds_dwordx4 v132, s[98:99]
	s_add_i32 m0, s4, 0x2000
	ds_read_b128 v[204:207], v160 offset:51200
	global_load_lds_dwordx4 v136, s[98:99]
	s_mov_b32 m0, s57
	ds_read_b128 v[208:211], v160 offset:52224
	global_load_lds_dwordx4 v130, s[94:95]
	s_mov_b32 m0, s58
	ds_read_b128 v[212:215], v160 offset:53248
	global_load_lds_dwordx4 v134, s[94:95]
	ds_read_b128 v[216:219], v160 offset:54272
	ds_read_b128 v[220:223], v160 offset:55296
	ds_read_b128 v[224:227], v160 offset:56320
	s_waitcnt vmcnt(8)
	s_waitcnt lgkmcnt(0)
	s_setprio 1
	s_barrier
	v_mfma_f32_16x16x32_bf16 v[62:65], v[164:167], v[196:199], v[62:65]
	v_mfma_f32_16x16x32_bf16 v[54:57], v[172:175], v[196:199], v[54:57]
	v_mfma_f32_16x16x32_bf16 v[46:49], v[164:167], v[204:207], v[46:49]
	v_mfma_f32_16x16x32_bf16 v[38:41], v[172:175], v[204:207], v[38:41]
	v_mfma_f32_16x16x32_bf16 v[30:33], v[164:167], v[212:215], v[30:33]
	v_mfma_f32_16x16x32_bf16 v[22:25], v[172:175], v[212:215], v[22:25]
	v_mfma_f32_16x16x32_bf16 v[14:17], v[164:167], v[220:223], v[14:17]
	v_mfma_f32_16x16x32_bf16 v[6:9], v[172:175], v[220:223], v[6:9]
	v_mfma_f32_16x16x32_bf16 v[62:65], v[168:171], v[200:203], v[62:65]
	v_mfma_f32_16x16x32_bf16 v[54:57], v[176:179], v[200:203], v[54:57]
	v_mfma_f32_16x16x32_bf16 v[46:49], v[168:171], v[208:211], v[46:49]
	v_mfma_f32_16x16x32_bf16 v[38:41], v[176:179], v[208:211], v[38:41]
	v_mfma_f32_16x16x32_bf16 v[30:33], v[168:171], v[216:219], v[30:33]
	v_mfma_f32_16x16x32_bf16 v[22:25], v[176:179], v[216:219], v[22:25]
	v_mfma_f32_16x16x32_bf16 v[14:17], v[168:171], v[224:227], v[14:17]
	v_mfma_f32_16x16x32_bf16 v[6:9], v[176:179], v[224:227], v[6:9]
	v_mfma_f32_16x16x32_bf16 v[58:61], v[180:183], v[196:199], v[58:61]
	v_mfma_f32_16x16x32_bf16 v[50:53], v[188:191], v[196:199], v[50:53]
	v_mfma_f32_16x16x32_bf16 v[42:45], v[180:183], v[204:207], v[42:45]
	v_mfma_f32_16x16x32_bf16 v[34:37], v[188:191], v[204:207], v[34:37]
	v_mfma_f32_16x16x32_bf16 v[26:29], v[180:183], v[212:215], v[26:29]
	v_mfma_f32_16x16x32_bf16 v[18:21], v[188:191], v[212:215], v[18:21]
	v_mfma_f32_16x16x32_bf16 v[10:13], v[180:183], v[220:223], v[10:13]
	v_mfma_f32_16x16x32_bf16 v[2:5], v[188:191], v[220:223], v[2:5]
	v_mfma_f32_16x16x32_bf16 v[58:61], v[184:187], v[200:203], v[58:61]
	v_mfma_f32_16x16x32_bf16 v[50:53], v[192:195], v[200:203], v[50:53]
	v_mfma_f32_16x16x32_bf16 v[42:45], v[184:187], v[208:211], v[42:45]
	v_mfma_f32_16x16x32_bf16 v[34:37], v[192:195], v[208:211], v[34:37]
	v_mfma_f32_16x16x32_bf16 v[26:29], v[184:187], v[216:219], v[26:29]
	v_mfma_f32_16x16x32_bf16 v[18:21], v[192:195], v[216:219], v[18:21]
	v_mfma_f32_16x16x32_bf16 v[10:13], v[184:187], v[224:227], v[10:13]
	v_mfma_f32_16x16x32_bf16 v[2:5], v[192:195], v[224:227], v[2:5]
	s_barrier
	s_setprio 0
	s_mov_b32 s4, s5
	s_add_u32 s88, s88, 0x100
	s_addc_u32 s89, s89, 0
	s_add_u32 s86, s86, 0x100
	s_addc_u32 s87, s87, 0
	s_cmp_ge_i32 s5, s101
	s_cbranch_scc1 .Lmy_kexit_11
.LBB0_2075:
	s_add_u32 s98, s86, 0x100
	s_addc_u32 s99, s87, 0
	s_cmp_eq_u32 s4, s100
	s_cselect_b64 s[94:95], s[90:91], s[98:99]
	s_cselect_b64 s[96:97], s[92:93], s[88:89]
	s_add_i32 s5, s4, 2
	s_add_i32 m0, s44, 0xc000
	ds_read_b128 v[164:167], v230
	global_load_lds_dwordx4 v144, s[86:87]
	s_add_i32 m0, s44, 0xe000
	ds_read_b128 v[168:171], v230 offset:1024
	global_load_lds_dwordx4 v142, s[86:87]
	ds_read_b128 v[172:175], v230 offset:2048
	ds_read_b128 v[176:179], v230 offset:3072
	ds_read_b128 v[180:183], v231
	ds_read_b128 v[184:187], v231 offset:1024
	ds_read_b128 v[188:191], v231 offset:2048
	ds_read_b128 v[192:195], v231 offset:3072
	ds_read_b128 v[196:199], v160
	ds_read_b128 v[200:203], v160 offset:1024
	ds_read_b128 v[204:207], v160 offset:2048
	ds_read_b128 v[208:211], v160 offset:3072
	ds_read_b128 v[212:215], v160 offset:4096
	ds_read_b128 v[216:219], v160 offset:5120
	ds_read_b128 v[220:223], v160 offset:6144
	ds_read_b128 v[224:227], v160 offset:7168
	s_waitcnt vmcnt(8)
	s_waitcnt lgkmcnt(0)
	s_setprio 1
	s_barrier
	v_mfma_f32_16x16x32_bf16 v[122:125], v[164:167], v[196:199], v[122:125]
	v_mfma_f32_16x16x32_bf16 v[118:121], v[172:175], v[196:199], v[118:121]
	v_mfma_f32_16x16x32_bf16 v[110:113], v[164:167], v[204:207], v[110:113]
	v_mfma_f32_16x16x32_bf16 v[102:105], v[172:175], v[204:207], v[102:105]
	v_mfma_f32_16x16x32_bf16 v[94:97], v[164:167], v[212:215], v[94:97]
	v_mfma_f32_16x16x32_bf16 v[86:89], v[172:175], v[212:215], v[86:89]
	v_mfma_f32_16x16x32_bf16 v[78:81], v[164:167], v[220:223], v[78:81]
	v_mfma_f32_16x16x32_bf16 v[70:73], v[172:175], v[220:223], v[70:73]
	v_mfma_f32_16x16x32_bf16 v[122:125], v[168:171], v[200:203], v[122:125]
	v_mfma_f32_16x16x32_bf16 v[118:121], v[176:179], v[200:203], v[118:121]
	v_mfma_f32_16x16x32_bf16 v[110:113], v[168:171], v[208:211], v[110:113]
	v_mfma_f32_16x16x32_bf16 v[102:105], v[176:179], v[208:211], v[102:105]
	v_mfma_f32_16x16x32_bf16 v[94:97], v[168:171], v[216:219], v[94:97]
	v_mfma_f32_16x16x32_bf16 v[86:89], v[176:179], v[216:219], v[86:89]
	v_mfma_f32_16x16x32_bf16 v[78:81], v[168:171], v[224:227], v[78:81]
	v_mfma_f32_16x16x32_bf16 v[70:73], v[176:179], v[224:227], v[70:73]
	v_mfma_f32_16x16x32_bf16 v[126:129], v[180:183], v[196:199], v[126:129]
	v_mfma_f32_16x16x32_bf16 v[114:117], v[188:191], v[196:199], v[114:117]
	v_mfma_f32_16x16x32_bf16 v[106:109], v[180:183], v[204:207], v[106:109]
	v_mfma_f32_16x16x32_bf16 v[98:101], v[188:191], v[204:207], v[98:101]
	v_mfma_f32_16x16x32_bf16 v[90:93], v[180:183], v[212:215], v[90:93]
	v_mfma_f32_16x16x32_bf16 v[82:85], v[188:191], v[212:215], v[82:85]
	v_mfma_f32_16x16x32_bf16 v[74:77], v[180:183], v[220:223], v[74:77]
	v_mfma_f32_16x16x32_bf16 v[66:69], v[188:191], v[220:223], v[66:69]
	v_mfma_f32_16x16x32_bf16 v[126:129], v[184:187], v[200:203], v[126:129]
	v_mfma_f32_16x16x32_bf16 v[114:117], v[192:195], v[200:203], v[114:117]
	v_mfma_f32_16x16x32_bf16 v[106:109], v[184:187], v[208:211], v[106:109]
	v_mfma_f32_16x16x32_bf16 v[98:101], v[192:195], v[208:211], v[98:101]
	v_mfma_f32_16x16x32_bf16 v[90:93], v[184:187], v[216:219], v[90:93]
	v_mfma_f32_16x16x32_bf16 v[82:85], v[192:195], v[216:219], v[82:85]
	v_mfma_f32_16x16x32_bf16 v[74:77], v[184:187], v[224:227], v[74:77]
	v_mfma_f32_16x16x32_bf16 v[66:69], v[192:195], v[224:227], v[66:69]
	s_barrier
	s_setprio 0
	s_add_u32 s98, s96, 0xb0000
	s_addc_u32 s99, s97, 0
	s_add_i32 s4, s65, s21
	s_mov_b32 m0, s4
	ds_read_b128 v[196:199], v160 offset:16384
	global_load_lds_dwordx4 v132, s[96:97]
	s_add_i32 m0, s4, 0x2000
	s_add_i32 s4, s66, s21
	global_load_lds_dwordx4 v136, s[96:97]
	s_mov_b32 m0, s4
	ds_read_b128 v[200:203], v160 offset:17408
	global_load_lds_dwordx4 v132, s[98:99]
	s_add_i32 m0, s4, 0x2000
	ds_read_b128 v[204:207], v160 offset:18432
	global_load_lds_dwordx4 v136, s[98:99]
	s_mov_b32 m0, s44
	ds_read_b128 v[208:211], v160 offset:19456
	global_load_lds_dwordx4 v130, s[94:95]
	s_mov_b32 m0, s45
	ds_read_b128 v[212:215], v160 offset:20480
	global_load_lds_dwordx4 v134, s[94:95]
	ds_read_b128 v[216:219], v160 offset:21504
	ds_read_b128 v[220:223], v160 offset:22528
	ds_read_b128 v[224:227], v160 offset:23552
	s_waitcnt vmcnt(8)
	s_waitcnt lgkmcnt(0)
	s_setprio 1
	s_barrier
	v_mfma_f32_16x16x32_bf16 v[62:65], v[164:167], v[196:199], v[62:65]
	v_mfma_f32_16x16x32_bf16 v[54:57], v[172:175], v[196:199], v[54:57]
	v_mfma_f32_16x16x32_bf16 v[46:49], v[164:167], v[204:207], v[46:49]
	v_mfma_f32_16x16x32_bf16 v[38:41], v[172:175], v[204:207], v[38:41]
	v_mfma_f32_16x16x32_bf16 v[30:33], v[164:167], v[212:215], v[30:33]
	v_mfma_f32_16x16x32_bf16 v[22:25], v[172:175], v[212:215], v[22:25]
	v_mfma_f32_16x16x32_bf16 v[14:17], v[164:167], v[220:223], v[14:17]
	v_mfma_f32_16x16x32_bf16 v[6:9], v[172:175], v[220:223], v[6:9]
	v_mfma_f32_16x16x32_bf16 v[62:65], v[168:171], v[200:203], v[62:65]
	v_mfma_f32_16x16x32_bf16 v[54:57], v[176:179], v[200:203], v[54:57]
	v_mfma_f32_16x16x32_bf16 v[46:49], v[168:171], v[208:211], v[46:49]
	v_mfma_f32_16x16x32_bf16 v[38:41], v[176:179], v[208:211], v[38:41]
	v_mfma_f32_16x16x32_bf16 v[30:33], v[168:171], v[216:219], v[30:33]
	v_mfma_f32_16x16x32_bf16 v[22:25], v[176:179], v[216:219], v[22:25]
	v_mfma_f32_16x16x32_bf16 v[14:17], v[168:171], v[224:227], v[14:17]
	v_mfma_f32_16x16x32_bf16 v[6:9], v[176:179], v[224:227], v[6:9]
	v_mfma_f32_16x16x32_bf16 v[58:61], v[180:183], v[196:199], v[58:61]
	v_mfma_f32_16x16x32_bf16 v[50:53], v[188:191], v[196:199], v[50:53]
	v_mfma_f32_16x16x32_bf16 v[42:45], v[180:183], v[204:207], v[42:45]
	v_mfma_f32_16x16x32_bf16 v[34:37], v[188:191], v[204:207], v[34:37]
	v_mfma_f32_16x16x32_bf16 v[26:29], v[180:183], v[212:215], v[26:29]
	v_mfma_f32_16x16x32_bf16 v[18:21], v[188:191], v[212:215], v[18:21]
	v_mfma_f32_16x16x32_bf16 v[10:13], v[180:183], v[220:223], v[10:13]
	v_mfma_f32_16x16x32_bf16 v[2:5], v[188:191], v[220:223], v[2:5]
	v_mfma_f32_16x16x32_bf16 v[58:61], v[184:187], v[200:203], v[58:61]
	v_mfma_f32_16x16x32_bf16 v[50:53], v[192:195], v[200:203], v[50:53]
	v_mfma_f32_16x16x32_bf16 v[42:45], v[184:187], v[208:211], v[42:45]
	v_mfma_f32_16x16x32_bf16 v[34:37], v[192:195], v[208:211], v[34:37]
	v_mfma_f32_16x16x32_bf16 v[26:29], v[184:187], v[216:219], v[26:29]
	v_mfma_f32_16x16x32_bf16 v[18:21], v[192:195], v[216:219], v[18:21]
	v_mfma_f32_16x16x32_bf16 v[10:13], v[184:187], v[224:227], v[10:13]
	v_mfma_f32_16x16x32_bf16 v[2:5], v[192:195], v[224:227], v[2:5]
	s_barrier
	s_setprio 0
	s_add_u32 s98, s94, 0xb0000
	s_addc_u32 s99, s95, 0
	s_add_i32 s4, 0, 0x18000
	s_add_i32 s25, 0, 0x1c000
	s_mov_b32 m0, s46
	ds_read_b128 v[164:167], v232
	global_load_lds_dwordx4 v130, s[98:99]
	s_mov_b32 m0, s47
	ds_read_b128 v[168:171], v232 offset:1024
	global_load_lds_dwordx4 v134, s[98:99]
	ds_read_b128 v[172:175], v232 offset:2048
	ds_read_b128 v[176:179], v232 offset:3072
	ds_read_b128 v[180:183], v233
	ds_read_b128 v[184:187], v233 offset:1024
	ds_read_b128 v[188:191], v233 offset:2048
	ds_read_b128 v[192:195], v233 offset:3072
	ds_read_b128 v[196:199], v160 offset:32768
	ds_read_b128 v[200:203], v160 offset:33792
	ds_read_b128 v[204:207], v160 offset:34816
	ds_read_b128 v[208:211], v160 offset:35840
	ds_read_b128 v[212:215], v160 offset:36864
	ds_read_b128 v[216:219], v160 offset:37888
	ds_read_b128 v[220:223], v160 offset:38912
	ds_read_b128 v[224:227], v160 offset:39936
	s_waitcnt vmcnt(8)
	s_waitcnt lgkmcnt(0)
	s_setprio 1
	s_barrier
	v_mfma_f32_16x16x32_bf16 v[122:125], v[164:167], v[196:199], v[122:125]
	v_mfma_f32_16x16x32_bf16 v[118:121], v[172:175], v[196:199], v[118:121]
	v_mfma_f32_16x16x32_bf16 v[110:113], v[164:167], v[204:207], v[110:113]
	v_mfma_f32_16x16x32_bf16 v[102:105], v[172:175], v[204:207], v[102:105]
	v_mfma_f32_16x16x32_bf16 v[94:97], v[164:167], v[212:215], v[94:97]
	v_mfma_f32_16x16x32_bf16 v[86:89], v[172:175], v[212:215], v[86:89]
	v_mfma_f32_16x16x32_bf16 v[78:81], v[164:167], v[220:223], v[78:81]
	v_mfma_f32_16x16x32_bf16 v[70:73], v[172:175], v[220:223], v[70:73]
	v_mfma_f32_16x16x32_bf16 v[122:125], v[168:171], v[200:203], v[122:125]
	v_mfma_f32_16x16x32_bf16 v[118:121], v[176:179], v[200:203], v[118:121]
	v_mfma_f32_16x16x32_bf16 v[110:113], v[168:171], v[208:211], v[110:113]
	v_mfma_f32_16x16x32_bf16 v[102:105], v[176:179], v[208:211], v[102:105]
	v_mfma_f32_16x16x32_bf16 v[94:97], v[168:171], v[216:219], v[94:97]
	v_mfma_f32_16x16x32_bf16 v[86:89], v[176:179], v[216:219], v[86:89]
	v_mfma_f32_16x16x32_bf16 v[78:81], v[168:171], v[224:227], v[78:81]
	v_mfma_f32_16x16x32_bf16 v[70:73], v[176:179], v[224:227], v[70:73]
	v_mfma_f32_16x16x32_bf16 v[126:129], v[180:183], v[196:199], v[126:129]
	v_mfma_f32_16x16x32_bf16 v[114:117], v[188:191], v[196:199], v[114:117]
	v_mfma_f32_16x16x32_bf16 v[106:109], v[180:183], v[204:207], v[106:109]
	v_mfma_f32_16x16x32_bf16 v[98:101], v[188:191], v[204:207], v[98:101]
	v_mfma_f32_16x16x32_bf16 v[90:93], v[180:183], v[212:215], v[90:93]
	v_mfma_f32_16x16x32_bf16 v[82:85], v[188:191], v[212:215], v[82:85]
	v_mfma_f32_16x16x32_bf16 v[74:77], v[180:183], v[220:223], v[74:77]
	v_mfma_f32_16x16x32_bf16 v[66:69], v[188:191], v[220:223], v[66:69]
	v_mfma_f32_16x16x32_bf16 v[126:129], v[184:187], v[200:203], v[126:129]
	v_mfma_f32_16x16x32_bf16 v[114:117], v[192:195], v[200:203], v[114:117]
	v_mfma_f32_16x16x32_bf16 v[106:109], v[184:187], v[208:211], v[106:109]
	v_mfma_f32_16x16x32_bf16 v[98:101], v[192:195], v[208:211], v[98:101]
	v_mfma_f32_16x16x32_bf16 v[90:93], v[184:187], v[216:219], v[90:93]
	v_mfma_f32_16x16x32_bf16 v[82:85], v[192:195], v[216:219], v[82:85]
	v_mfma_f32_16x16x32_bf16 v[74:77], v[184:187], v[224:227], v[74:77]
	v_mfma_f32_16x16x32_bf16 v[66:69], v[192:195], v[224:227], v[66:69]
	s_barrier
	s_setprio 0
	s_add_u32 s96, s96, 0x80
	s_addc_u32 s97, s97, 0
	s_add_u32 s98, s96, 0xb0000
	s_addc_u32 s99, s97, 0
	s_add_u32 s94, s94, 0x80
	s_addc_u32 s95, s95, 0
	s_add_i32 s4, s4, s21
	s_mov_b32 m0, s4
	ds_read_b128 v[196:199], v160 offset:49152
	global_load_lds_dwordx4 v132, s[96:97]
	s_add_i32 m0, s4, 0x2000
	s_add_i32 s4, s25, s21
	global_load_lds_dwordx4 v136, s[96:97]
	s_mov_b32 m0, s4
	ds_read_b128 v[200:203], v160 offset:50176
	global_load_lds_dwordx4 v132, s[98:99]
	s_add_i32 m0, s4, 0x2000
	ds_read_b128 v[204:207], v160 offset:51200
	global_load_lds_dwordx4 v136, s[98:99]
	s_mov_b32 m0, s57
	ds_read_b128 v[208:211], v160 offset:52224
	global_load_lds_dwordx4 v130, s[94:95]
	s_mov_b32 m0, s58
	ds_read_b128 v[212:215], v160 offset:53248
	global_load_lds_dwordx4 v134, s[94:95]
	ds_read_b128 v[216:219], v160 offset:54272
	ds_read_b128 v[220:223], v160 offset:55296
	ds_read_b128 v[224:227], v160 offset:56320
	s_waitcnt vmcnt(8)
	s_waitcnt lgkmcnt(0)
	s_setprio 1
	s_barrier
	v_mfma_f32_16x16x32_bf16 v[62:65], v[164:167], v[196:199], v[62:65]
	v_mfma_f32_16x16x32_bf16 v[54:57], v[172:175], v[196:199], v[54:57]
	v_mfma_f32_16x16x32_bf16 v[46:49], v[164:167], v[204:207], v[46:49]
	v_mfma_f32_16x16x32_bf16 v[38:41], v[172:175], v[204:207], v[38:41]
	v_mfma_f32_16x16x32_bf16 v[30:33], v[164:167], v[212:215], v[30:33]
	v_mfma_f32_16x16x32_bf16 v[22:25], v[172:175], v[212:215], v[22:25]
	v_mfma_f32_16x16x32_bf16 v[14:17], v[164:167], v[220:223], v[14:17]
	v_mfma_f32_16x16x32_bf16 v[6:9], v[172:175], v[220:223], v[6:9]
	v_mfma_f32_16x16x32_bf16 v[62:65], v[168:171], v[200:203], v[62:65]
	v_mfma_f32_16x16x32_bf16 v[54:57], v[176:179], v[200:203], v[54:57]
	v_mfma_f32_16x16x32_bf16 v[46:49], v[168:171], v[208:211], v[46:49]
	v_mfma_f32_16x16x32_bf16 v[38:41], v[176:179], v[208:211], v[38:41]
	v_mfma_f32_16x16x32_bf16 v[30:33], v[168:171], v[216:219], v[30:33]
	v_mfma_f32_16x16x32_bf16 v[22:25], v[176:179], v[216:219], v[22:25]
	v_mfma_f32_16x16x32_bf16 v[14:17], v[168:171], v[224:227], v[14:17]
	v_mfma_f32_16x16x32_bf16 v[6:9], v[176:179], v[224:227], v[6:9]
	v_mfma_f32_16x16x32_bf16 v[58:61], v[180:183], v[196:199], v[58:61]
	v_mfma_f32_16x16x32_bf16 v[50:53], v[188:191], v[196:199], v[50:53]
	v_mfma_f32_16x16x32_bf16 v[42:45], v[180:183], v[204:207], v[42:45]
	v_mfma_f32_16x16x32_bf16 v[34:37], v[188:191], v[204:207], v[34:37]
	v_mfma_f32_16x16x32_bf16 v[26:29], v[180:183], v[212:215], v[26:29]
	v_mfma_f32_16x16x32_bf16 v[18:21], v[188:191], v[212:215], v[18:21]
	v_mfma_f32_16x16x32_bf16 v[10:13], v[180:183], v[220:223], v[10:13]
	v_mfma_f32_16x16x32_bf16 v[2:5], v[188:191], v[220:223], v[2:5]
	v_mfma_f32_16x16x32_bf16 v[58:61], v[184:187], v[200:203], v[58:61]
	v_mfma_f32_16x16x32_bf16 v[50:53], v[192:195], v[200:203], v[50:53]
	v_mfma_f32_16x16x32_bf16 v[42:45], v[184:187], v[208:211], v[42:45]
	v_mfma_f32_16x16x32_bf16 v[34:37], v[192:195], v[208:211], v[34:37]
	v_mfma_f32_16x16x32_bf16 v[26:29], v[184:187], v[216:219], v[26:29]
	v_mfma_f32_16x16x32_bf16 v[18:21], v[192:195], v[216:219], v[18:21]
	v_mfma_f32_16x16x32_bf16 v[10:13], v[184:187], v[224:227], v[10:13]
	v_mfma_f32_16x16x32_bf16 v[2:5], v[192:195], v[224:227], v[2:5]
	s_barrier
	s_setprio 0
	s_mov_b32 s4, s5
	s_add_u32 s88, s88, 0x100
	s_addc_u32 s89, s89, 0
	s_add_u32 s86, s86, 0x100
	s_addc_u32 s87, s87, 0
	s_cmp_ge_i32 s5, s101
	s_cbranch_scc0 .LBB0_2075
